# K-loops: LDS read pacing wait loosened from lgkmcnt(8) to lgkmcnt(12) before the 13th read of a burst
# baseline (speedup 1.0000x reference)
; #define PG8_STAGE(bufoff, gbase, voff) do { _Pragma("unroll") for (int _i = 0; _i < 2; ++_i) \
;         __builtin_amdgcn_global_load_lds((const unsigned*)((const char*)(gbase) + (voff)[_i]), (PG8_LAS unsigned*)(lds + (bufoff) + ldsw + _i * 8192), 16, 0, 0); } while (0)
; #define PG8_LDA(dst, b, h) do { _Pragma("unroll") for (int m = 0; m < 4; ++m) _Pragma("unroll") for (int k = 0; k < 2; ++k) dst[m][k] = *(const PG8_LAS bf16x8*)(lds + PG8_SA(b, h) + aoff + m * 2048 + k * 1024); } while (0)
; #define PG8_LDB(dst, b, h) do { _Pragma("unroll") for (int n = 0; n < 2; ++n) _Pragma("unroll") for (int k = 0; k < 2; ++k) dst[n][k] = *(const PG8_LAS bf16x8*)(lds + PG8_SB(b, h) + boff + n * 2048 + k * 1024); } while (0)
; #define PG8_WAIT_V(n) asm volatile("s_waitcnt vmcnt(" #n ")" ::: "memory")
; #define PG8_WAIT_L(n) asm volatile("s_waitcnt lgkmcnt(" #n ")" ::: "memory")
; #define PG8_BAR __builtin_amdgcn_s_barrier()
; #define PG8_SCHED __builtin_amdgcn_sched_barrier(0)
; template <class Epi, class Sched>
; __device__ __forceinline__ void gemm_phase(PG8_LAS unsigned char* lds, const Gemm g, const Sched& S, const Epi& E) {
;     ...
;         const bool has_next = S.next(ui + 1, nxt);
;         const char* nA = has_next ? (const char*)g.A + (size_t)nxt.pm * tstep : cA; const char* nB = has_next ? (const char*)g.Bt + (size_t)nxt.pn * tstep : cB;
;         for (int t = 0; t < nt; t += 2) {
;             const bool last = (t == nt - 2);
;             const char* a1 = cA + (size_t)(t + 1) * kstep;
;             const char* a2 = last ? nA : cA + (size_t)(t + 2) * kstep; const char* b2 = last ? nB : cB + (size_t)(t + 2) * kstep;
;             const char* a3 = a2 + kstep; const char* b3 = b2 + kstep;
;             if (last && has_next) S.a_ready(nxt);
;             PG8_LDB(B0, 0, 0); PG8_SCHED; PG8_LDA(At, 0, 0); PG8_STAGE(PG8_SA(1, 1), a1 + hstep, voffA);
;             PG8_WAIT_L(8); PG8_BAR; PG8_WAIT_L(0); PG8_MMA(0, 0, At, B0); PG8_BAR; PG8_SCHED;
;             PG8_LDB(B1, 0, 1); PG8_STAGE(PG8_SB(0, 0), b2, voffB);
;             PG8_BAR; PG8_WAIT_L(0); PG8_MMA(0, 1, At, B1); PG8_BAR;
;             PG8_LDA(At, 0, 1); PG8_STAGE(PG8_SA(0, 0), a2, voffA);
;             PG8_BAR; PG8_WAIT_L(0); PG8_MMA(1, 0, At, B0); PG8_BAR; PG8_SCHED;
;             PG8_STAGE(PG8_SB(0, 1), b2 + hstep, voffB);
;             PG8_WAIT_V(6); PG8_BAR; PG8_MMA(1, 1, At, B1); PG8_BAR;
.LBB0_194:
	s_ashr_i32 s17, s16, 31
	v_cmp_lt_i64_e32 vcc, s[18:19], v[140:141]
	s_lshl_b64 s[18:19], s[16:17], 19
	s_add_u32 s18, s38, s18
	s_addc_u32 s19, s39, s19
	s_and_b64 s[24:25], vcc, exec
	s_cselect_b32 s17, s19, s29
	s_cselect_b32 s54, s18, s28
	s_ashr_i32 s15, s14, 31
	s_lshl_b64 s[24:25], s[14:15], 19
	s_add_u32 s24, s90, s24
	s_addc_u32 s25, s91, s25
	s_and_b64 s[34:35], vcc, exec
	s_cselect_b32 s15, s25, s31
	s_cselect_b32 s55, s24, s30
	s_add_u32 s28, s28, 0x40080
	s_addc_u32 s29, s29, 0
	s_add_u32 s56, s30, 0x100
	s_addc_u32 s57, s31, 0
	s_mov_b32 s58, -2
	ds_read_b128 v[144:147], v151
	ds_read_b128 v[156:159], v151 offset:1024
	ds_read_b128 v[160:163], v151 offset:2048
	ds_read_b128 v[166:169], v151 offset:3072
	s_add_u32 s30, s28, 0xfffc0080
	s_addc_u32 s31, s29, -1
	s_cmp_eq_u32 s58, 12
	s_cselect_b32 s35, s17, s31
	s_cselect_b32 s34, s54, s30
	s_cselect_b32 s31, s15, s57
	s_cselect_b32 s30, s55, s56
	s_add_i32 m0, s27, 0xc000
	ds_read_b128 v[170:173], v153
	ds_read_b128 v[182:185], v153 offset:1024
	ds_read_b128 v[190:193], v153 offset:2048
	ds_read_b128 v[194:197], v153 offset:3072
	ds_read_b128 v[198:201], v153 offset:4096
	ds_read_b128 v[202:205], v153 offset:5120
	ds_read_b128 v[206:209], v153 offset:6144
	ds_read_b128 v[210:213], v153 offset:7168
	global_load_lds_dwordx4 v136, s[28:29]
	s_nop 1
	s_add_i32 m0, s27, 0xe000
	s_nop 0
	global_load_lds_dwordx4 v138, s[28:29]
	s_waitcnt lgkmcnt(12)
	ds_read_b128 v[214:217], v154
	ds_read_b128 v[218:221], v154 offset:1024
	ds_read_b128 v[222:225], v154 offset:2048
	ds_read_b128 v[226:229], v154 offset:3072
	s_waitcnt vmcnt(8) lgkmcnt(0)
	s_barrier
	v_mfma_f32_16x16x32_bf16 v[124:127], v[144:147], v[170:173], 0
	v_mfma_f32_16x16x32_bf16 v[120:123], v[160:163], v[170:173], 0
	v_mfma_f32_16x16x32_bf16 v[108:111], v[144:147], v[190:193], 0
	v_mfma_f32_16x16x32_bf16 v[104:107], v[160:163], v[190:193], 0
	v_mfma_f32_16x16x32_bf16 v[92:95], v[144:147], v[198:201], 0
	v_mfma_f32_16x16x32_bf16 v[88:91], v[160:163], v[198:201], 0
	v_mfma_f32_16x16x32_bf16 v[76:79], v[144:147], v[206:209], 0
	v_mfma_f32_16x16x32_bf16 v[72:75], v[160:163], v[206:209], 0
	v_mfma_f32_16x16x32_bf16 v[124:127], v[156:159], v[182:185], v[124:127]
	v_mfma_f32_16x16x32_bf16 v[120:123], v[166:169], v[182:185], v[120:123]
	v_mfma_f32_16x16x32_bf16 v[108:111], v[156:159], v[194:197], v[108:111]
	v_mfma_f32_16x16x32_bf16 v[104:107], v[166:169], v[194:197], v[104:107]
	v_mfma_f32_16x16x32_bf16 v[92:95], v[156:159], v[202:205], v[92:95]
	v_mfma_f32_16x16x32_bf16 v[88:91], v[166:169], v[202:205], v[88:91]
	v_mfma_f32_16x16x32_bf16 v[76:79], v[156:159], v[210:213], v[76:79]
	v_mfma_f32_16x16x32_bf16 v[72:75], v[166:169], v[210:213], v[72:75]
	v_mfma_f32_16x16x32_bf16 v[116:119], v[214:217], v[170:173], 0
	v_mfma_f32_16x16x32_bf16 v[112:115], v[222:225], v[170:173], 0
	v_mfma_f32_16x16x32_bf16 v[100:103], v[214:217], v[190:193], 0
	v_mfma_f32_16x16x32_bf16 v[96:99], v[222:225], v[190:193], 0
	v_mfma_f32_16x16x32_bf16 v[84:87], v[214:217], v[198:201], 0
	v_mfma_f32_16x16x32_bf16 v[80:83], v[222:225], v[198:201], 0
	v_mfma_f32_16x16x32_bf16 v[68:71], v[214:217], v[206:209], 0
	v_mfma_f32_16x16x32_bf16 v[64:67], v[222:225], v[206:209], 0
	v_mfma_f32_16x16x32_bf16 v[116:119], v[218:221], v[182:185], v[116:119]
	v_mfma_f32_16x16x32_bf16 v[112:115], v[226:229], v[182:185], v[112:115]
	v_mfma_f32_16x16x32_bf16 v[100:103], v[218:221], v[194:197], v[100:103]
	v_mfma_f32_16x16x32_bf16 v[96:99], v[226:229], v[194:197], v[96:99]
	v_mfma_f32_16x16x32_bf16 v[84:87], v[218:221], v[202:205], v[84:87]
	v_mfma_f32_16x16x32_bf16 v[80:83], v[226:229], v[202:205], v[80:83]
	v_mfma_f32_16x16x32_bf16 v[68:71], v[218:221], v[210:213], v[68:71]
	v_mfma_f32_16x16x32_bf16 v[64:67], v[226:229], v[210:213], v[64:67]
	s_barrier
	ds_read_b128 v[170:173], v153 offset:16384
	ds_read_b128 v[182:185], v153 offset:17408
	ds_read_b128 v[190:193], v153 offset:18432
	ds_read_b128 v[194:197], v153 offset:19456
	ds_read_b128 v[198:201], v153 offset:20480
	ds_read_b128 v[202:205], v153 offset:21504
	ds_read_b128 v[206:209], v153 offset:22528
	ds_read_b128 v[210:213], v153 offset:23552
	s_add_i32 s59, s50, s40
	s_add_u32 s98, s30, s10
	s_addc_u32 s99, s31, s11
	s_mov_b32 m0, s59
	s_nop 0
	global_load_lds_dwordx4 v132, s[30:31]
	s_nop 1
	s_add_i32 m0, s59, 0x2000
	s_nop 0
	global_load_lds_dwordx4 v128, s[30:31]
	s_nop 1
	s_mov_b32 m0, s27
	s_add_u32 s100, s34, s10
	s_addc_u32 s101, s35, s11
	global_load_lds_dwordx4 v134, s[34:35]
	s_nop 1
	s_mov_b32 m0, s43
	s_nop 0
	global_load_lds_dwordx4 v130, s[34:35]
	s_add_u32 s60, s30, 0x40000
	s_addc_u32 s61, s31, 0
	s_add_i32 s59, s51, s40
	s_mov_b32 m0, s59
	s_nop 0
	global_load_lds_dwordx4 v132, s[60:61]
	s_nop 1
	s_add_i32 m0, s59, 0x2000
	s_nop 0
	global_load_lds_dwordx4 v128, s[60:61]
	s_waitcnt vmcnt(8) lgkmcnt(0)
	s_barrier
; #define PG8_STAGE(bufoff, gbase, voff) do { _Pragma("unroll") for (int _i = 0; _i < 2; ++_i) \
;         __builtin_amdgcn_global_load_lds((const unsigned*)((const char*)(gbase) + (voff)[_i]), (PG8_LAS unsigned*)(lds + (bufoff) + ldsw + _i * 8192), 16, 0, 0); } while (0)
; #define PG8_LDA(dst, b, h) do { _Pragma("unroll") for (int m = 0; m < 4; ++m) _Pragma("unroll") for (int k = 0; k < 2; ++k) dst[m][k] = *(const PG8_LAS bf16x8*)(lds + PG8_SA(b, h) + aoff + m * 2048 + k * 1024); } while (0)
; #define PG8_LDB(dst, b, h) do { _Pragma("unroll") for (int n = 0; n < 2; ++n) _Pragma("unroll") for (int k = 0; k < 2; ++k) dst[n][k] = *(const PG8_LAS bf16x8*)(lds + PG8_SB(b, h) + boff + n * 2048 + k * 1024); } while (0)
; #define PG8_MMA(ai, bj, At, Bt) do { __builtin_amdgcn_s_setprio(1); _Pragma("unroll") for (int m = 0; m < 4; ++m) _Pragma("unroll") for (int n = 0; n < 2; ++n) _Pragma("unroll") for (int k = 0; k < 2; ++k) \
;         acc[ai][bj][m][n] = __builtin_amdgcn_mfma_f32_16x16x32_bf16(Bt[n][k], At[m][k], acc[ai][bj][m][n], 0, 0, 0); __builtin_amdgcn_s_setprio(0); } while (0)
; #define PG8_WAIT_V(n) asm volatile("s_waitcnt vmcnt(" #n ")" ::: "memory")
; #define PG8_WAIT_L(n) asm volatile("s_waitcnt lgkmcnt(" #n ")" ::: "memory")
; #define PG8_BAR __builtin_amdgcn_s_barrier()
; #define PG8_SCHED __builtin_amdgcn_sched_barrier(0)
; template <class Epi, class Sched>
; __device__ __forceinline__ void gemm_phase(PG8_LAS unsigned char* lds, const Gemm g, const Sched& S, const Epi& E) {
;     ...
;             PG8_BAR; PG8_WAIT_L(0); PG8_MMA(1, 0, At, B0); PG8_BAR; PG8_SCHED;
;             PG8_STAGE(PG8_SB(0, 1), b2 + hstep, voffB);
;             PG8_WAIT_V(6); PG8_BAR; PG8_MMA(1, 1, At, B1); PG8_BAR;
;             PG8_LDB(B0, 1, 0); PG8_SCHED; PG8_LDA(At, 1, 0); PG8_STAGE(PG8_SA(0, 1), a2 + hstep, voffA);
;             PG8_WAIT_L(8); PG8_BAR; PG8_WAIT_L(0); PG8_MMA(0, 0, At, B0); PG8_BAR; PG8_SCHED;
;             PG8_LDB(B1, 1, 1); PG8_STAGE(PG8_SB(1, 0), b3, voffB);
;             PG8_BAR; PG8_WAIT_L(0); PG8_MMA(0, 1, At, B1); PG8_BAR;
	v_mfma_f32_16x16x32_bf16 v[60:63], v[144:147], v[170:173], 0
	v_mfma_f32_16x16x32_bf16 v[56:59], v[160:163], v[170:173], 0
	v_mfma_f32_16x16x32_bf16 v[44:47], v[144:147], v[190:193], 0
	v_mfma_f32_16x16x32_bf16 v[40:43], v[160:163], v[190:193], 0
	v_mfma_f32_16x16x32_bf16 v[28:31], v[144:147], v[198:201], 0
	v_mfma_f32_16x16x32_bf16 v[24:27], v[160:163], v[198:201], 0
	v_mfma_f32_16x16x32_bf16 v[12:15], v[144:147], v[206:209], 0
	v_mfma_f32_16x16x32_bf16 v[8:11], v[160:163], v[206:209], 0
	v_mfma_f32_16x16x32_bf16 v[60:63], v[156:159], v[182:185], v[60:63]
	v_mfma_f32_16x16x32_bf16 v[56:59], v[166:169], v[182:185], v[56:59]
	v_mfma_f32_16x16x32_bf16 v[44:47], v[156:159], v[194:197], v[44:47]
	v_mfma_f32_16x16x32_bf16 v[40:43], v[166:169], v[194:197], v[40:43]
	v_mfma_f32_16x16x32_bf16 v[28:31], v[156:159], v[202:205], v[28:31]
	v_mfma_f32_16x16x32_bf16 v[24:27], v[166:169], v[202:205], v[24:27]
	v_mfma_f32_16x16x32_bf16 v[12:15], v[156:159], v[210:213], v[12:15]
	v_mfma_f32_16x16x32_bf16 v[8:11], v[166:169], v[210:213], v[8:11]
	v_mfma_f32_16x16x32_bf16 v[52:55], v[214:217], v[170:173], 0
	v_mfma_f32_16x16x32_bf16 v[48:51], v[222:225], v[170:173], 0
	v_mfma_f32_16x16x32_bf16 v[36:39], v[214:217], v[190:193], 0
	v_mfma_f32_16x16x32_bf16 v[32:35], v[222:225], v[190:193], 0
	v_mfma_f32_16x16x32_bf16 v[20:23], v[214:217], v[198:201], 0
	v_mfma_f32_16x16x32_bf16 v[16:19], v[222:225], v[198:201], 0
	v_mfma_f32_16x16x32_bf16 v[4:7], v[214:217], v[206:209], 0
	v_mfma_f32_16x16x32_bf16 v[0:3], v[222:225], v[206:209], 0
	v_mfma_f32_16x16x32_bf16 v[52:55], v[218:221], v[182:185], v[52:55]
	v_mfma_f32_16x16x32_bf16 v[48:51], v[226:229], v[182:185], v[48:51]
	v_mfma_f32_16x16x32_bf16 v[36:39], v[218:221], v[194:197], v[36:39]
	v_mfma_f32_16x16x32_bf16 v[32:35], v[226:229], v[194:197], v[32:35]
	v_mfma_f32_16x16x32_bf16 v[20:23], v[218:221], v[202:205], v[20:23]
	v_mfma_f32_16x16x32_bf16 v[16:19], v[226:229], v[202:205], v[16:19]
	v_mfma_f32_16x16x32_bf16 v[4:7], v[218:221], v[210:213], v[4:7]
	v_mfma_f32_16x16x32_bf16 v[0:3], v[226:229], v[210:213], v[0:3]
	s_barrier
	s_add_i32 s59, 0, 0x18000
	v_add_u32_e32 v155, s59, v149
	ds_read_b128 v[144:147], v155
	ds_read_b128 v[156:159], v155 offset:1024
	ds_read_b128 v[160:163], v155 offset:2048
	ds_read_b128 v[166:169], v155 offset:3072
	s_add_u32 s34, s34, 0x40000
	s_addc_u32 s35, s35, 0
	s_mov_b32 m0, s44
	ds_read_b128 v[170:173], v153 offset:32768
	ds_read_b128 v[182:185], v153 offset:33792
	ds_read_b128 v[190:193], v153 offset:34816
	ds_read_b128 v[194:197], v153 offset:35840
	ds_read_b128 v[198:201], v153 offset:36864
	ds_read_b128 v[202:205], v153 offset:37888
	ds_read_b128 v[206:209], v153 offset:38912
	ds_read_b128 v[210:213], v153 offset:39936
	global_load_lds_dwordx4 v134, s[34:35]
	s_nop 1
	s_mov_b32 m0, s45
	s_nop 0
	global_load_lds_dwordx4 v130, s[34:35]
	s_add_i32 s34, 0, 0x1c000
	v_add_u32_e32 v155, s34, v149
	s_waitcnt lgkmcnt(12)
	ds_read_b128 v[214:217], v155
	ds_read_b128 v[218:221], v155 offset:1024
	ds_read_b128 v[222:225], v155 offset:2048
	ds_read_b128 v[226:229], v155 offset:3072
	s_waitcnt vmcnt(8) lgkmcnt(0)
	s_barrier
	v_mfma_f32_16x16x32_bf16 v[124:127], v[144:147], v[170:173], v[124:127]
	v_mfma_f32_16x16x32_bf16 v[120:123], v[160:163], v[170:173], v[120:123]
	v_mfma_f32_16x16x32_bf16 v[108:111], v[144:147], v[190:193], v[108:111]
	v_mfma_f32_16x16x32_bf16 v[104:107], v[160:163], v[190:193], v[104:107]
	v_mfma_f32_16x16x32_bf16 v[92:95], v[144:147], v[198:201], v[92:95]
	v_mfma_f32_16x16x32_bf16 v[88:91], v[160:163], v[198:201], v[88:91]
	v_mfma_f32_16x16x32_bf16 v[76:79], v[144:147], v[206:209], v[76:79]
	v_mfma_f32_16x16x32_bf16 v[72:75], v[160:163], v[206:209], v[72:75]
	v_mfma_f32_16x16x32_bf16 v[124:127], v[156:159], v[182:185], v[124:127]
	v_mfma_f32_16x16x32_bf16 v[120:123], v[166:169], v[182:185], v[120:123]
	v_mfma_f32_16x16x32_bf16 v[108:111], v[156:159], v[194:197], v[108:111]
	v_mfma_f32_16x16x32_bf16 v[104:107], v[166:169], v[194:197], v[104:107]
	v_mfma_f32_16x16x32_bf16 v[92:95], v[156:159], v[202:205], v[92:95]
	v_mfma_f32_16x16x32_bf16 v[88:91], v[166:169], v[202:205], v[88:91]
	v_mfma_f32_16x16x32_bf16 v[76:79], v[156:159], v[210:213], v[76:79]
	v_mfma_f32_16x16x32_bf16 v[72:75], v[166:169], v[210:213], v[72:75]
	v_mfma_f32_16x16x32_bf16 v[116:119], v[214:217], v[170:173], v[116:119]
	v_mfma_f32_16x16x32_bf16 v[112:115], v[222:225], v[170:173], v[112:115]
	v_mfma_f32_16x16x32_bf16 v[100:103], v[214:217], v[190:193], v[100:103]
	v_mfma_f32_16x16x32_bf16 v[96:99], v[222:225], v[190:193], v[96:99]
	v_mfma_f32_16x16x32_bf16 v[84:87], v[214:217], v[198:201], v[84:87]
	v_mfma_f32_16x16x32_bf16 v[80:83], v[222:225], v[198:201], v[80:83]
	v_mfma_f32_16x16x32_bf16 v[68:71], v[214:217], v[206:209], v[68:71]
	v_mfma_f32_16x16x32_bf16 v[64:67], v[222:225], v[206:209], v[64:67]
	v_mfma_f32_16x16x32_bf16 v[116:119], v[218:221], v[182:185], v[116:119]
	v_mfma_f32_16x16x32_bf16 v[112:115], v[226:229], v[182:185], v[112:115]
	v_mfma_f32_16x16x32_bf16 v[100:103], v[218:221], v[194:197], v[100:103]
	v_mfma_f32_16x16x32_bf16 v[96:99], v[226:229], v[194:197], v[96:99]
	v_mfma_f32_16x16x32_bf16 v[84:87], v[218:221], v[202:205], v[84:87]
	v_mfma_f32_16x16x32_bf16 v[80:83], v[226:229], v[202:205], v[80:83]
	v_mfma_f32_16x16x32_bf16 v[68:71], v[218:221], v[210:213], v[68:71]
	v_mfma_f32_16x16x32_bf16 v[64:67], v[226:229], v[210:213], v[64:67]
	s_barrier
; #define PG8_STAGE(bufoff, gbase, voff) do { _Pragma("unroll") for (int _i = 0; _i < 2; ++_i) \
;         __builtin_amdgcn_global_load_lds((const unsigned*)((const char*)(gbase) + (voff)[_i]), (PG8_LAS unsigned*)(lds + (bufoff) + ldsw + _i * 8192), 16, 0, 0); } while (0)
; #define PG8_LDA(dst, b, h) do { _Pragma("unroll") for (int m = 0; m < 4; ++m) _Pragma("unroll") for (int k = 0; k < 2; ++k) dst[m][k] = *(const PG8_LAS bf16x8*)(lds + PG8_SA(b, h) + aoff + m * 2048 + k * 1024); } while (0)
; #define PG8_WAIT_V(n) asm volatile("s_waitcnt vmcnt(" #n ")" ::: "memory")
; template <class Epi, class Sched>
; __device__ __forceinline__ void gemm_phase(PG8_LAS unsigned char* lds, const Gemm g, const Sched& S, const Epi& E) {
;     ...
;         for (int t = 0; t < nt; t += 2) {
;             const bool last = (t == nt - 2);
;             const char* a1 = cA + (size_t)(t + 1) * kstep;
;             const char* a2 = last ? nA : cA + (size_t)(t + 2) * kstep; const char* b2 = last ? nB : cB + (size_t)(t + 2) * kstep;
;             const char* a3 = a2 + kstep; const char* b3 = b2 + kstep;
;             if (last && has_next) S.a_ready(nxt);
;             PG8_LDB(B0, 0, 0); PG8_SCHED; PG8_LDA(At, 0, 0); PG8_STAGE(PG8_SA(1, 1), a1 + hstep, voffA);
;             PG8_WAIT_L(8); PG8_BAR; PG8_WAIT_L(0); PG8_MMA(0, 0, At, B0); PG8_BAR; PG8_SCHED;
;             PG8_LDB(B1, 0, 1); PG8_STAGE(PG8_SB(0, 0), b2, voffB);
;             PG8_BAR; PG8_WAIT_L(0); PG8_MMA(0, 1, At, B1); PG8_BAR;
;             PG8_LDA(At, 0, 1); PG8_STAGE(PG8_SA(0, 0), a2, voffA);
;             PG8_BAR; PG8_WAIT_L(0); PG8_MMA(1, 0, At, B0); PG8_BAR; PG8_SCHED;
;             PG8_STAGE(PG8_SB(0, 1), b2 + hstep, voffB);
;             PG8_WAIT_V(6); PG8_BAR; PG8_MMA(1, 1, At, B1); PG8_BAR;
;             PG8_LDB(B0, 1, 0); PG8_SCHED; PG8_LDA(At, 1, 0); PG8_STAGE(PG8_SA(0, 1), a2 + hstep, voffA);
;             PG8_WAIT_L(8); PG8_BAR; PG8_WAIT_L(0); PG8_MMA(0, 0, At, B0); PG8_BAR; PG8_SCHED;
;             PG8_LDB(B1, 1, 1); PG8_STAGE(PG8_SB(1, 0), b3, voffB);
;             PG8_BAR; PG8_WAIT_L(0); PG8_MMA(0, 1, At, B1); PG8_BAR;
;             PG8_LDA(At, 1, 1); PG8_STAGE(PG8_SA(1, 0), a3, voffA);
;             PG8_BAR; PG8_WAIT_L(0); PG8_MMA(1, 0, At, B0); PG8_BAR; PG8_SCHED;
;             PG8_STAGE(PG8_SB(1, 1), b3 + hstep, voffB);
;             PG8_WAIT_V(6); PG8_BAR; PG8_MMA(1, 1, At, B1); PG8_BAR;
	ds_read_b128 v[170:173], v153 offset:49152
	ds_read_b128 v[182:185], v153 offset:50176
	ds_read_b128 v[190:193], v153 offset:51200
	ds_read_b128 v[194:197], v153 offset:52224
	ds_read_b128 v[198:201], v153 offset:53248
	ds_read_b128 v[202:205], v153 offset:54272
	ds_read_b128 v[206:209], v153 offset:55296
	ds_read_b128 v[210:213], v153 offset:56320
	s_add_i32 s35, s59, s40
	s_mov_b32 m0, s35
	s_nop 0
	global_load_lds_dwordx4 v132, s[98:99]
	s_nop 1
	s_add_i32 m0, s35, 0x2000
	s_nop 0
	global_load_lds_dwordx4 v128, s[98:99]
	s_nop 1
	s_mov_b32 m0, s47
	s_nop 0
	global_load_lds_dwordx4 v134, s[100:101]
	s_nop 1
	s_mov_b32 m0, s48
	s_nop 0
	global_load_lds_dwordx4 v130, s[100:101]
	s_add_u32 s30, s30, 0x40080
	s_addc_u32 s31, s31, 0
	s_add_i32 s34, s34, s40
	s_mov_b32 m0, s34
	s_nop 0
	global_load_lds_dwordx4 v132, s[30:31]
	s_nop 1
	s_add_i32 m0, s34, 0x2000
	s_nop 0
	global_load_lds_dwordx4 v128, s[30:31]
	s_waitcnt vmcnt(8) lgkmcnt(0)
	s_barrier
	v_mfma_f32_16x16x32_bf16 v[60:63], v[144:147], v[170:173], v[60:63]
	v_mfma_f32_16x16x32_bf16 v[56:59], v[160:163], v[170:173], v[56:59]
	v_mfma_f32_16x16x32_bf16 v[44:47], v[144:147], v[190:193], v[44:47]
	v_mfma_f32_16x16x32_bf16 v[40:43], v[160:163], v[190:193], v[40:43]
	v_mfma_f32_16x16x32_bf16 v[28:31], v[144:147], v[198:201], v[28:31]
	v_mfma_f32_16x16x32_bf16 v[24:27], v[160:163], v[198:201], v[24:27]
	v_mfma_f32_16x16x32_bf16 v[12:15], v[144:147], v[206:209], v[12:15]
	v_mfma_f32_16x16x32_bf16 v[8:11], v[160:163], v[206:209], v[8:11]
	v_mfma_f32_16x16x32_bf16 v[60:63], v[156:159], v[182:185], v[60:63]
	v_mfma_f32_16x16x32_bf16 v[56:59], v[166:169], v[182:185], v[56:59]
	v_mfma_f32_16x16x32_bf16 v[44:47], v[156:159], v[194:197], v[44:47]
	v_mfma_f32_16x16x32_bf16 v[40:43], v[166:169], v[194:197], v[40:43]
	v_mfma_f32_16x16x32_bf16 v[28:31], v[156:159], v[202:205], v[28:31]
	v_mfma_f32_16x16x32_bf16 v[24:27], v[166:169], v[202:205], v[24:27]
	v_mfma_f32_16x16x32_bf16 v[12:15], v[156:159], v[210:213], v[12:15]
	v_mfma_f32_16x16x32_bf16 v[8:11], v[166:169], v[210:213], v[8:11]
	v_mfma_f32_16x16x32_bf16 v[52:55], v[214:217], v[170:173], v[52:55]
	v_mfma_f32_16x16x32_bf16 v[48:51], v[222:225], v[170:173], v[48:51]
	v_mfma_f32_16x16x32_bf16 v[36:39], v[214:217], v[190:193], v[36:39]
	v_mfma_f32_16x16x32_bf16 v[32:35], v[222:225], v[190:193], v[32:35]
	v_mfma_f32_16x16x32_bf16 v[20:23], v[214:217], v[198:201], v[20:23]
	v_mfma_f32_16x16x32_bf16 v[16:19], v[222:225], v[198:201], v[16:19]
	v_mfma_f32_16x16x32_bf16 v[4:7], v[214:217], v[206:209], v[4:7]
	v_mfma_f32_16x16x32_bf16 v[0:3], v[222:225], v[206:209], v[0:3]
	v_mfma_f32_16x16x32_bf16 v[52:55], v[218:221], v[182:185], v[52:55]
	v_mfma_f32_16x16x32_bf16 v[48:51], v[226:229], v[182:185], v[48:51]
	v_mfma_f32_16x16x32_bf16 v[36:39], v[218:221], v[194:197], v[36:39]
	v_mfma_f32_16x16x32_bf16 v[32:35], v[226:229], v[194:197], v[32:35]
	v_mfma_f32_16x16x32_bf16 v[20:23], v[218:221], v[202:205], v[20:23]
	v_mfma_f32_16x16x32_bf16 v[16:19], v[226:229], v[202:205], v[16:19]
	v_mfma_f32_16x16x32_bf16 v[4:7], v[218:221], v[210:213], v[4:7]
	v_mfma_f32_16x16x32_bf16 v[0:3], v[226:229], v[210:213], v[0:3]
	s_barrier
	s_add_i32 s58, s58, 2
	s_add_u32 s28, s28, 0x100
	s_addc_u32 s29, s29, 0
	s_add_u32 s56, s56, 0x100
	s_addc_u32 s57, s57, 0
	s_cmp_gt_u32 s58, 13
.LBB0_195:
	ds_read_b128 v[144:147], v151
	ds_read_b128 v[156:159], v151 offset:1024
	ds_read_b128 v[160:163], v151 offset:2048
	ds_read_b128 v[166:169], v151 offset:3072
	s_add_u32 s30, s28, 0xfffc0080
	s_addc_u32 s31, s29, -1
	s_cmp_eq_u32 s58, 12
	s_cselect_b32 s35, s17, s31
	s_cselect_b32 s34, s54, s30
	s_cselect_b32 s31, s15, s57
	s_cselect_b32 s30, s55, s56
	s_add_i32 m0, s27, 0xc000
	ds_read_b128 v[170:173], v153
	ds_read_b128 v[182:185], v153 offset:1024
	ds_read_b128 v[190:193], v153 offset:2048
	ds_read_b128 v[194:197], v153 offset:3072
	ds_read_b128 v[198:201], v153 offset:4096
	ds_read_b128 v[202:205], v153 offset:5120
	ds_read_b128 v[206:209], v153 offset:6144
	ds_read_b128 v[210:213], v153 offset:7168
	global_load_lds_dwordx4 v136, s[28:29]
	s_nop 1
	s_add_i32 m0, s27, 0xe000
	s_nop 0
	global_load_lds_dwordx4 v138, s[28:29]
	s_waitcnt lgkmcnt(12)
	ds_read_b128 v[214:217], v154
	ds_read_b128 v[218:221], v154 offset:1024
	ds_read_b128 v[222:225], v154 offset:2048
	ds_read_b128 v[226:229], v154 offset:3072
	s_waitcnt vmcnt(8) lgkmcnt(0)
	s_barrier
	v_mfma_f32_16x16x32_bf16 v[124:127], v[144:147], v[170:173], v[124:127]
	v_mfma_f32_16x16x32_bf16 v[120:123], v[160:163], v[170:173], v[120:123]
	v_mfma_f32_16x16x32_bf16 v[108:111], v[144:147], v[190:193], v[108:111]
	v_mfma_f32_16x16x32_bf16 v[104:107], v[160:163], v[190:193], v[104:107]
	v_mfma_f32_16x16x32_bf16 v[92:95], v[144:147], v[198:201], v[92:95]
	v_mfma_f32_16x16x32_bf16 v[88:91], v[160:163], v[198:201], v[88:91]
	v_mfma_f32_16x16x32_bf16 v[76:79], v[144:147], v[206:209], v[76:79]
	v_mfma_f32_16x16x32_bf16 v[72:75], v[160:163], v[206:209], v[72:75]
	v_mfma_f32_16x16x32_bf16 v[124:127], v[156:159], v[182:185], v[124:127]
	v_mfma_f32_16x16x32_bf16 v[120:123], v[166:169], v[182:185], v[120:123]
	v_mfma_f32_16x16x32_bf16 v[108:111], v[156:159], v[194:197], v[108:111]
	v_mfma_f32_16x16x32_bf16 v[104:107], v[166:169], v[194:197], v[104:107]
	v_mfma_f32_16x16x32_bf16 v[92:95], v[156:159], v[202:205], v[92:95]
	v_mfma_f32_16x16x32_bf16 v[88:91], v[166:169], v[202:205], v[88:91]
	v_mfma_f32_16x16x32_bf16 v[76:79], v[156:159], v[210:213], v[76:79]
	v_mfma_f32_16x16x32_bf16 v[72:75], v[166:169], v[210:213], v[72:75]
	v_mfma_f32_16x16x32_bf16 v[116:119], v[214:217], v[170:173], v[116:119]
	v_mfma_f32_16x16x32_bf16 v[112:115], v[222:225], v[170:173], v[112:115]
	v_mfma_f32_16x16x32_bf16 v[100:103], v[214:217], v[190:193], v[100:103]
	v_mfma_f32_16x16x32_bf16 v[96:99], v[222:225], v[190:193], v[96:99]
	v_mfma_f32_16x16x32_bf16 v[84:87], v[214:217], v[198:201], v[84:87]
	v_mfma_f32_16x16x32_bf16 v[80:83], v[222:225], v[198:201], v[80:83]
	v_mfma_f32_16x16x32_bf16 v[68:71], v[214:217], v[206:209], v[68:71]
	v_mfma_f32_16x16x32_bf16 v[64:67], v[222:225], v[206:209], v[64:67]
	v_mfma_f32_16x16x32_bf16 v[116:119], v[218:221], v[182:185], v[116:119]
	v_mfma_f32_16x16x32_bf16 v[112:115], v[226:229], v[182:185], v[112:115]
	v_mfma_f32_16x16x32_bf16 v[100:103], v[218:221], v[194:197], v[100:103]
	v_mfma_f32_16x16x32_bf16 v[96:99], v[226:229], v[194:197], v[96:99]
	v_mfma_f32_16x16x32_bf16 v[84:87], v[218:221], v[202:205], v[84:87]
	v_mfma_f32_16x16x32_bf16 v[80:83], v[226:229], v[202:205], v[80:83]
	v_mfma_f32_16x16x32_bf16 v[68:71], v[218:221], v[210:213], v[68:71]
	v_mfma_f32_16x16x32_bf16 v[64:67], v[226:229], v[210:213], v[64:67]
	s_barrier
; #define PG8_STAGE(bufoff, gbase, voff) do { _Pragma("unroll") for (int _i = 0; _i < 2; ++_i) \
;         __builtin_amdgcn_global_load_lds((const unsigned*)((const char*)(gbase) + (voff)[_i]), (PG8_LAS unsigned*)(lds + (bufoff) + ldsw + _i * 8192), 16, 0, 0); } while (0)
; #define PG8_LDA(dst, b, h) do { _Pragma("unroll") for (int m = 0; m < 4; ++m) _Pragma("unroll") for (int k = 0; k < 2; ++k) dst[m][k] = *(const PG8_LAS bf16x8*)(lds + PG8_SA(b, h) + aoff + m * 2048 + k * 1024); } while (0)
; #define PG8_LDB(dst, b, h) do { _Pragma("unroll") for (int n = 0; n < 2; ++n) _Pragma("unroll") for (int k = 0; k < 2; ++k) dst[n][k] = *(const PG8_LAS bf16x8*)(lds + PG8_SB(b, h) + boff + n * 2048 + k * 1024); } while (0)
; #define PG8_MMA(ai, bj, At, Bt) do { __builtin_amdgcn_s_setprio(1); _Pragma("unroll") for (int m = 0; m < 4; ++m) _Pragma("unroll") for (int n = 0; n < 2; ++n) _Pragma("unroll") for (int k = 0; k < 2; ++k) \
;         acc[ai][bj][m][n] = __builtin_amdgcn_mfma_f32_16x16x32_bf16(Bt[n][k], At[m][k], acc[ai][bj][m][n], 0, 0, 0); __builtin_amdgcn_s_setprio(0); } while (0)
; #define PG8_WAIT_V(n) asm volatile("s_waitcnt vmcnt(" #n ")" ::: "memory")
; #define PG8_WAIT_L(n) asm volatile("s_waitcnt lgkmcnt(" #n ")" ::: "memory")
; #define PG8_BAR __builtin_amdgcn_s_barrier()
; #define PG8_SCHED __builtin_amdgcn_sched_barrier(0)
; template <class Epi, class Sched>
; __device__ __forceinline__ void gemm_phase(PG8_LAS unsigned char* lds, const Gemm g, const Sched& S, const Epi& E) {
;     ...
;             PG8_LDA(At, 0, 1); PG8_STAGE(PG8_SA(0, 0), a2, voffA);
;             PG8_BAR; PG8_WAIT_L(0); PG8_MMA(1, 0, At, B0); PG8_BAR; PG8_SCHED;
;             PG8_STAGE(PG8_SB(0, 1), b2 + hstep, voffB);
;             PG8_WAIT_V(6); PG8_BAR; PG8_MMA(1, 1, At, B1); PG8_BAR;
;             PG8_LDB(B0, 1, 0); PG8_SCHED; PG8_LDA(At, 1, 0); PG8_STAGE(PG8_SA(0, 1), a2 + hstep, voffA);
;             PG8_WAIT_L(8); PG8_BAR; PG8_WAIT_L(0); PG8_MMA(0, 0, At, B0); PG8_BAR; PG8_SCHED;
;             PG8_LDB(B1, 1, 1); PG8_STAGE(PG8_SB(1, 0), b3, voffB);
;             PG8_BAR; PG8_WAIT_L(0); PG8_MMA(0, 1, At, B1); PG8_BAR;
;             PG8_LDA(At, 1, 1); PG8_STAGE(PG8_SA(1, 0), a3, voffA);
;             PG8_BAR; PG8_WAIT_L(0); PG8_MMA(1, 0, At, B0); PG8_BAR; PG8_SCHED;
	ds_read_b128 v[170:173], v153 offset:16384
	ds_read_b128 v[182:185], v153 offset:17408
	ds_read_b128 v[190:193], v153 offset:18432
	ds_read_b128 v[194:197], v153 offset:19456
	ds_read_b128 v[198:201], v153 offset:20480
	ds_read_b128 v[202:205], v153 offset:21504
	ds_read_b128 v[206:209], v153 offset:22528
	ds_read_b128 v[210:213], v153 offset:23552
	s_add_i32 s59, s50, s40
	s_add_u32 s98, s30, s10
	s_addc_u32 s99, s31, s11
	s_mov_b32 m0, s59
	s_nop 0
	global_load_lds_dwordx4 v132, s[30:31]
	s_nop 1
	s_add_i32 m0, s59, 0x2000
	s_nop 0
	global_load_lds_dwordx4 v128, s[30:31]
	s_nop 1
	s_mov_b32 m0, s27
	s_add_u32 s100, s34, s10
	s_addc_u32 s101, s35, s11
	global_load_lds_dwordx4 v134, s[34:35]
	s_nop 1
	s_mov_b32 m0, s43
	s_nop 0
	global_load_lds_dwordx4 v130, s[34:35]
	s_add_u32 s60, s30, 0x40000
	s_addc_u32 s61, s31, 0
	s_add_i32 s59, s51, s40
	s_mov_b32 m0, s59
	s_nop 0
	global_load_lds_dwordx4 v132, s[60:61]
	s_nop 1
	s_add_i32 m0, s59, 0x2000
	s_nop 0
	global_load_lds_dwordx4 v128, s[60:61]
	s_waitcnt vmcnt(8) lgkmcnt(0)
	s_barrier
	v_mfma_f32_16x16x32_bf16 v[60:63], v[144:147], v[170:173], v[60:63]
	v_mfma_f32_16x16x32_bf16 v[56:59], v[160:163], v[170:173], v[56:59]
	v_mfma_f32_16x16x32_bf16 v[44:47], v[144:147], v[190:193], v[44:47]
	v_mfma_f32_16x16x32_bf16 v[40:43], v[160:163], v[190:193], v[40:43]
	v_mfma_f32_16x16x32_bf16 v[28:31], v[144:147], v[198:201], v[28:31]
	v_mfma_f32_16x16x32_bf16 v[24:27], v[160:163], v[198:201], v[24:27]
	v_mfma_f32_16x16x32_bf16 v[12:15], v[144:147], v[206:209], v[12:15]
	v_mfma_f32_16x16x32_bf16 v[8:11], v[160:163], v[206:209], v[8:11]
	v_mfma_f32_16x16x32_bf16 v[60:63], v[156:159], v[182:185], v[60:63]
	v_mfma_f32_16x16x32_bf16 v[56:59], v[166:169], v[182:185], v[56:59]
	v_mfma_f32_16x16x32_bf16 v[44:47], v[156:159], v[194:197], v[44:47]
	v_mfma_f32_16x16x32_bf16 v[40:43], v[166:169], v[194:197], v[40:43]
	v_mfma_f32_16x16x32_bf16 v[28:31], v[156:159], v[202:205], v[28:31]
	v_mfma_f32_16x16x32_bf16 v[24:27], v[166:169], v[202:205], v[24:27]
	v_mfma_f32_16x16x32_bf16 v[12:15], v[156:159], v[210:213], v[12:15]
	v_mfma_f32_16x16x32_bf16 v[8:11], v[166:169], v[210:213], v[8:11]
	v_mfma_f32_16x16x32_bf16 v[52:55], v[214:217], v[170:173], v[52:55]
	v_mfma_f32_16x16x32_bf16 v[48:51], v[222:225], v[170:173], v[48:51]
	v_mfma_f32_16x16x32_bf16 v[36:39], v[214:217], v[190:193], v[36:39]
	v_mfma_f32_16x16x32_bf16 v[32:35], v[222:225], v[190:193], v[32:35]
	v_mfma_f32_16x16x32_bf16 v[20:23], v[214:217], v[198:201], v[20:23]
	v_mfma_f32_16x16x32_bf16 v[16:19], v[222:225], v[198:201], v[16:19]
	v_mfma_f32_16x16x32_bf16 v[4:7], v[214:217], v[206:209], v[4:7]
	v_mfma_f32_16x16x32_bf16 v[0:3], v[222:225], v[206:209], v[0:3]
	v_mfma_f32_16x16x32_bf16 v[52:55], v[218:221], v[182:185], v[52:55]
	v_mfma_f32_16x16x32_bf16 v[48:51], v[226:229], v[182:185], v[48:51]
	v_mfma_f32_16x16x32_bf16 v[36:39], v[218:221], v[194:197], v[36:39]
	v_mfma_f32_16x16x32_bf16 v[32:35], v[226:229], v[194:197], v[32:35]
	v_mfma_f32_16x16x32_bf16 v[20:23], v[218:221], v[202:205], v[20:23]
	v_mfma_f32_16x16x32_bf16 v[16:19], v[226:229], v[202:205], v[16:19]
	v_mfma_f32_16x16x32_bf16 v[4:7], v[218:221], v[210:213], v[4:7]
	v_mfma_f32_16x16x32_bf16 v[0:3], v[226:229], v[210:213], v[0:3]
	s_barrier
	s_add_i32 s59, 0, 0x18000
	v_add_u32_e32 v155, s59, v149
	ds_read_b128 v[144:147], v155
	ds_read_b128 v[156:159], v155 offset:1024
	ds_read_b128 v[160:163], v155 offset:2048
	ds_read_b128 v[166:169], v155 offset:3072
	s_add_u32 s34, s34, 0x40000
	s_addc_u32 s35, s35, 0
	s_mov_b32 m0, s44
	ds_read_b128 v[170:173], v153 offset:32768
	ds_read_b128 v[182:185], v153 offset:33792
	ds_read_b128 v[190:193], v153 offset:34816
	ds_read_b128 v[194:197], v153 offset:35840
	ds_read_b128 v[198:201], v153 offset:36864
	ds_read_b128 v[202:205], v153 offset:37888
	ds_read_b128 v[206:209], v153 offset:38912
	ds_read_b128 v[210:213], v153 offset:39936
	global_load_lds_dwordx4 v134, s[34:35]
	s_nop 1
	s_mov_b32 m0, s45
	s_nop 0
	global_load_lds_dwordx4 v130, s[34:35]
	s_add_i32 s34, 0, 0x1c000
	v_add_u32_e32 v155, s34, v149
	s_waitcnt lgkmcnt(12)
	ds_read_b128 v[214:217], v155
	ds_read_b128 v[218:221], v155 offset:1024
	ds_read_b128 v[222:225], v155 offset:2048
	ds_read_b128 v[226:229], v155 offset:3072
	s_waitcnt vmcnt(8) lgkmcnt(0)
	s_barrier
	v_mfma_f32_16x16x32_bf16 v[124:127], v[144:147], v[170:173], v[124:127]
	v_mfma_f32_16x16x32_bf16 v[120:123], v[160:163], v[170:173], v[120:123]
	v_mfma_f32_16x16x32_bf16 v[108:111], v[144:147], v[190:193], v[108:111]
	v_mfma_f32_16x16x32_bf16 v[104:107], v[160:163], v[190:193], v[104:107]
	v_mfma_f32_16x16x32_bf16 v[92:95], v[144:147], v[198:201], v[92:95]
	v_mfma_f32_16x16x32_bf16 v[88:91], v[160:163], v[198:201], v[88:91]
	v_mfma_f32_16x16x32_bf16 v[76:79], v[144:147], v[206:209], v[76:79]
	v_mfma_f32_16x16x32_bf16 v[72:75], v[160:163], v[206:209], v[72:75]
	v_mfma_f32_16x16x32_bf16 v[124:127], v[156:159], v[182:185], v[124:127]
	v_mfma_f32_16x16x32_bf16 v[120:123], v[166:169], v[182:185], v[120:123]
	v_mfma_f32_16x16x32_bf16 v[108:111], v[156:159], v[194:197], v[108:111]
	v_mfma_f32_16x16x32_bf16 v[104:107], v[166:169], v[194:197], v[104:107]
	v_mfma_f32_16x16x32_bf16 v[92:95], v[156:159], v[202:205], v[92:95]
	v_mfma_f32_16x16x32_bf16 v[88:91], v[166:169], v[202:205], v[88:91]
	v_mfma_f32_16x16x32_bf16 v[76:79], v[156:159], v[210:213], v[76:79]
	v_mfma_f32_16x16x32_bf16 v[72:75], v[166:169], v[210:213], v[72:75]
	v_mfma_f32_16x16x32_bf16 v[116:119], v[214:217], v[170:173], v[116:119]
	v_mfma_f32_16x16x32_bf16 v[112:115], v[222:225], v[170:173], v[112:115]
	v_mfma_f32_16x16x32_bf16 v[100:103], v[214:217], v[190:193], v[100:103]
	v_mfma_f32_16x16x32_bf16 v[96:99], v[222:225], v[190:193], v[96:99]
	v_mfma_f32_16x16x32_bf16 v[84:87], v[214:217], v[198:201], v[84:87]
	v_mfma_f32_16x16x32_bf16 v[80:83], v[222:225], v[198:201], v[80:83]
	v_mfma_f32_16x16x32_bf16 v[68:71], v[214:217], v[206:209], v[68:71]
	v_mfma_f32_16x16x32_bf16 v[64:67], v[222:225], v[206:209], v[64:67]
	v_mfma_f32_16x16x32_bf16 v[116:119], v[218:221], v[182:185], v[116:119]
	v_mfma_f32_16x16x32_bf16 v[112:115], v[226:229], v[182:185], v[112:115]
	v_mfma_f32_16x16x32_bf16 v[100:103], v[218:221], v[194:197], v[100:103]
	v_mfma_f32_16x16x32_bf16 v[96:99], v[226:229], v[194:197], v[96:99]
	v_mfma_f32_16x16x32_bf16 v[84:87], v[218:221], v[202:205], v[84:87]
	v_mfma_f32_16x16x32_bf16 v[80:83], v[226:229], v[202:205], v[80:83]
	v_mfma_f32_16x16x32_bf16 v[68:71], v[218:221], v[210:213], v[68:71]
	v_mfma_f32_16x16x32_bf16 v[64:67], v[226:229], v[210:213], v[64:67]
	s_barrier
; __device__ __forceinline__ unsigned cvt_pk_bf16(float lo, float hi) { unsigned r; asm volatile("v_cvt_pk_bf16_f32 %0, %1, %2" : "=v"(r) : "v"(lo), "v"(hi)); return r; }
; #define PG8_STAGE(bufoff, gbase, voff) do { _Pragma("unroll") for (int _i = 0; _i < 2; ++_i) \
;         __builtin_amdgcn_global_load_lds((const unsigned*)((const char*)(gbase) + (voff)[_i]), (PG8_LAS unsigned*)(lds + (bufoff) + ldsw + _i * 8192), 16, 0, 0); } while (0)
; #define PG8_LDA(dst, b, h) do { _Pragma("unroll") for (int m = 0; m < 4; ++m) _Pragma("unroll") for (int k = 0; k < 2; ++k) dst[m][k] = *(const PG8_LAS bf16x8*)(lds + PG8_SA(b, h) + aoff + m * 2048 + k * 1024); } while (0)
; #define PG8_WAIT_V(n) asm volatile("s_waitcnt vmcnt(" #n ")" ::: "memory")
; #define PG8_WAIT_L(n) asm volatile("s_waitcnt lgkmcnt(" #n ")" ::: "memory")
; #define PG8_BAR __builtin_amdgcn_s_barrier()
; #define PG8_SCHED __builtin_amdgcn_sched_barrier(0)
;     __device__ __forceinline__ void operator()(const f32x4 (&acc)[2][2][4][2], const Unit& u, int wr, int wc, int fr, int fq) const {
;         const int row0 = u.pm * BM + wr * 64 + fr, col0 = u.pn * HALF + wc * 32 + 8 * fq;
; #pragma unroll
;         for (int ai = 0; ai < 2; ++ai)
; #pragma unroll
;             for (int m = 0; m < 4; ++m) { bf16_t* rowp = O + (size_t)(row0 + ai * HALF + m * 16) * ldc + col0;
;                 f32x4 v0, v1;
; #pragma unroll
;                 for (int j = 0; j < 1; ++j) { v0 = acc[ai][0][m][0] * sigmoid4(acc[ai][0][m][0]) * acc[ai][1][m][0]; v1 = acc[ai][0][m][1] * sigmoid4(acc[ai][0][m][1]) * acc[ai][1][m][1]; }
;                 u32x4 w; w.x = cvt_pk_bf16(v0[0], v0[1]); w.y = cvt_pk_bf16(v0[2], v0[3]); w.z = cvt_pk_bf16(v1[0], v1[1]); w.w = cvt_pk_bf16(v1[2], v1[3]);
;                 *(u32x4*)rowp = w; }
; template <class Epi, class Sched>
; __device__ __forceinline__ void gemm_phase(PG8_LAS unsigned char* lds, const Gemm g, const Sched& S, const Epi& E) {
;     ...
;             PG8_LDA(At, 1, 1); PG8_STAGE(PG8_SA(1, 0), a3, voffA);
;             PG8_BAR; PG8_WAIT_L(0); PG8_MMA(1, 0, At, B0); PG8_BAR; PG8_SCHED;
;             PG8_STAGE(PG8_SB(1, 1), b3 + hstep, voffB);
;             PG8_WAIT_V(6); PG8_BAR; PG8_MMA(1, 1, At, B1); PG8_BAR;
;         }
;         if constexpr (!Epi::AFTER_DRAIN) { E(acc, cur, wr, wc, fr, fq); S.done(cur); }
	ds_read_b128 v[170:173], v153 offset:49152
	ds_read_b128 v[182:185], v153 offset:50176
	ds_read_b128 v[190:193], v153 offset:51200
	ds_read_b128 v[194:197], v153 offset:52224
	ds_read_b128 v[198:201], v153 offset:53248
	ds_read_b128 v[202:205], v153 offset:54272
	ds_read_b128 v[206:209], v153 offset:55296
	ds_read_b128 v[210:213], v153 offset:56320
	s_add_i32 s35, s59, s40
	s_mov_b32 m0, s35
	s_nop 0
	global_load_lds_dwordx4 v132, s[98:99]
	s_nop 1
	s_add_i32 m0, s35, 0x2000
	s_nop 0
	global_load_lds_dwordx4 v128, s[98:99]
	s_nop 1
	s_mov_b32 m0, s47
	s_nop 0
	global_load_lds_dwordx4 v134, s[100:101]
	s_nop 1
	s_mov_b32 m0, s48
	s_nop 0
	global_load_lds_dwordx4 v130, s[100:101]
	s_add_u32 s30, s30, 0x40080
	s_addc_u32 s31, s31, 0
	s_add_i32 s34, s34, s40
	s_mov_b32 m0, s34
	s_nop 0
	global_load_lds_dwordx4 v132, s[30:31]
	s_nop 1
	s_add_i32 m0, s34, 0x2000
	s_nop 0
	global_load_lds_dwordx4 v128, s[30:31]
	s_waitcnt vmcnt(8) lgkmcnt(0)
	s_barrier
	v_mfma_f32_16x16x32_bf16 v[60:63], v[144:147], v[170:173], v[60:63]
	v_mfma_f32_16x16x32_bf16 v[56:59], v[160:163], v[170:173], v[56:59]
	v_mfma_f32_16x16x32_bf16 v[44:47], v[144:147], v[190:193], v[44:47]
	v_mfma_f32_16x16x32_bf16 v[40:43], v[160:163], v[190:193], v[40:43]
	v_mfma_f32_16x16x32_bf16 v[28:31], v[144:147], v[198:201], v[28:31]
	v_mfma_f32_16x16x32_bf16 v[24:27], v[160:163], v[198:201], v[24:27]
	v_mfma_f32_16x16x32_bf16 v[12:15], v[144:147], v[206:209], v[12:15]
	v_mfma_f32_16x16x32_bf16 v[8:11], v[160:163], v[206:209], v[8:11]
	v_mfma_f32_16x16x32_bf16 v[60:63], v[156:159], v[182:185], v[60:63]
	v_mfma_f32_16x16x32_bf16 v[56:59], v[166:169], v[182:185], v[56:59]
	v_mfma_f32_16x16x32_bf16 v[44:47], v[156:159], v[194:197], v[44:47]
	v_mfma_f32_16x16x32_bf16 v[40:43], v[166:169], v[194:197], v[40:43]
	v_mfma_f32_16x16x32_bf16 v[28:31], v[156:159], v[202:205], v[28:31]
	v_mfma_f32_16x16x32_bf16 v[24:27], v[166:169], v[202:205], v[24:27]
	v_mfma_f32_16x16x32_bf16 v[12:15], v[156:159], v[210:213], v[12:15]
	v_mfma_f32_16x16x32_bf16 v[8:11], v[166:169], v[210:213], v[8:11]
	v_mfma_f32_16x16x32_bf16 v[52:55], v[214:217], v[170:173], v[52:55]
	v_mfma_f32_16x16x32_bf16 v[48:51], v[222:225], v[170:173], v[48:51]
	v_mfma_f32_16x16x32_bf16 v[36:39], v[214:217], v[190:193], v[36:39]
	v_mfma_f32_16x16x32_bf16 v[32:35], v[222:225], v[190:193], v[32:35]
	v_mfma_f32_16x16x32_bf16 v[20:23], v[214:217], v[198:201], v[20:23]
	v_mfma_f32_16x16x32_bf16 v[16:19], v[222:225], v[198:201], v[16:19]
	v_mfma_f32_16x16x32_bf16 v[4:7], v[214:217], v[206:209], v[4:7]
	v_mfma_f32_16x16x32_bf16 v[0:3], v[222:225], v[206:209], v[0:3]
	v_mfma_f32_16x16x32_bf16 v[52:55], v[218:221], v[182:185], v[52:55]
	v_mfma_f32_16x16x32_bf16 v[48:51], v[226:229], v[182:185], v[48:51]
	v_mfma_f32_16x16x32_bf16 v[36:39], v[218:221], v[194:197], v[36:39]
	v_mfma_f32_16x16x32_bf16 v[32:35], v[226:229], v[194:197], v[32:35]
	v_mfma_f32_16x16x32_bf16 v[20:23], v[218:221], v[202:205], v[20:23]
	v_mfma_f32_16x16x32_bf16 v[16:19], v[226:229], v[202:205], v[16:19]
	v_mfma_f32_16x16x32_bf16 v[4:7], v[218:221], v[210:213], v[4:7]
	v_mfma_f32_16x16x32_bf16 v[0:3], v[226:229], v[210:213], v[0:3]
	s_barrier
	s_add_i32 s58, s58, 2
	s_add_u32 s28, s28, 0x100
	s_addc_u32 s29, s29, 0
	s_add_u32 s56, s56, 0x100
	s_addc_u32 s57, s57, 0
	s_cmp_gt_u32 s58, 13
	s_cbranch_scc0 .LBB0_195
	v_max_f32_e32 v144, 0xc1a00000, v124
	v_mul_f32_e32 v144, 0xbfb8aa3b, v144
	v_exp_f32_e32 v157, v144
	v_max_f32_e32 v144, 0xc1a00000, v125
	v_mul_f32_e32 v144, 0xbfb8aa3b, v144
	v_exp_f32_e32 v156, v144
	v_max_f32_e32 v144, 0xc1a00000, v126
	v_mul_f32_e32 v144, 0xbfb8aa3b, v144
	v_exp_f32_e32 v159, v144
	v_max_f32_e32 v144, 0xc1a00000, v127
	v_mul_f32_e32 v144, 0xbfb8aa3b, v144
	v_exp_f32_e32 v158, v144
	v_pk_add_f32 v[156:157], v[156:157], 1.0 op_sel_hi:[1,0]
	v_lshl_or_b32 v146, s53, 7, v150
	v_pk_add_f32 v[158:159], v[158:159], 1.0 op_sel_hi:[1,0]
	v_mul_f32_e32 v160, v157, v156
	v_mul_f32_e32 v161, v159, v158
	v_lshl_add_u32 v155, s26, 8, v148
	v_mul_f32_e32 v162, v160, v161
	v_rcp_f32_e32 v166, v162
	v_ashrrev_i32_e32 v147, 31, v146
	v_mov_b64_e32 v[144:145], s[4:5]
	v_mad_i64_i32 v[162:163], s[28:29], v155, s52, v[144:145]
	v_mul_f32_e32 v160, v160, v166
	v_mul_f32_e32 v164, v161, v166
	v_pk_mul_f32 v[158:159], v[158:159], v[160:161] op_sel_hi:[1,0]
	v_max_f32_e32 v160, 0xc1a00000, v120
	v_max_f32_e32 v166, 0xc1a00000, v122
	v_mul_f32_e32 v160, 0xbfb8aa3b, v160
	v_mul_f32_e32 v166, 0xbfb8aa3b, v166
	v_exp_f32_e32 v161, v160
	v_exp_f32_e32 v167, v166
	v_max_f32_e32 v160, 0xc1a00000, v121
	v_max_f32_e32 v166, 0xc1a00000, v123
	v_mul_f32_e32 v160, 0xbfb8aa3b, v160
	v_mul_f32_e32 v166, 0xbfb8aa3b, v166
	v_exp_f32_e32 v160, v160
	v_exp_f32_e32 v166, v166
	v_pk_mul_f32 v[156:157], v[156:157], v[164:165] op_sel_hi:[1,0]
	v_pk_mul_f32 v[126:127], v[126:127], v[158:159]
	v_pk_mul_f32 v[124:125], v[124:125], v[156:157]
	v_pk_add_f32 v[156:157], v[160:161], 1.0 op_sel_hi:[1,0]
	v_pk_add_f32 v[160:161], v[166:167], 1.0 op_sel_hi:[1,0]
	v_mul_f32_e32 v166, v157, v156
	v_mul_f32_e32 v167, v161, v160
	v_pk_mul_f32 v[118:119], v[126:127], v[118:119]
	v_mul_f32_e32 v164, v166, v167
	v_rcp_f32_e32 v164, v164
	v_pk_mul_f32 v[116:117], v[124:125], v[116:117]
	v_lshlrev_b64 v[146:147], 1, v[146:147]
	v_lshl_add_u64 v[162:163], v[162:163], 0, v[146:147]
	v_mul_f32_e32 v124, v167, v164
	v_mul_f32_e32 v126, v166, v164
	v_pk_mul_f32 v[126:127], v[160:161], v[126:127] op_sel_hi:[1,0]
	v_pk_mul_f32 v[124:125], v[156:157], v[124:125] op_sel_hi:[1,0]
	v_pk_mul_f32 v[122:123], v[122:123], v[126:127]
	v_pk_mul_f32 v[120:121], v[120:121], v[124:125]
	v_pk_mul_f32 v[122:123], v[122:123], v[114:115]
; __device__ __forceinline__ unsigned cvt_pk_bf16(float lo, float hi) { unsigned r; asm volatile("v_cvt_pk_bf16_f32 %0, %1, %2" : "=v"(r) : "v"(lo), "v"(hi)); return r; }
; __device__ __forceinline__ f32x4 sigmoid4(f32x4 x) {
;     f32x4 d;
; #pragma unroll
;     for (int j = 0; j < 4; ++j) d[j] = 1.0f + __expf(-fmaxf(x[j], -20.0f));
;     const float p01 = d[0] * d[1], p23 = d[2] * d[3], r = __builtin_amdgcn_rcpf(p01 * p23), r01 = r * p23, r23 = r * p01;
;     return (f32x4){r01 * d[1], r01 * d[0], r23 * d[3], r23 * d[2]};
; }
;     __device__ __forceinline__ void operator()(const f32x4 (&acc)[2][2][4][2], const Unit& u, int wr, int wc, int fr, int fq) const {
;     ...
;         for (int ai = 0; ai < 2; ++ai)
; #pragma unroll
;             for (int m = 0; m < 4; ++m) { bf16_t* rowp = O + (size_t)(row0 + ai * HALF + m * 16) * ldc + col0;
;                 f32x4 v0, v1;
; #pragma unroll
;                 for (int j = 0; j < 1; ++j) { v0 = acc[ai][0][m][0] * sigmoid4(acc[ai][0][m][0]) * acc[ai][1][m][0]; v1 = acc[ai][0][m][1] * sigmoid4(acc[ai][0][m][1]) * acc[ai][1][m][1]; }
;                 u32x4 w; w.x = cvt_pk_bf16(v0[0], v0[1]); w.y = cvt_pk_bf16(v0[2], v0[3]); w.z = cvt_pk_bf16(v1[0], v1[1]); w.w = cvt_pk_bf16(v1[2], v1[3]);
;                 *(u32x4*)rowp = w; }
	v_pk_mul_f32 v[114:115], v[120:121], v[112:113]
	v_cvt_pk_bf16_f32 v112, v116, v117
	v_cvt_pk_bf16_f32 v113, v118, v119
	v_max_f32_e32 v116, 0xc1a00000, v108
	v_max_f32_e32 v118, 0xc1a00000, v110
	v_mul_f32_e32 v116, 0xbfb8aa3b, v116
	v_mul_f32_e32 v118, 0xbfb8aa3b, v118
	v_exp_f32_e32 v117, v116
	v_exp_f32_e32 v119, v118
	v_max_f32_e32 v116, 0xc1a00000, v109
	v_max_f32_e32 v118, 0xc1a00000, v111
	v_mul_f32_e32 v116, 0xbfb8aa3b, v116
	v_mul_f32_e32 v118, 0xbfb8aa3b, v118
	v_exp_f32_e32 v116, v116
	v_exp_f32_e32 v118, v118
	v_cvt_pk_bf16_f32 v114, v114, v115
	v_cvt_pk_bf16_f32 v115, v122, v123
	global_store_dwordx4 v[162:163], v[112:115], off
	v_or_b32_e32 v120, 16, v155
	s_and_b64 vcc, exec, s[2:3]
	v_pk_add_f32 v[112:113], v[116:117], 1.0 op_sel_hi:[1,0]
	v_pk_add_f32 v[114:115], v[118:119], 1.0 op_sel_hi:[1,0]
	v_mul_f32_e32 v116, v113, v112
	v_mul_f32_e32 v117, v115, v114
	s_mov_b32 s53, s14
	v_mul_f32_e32 v118, v116, v117
	v_rcp_f32_e32 v121, v118
	v_mad_i64_i32 v[118:119], s[28:29], v120, s52, v[144:145]
	v_lshl_add_u64 v[118:119], v[118:119], 0, v[146:147]
	v_mul_f32_e32 v116, v116, v121
	v_mul_f32_e32 v120, v117, v121
	v_pk_mul_f32 v[114:115], v[114:115], v[116:117] op_sel_hi:[1,0]
	v_max_f32_e32 v116, 0xc1a00000, v104
	v_max_f32_e32 v121, 0xc1a00000, v106
	v_mul_f32_e32 v116, 0xbfb8aa3b, v116
	v_mul_f32_e32 v121, 0xbfb8aa3b, v121
	v_exp_f32_e32 v117, v116
	v_exp_f32_e32 v123, v121
	v_max_f32_e32 v116, 0xc1a00000, v105
	v_max_f32_e32 v121, 0xc1a00000, v107
	v_mul_f32_e32 v116, 0xbfb8aa3b, v116
	v_mul_f32_e32 v121, 0xbfb8aa3b, v121
	v_exp_f32_e32 v116, v116
	v_exp_f32_e32 v122, v121
	v_pk_mul_f32 v[112:113], v[112:113], v[120:121] op_sel_hi:[1,0]
	v_pk_mul_f32 v[110:111], v[110:111], v[114:115]
	v_pk_mul_f32 v[108:109], v[108:109], v[112:113]
	v_pk_add_f32 v[112:113], v[116:117], 1.0 op_sel_hi:[1,0]
	v_pk_add_f32 v[116:117], v[122:123], 1.0 op_sel_hi:[1,0]
	v_mul_f32_e32 v120, v113, v112
	v_mul_f32_e32 v121, v117, v116
	v_pk_mul_f32 v[102:103], v[110:111], v[102:103]
	v_mul_f32_e32 v122, v120, v121
	v_rcp_f32_e32 v122, v122
	v_pk_mul_f32 v[100:101], v[108:109], v[100:101]
	s_mov_b32 s26, s16
	s_mov_b64 s[30:31], s[24:25]
	v_mul_f32_e32 v108, v121, v122
	v_mul_f32_e32 v110, v120, v122
	v_pk_mul_f32 v[110:111], v[116:117], v[110:111] op_sel_hi:[1,0]
	v_pk_mul_f32 v[108:109], v[112:113], v[108:109] op_sel_hi:[1,0]
	v_pk_mul_f32 v[106:107], v[106:107], v[110:111]
	v_pk_mul_f32 v[104:105], v[104:105], v[108:109]
	v_pk_mul_f32 v[106:107], v[106:107], v[98:99]
	v_pk_mul_f32 v[98:99], v[104:105], v[96:97]
	v_cvt_pk_bf16_f32 v96, v100, v101
	v_cvt_pk_bf16_f32 v97, v102, v103
	v_max_f32_e32 v100, 0xc1a00000, v92
	v_max_f32_e32 v102, 0xc1a00000, v94
	v_mul_f32_e32 v100, 0xbfb8aa3b, v100
	v_mul_f32_e32 v102, 0xbfb8aa3b, v102
	v_exp_f32_e32 v101, v100
	v_exp_f32_e32 v103, v102
	v_max_f32_e32 v100, 0xc1a00000, v93
	v_max_f32_e32 v102, 0xc1a00000, v95
	v_mul_f32_e32 v100, 0xbfb8aa3b, v100
	v_mul_f32_e32 v102, 0xbfb8aa3b, v102
	v_exp_f32_e32 v100, v100
	v_exp_f32_e32 v102, v102
	v_cvt_pk_bf16_f32 v98, v98, v99
	v_cvt_pk_bf16_f32 v99, v106, v107
	global_store_dwordx4 v[118:119], v[96:99], off
	v_or_b32_e32 v104, 32, v155
	s_nop 0
	v_pk_add_f32 v[96:97], v[100:101], 1.0 op_sel_hi:[1,0]
	v_pk_add_f32 v[98:99], v[102:103], 1.0 op_sel_hi:[1,0]
	v_mul_f32_e32 v100, v97, v96
	v_mul_f32_e32 v101, v99, v98
	s_nop 0
	v_mul_f32_e32 v102, v100, v101
	v_rcp_f32_e32 v105, v102
	v_mad_i64_i32 v[102:103], s[28:29], v104, s52, v[144:145]
	v_lshl_add_u64 v[102:103], v[102:103], 0, v[146:147]
	v_mul_f32_e32 v100, v100, v105
	v_mul_f32_e32 v104, v101, v105
	v_pk_mul_f32 v[98:99], v[98:99], v[100:101] op_sel_hi:[1,0]
	v_max_f32_e32 v100, 0xc1a00000, v88
	v_max_f32_e32 v105, 0xc1a00000, v90
	v_mul_f32_e32 v100, 0xbfb8aa3b, v100
	v_mul_f32_e32 v105, 0xbfb8aa3b, v105
	v_exp_f32_e32 v101, v100
	v_exp_f32_e32 v107, v105
	v_max_f32_e32 v100, 0xc1a00000, v89
	v_max_f32_e32 v105, 0xc1a00000, v91
	v_mul_f32_e32 v100, 0xbfb8aa3b, v100
	v_mul_f32_e32 v105, 0xbfb8aa3b, v105
	v_exp_f32_e32 v100, v100
	v_exp_f32_e32 v106, v105
	v_pk_mul_f32 v[96:97], v[96:97], v[104:105] op_sel_hi:[1,0]
	v_pk_mul_f32 v[94:95], v[94:95], v[98:99]
	v_pk_mul_f32 v[92:93], v[92:93], v[96:97]
	v_pk_add_f32 v[96:97], v[100:101], 1.0 op_sel_hi:[1,0]
	v_pk_add_f32 v[100:101], v[106:107], 1.0 op_sel_hi:[1,0]
	v_mul_f32_e32 v104, v97, v96
	v_mul_f32_e32 v105, v101, v100
	v_pk_mul_f32 v[86:87], v[94:95], v[86:87]
	v_mul_f32_e32 v106, v104, v105
	v_rcp_f32_e32 v106, v106
	v_pk_mul_f32 v[84:85], v[92:93], v[84:85]
	v_mul_f32_e32 v92, v105, v106
	v_mul_f32_e32 v94, v104, v106
	v_pk_mul_f32 v[94:95], v[100:101], v[94:95] op_sel_hi:[1,0]
	v_pk_mul_f32 v[92:93], v[96:97], v[92:93] op_sel_hi:[1,0]
	v_pk_mul_f32 v[90:91], v[90:91], v[94:95]
	v_pk_mul_f32 v[88:89], v[88:89], v[92:93]
	v_pk_mul_f32 v[90:91], v[90:91], v[82:83]
	v_pk_mul_f32 v[82:83], v[88:89], v[80:81]
	v_cvt_pk_bf16_f32 v80, v84, v85
	v_cvt_pk_bf16_f32 v81, v86, v87
	v_max_f32_e32 v84, 0xc1a00000, v76
	v_max_f32_e32 v86, 0xc1a00000, v78
	v_mul_f32_e32 v84, 0xbfb8aa3b, v84
	v_mul_f32_e32 v86, 0xbfb8aa3b, v86
	v_exp_f32_e32 v85, v84
	v_exp_f32_e32 v87, v86
	v_max_f32_e32 v84, 0xc1a00000, v77
	v_max_f32_e32 v86, 0xc1a00000, v79
	v_mul_f32_e32 v84, 0xbfb8aa3b, v84
	v_mul_f32_e32 v86, 0xbfb8aa3b, v86
	v_exp_f32_e32 v84, v84
	v_exp_f32_e32 v86, v86
	v_cvt_pk_bf16_f32 v82, v82, v83
	v_cvt_pk_bf16_f32 v83, v90, v91
	global_store_dwordx4 v[102:103], v[80:83], off
	v_or_b32_e32 v88, 48, v155
	s_nop 0
	v_pk_add_f32 v[80:81], v[84:85], 1.0 op_sel_hi:[1,0]
	v_pk_add_f32 v[82:83], v[86:87], 1.0 op_sel_hi:[1,0]
	v_mul_f32_e32 v84, v81, v80
	v_mul_f32_e32 v85, v83, v82
; __device__ __forceinline__ unsigned cvt_pk_bf16(float lo, float hi) { unsigned r; asm volatile("v_cvt_pk_bf16_f32 %0, %1, %2" : "=v"(r) : "v"(lo), "v"(hi)); return r; }
; __device__ __forceinline__ f32x4 sigmoid4(f32x4 x) {
;     f32x4 d;
; #pragma unroll
;     for (int j = 0; j < 4; ++j) d[j] = 1.0f + __expf(-fmaxf(x[j], -20.0f));
;     const float p01 = d[0] * d[1], p23 = d[2] * d[3], r = __builtin_amdgcn_rcpf(p01 * p23), r01 = r * p23, r23 = r * p01;
;     return (f32x4){r01 * d[1], r01 * d[0], r23 * d[3], r23 * d[2]};
; }
;     __device__ __forceinline__ void operator()(const f32x4 (&acc)[2][2][4][2], const Unit& u, int wr, int wc, int fr, int fq) const {
;     ...
;         for (int ai = 0; ai < 2; ++ai)
; #pragma unroll
;             for (int m = 0; m < 4; ++m) { bf16_t* rowp = O + (size_t)(row0 + ai * HALF + m * 16) * ldc + col0;
;                 f32x4 v0, v1;
; #pragma unroll
;                 for (int j = 0; j < 1; ++j) { v0 = acc[ai][0][m][0] * sigmoid4(acc[ai][0][m][0]) * acc[ai][1][m][0]; v1 = acc[ai][0][m][1] * sigmoid4(acc[ai][0][m][1]) * acc[ai][1][m][1]; }
;                 u32x4 w; w.x = cvt_pk_bf16(v0[0], v0[1]); w.y = cvt_pk_bf16(v0[2], v0[3]); w.z = cvt_pk_bf16(v1[0], v1[1]); w.w = cvt_pk_bf16(v1[2], v1[3]);
;                 *(u32x4*)rowp = w; }
	s_nop 0
	v_mul_f32_e32 v86, v84, v85
	v_rcp_f32_e32 v89, v86
	v_mad_i64_i32 v[86:87], s[28:29], v88, s52, v[144:145]
	v_lshl_add_u64 v[86:87], v[86:87], 0, v[146:147]
	v_mul_f32_e32 v84, v84, v89
	v_mul_f32_e32 v88, v85, v89
	v_pk_mul_f32 v[82:83], v[82:83], v[84:85] op_sel_hi:[1,0]
	v_max_f32_e32 v84, 0xc1a00000, v72
	v_max_f32_e32 v89, 0xc1a00000, v74
	v_mul_f32_e32 v84, 0xbfb8aa3b, v84
	v_mul_f32_e32 v89, 0xbfb8aa3b, v89
	v_exp_f32_e32 v85, v84
	v_exp_f32_e32 v91, v89
	v_max_f32_e32 v84, 0xc1a00000, v73
	v_max_f32_e32 v89, 0xc1a00000, v75
	v_mul_f32_e32 v84, 0xbfb8aa3b, v84
	v_mul_f32_e32 v89, 0xbfb8aa3b, v89
	v_exp_f32_e32 v84, v84
	v_exp_f32_e32 v90, v89
	v_pk_mul_f32 v[80:81], v[80:81], v[88:89] op_sel_hi:[1,0]
	v_pk_mul_f32 v[78:79], v[78:79], v[82:83]
	v_pk_mul_f32 v[76:77], v[76:77], v[80:81]
	v_pk_add_f32 v[80:81], v[84:85], 1.0 op_sel_hi:[1,0]
	v_pk_add_f32 v[84:85], v[90:91], 1.0 op_sel_hi:[1,0]
	v_mul_f32_e32 v88, v81, v80
	v_mul_f32_e32 v89, v85, v84
	v_pk_mul_f32 v[70:71], v[78:79], v[70:71]
	v_mul_f32_e32 v90, v88, v89
	v_rcp_f32_e32 v90, v90
	v_pk_mul_f32 v[68:69], v[76:77], v[68:69]
	v_mul_f32_e32 v76, v89, v90
	v_mul_f32_e32 v78, v88, v90
	v_pk_mul_f32 v[78:79], v[84:85], v[78:79] op_sel_hi:[1,0]
	v_pk_mul_f32 v[76:77], v[80:81], v[76:77] op_sel_hi:[1,0]
	v_pk_mul_f32 v[74:75], v[74:75], v[78:79]
	v_pk_mul_f32 v[72:73], v[72:73], v[76:77]
	v_pk_mul_f32 v[74:75], v[74:75], v[66:67]
	v_pk_mul_f32 v[66:67], v[72:73], v[64:65]
	v_cvt_pk_bf16_f32 v64, v68, v69
	v_cvt_pk_bf16_f32 v65, v70, v71
	v_max_f32_e32 v68, 0xc1a00000, v60
	v_max_f32_e32 v70, 0xc1a00000, v62
	v_mul_f32_e32 v68, 0xbfb8aa3b, v68
	v_mul_f32_e32 v70, 0xbfb8aa3b, v70
	v_exp_f32_e32 v69, v68
	v_exp_f32_e32 v71, v70
	v_max_f32_e32 v68, 0xc1a00000, v61
	v_max_f32_e32 v70, 0xc1a00000, v63
	v_mul_f32_e32 v68, 0xbfb8aa3b, v68
	v_mul_f32_e32 v70, 0xbfb8aa3b, v70
	v_exp_f32_e32 v68, v68
	v_exp_f32_e32 v70, v70
	v_cvt_pk_bf16_f32 v66, v66, v67
	v_cvt_pk_bf16_f32 v67, v74, v75
	global_store_dwordx4 v[86:87], v[64:67], off
	v_add_u32_e32 v72, 0x80, v155
	s_nop 0
	v_pk_add_f32 v[64:65], v[68:69], 1.0 op_sel_hi:[1,0]
	v_pk_add_f32 v[66:67], v[70:71], 1.0 op_sel_hi:[1,0]
	v_mul_f32_e32 v68, v65, v64
	v_mul_f32_e32 v69, v67, v66
	s_nop 0
	v_mul_f32_e32 v70, v68, v69
	v_rcp_f32_e32 v73, v70
	v_mad_i64_i32 v[70:71], s[28:29], v72, s52, v[144:145]
	v_lshl_add_u64 v[70:71], v[70:71], 0, v[146:147]
	v_mul_f32_e32 v68, v68, v73
	v_mul_f32_e32 v72, v69, v73
	v_pk_mul_f32 v[66:67], v[66:67], v[68:69] op_sel_hi:[1,0]
	v_max_f32_e32 v68, 0xc1a00000, v56
	v_max_f32_e32 v73, 0xc1a00000, v58
	v_mul_f32_e32 v68, 0xbfb8aa3b, v68
	v_mul_f32_e32 v73, 0xbfb8aa3b, v73
	v_exp_f32_e32 v69, v68
	v_exp_f32_e32 v75, v73
	v_max_f32_e32 v68, 0xc1a00000, v57
	v_max_f32_e32 v73, 0xc1a00000, v59
	v_mul_f32_e32 v68, 0xbfb8aa3b, v68
	v_mul_f32_e32 v73, 0xbfb8aa3b, v73
	v_exp_f32_e32 v68, v68
	v_exp_f32_e32 v74, v73
	v_pk_mul_f32 v[64:65], v[64:65], v[72:73] op_sel_hi:[1,0]
	v_pk_mul_f32 v[62:63], v[62:63], v[66:67]
	v_pk_mul_f32 v[60:61], v[60:61], v[64:65]
	v_pk_add_f32 v[64:65], v[68:69], 1.0 op_sel_hi:[1,0]
	v_pk_add_f32 v[68:69], v[74:75], 1.0 op_sel_hi:[1,0]
	v_mul_f32_e32 v72, v65, v64
	v_mul_f32_e32 v73, v69, v68
	v_pk_mul_f32 v[54:55], v[62:63], v[54:55]
	v_mul_f32_e32 v74, v72, v73
	v_rcp_f32_e32 v74, v74
	v_pk_mul_f32 v[52:53], v[60:61], v[52:53]
	v_mul_f32_e32 v60, v73, v74
	v_mul_f32_e32 v62, v72, v74
	v_pk_mul_f32 v[62:63], v[68:69], v[62:63] op_sel_hi:[1,0]
	v_pk_mul_f32 v[60:61], v[64:65], v[60:61] op_sel_hi:[1,0]
	v_pk_mul_f32 v[58:59], v[58:59], v[62:63]
	v_pk_mul_f32 v[56:57], v[56:57], v[60:61]
	v_pk_mul_f32 v[58:59], v[58:59], v[50:51]
	v_pk_mul_f32 v[50:51], v[56:57], v[48:49]
	v_cvt_pk_bf16_f32 v48, v52, v53
	v_cvt_pk_bf16_f32 v49, v54, v55
	v_max_f32_e32 v52, 0xc1a00000, v44
	v_max_f32_e32 v54, 0xc1a00000, v46
	v_mul_f32_e32 v52, 0xbfb8aa3b, v52
	v_mul_f32_e32 v54, 0xbfb8aa3b, v54
	v_exp_f32_e32 v53, v52
	v_exp_f32_e32 v55, v54
	v_max_f32_e32 v52, 0xc1a00000, v45
	v_max_f32_e32 v54, 0xc1a00000, v47
	v_mul_f32_e32 v52, 0xbfb8aa3b, v52
	v_mul_f32_e32 v54, 0xbfb8aa3b, v54
	v_exp_f32_e32 v52, v52
	v_exp_f32_e32 v54, v54
	v_cvt_pk_bf16_f32 v50, v50, v51
	v_cvt_pk_bf16_f32 v51, v58, v59
	global_store_dwordx4 v[70:71], v[48:51], off
	v_add_u32_e32 v56, 0x90, v155
	s_nop 0
	v_pk_add_f32 v[48:49], v[52:53], 1.0 op_sel_hi:[1,0]
	v_pk_add_f32 v[50:51], v[54:55], 1.0 op_sel_hi:[1,0]
	v_mul_f32_e32 v52, v49, v48
	v_mul_f32_e32 v53, v51, v50
	s_nop 0
	v_mul_f32_e32 v54, v52, v53
	v_rcp_f32_e32 v57, v54
	v_mad_i64_i32 v[54:55], s[28:29], v56, s52, v[144:145]
	v_lshl_add_u64 v[54:55], v[54:55], 0, v[146:147]
	v_mul_f32_e32 v52, v52, v57
	v_mul_f32_e32 v56, v53, v57
	v_pk_mul_f32 v[50:51], v[50:51], v[52:53] op_sel_hi:[1,0]
	v_max_f32_e32 v52, 0xc1a00000, v40
	v_max_f32_e32 v57, 0xc1a00000, v42
	v_mul_f32_e32 v52, 0xbfb8aa3b, v52
	v_mul_f32_e32 v57, 0xbfb8aa3b, v57
	v_exp_f32_e32 v53, v52
	v_exp_f32_e32 v59, v57
	v_max_f32_e32 v52, 0xc1a00000, v41
	v_max_f32_e32 v57, 0xc1a00000, v43
	v_mul_f32_e32 v52, 0xbfb8aa3b, v52
	v_mul_f32_e32 v57, 0xbfb8aa3b, v57
	v_exp_f32_e32 v52, v52
	v_exp_f32_e32 v58, v57
	v_pk_mul_f32 v[48:49], v[48:49], v[56:57] op_sel_hi:[1,0]
	v_pk_mul_f32 v[46:47], v[46:47], v[50:51]
	v_pk_mul_f32 v[44:45], v[44:45], v[48:49]
	v_pk_add_f32 v[48:49], v[52:53], 1.0 op_sel_hi:[1,0]
; __device__ __forceinline__ unsigned cvt_pk_bf16(float lo, float hi) { unsigned r; asm volatile("v_cvt_pk_bf16_f32 %0, %1, %2" : "=v"(r) : "v"(lo), "v"(hi)); return r; }
; __device__ __forceinline__ f32x4 sigmoid4(f32x4 x) {
;     f32x4 d;
; #pragma unroll
;     for (int j = 0; j < 4; ++j) d[j] = 1.0f + __expf(-fmaxf(x[j], -20.0f));
;     const float p01 = d[0] * d[1], p23 = d[2] * d[3], r = __builtin_amdgcn_rcpf(p01 * p23), r01 = r * p23, r23 = r * p01;
;     return (f32x4){r01 * d[1], r01 * d[0], r23 * d[3], r23 * d[2]};
; }
;     __device__ __forceinline__ void operator()(const f32x4 (&acc)[2][2][4][2], const Unit& u, int wr, int wc, int fr, int fq) const {
;     ...
;         for (int ai = 0; ai < 2; ++ai)
; #pragma unroll
;             for (int m = 0; m < 4; ++m) { bf16_t* rowp = O + (size_t)(row0 + ai * HALF + m * 16) * ldc + col0;
;                 f32x4 v0, v1;
; #pragma unroll
;                 for (int j = 0; j < 1; ++j) { v0 = acc[ai][0][m][0] * sigmoid4(acc[ai][0][m][0]) * acc[ai][1][m][0]; v1 = acc[ai][0][m][1] * sigmoid4(acc[ai][0][m][1]) * acc[ai][1][m][1]; }
;                 u32x4 w; w.x = cvt_pk_bf16(v0[0], v0[1]); w.y = cvt_pk_bf16(v0[2], v0[3]); w.z = cvt_pk_bf16(v1[0], v1[1]); w.w = cvt_pk_bf16(v1[2], v1[3]);
;                 *(u32x4*)rowp = w; }
	v_pk_add_f32 v[52:53], v[58:59], 1.0 op_sel_hi:[1,0]
	v_mul_f32_e32 v56, v49, v48
	v_mul_f32_e32 v57, v53, v52
	v_pk_mul_f32 v[38:39], v[46:47], v[38:39]
	v_mul_f32_e32 v58, v56, v57
	v_rcp_f32_e32 v58, v58
	v_pk_mul_f32 v[36:37], v[44:45], v[36:37]
	v_mul_f32_e32 v44, v57, v58
	v_mul_f32_e32 v46, v56, v58
	v_pk_mul_f32 v[46:47], v[52:53], v[46:47] op_sel_hi:[1,0]
	v_pk_mul_f32 v[44:45], v[48:49], v[44:45] op_sel_hi:[1,0]
	v_pk_mul_f32 v[42:43], v[42:43], v[46:47]
	v_pk_mul_f32 v[40:41], v[40:41], v[44:45]
	v_pk_mul_f32 v[42:43], v[42:43], v[34:35]
	v_pk_mul_f32 v[34:35], v[40:41], v[32:33]
	v_cvt_pk_bf16_f32 v32, v36, v37
	v_cvt_pk_bf16_f32 v33, v38, v39
	v_max_f32_e32 v36, 0xc1a00000, v28
	v_max_f32_e32 v38, 0xc1a00000, v30
	v_mul_f32_e32 v36, 0xbfb8aa3b, v36
	v_mul_f32_e32 v38, 0xbfb8aa3b, v38
	v_exp_f32_e32 v37, v36
	v_exp_f32_e32 v39, v38
	v_max_f32_e32 v36, 0xc1a00000, v29
	v_max_f32_e32 v38, 0xc1a00000, v31
	v_mul_f32_e32 v36, 0xbfb8aa3b, v36
	v_mul_f32_e32 v38, 0xbfb8aa3b, v38
	v_exp_f32_e32 v36, v36
	v_exp_f32_e32 v38, v38
	v_cvt_pk_bf16_f32 v34, v34, v35
	v_cvt_pk_bf16_f32 v35, v42, v43
	global_store_dwordx4 v[54:55], v[32:35], off
	v_add_u32_e32 v40, 0xa0, v155
	s_nop 0
	v_pk_add_f32 v[32:33], v[36:37], 1.0 op_sel_hi:[1,0]
	v_pk_add_f32 v[34:35], v[38:39], 1.0 op_sel_hi:[1,0]
	v_mul_f32_e32 v36, v33, v32
	v_mul_f32_e32 v37, v35, v34
	s_nop 0
	v_mul_f32_e32 v38, v36, v37
	v_rcp_f32_e32 v41, v38
	v_mad_i64_i32 v[38:39], s[28:29], v40, s52, v[144:145]
	v_lshl_add_u64 v[38:39], v[38:39], 0, v[146:147]
	v_mul_f32_e32 v36, v36, v41
	v_mul_f32_e32 v40, v37, v41
	v_pk_mul_f32 v[34:35], v[34:35], v[36:37] op_sel_hi:[1,0]
	v_max_f32_e32 v36, 0xc1a00000, v24
	v_max_f32_e32 v41, 0xc1a00000, v26
	v_mul_f32_e32 v36, 0xbfb8aa3b, v36
	v_mul_f32_e32 v41, 0xbfb8aa3b, v41
	v_exp_f32_e32 v37, v36
	v_exp_f32_e32 v43, v41
	v_max_f32_e32 v36, 0xc1a00000, v25
	v_max_f32_e32 v41, 0xc1a00000, v27
	v_mul_f32_e32 v36, 0xbfb8aa3b, v36
	v_mul_f32_e32 v41, 0xbfb8aa3b, v41
	v_exp_f32_e32 v36, v36
	v_exp_f32_e32 v42, v41
	v_pk_mul_f32 v[32:33], v[32:33], v[40:41] op_sel_hi:[1,0]
	v_pk_mul_f32 v[30:31], v[30:31], v[34:35]
	v_pk_mul_f32 v[28:29], v[28:29], v[32:33]
	v_pk_add_f32 v[32:33], v[36:37], 1.0 op_sel_hi:[1,0]
	v_pk_add_f32 v[36:37], v[42:43], 1.0 op_sel_hi:[1,0]
	v_mul_f32_e32 v40, v33, v32
	v_mul_f32_e32 v41, v37, v36
	v_pk_mul_f32 v[22:23], v[30:31], v[22:23]
	v_mul_f32_e32 v42, v40, v41
	v_rcp_f32_e32 v42, v42
	v_pk_mul_f32 v[20:21], v[28:29], v[20:21]
	v_mul_f32_e32 v28, v41, v42
	v_mul_f32_e32 v30, v40, v42
	v_pk_mul_f32 v[30:31], v[36:37], v[30:31] op_sel_hi:[1,0]
	v_pk_mul_f32 v[28:29], v[32:33], v[28:29] op_sel_hi:[1,0]
	v_pk_mul_f32 v[26:27], v[26:27], v[30:31]
	v_pk_mul_f32 v[24:25], v[24:25], v[28:29]
	v_pk_mul_f32 v[26:27], v[26:27], v[18:19]
	v_pk_mul_f32 v[18:19], v[24:25], v[16:17]
	v_cvt_pk_bf16_f32 v16, v20, v21
	v_cvt_pk_bf16_f32 v17, v22, v23
	v_max_f32_e32 v20, 0xc1a00000, v12
	v_max_f32_e32 v22, 0xc1a00000, v14
	v_mul_f32_e32 v20, 0xbfb8aa3b, v20
	v_mul_f32_e32 v22, 0xbfb8aa3b, v22
	v_exp_f32_e32 v21, v20
	v_exp_f32_e32 v23, v22
	v_max_f32_e32 v20, 0xc1a00000, v13
	v_max_f32_e32 v22, 0xc1a00000, v15
	v_mul_f32_e32 v20, 0xbfb8aa3b, v20
	v_mul_f32_e32 v22, 0xbfb8aa3b, v22
	v_exp_f32_e32 v20, v20
	v_exp_f32_e32 v22, v22
	v_cvt_pk_bf16_f32 v18, v18, v19
	v_cvt_pk_bf16_f32 v19, v26, v27
	global_store_dwordx4 v[38:39], v[16:19], off
	v_add_u32_e32 v24, 0xb0, v155
	s_nop 0
	v_pk_add_f32 v[16:17], v[20:21], 1.0 op_sel_hi:[1,0]
	v_pk_add_f32 v[18:19], v[22:23], 1.0 op_sel_hi:[1,0]
	v_mul_f32_e32 v20, v17, v16
	v_mul_f32_e32 v21, v19, v18
	s_nop 0
	v_mul_f32_e32 v22, v20, v21
	v_rcp_f32_e32 v25, v22
	v_mad_i64_i32 v[22:23], s[28:29], v24, s52, v[144:145]
	v_lshl_add_u64 v[22:23], v[22:23], 0, v[146:147]
	v_mul_f32_e32 v20, v20, v25
	v_mul_f32_e32 v24, v21, v25
	v_pk_mul_f32 v[18:19], v[18:19], v[20:21] op_sel_hi:[1,0]
	v_max_f32_e32 v20, 0xc1a00000, v8
	v_max_f32_e32 v25, 0xc1a00000, v10
	v_mul_f32_e32 v20, 0xbfb8aa3b, v20
	v_mul_f32_e32 v25, 0xbfb8aa3b, v25
	v_exp_f32_e32 v21, v20
	v_exp_f32_e32 v27, v25
	v_max_f32_e32 v20, 0xc1a00000, v9
	v_max_f32_e32 v25, 0xc1a00000, v11
	v_mul_f32_e32 v20, 0xbfb8aa3b, v20
	v_mul_f32_e32 v25, 0xbfb8aa3b, v25
	v_exp_f32_e32 v20, v20
	v_exp_f32_e32 v26, v25
	v_pk_mul_f32 v[16:17], v[16:17], v[24:25] op_sel_hi:[1,0]
	v_pk_mul_f32 v[14:15], v[14:15], v[18:19]
	v_pk_mul_f32 v[12:13], v[12:13], v[16:17]
	v_pk_add_f32 v[16:17], v[20:21], 1.0 op_sel_hi:[1,0]
	v_pk_add_f32 v[20:21], v[26:27], 1.0 op_sel_hi:[1,0]
	v_mul_f32_e32 v24, v17, v16
	v_mul_f32_e32 v25, v21, v20
	v_pk_mul_f32 v[6:7], v[14:15], v[6:7]
	v_mul_f32_e32 v26, v24, v25
	v_rcp_f32_e32 v26, v26
	v_pk_mul_f32 v[4:5], v[12:13], v[4:5]
	s_mov_b64 s[28:29], s[18:19]
	v_mul_f32_e32 v12, v25, v26
	v_mul_f32_e32 v14, v24, v26
	v_pk_mul_f32 v[14:15], v[20:21], v[14:15] op_sel_hi:[1,0]
	v_pk_mul_f32 v[12:13], v[16:17], v[12:13] op_sel_hi:[1,0]
	v_pk_mul_f32 v[10:11], v[10:11], v[14:15]
	v_pk_mul_f32 v[8:9], v[8:9], v[12:13]
	v_pk_mul_f32 v[10:11], v[10:11], v[2:3]
	v_pk_mul_f32 v[2:3], v[8:9], v[0:1]
	v_cvt_pk_bf16_f32 v0, v4, v5
	v_cvt_pk_bf16_f32 v1, v6, v7
	s_nop 0
	v_cvt_pk_bf16_f32 v2, v2, v3
	v_cvt_pk_bf16_f32 v3, v10, v11
	global_store_dwordx4 v[22:23], v[0:3], off
	s_cbranch_vccz .LBB0_192
	s_waitcnt vmcnt(0)
	s_cmpk_gt_u32 s37, 0xff
	s_cbranch_scc1 .LBB0_199
	s_barrier

; #define PG8_STAGE(bufoff, gbase, voff) do { _Pragma("unroll") for (int _i = 0; _i < 2; ++_i) \
;         __builtin_amdgcn_global_load_lds((const unsigned*)((const char*)(gbase) + (voff)[_i]), (PG8_LAS unsigned*)(lds + (bufoff) + ldsw + _i * 8192), 16, 0, 0); } while (0)
; #define PG8_LDA(dst, b, h) do { _Pragma("unroll") for (int m = 0; m < 4; ++m) _Pragma("unroll") for (int k = 0; k < 2; ++k) dst[m][k] = *(const PG8_LAS bf16x8*)(lds + PG8_SA(b, h) + aoff + m * 2048 + k * 1024); } while (0)
; #define PG8_LDB(dst, b, h) do { _Pragma("unroll") for (int n = 0; n < 2; ++n) _Pragma("unroll") for (int k = 0; k < 2; ++k) dst[n][k] = *(const PG8_LAS bf16x8*)(lds + PG8_SB(b, h) + boff + n * 2048 + k * 1024); } while (0)
; #define PG8_MMA(ai, bj, At, Bt) do { __builtin_amdgcn_s_setprio(1); _Pragma("unroll") for (int m = 0; m < 4; ++m) _Pragma("unroll") for (int n = 0; n < 2; ++n) _Pragma("unroll") for (int k = 0; k < 2; ++k) \
;         acc[ai][bj][m][n] = __builtin_amdgcn_mfma_f32_16x16x32_bf16(Bt[n][k], At[m][k], acc[ai][bj][m][n], 0, 0, 0); __builtin_amdgcn_s_setprio(0); } while (0)
; #define PG8_WAIT_V(n) asm volatile("s_waitcnt vmcnt(" #n ")" ::: "memory")
; template <class Epi, class Sched>
; __device__ __forceinline__ void gemm_phase(PG8_LAS unsigned char* lds, const Gemm g, const Sched& S, const Epi& E) {
;     ...
;         for (int t = 0; t < nt; t += 2) {
;             const bool last = (t == nt - 2);
;             const char* a1 = cA + (size_t)(t + 1) * kstep;
;             const char* a2 = last ? nA : cA + (size_t)(t + 2) * kstep; const char* b2 = last ? nB : cB + (size_t)(t + 2) * kstep;
;             const char* a3 = a2 + kstep; const char* b3 = b2 + kstep;
;             if (last && has_next) S.a_ready(nxt);
;             PG8_LDB(B0, 0, 0); PG8_SCHED; PG8_LDA(At, 0, 0); PG8_STAGE(PG8_SA(1, 1), a1 + hstep, voffA);
;             PG8_WAIT_L(8); PG8_BAR; PG8_WAIT_L(0); PG8_MMA(0, 0, At, B0); PG8_BAR; PG8_SCHED;
;             PG8_LDB(B1, 0, 1); PG8_STAGE(PG8_SB(0, 0), b2, voffB);
;             PG8_BAR; PG8_WAIT_L(0); PG8_MMA(0, 1, At, B1); PG8_BAR;
;             PG8_LDA(At, 0, 1); PG8_STAGE(PG8_SA(0, 0), a2, voffA);
;             PG8_BAR; PG8_WAIT_L(0); PG8_MMA(1, 0, At, B0); PG8_BAR; PG8_SCHED;
;             PG8_STAGE(PG8_SB(0, 1), b2 + hstep, voffB);
;             PG8_WAIT_V(6); PG8_BAR; PG8_MMA(1, 1, At, B1); PG8_BAR;
.LBB0_285:
	s_add_u32 s55, s24, 0x100
	s_addc_u32 s56, s25, 0
	s_mov_b32 s57, -2
	ds_read_b128 v[154:157], v149
	ds_read_b128 v[158:161], v149 offset:1024
	ds_read_b128 v[166:169], v149 offset:2048
	ds_read_b128 v[170:173], v149 offset:3072
	s_add_u32 s24, s22, 0x100
	s_addc_u32 s25, s23, 0
	s_cmp_eq_u32 s57, 40
	s_cselect_b32 s29, s1, s25
	s_cselect_b32 s28, s0, s24
	s_cselect_b32 s27, s5, s56
	s_cselect_b32 s26, s4, s55
	s_add_i32 m0, s38, 0xc000
	ds_read_b128 v[182:185], v150
	ds_read_b128 v[190:193], v150 offset:1024
	ds_read_b128 v[194:197], v150 offset:2048
	ds_read_b128 v[198:201], v150 offset:3072
	ds_read_b128 v[202:205], v150 offset:4096
	ds_read_b128 v[206:209], v150 offset:5120
	ds_read_b128 v[210:213], v150 offset:6144
	ds_read_b128 v[214:217], v150 offset:7168
	global_load_lds_dwordx4 v136, s[22:23]
	s_nop 1
	s_add_i32 m0, s38, 0xe000
	s_nop 0
	global_load_lds_dwordx4 v138, s[22:23]
	s_waitcnt lgkmcnt(12)
	ds_read_b128 v[218:221], v151
	ds_read_b128 v[222:225], v151 offset:1024
	ds_read_b128 v[226:229], v151 offset:2048
	ds_read_b128 v[230:233], v151 offset:3072
	s_waitcnt vmcnt(8) lgkmcnt(0)
	s_barrier
	v_mfma_f32_16x16x32_bf16 v[124:127], v[154:157], v[182:185], 0
	v_mfma_f32_16x16x32_bf16 v[120:123], v[166:169], v[182:185], 0
	v_mfma_f32_16x16x32_bf16 v[108:111], v[154:157], v[194:197], 0
	v_mfma_f32_16x16x32_bf16 v[104:107], v[166:169], v[194:197], 0
	v_mfma_f32_16x16x32_bf16 v[92:95], v[154:157], v[202:205], 0
	v_mfma_f32_16x16x32_bf16 v[88:91], v[166:169], v[202:205], 0
	v_mfma_f32_16x16x32_bf16 v[76:79], v[154:157], v[210:213], 0
	v_mfma_f32_16x16x32_bf16 v[72:75], v[166:169], v[210:213], 0
	v_mfma_f32_16x16x32_bf16 v[124:127], v[158:161], v[190:193], v[124:127]
	v_mfma_f32_16x16x32_bf16 v[120:123], v[170:173], v[190:193], v[120:123]
	v_mfma_f32_16x16x32_bf16 v[108:111], v[158:161], v[198:201], v[108:111]
	v_mfma_f32_16x16x32_bf16 v[104:107], v[170:173], v[198:201], v[104:107]
	v_mfma_f32_16x16x32_bf16 v[92:95], v[158:161], v[206:209], v[92:95]
	v_mfma_f32_16x16x32_bf16 v[88:91], v[170:173], v[206:209], v[88:91]
	v_mfma_f32_16x16x32_bf16 v[76:79], v[158:161], v[214:217], v[76:79]
	v_mfma_f32_16x16x32_bf16 v[72:75], v[170:173], v[214:217], v[72:75]
	v_mfma_f32_16x16x32_bf16 v[116:119], v[218:221], v[182:185], 0
	v_mfma_f32_16x16x32_bf16 v[112:115], v[226:229], v[182:185], 0
	v_mfma_f32_16x16x32_bf16 v[100:103], v[218:221], v[194:197], 0
	v_mfma_f32_16x16x32_bf16 v[96:99], v[226:229], v[194:197], 0
	v_mfma_f32_16x16x32_bf16 v[84:87], v[218:221], v[202:205], 0
	v_mfma_f32_16x16x32_bf16 v[80:83], v[226:229], v[202:205], 0
	v_mfma_f32_16x16x32_bf16 v[68:71], v[218:221], v[210:213], 0
	v_mfma_f32_16x16x32_bf16 v[64:67], v[226:229], v[210:213], 0
	v_mfma_f32_16x16x32_bf16 v[116:119], v[222:225], v[190:193], v[116:119]
	v_mfma_f32_16x16x32_bf16 v[112:115], v[230:233], v[190:193], v[112:115]
	v_mfma_f32_16x16x32_bf16 v[100:103], v[222:225], v[198:201], v[100:103]
	v_mfma_f32_16x16x32_bf16 v[96:99], v[230:233], v[198:201], v[96:99]
	v_mfma_f32_16x16x32_bf16 v[84:87], v[222:225], v[206:209], v[84:87]
	v_mfma_f32_16x16x32_bf16 v[80:83], v[230:233], v[206:209], v[80:83]
	v_mfma_f32_16x16x32_bf16 v[68:71], v[222:225], v[214:217], v[68:71]
	v_mfma_f32_16x16x32_bf16 v[64:67], v[230:233], v[214:217], v[64:67]
	s_barrier
	ds_read_b128 v[182:185], v150 offset:16384
	ds_read_b128 v[190:193], v150 offset:17408
	ds_read_b128 v[194:197], v150 offset:18432
	ds_read_b128 v[198:201], v150 offset:19456
	ds_read_b128 v[202:205], v150 offset:20480
	ds_read_b128 v[206:209], v150 offset:21504
	ds_read_b128 v[210:213], v150 offset:22528
	ds_read_b128 v[214:217], v150 offset:23552
	s_add_i32 s22, s46, s37
	s_add_u32 s98, s26, s14
	s_addc_u32 s99, s27, s15
	s_mov_b32 m0, s22
	s_nop 0
	global_load_lds_dwordx4 v130, s[26:27]
	s_nop 1
	s_add_i32 m0, s22, 0x2000
	s_nop 0
	global_load_lds_dwordx4 v134, s[26:27]
	s_nop 1
	s_mov_b32 m0, s38
	s_add_u32 s100, s28, s14
	s_addc_u32 s101, s29, s15
	global_load_lds_dwordx4 v128, s[28:29]
	s_nop 1
	s_mov_b32 m0, s39
	s_nop 0
	global_load_lds_dwordx4 v132, s[28:29]
	s_add_u32 s22, s26, 0xb0000
	s_addc_u32 s23, s27, 0
	s_add_i32 s58, s47, s37
	s_mov_b32 m0, s58
	s_nop 0
	global_load_lds_dwordx4 v130, s[22:23]
	s_nop 1
	s_add_i32 m0, s58, 0x2000
	s_nop 0
	global_load_lds_dwordx4 v134, s[22:23]
	s_waitcnt vmcnt(8) lgkmcnt(0)
	s_barrier
	v_mfma_f32_16x16x32_bf16 v[60:63], v[154:157], v[182:185], 0
	v_mfma_f32_16x16x32_bf16 v[56:59], v[166:169], v[182:185], 0
	v_mfma_f32_16x16x32_bf16 v[48:51], v[154:157], v[194:197], 0
	v_mfma_f32_16x16x32_bf16 v[40:43], v[166:169], v[194:197], 0
	v_mfma_f32_16x16x32_bf16 v[32:35], v[154:157], v[202:205], 0
	v_mfma_f32_16x16x32_bf16 v[24:27], v[166:169], v[202:205], 0
	v_mfma_f32_16x16x32_bf16 v[16:19], v[154:157], v[210:213], 0
	v_mfma_f32_16x16x32_bf16 v[8:11], v[166:169], v[210:213], 0
	v_mfma_f32_16x16x32_bf16 v[60:63], v[158:161], v[190:193], v[60:63]
	v_mfma_f32_16x16x32_bf16 v[56:59], v[170:173], v[190:193], v[56:59]
	v_mfma_f32_16x16x32_bf16 v[48:51], v[158:161], v[198:201], v[48:51]
	v_mfma_f32_16x16x32_bf16 v[40:43], v[170:173], v[198:201], v[40:43]
	v_mfma_f32_16x16x32_bf16 v[32:35], v[158:161], v[206:209], v[32:35]
	v_mfma_f32_16x16x32_bf16 v[24:27], v[170:173], v[206:209], v[24:27]
	v_mfma_f32_16x16x32_bf16 v[16:19], v[158:161], v[214:217], v[16:19]
	v_mfma_f32_16x16x32_bf16 v[8:11], v[170:173], v[214:217], v[8:11]
	v_mfma_f32_16x16x32_bf16 v[52:55], v[218:221], v[182:185], 0
	v_mfma_f32_16x16x32_bf16 v[44:47], v[226:229], v[182:185], 0
	v_mfma_f32_16x16x32_bf16 v[36:39], v[218:221], v[194:197], 0
	v_mfma_f32_16x16x32_bf16 v[28:31], v[226:229], v[194:197], 0
	v_mfma_f32_16x16x32_bf16 v[20:23], v[218:221], v[202:205], 0
	v_mfma_f32_16x16x32_bf16 v[12:15], v[226:229], v[202:205], 0
	v_mfma_f32_16x16x32_bf16 v[4:7], v[218:221], v[210:213], 0
	v_mfma_f32_16x16x32_bf16 v[0:3], v[226:229], v[210:213], 0
	v_mfma_f32_16x16x32_bf16 v[52:55], v[222:225], v[190:193], v[52:55]
	v_mfma_f32_16x16x32_bf16 v[44:47], v[230:233], v[190:193], v[44:47]
	v_mfma_f32_16x16x32_bf16 v[36:39], v[222:225], v[198:201], v[36:39]
	v_mfma_f32_16x16x32_bf16 v[28:31], v[230:233], v[198:201], v[28:31]
	v_mfma_f32_16x16x32_bf16 v[20:23], v[222:225], v[206:209], v[20:23]
	v_mfma_f32_16x16x32_bf16 v[12:15], v[230:233], v[206:209], v[12:15]
	v_mfma_f32_16x16x32_bf16 v[4:7], v[222:225], v[214:217], v[4:7]
	v_mfma_f32_16x16x32_bf16 v[0:3], v[230:233], v[214:217], v[0:3]
	s_barrier
; #define PG8_STAGE(bufoff, gbase, voff) do { _Pragma("unroll") for (int _i = 0; _i < 2; ++_i) \
;         __builtin_amdgcn_global_load_lds((const unsigned*)((const char*)(gbase) + (voff)[_i]), (PG8_LAS unsigned*)(lds + (bufoff) + ldsw + _i * 8192), 16, 0, 0); } while (0)
; #define PG8_LDA(dst, b, h) do { _Pragma("unroll") for (int m = 0; m < 4; ++m) _Pragma("unroll") for (int k = 0; k < 2; ++k) dst[m][k] = *(const PG8_LAS bf16x8*)(lds + PG8_SA(b, h) + aoff + m * 2048 + k * 1024); } while (0)
; #define PG8_LDB(dst, b, h) do { _Pragma("unroll") for (int n = 0; n < 2; ++n) _Pragma("unroll") for (int k = 0; k < 2; ++k) dst[n][k] = *(const PG8_LAS bf16x8*)(lds + PG8_SB(b, h) + boff + n * 2048 + k * 1024); } while (0)
; #define PG8_MMA(ai, bj, At, Bt) do { __builtin_amdgcn_s_setprio(1); _Pragma("unroll") for (int m = 0; m < 4; ++m) _Pragma("unroll") for (int n = 0; n < 2; ++n) _Pragma("unroll") for (int k = 0; k < 2; ++k) \
;         acc[ai][bj][m][n] = __builtin_amdgcn_mfma_f32_16x16x32_bf16(Bt[n][k], At[m][k], acc[ai][bj][m][n], 0, 0, 0); __builtin_amdgcn_s_setprio(0); } while (0)
; #define PG8_WAIT_V(n) asm volatile("s_waitcnt vmcnt(" #n ")" ::: "memory")
; #define PG8_WAIT_L(n) asm volatile("s_waitcnt lgkmcnt(" #n ")" ::: "memory")
; #define PG8_BAR __builtin_amdgcn_s_barrier()
; #define PG8_SCHED __builtin_amdgcn_sched_barrier(0)
; template <class Epi, class Sched>
; __device__ __forceinline__ void gemm_phase(PG8_LAS unsigned char* lds, const Gemm g, const Sched& S, const Epi& E) {
;     ...
;             PG8_WAIT_V(6); PG8_BAR; PG8_MMA(1, 1, At, B1); PG8_BAR;
;             PG8_LDB(B0, 1, 0); PG8_SCHED; PG8_LDA(At, 1, 0); PG8_STAGE(PG8_SA(0, 1), a2 + hstep, voffA);
;             PG8_WAIT_L(8); PG8_BAR; PG8_WAIT_L(0); PG8_MMA(0, 0, At, B0); PG8_BAR; PG8_SCHED;
;             PG8_LDB(B1, 1, 1); PG8_STAGE(PG8_SB(1, 0), b3, voffB);
;             PG8_BAR; PG8_WAIT_L(0); PG8_MMA(0, 1, At, B1); PG8_BAR;
;             PG8_LDA(At, 1, 1); PG8_STAGE(PG8_SA(1, 0), a3, voffA);
;             PG8_BAR; PG8_WAIT_L(0); PG8_MMA(1, 0, At, B0); PG8_BAR; PG8_SCHED;
;             PG8_STAGE(PG8_SB(1, 1), b3 + hstep, voffB);
;             PG8_WAIT_V(6); PG8_BAR; PG8_MMA(1, 1, At, B1); PG8_BAR;
	s_add_i32 s58, 0, 0x18000
	v_add_u32_e32 v153, s58, v147
	ds_read_b128 v[154:157], v153
	ds_read_b128 v[158:161], v153 offset:1024
	ds_read_b128 v[166:169], v153 offset:2048
	ds_read_b128 v[170:173], v153 offset:3072
	s_add_u32 s22, s28, 0xb0000
	s_addc_u32 s23, s29, 0
	s_mov_b32 m0, s40
	ds_read_b128 v[182:185], v150 offset:32768
	ds_read_b128 v[190:193], v150 offset:33792
	ds_read_b128 v[194:197], v150 offset:34816
	ds_read_b128 v[198:201], v150 offset:35840
	ds_read_b128 v[202:205], v150 offset:36864
	ds_read_b128 v[206:209], v150 offset:37888
	ds_read_b128 v[210:213], v150 offset:38912
	ds_read_b128 v[214:217], v150 offset:39936
	global_load_lds_dwordx4 v128, s[22:23]
	s_nop 1
	s_mov_b32 m0, s41
	s_nop 0
	global_load_lds_dwordx4 v132, s[22:23]
	s_add_i32 s28, 0, 0x1c000
	v_add_u32_e32 v153, s28, v147
	s_waitcnt lgkmcnt(12)
	ds_read_b128 v[218:221], v153
	ds_read_b128 v[222:225], v153 offset:1024
	ds_read_b128 v[226:229], v153 offset:2048
	ds_read_b128 v[230:233], v153 offset:3072
	s_waitcnt vmcnt(8) lgkmcnt(0)
	s_barrier
	v_mfma_f32_16x16x32_bf16 v[124:127], v[154:157], v[182:185], v[124:127]
	v_mfma_f32_16x16x32_bf16 v[120:123], v[166:169], v[182:185], v[120:123]
	v_mfma_f32_16x16x32_bf16 v[108:111], v[154:157], v[194:197], v[108:111]
	v_mfma_f32_16x16x32_bf16 v[104:107], v[166:169], v[194:197], v[104:107]
	v_mfma_f32_16x16x32_bf16 v[92:95], v[154:157], v[202:205], v[92:95]
	v_mfma_f32_16x16x32_bf16 v[88:91], v[166:169], v[202:205], v[88:91]
	v_mfma_f32_16x16x32_bf16 v[76:79], v[154:157], v[210:213], v[76:79]
	v_mfma_f32_16x16x32_bf16 v[72:75], v[166:169], v[210:213], v[72:75]
	v_mfma_f32_16x16x32_bf16 v[124:127], v[158:161], v[190:193], v[124:127]
	v_mfma_f32_16x16x32_bf16 v[120:123], v[170:173], v[190:193], v[120:123]
	v_mfma_f32_16x16x32_bf16 v[108:111], v[158:161], v[198:201], v[108:111]
	v_mfma_f32_16x16x32_bf16 v[104:107], v[170:173], v[198:201], v[104:107]
	v_mfma_f32_16x16x32_bf16 v[92:95], v[158:161], v[206:209], v[92:95]
	v_mfma_f32_16x16x32_bf16 v[88:91], v[170:173], v[206:209], v[88:91]
	v_mfma_f32_16x16x32_bf16 v[76:79], v[158:161], v[214:217], v[76:79]
	v_mfma_f32_16x16x32_bf16 v[72:75], v[170:173], v[214:217], v[72:75]
	v_mfma_f32_16x16x32_bf16 v[116:119], v[218:221], v[182:185], v[116:119]
	v_mfma_f32_16x16x32_bf16 v[112:115], v[226:229], v[182:185], v[112:115]
	v_mfma_f32_16x16x32_bf16 v[100:103], v[218:221], v[194:197], v[100:103]
	v_mfma_f32_16x16x32_bf16 v[96:99], v[226:229], v[194:197], v[96:99]
	v_mfma_f32_16x16x32_bf16 v[84:87], v[218:221], v[202:205], v[84:87]
	v_mfma_f32_16x16x32_bf16 v[80:83], v[226:229], v[202:205], v[80:83]
	v_mfma_f32_16x16x32_bf16 v[68:71], v[218:221], v[210:213], v[68:71]
	v_mfma_f32_16x16x32_bf16 v[64:67], v[226:229], v[210:213], v[64:67]
	v_mfma_f32_16x16x32_bf16 v[116:119], v[222:225], v[190:193], v[116:119]
	v_mfma_f32_16x16x32_bf16 v[112:115], v[230:233], v[190:193], v[112:115]
	v_mfma_f32_16x16x32_bf16 v[100:103], v[222:225], v[198:201], v[100:103]
	v_mfma_f32_16x16x32_bf16 v[96:99], v[230:233], v[198:201], v[96:99]
	v_mfma_f32_16x16x32_bf16 v[84:87], v[222:225], v[206:209], v[84:87]
	v_mfma_f32_16x16x32_bf16 v[80:83], v[230:233], v[206:209], v[80:83]
	v_mfma_f32_16x16x32_bf16 v[68:71], v[222:225], v[214:217], v[68:71]
	v_mfma_f32_16x16x32_bf16 v[64:67], v[230:233], v[214:217], v[64:67]
	s_barrier
	ds_read_b128 v[182:185], v150 offset:49152
	ds_read_b128 v[190:193], v150 offset:50176
	ds_read_b128 v[194:197], v150 offset:51200
	ds_read_b128 v[198:201], v150 offset:52224
	ds_read_b128 v[202:205], v150 offset:53248
	ds_read_b128 v[206:209], v150 offset:54272
	ds_read_b128 v[210:213], v150 offset:55296
	ds_read_b128 v[214:217], v150 offset:56320
	s_add_i32 s22, s58, s37
	s_mov_b32 m0, s22
	s_nop 0
	global_load_lds_dwordx4 v130, s[98:99]
	s_nop 1
	s_add_i32 m0, s22, 0x2000
	s_nop 0
	global_load_lds_dwordx4 v134, s[98:99]
	s_nop 1
	s_mov_b32 m0, s43
	s_nop 0
	global_load_lds_dwordx4 v128, s[100:101]
	s_nop 1
	s_mov_b32 m0, s44
	s_nop 0
	global_load_lds_dwordx4 v132, s[100:101]
	s_add_u32 s22, s26, 0xb0080
	s_addc_u32 s23, s27, 0
	s_add_i32 s26, s28, s37
	s_mov_b32 m0, s26
	s_nop 0
	global_load_lds_dwordx4 v130, s[22:23]
	s_nop 1
	s_add_i32 m0, s26, 0x2000
	s_nop 0
	global_load_lds_dwordx4 v134, s[22:23]
	s_waitcnt vmcnt(8) lgkmcnt(0)
	s_barrier
	v_mfma_f32_16x16x32_bf16 v[60:63], v[154:157], v[182:185], v[60:63]
	v_mfma_f32_16x16x32_bf16 v[56:59], v[166:169], v[182:185], v[56:59]
	v_mfma_f32_16x16x32_bf16 v[48:51], v[154:157], v[194:197], v[48:51]
	v_mfma_f32_16x16x32_bf16 v[40:43], v[166:169], v[194:197], v[40:43]
	v_mfma_f32_16x16x32_bf16 v[32:35], v[154:157], v[202:205], v[32:35]
	v_mfma_f32_16x16x32_bf16 v[24:27], v[166:169], v[202:205], v[24:27]
	v_mfma_f32_16x16x32_bf16 v[16:19], v[154:157], v[210:213], v[16:19]
	v_mfma_f32_16x16x32_bf16 v[8:11], v[166:169], v[210:213], v[8:11]
	v_mfma_f32_16x16x32_bf16 v[60:63], v[158:161], v[190:193], v[60:63]
	v_mfma_f32_16x16x32_bf16 v[56:59], v[170:173], v[190:193], v[56:59]
	v_mfma_f32_16x16x32_bf16 v[48:51], v[158:161], v[198:201], v[48:51]
	v_mfma_f32_16x16x32_bf16 v[40:43], v[170:173], v[198:201], v[40:43]
	v_mfma_f32_16x16x32_bf16 v[32:35], v[158:161], v[206:209], v[32:35]
	v_mfma_f32_16x16x32_bf16 v[24:27], v[170:173], v[206:209], v[24:27]
	v_mfma_f32_16x16x32_bf16 v[16:19], v[158:161], v[214:217], v[16:19]
	v_mfma_f32_16x16x32_bf16 v[8:11], v[170:173], v[214:217], v[8:11]
	v_mfma_f32_16x16x32_bf16 v[52:55], v[218:221], v[182:185], v[52:55]
	v_mfma_f32_16x16x32_bf16 v[44:47], v[226:229], v[182:185], v[44:47]
	v_mfma_f32_16x16x32_bf16 v[36:39], v[218:221], v[194:197], v[36:39]
	v_mfma_f32_16x16x32_bf16 v[28:31], v[226:229], v[194:197], v[28:31]
	v_mfma_f32_16x16x32_bf16 v[20:23], v[218:221], v[202:205], v[20:23]
	v_mfma_f32_16x16x32_bf16 v[12:15], v[226:229], v[202:205], v[12:15]
	v_mfma_f32_16x16x32_bf16 v[4:7], v[218:221], v[210:213], v[4:7]
	v_mfma_f32_16x16x32_bf16 v[0:3], v[226:229], v[210:213], v[0:3]
	v_mfma_f32_16x16x32_bf16 v[52:55], v[222:225], v[190:193], v[52:55]
	v_mfma_f32_16x16x32_bf16 v[44:47], v[230:233], v[190:193], v[44:47]
	v_mfma_f32_16x16x32_bf16 v[36:39], v[222:225], v[198:201], v[36:39]
	v_mfma_f32_16x16x32_bf16 v[28:31], v[230:233], v[198:201], v[28:31]
	v_mfma_f32_16x16x32_bf16 v[20:23], v[222:225], v[206:209], v[20:23]
	v_mfma_f32_16x16x32_bf16 v[12:15], v[230:233], v[206:209], v[12:15]
	v_mfma_f32_16x16x32_bf16 v[4:7], v[222:225], v[214:217], v[4:7]
	v_mfma_f32_16x16x32_bf16 v[0:3], v[230:233], v[214:217], v[0:3]
	s_barrier
	s_add_i32 s57, s57, 2
	s_add_u32 s55, s55, 0x100
	s_addc_u32 s56, s56, 0
	s_cmp_gt_u32 s57, 41
	s_mov_b64 s[22:23], s[24:25]
; #define PG8_STAGE(bufoff, gbase, voff) do { _Pragma("unroll") for (int _i = 0; _i < 2; ++_i) \
;         __builtin_amdgcn_global_load_lds((const unsigned*)((const char*)(gbase) + (voff)[_i]), (PG8_LAS unsigned*)(lds + (bufoff) + ldsw + _i * 8192), 16, 0, 0); } while (0)
; #define PG8_LDA(dst, b, h) do { _Pragma("unroll") for (int m = 0; m < 4; ++m) _Pragma("unroll") for (int k = 0; k < 2; ++k) dst[m][k] = *(const PG8_LAS bf16x8*)(lds + PG8_SA(b, h) + aoff + m * 2048 + k * 1024); } while (0)
; #define PG8_LDB(dst, b, h) do { _Pragma("unroll") for (int n = 0; n < 2; ++n) _Pragma("unroll") for (int k = 0; k < 2; ++k) dst[n][k] = *(const PG8_LAS bf16x8*)(lds + PG8_SB(b, h) + boff + n * 2048 + k * 1024); } while (0)
; #define PG8_MMA(ai, bj, At, Bt) do { __builtin_amdgcn_s_setprio(1); _Pragma("unroll") for (int m = 0; m < 4; ++m) _Pragma("unroll") for (int n = 0; n < 2; ++n) _Pragma("unroll") for (int k = 0; k < 2; ++k) \
;         acc[ai][bj][m][n] = __builtin_amdgcn_mfma_f32_16x16x32_bf16(Bt[n][k], At[m][k], acc[ai][bj][m][n], 0, 0, 0); __builtin_amdgcn_s_setprio(0); } while (0)
; #define PG8_WAIT_V(n) asm volatile("s_waitcnt vmcnt(" #n ")" ::: "memory")
; template <class Epi, class Sched>
; __device__ __forceinline__ void gemm_phase(PG8_LAS unsigned char* lds, const Gemm g, const Sched& S, const Epi& E) {
;     ...
;         for (int t = 0; t < nt; t += 2) {
;             const bool last = (t == nt - 2);
;             const char* a1 = cA + (size_t)(t + 1) * kstep;
;             const char* a2 = last ? nA : cA + (size_t)(t + 2) * kstep; const char* b2 = last ? nB : cB + (size_t)(t + 2) * kstep;
;             const char* a3 = a2 + kstep; const char* b3 = b2 + kstep;
;             if (last && has_next) S.a_ready(nxt);
;             PG8_LDB(B0, 0, 0); PG8_SCHED; PG8_LDA(At, 0, 0); PG8_STAGE(PG8_SA(1, 1), a1 + hstep, voffA);
;             PG8_WAIT_L(8); PG8_BAR; PG8_WAIT_L(0); PG8_MMA(0, 0, At, B0); PG8_BAR; PG8_SCHED;
;             PG8_LDB(B1, 0, 1); PG8_STAGE(PG8_SB(0, 0), b2, voffB);
;             PG8_BAR; PG8_WAIT_L(0); PG8_MMA(0, 1, At, B1); PG8_BAR;
;             PG8_LDA(At, 0, 1); PG8_STAGE(PG8_SA(0, 0), a2, voffA);
;             PG8_BAR; PG8_WAIT_L(0); PG8_MMA(1, 0, At, B0); PG8_BAR; PG8_SCHED;
;             PG8_STAGE(PG8_SB(0, 1), b2 + hstep, voffB);
;             PG8_WAIT_V(6); PG8_BAR; PG8_MMA(1, 1, At, B1); PG8_BAR;
.LBB0_286:
	ds_read_b128 v[154:157], v149
	ds_read_b128 v[158:161], v149 offset:1024
	ds_read_b128 v[166:169], v149 offset:2048
	ds_read_b128 v[170:173], v149 offset:3072
	s_add_u32 s24, s22, 0x100
	s_addc_u32 s25, s23, 0
	s_cmp_eq_u32 s57, 40
	s_cselect_b32 s29, s1, s25
	s_cselect_b32 s28, s0, s24
	s_cselect_b32 s27, s5, s56
	s_cselect_b32 s26, s4, s55
	s_add_i32 m0, s38, 0xc000
	ds_read_b128 v[182:185], v150
	ds_read_b128 v[190:193], v150 offset:1024
	ds_read_b128 v[194:197], v150 offset:2048
	ds_read_b128 v[198:201], v150 offset:3072
	ds_read_b128 v[202:205], v150 offset:4096
	ds_read_b128 v[206:209], v150 offset:5120
	ds_read_b128 v[210:213], v150 offset:6144
	ds_read_b128 v[214:217], v150 offset:7168
	global_load_lds_dwordx4 v136, s[22:23]
	s_nop 1
	s_add_i32 m0, s38, 0xe000
	s_nop 0
	global_load_lds_dwordx4 v138, s[22:23]
	s_waitcnt lgkmcnt(12)
	ds_read_b128 v[218:221], v151
	ds_read_b128 v[222:225], v151 offset:1024
	ds_read_b128 v[226:229], v151 offset:2048
	ds_read_b128 v[230:233], v151 offset:3072
	s_waitcnt vmcnt(8) lgkmcnt(0)
	s_barrier
	v_mfma_f32_16x16x32_bf16 v[124:127], v[154:157], v[182:185], v[124:127]
	v_mfma_f32_16x16x32_bf16 v[120:123], v[166:169], v[182:185], v[120:123]
	v_mfma_f32_16x16x32_bf16 v[108:111], v[154:157], v[194:197], v[108:111]
	v_mfma_f32_16x16x32_bf16 v[104:107], v[166:169], v[194:197], v[104:107]
	v_mfma_f32_16x16x32_bf16 v[92:95], v[154:157], v[202:205], v[92:95]
	v_mfma_f32_16x16x32_bf16 v[88:91], v[166:169], v[202:205], v[88:91]
	v_mfma_f32_16x16x32_bf16 v[76:79], v[154:157], v[210:213], v[76:79]
	v_mfma_f32_16x16x32_bf16 v[72:75], v[166:169], v[210:213], v[72:75]
	v_mfma_f32_16x16x32_bf16 v[124:127], v[158:161], v[190:193], v[124:127]
	v_mfma_f32_16x16x32_bf16 v[120:123], v[170:173], v[190:193], v[120:123]
	v_mfma_f32_16x16x32_bf16 v[108:111], v[158:161], v[198:201], v[108:111]
	v_mfma_f32_16x16x32_bf16 v[104:107], v[170:173], v[198:201], v[104:107]
	v_mfma_f32_16x16x32_bf16 v[92:95], v[158:161], v[206:209], v[92:95]
	v_mfma_f32_16x16x32_bf16 v[88:91], v[170:173], v[206:209], v[88:91]
	v_mfma_f32_16x16x32_bf16 v[76:79], v[158:161], v[214:217], v[76:79]
	v_mfma_f32_16x16x32_bf16 v[72:75], v[170:173], v[214:217], v[72:75]
	v_mfma_f32_16x16x32_bf16 v[116:119], v[218:221], v[182:185], v[116:119]
	v_mfma_f32_16x16x32_bf16 v[112:115], v[226:229], v[182:185], v[112:115]
	v_mfma_f32_16x16x32_bf16 v[100:103], v[218:221], v[194:197], v[100:103]
	v_mfma_f32_16x16x32_bf16 v[96:99], v[226:229], v[194:197], v[96:99]
	v_mfma_f32_16x16x32_bf16 v[84:87], v[218:221], v[202:205], v[84:87]
	v_mfma_f32_16x16x32_bf16 v[80:83], v[226:229], v[202:205], v[80:83]
	v_mfma_f32_16x16x32_bf16 v[68:71], v[218:221], v[210:213], v[68:71]
	v_mfma_f32_16x16x32_bf16 v[64:67], v[226:229], v[210:213], v[64:67]
	v_mfma_f32_16x16x32_bf16 v[116:119], v[222:225], v[190:193], v[116:119]
	v_mfma_f32_16x16x32_bf16 v[112:115], v[230:233], v[190:193], v[112:115]
	v_mfma_f32_16x16x32_bf16 v[100:103], v[222:225], v[198:201], v[100:103]
	v_mfma_f32_16x16x32_bf16 v[96:99], v[230:233], v[198:201], v[96:99]
	v_mfma_f32_16x16x32_bf16 v[84:87], v[222:225], v[206:209], v[84:87]
	v_mfma_f32_16x16x32_bf16 v[80:83], v[230:233], v[206:209], v[80:83]
	v_mfma_f32_16x16x32_bf16 v[68:71], v[222:225], v[214:217], v[68:71]
	v_mfma_f32_16x16x32_bf16 v[64:67], v[230:233], v[214:217], v[64:67]
	s_barrier
	ds_read_b128 v[182:185], v150 offset:16384
	ds_read_b128 v[190:193], v150 offset:17408
	ds_read_b128 v[194:197], v150 offset:18432
	ds_read_b128 v[198:201], v150 offset:19456
	ds_read_b128 v[202:205], v150 offset:20480
	ds_read_b128 v[206:209], v150 offset:21504
	ds_read_b128 v[210:213], v150 offset:22528
	ds_read_b128 v[214:217], v150 offset:23552
	s_add_i32 s22, s46, s37
	s_add_u32 s98, s26, s14
	s_addc_u32 s99, s27, s15
	s_mov_b32 m0, s22
	s_nop 0
	global_load_lds_dwordx4 v130, s[26:27]
	s_nop 1
	s_add_i32 m0, s22, 0x2000
	s_nop 0
	global_load_lds_dwordx4 v134, s[26:27]
	s_nop 1
	s_mov_b32 m0, s38
	s_add_u32 s100, s28, s14
	s_addc_u32 s101, s29, s15
	global_load_lds_dwordx4 v128, s[28:29]
	s_nop 1
	s_mov_b32 m0, s39
	s_nop 0
	global_load_lds_dwordx4 v132, s[28:29]
	s_add_u32 s22, s26, 0xb0000
	s_addc_u32 s23, s27, 0
	s_add_i32 s58, s47, s37
	s_mov_b32 m0, s58
	s_nop 0
	global_load_lds_dwordx4 v130, s[22:23]
	s_nop 1
	s_add_i32 m0, s58, 0x2000
	s_nop 0
	global_load_lds_dwordx4 v134, s[22:23]
	s_waitcnt vmcnt(8) lgkmcnt(0)
	s_barrier
	v_mfma_f32_16x16x32_bf16 v[60:63], v[154:157], v[182:185], v[60:63]
	v_mfma_f32_16x16x32_bf16 v[56:59], v[166:169], v[182:185], v[56:59]
	v_mfma_f32_16x16x32_bf16 v[48:51], v[154:157], v[194:197], v[48:51]
	v_mfma_f32_16x16x32_bf16 v[40:43], v[166:169], v[194:197], v[40:43]
	v_mfma_f32_16x16x32_bf16 v[32:35], v[154:157], v[202:205], v[32:35]
	v_mfma_f32_16x16x32_bf16 v[24:27], v[166:169], v[202:205], v[24:27]
	v_mfma_f32_16x16x32_bf16 v[16:19], v[154:157], v[210:213], v[16:19]
	v_mfma_f32_16x16x32_bf16 v[8:11], v[166:169], v[210:213], v[8:11]
	v_mfma_f32_16x16x32_bf16 v[60:63], v[158:161], v[190:193], v[60:63]
	v_mfma_f32_16x16x32_bf16 v[56:59], v[170:173], v[190:193], v[56:59]
	v_mfma_f32_16x16x32_bf16 v[48:51], v[158:161], v[198:201], v[48:51]
	v_mfma_f32_16x16x32_bf16 v[40:43], v[170:173], v[198:201], v[40:43]
	v_mfma_f32_16x16x32_bf16 v[32:35], v[158:161], v[206:209], v[32:35]
	v_mfma_f32_16x16x32_bf16 v[24:27], v[170:173], v[206:209], v[24:27]
	v_mfma_f32_16x16x32_bf16 v[16:19], v[158:161], v[214:217], v[16:19]
	v_mfma_f32_16x16x32_bf16 v[8:11], v[170:173], v[214:217], v[8:11]
	v_mfma_f32_16x16x32_bf16 v[52:55], v[218:221], v[182:185], v[52:55]
	v_mfma_f32_16x16x32_bf16 v[44:47], v[226:229], v[182:185], v[44:47]
	v_mfma_f32_16x16x32_bf16 v[36:39], v[218:221], v[194:197], v[36:39]
	v_mfma_f32_16x16x32_bf16 v[28:31], v[226:229], v[194:197], v[28:31]
	v_mfma_f32_16x16x32_bf16 v[20:23], v[218:221], v[202:205], v[20:23]
	v_mfma_f32_16x16x32_bf16 v[12:15], v[226:229], v[202:205], v[12:15]
	v_mfma_f32_16x16x32_bf16 v[4:7], v[218:221], v[210:213], v[4:7]
	v_mfma_f32_16x16x32_bf16 v[0:3], v[226:229], v[210:213], v[0:3]
	v_mfma_f32_16x16x32_bf16 v[52:55], v[222:225], v[190:193], v[52:55]
	v_mfma_f32_16x16x32_bf16 v[44:47], v[230:233], v[190:193], v[44:47]
	v_mfma_f32_16x16x32_bf16 v[36:39], v[222:225], v[198:201], v[36:39]
	v_mfma_f32_16x16x32_bf16 v[28:31], v[230:233], v[198:201], v[28:31]
	v_mfma_f32_16x16x32_bf16 v[20:23], v[222:225], v[206:209], v[20:23]
	v_mfma_f32_16x16x32_bf16 v[12:15], v[230:233], v[206:209], v[12:15]
	v_mfma_f32_16x16x32_bf16 v[4:7], v[222:225], v[214:217], v[4:7]
	v_mfma_f32_16x16x32_bf16 v[0:3], v[230:233], v[214:217], v[0:3]
	s_barrier
; #define PG8_STAGE(bufoff, gbase, voff) do { _Pragma("unroll") for (int _i = 0; _i < 2; ++_i) \
;         __builtin_amdgcn_global_load_lds((const unsigned*)((const char*)(gbase) + (voff)[_i]), (PG8_LAS unsigned*)(lds + (bufoff) + ldsw + _i * 8192), 16, 0, 0); } while (0)
; #define PG8_LDA(dst, b, h) do { _Pragma("unroll") for (int m = 0; m < 4; ++m) _Pragma("unroll") for (int k = 0; k < 2; ++k) dst[m][k] = *(const PG8_LAS bf16x8*)(lds + PG8_SA(b, h) + aoff + m * 2048 + k * 1024); } while (0)
; #define PG8_LDB(dst, b, h) do { _Pragma("unroll") for (int n = 0; n < 2; ++n) _Pragma("unroll") for (int k = 0; k < 2; ++k) dst[n][k] = *(const PG8_LAS bf16x8*)(lds + PG8_SB(b, h) + boff + n * 2048 + k * 1024); } while (0)
; #define PG8_MMA(ai, bj, At, Bt) do { __builtin_amdgcn_s_setprio(1); _Pragma("unroll") for (int m = 0; m < 4; ++m) _Pragma("unroll") for (int n = 0; n < 2; ++n) _Pragma("unroll") for (int k = 0; k < 2; ++k) \
;         acc[ai][bj][m][n] = __builtin_amdgcn_mfma_f32_16x16x32_bf16(Bt[n][k], At[m][k], acc[ai][bj][m][n], 0, 0, 0); __builtin_amdgcn_s_setprio(0); } while (0)
; #define PG8_WAIT_V(n) asm volatile("s_waitcnt vmcnt(" #n ")" ::: "memory")
; #define PG8_WAIT_L(n) asm volatile("s_waitcnt lgkmcnt(" #n ")" ::: "memory")
; #define PG8_BAR __builtin_amdgcn_s_barrier()
; #define PG8_SCHED __builtin_amdgcn_sched_barrier(0)
; template <class Epi, class Sched>
; __device__ __forceinline__ void gemm_phase(PG8_LAS unsigned char* lds, const Gemm g, const Sched& S, const Epi& E) {
;     ...
;             PG8_WAIT_V(6); PG8_BAR; PG8_MMA(1, 1, At, B1); PG8_BAR;
;             PG8_LDB(B0, 1, 0); PG8_SCHED; PG8_LDA(At, 1, 0); PG8_STAGE(PG8_SA(0, 1), a2 + hstep, voffA);
;             PG8_WAIT_L(8); PG8_BAR; PG8_WAIT_L(0); PG8_MMA(0, 0, At, B0); PG8_BAR; PG8_SCHED;
;             PG8_LDB(B1, 1, 1); PG8_STAGE(PG8_SB(1, 0), b3, voffB);
;             PG8_BAR; PG8_WAIT_L(0); PG8_MMA(0, 1, At, B1); PG8_BAR;
;             PG8_LDA(At, 1, 1); PG8_STAGE(PG8_SA(1, 0), a3, voffA);
;             PG8_BAR; PG8_WAIT_L(0); PG8_MMA(1, 0, At, B0); PG8_BAR; PG8_SCHED;
;             PG8_STAGE(PG8_SB(1, 1), b3 + hstep, voffB);
;             PG8_WAIT_V(6); PG8_BAR; PG8_MMA(1, 1, At, B1); PG8_BAR;
	s_add_i32 s58, 0, 0x18000
	v_add_u32_e32 v153, s58, v147
	ds_read_b128 v[154:157], v153
	ds_read_b128 v[158:161], v153 offset:1024
	ds_read_b128 v[166:169], v153 offset:2048
	ds_read_b128 v[170:173], v153 offset:3072
	s_add_u32 s22, s28, 0xb0000
	s_addc_u32 s23, s29, 0
	s_mov_b32 m0, s40
	ds_read_b128 v[182:185], v150 offset:32768
	ds_read_b128 v[190:193], v150 offset:33792
	ds_read_b128 v[194:197], v150 offset:34816
	ds_read_b128 v[198:201], v150 offset:35840
	ds_read_b128 v[202:205], v150 offset:36864
	ds_read_b128 v[206:209], v150 offset:37888
	ds_read_b128 v[210:213], v150 offset:38912
	ds_read_b128 v[214:217], v150 offset:39936
	global_load_lds_dwordx4 v128, s[22:23]
	s_nop 1
	s_mov_b32 m0, s41
	s_nop 0
	global_load_lds_dwordx4 v132, s[22:23]
	s_add_i32 s28, 0, 0x1c000
	v_add_u32_e32 v153, s28, v147
	s_waitcnt lgkmcnt(12)
	ds_read_b128 v[218:221], v153
	ds_read_b128 v[222:225], v153 offset:1024
	ds_read_b128 v[226:229], v153 offset:2048
	ds_read_b128 v[230:233], v153 offset:3072
	s_waitcnt vmcnt(8) lgkmcnt(0)
	s_barrier
	v_mfma_f32_16x16x32_bf16 v[124:127], v[154:157], v[182:185], v[124:127]
	v_mfma_f32_16x16x32_bf16 v[120:123], v[166:169], v[182:185], v[120:123]
	v_mfma_f32_16x16x32_bf16 v[108:111], v[154:157], v[194:197], v[108:111]
	v_mfma_f32_16x16x32_bf16 v[104:107], v[166:169], v[194:197], v[104:107]
	v_mfma_f32_16x16x32_bf16 v[92:95], v[154:157], v[202:205], v[92:95]
	v_mfma_f32_16x16x32_bf16 v[88:91], v[166:169], v[202:205], v[88:91]
	v_mfma_f32_16x16x32_bf16 v[76:79], v[154:157], v[210:213], v[76:79]
	v_mfma_f32_16x16x32_bf16 v[72:75], v[166:169], v[210:213], v[72:75]
	v_mfma_f32_16x16x32_bf16 v[124:127], v[158:161], v[190:193], v[124:127]
	v_mfma_f32_16x16x32_bf16 v[120:123], v[170:173], v[190:193], v[120:123]
	v_mfma_f32_16x16x32_bf16 v[108:111], v[158:161], v[198:201], v[108:111]
	v_mfma_f32_16x16x32_bf16 v[104:107], v[170:173], v[198:201], v[104:107]
	v_mfma_f32_16x16x32_bf16 v[92:95], v[158:161], v[206:209], v[92:95]
	v_mfma_f32_16x16x32_bf16 v[88:91], v[170:173], v[206:209], v[88:91]
	v_mfma_f32_16x16x32_bf16 v[76:79], v[158:161], v[214:217], v[76:79]
	v_mfma_f32_16x16x32_bf16 v[72:75], v[170:173], v[214:217], v[72:75]
	v_mfma_f32_16x16x32_bf16 v[116:119], v[218:221], v[182:185], v[116:119]
	v_mfma_f32_16x16x32_bf16 v[112:115], v[226:229], v[182:185], v[112:115]
	v_mfma_f32_16x16x32_bf16 v[100:103], v[218:221], v[194:197], v[100:103]
	v_mfma_f32_16x16x32_bf16 v[96:99], v[226:229], v[194:197], v[96:99]
	v_mfma_f32_16x16x32_bf16 v[84:87], v[218:221], v[202:205], v[84:87]
	v_mfma_f32_16x16x32_bf16 v[80:83], v[226:229], v[202:205], v[80:83]
	v_mfma_f32_16x16x32_bf16 v[68:71], v[218:221], v[210:213], v[68:71]
	v_mfma_f32_16x16x32_bf16 v[64:67], v[226:229], v[210:213], v[64:67]
	v_mfma_f32_16x16x32_bf16 v[116:119], v[222:225], v[190:193], v[116:119]
	v_mfma_f32_16x16x32_bf16 v[112:115], v[230:233], v[190:193], v[112:115]
	v_mfma_f32_16x16x32_bf16 v[100:103], v[222:225], v[198:201], v[100:103]
	v_mfma_f32_16x16x32_bf16 v[96:99], v[230:233], v[198:201], v[96:99]
	v_mfma_f32_16x16x32_bf16 v[84:87], v[222:225], v[206:209], v[84:87]
	v_mfma_f32_16x16x32_bf16 v[80:83], v[230:233], v[206:209], v[80:83]
	v_mfma_f32_16x16x32_bf16 v[68:71], v[222:225], v[214:217], v[68:71]
	v_mfma_f32_16x16x32_bf16 v[64:67], v[230:233], v[214:217], v[64:67]
	s_barrier
	ds_read_b128 v[182:185], v150 offset:49152
	ds_read_b128 v[190:193], v150 offset:50176
	ds_read_b128 v[194:197], v150 offset:51200
	ds_read_b128 v[198:201], v150 offset:52224
	ds_read_b128 v[202:205], v150 offset:53248
	ds_read_b128 v[206:209], v150 offset:54272
	ds_read_b128 v[210:213], v150 offset:55296
	ds_read_b128 v[214:217], v150 offset:56320
	s_add_i32 s22, s58, s37
	s_mov_b32 m0, s22
	s_nop 0
	global_load_lds_dwordx4 v130, s[98:99]
	s_nop 1
	s_add_i32 m0, s22, 0x2000
	s_nop 0
	global_load_lds_dwordx4 v134, s[98:99]
	s_nop 1
	s_mov_b32 m0, s43
	s_nop 0
	global_load_lds_dwordx4 v128, s[100:101]
	s_nop 1
	s_mov_b32 m0, s44
	s_nop 0
	global_load_lds_dwordx4 v132, s[100:101]
	s_add_u32 s22, s26, 0xb0080
	s_addc_u32 s23, s27, 0
	s_add_i32 s26, s28, s37
	s_mov_b32 m0, s26
	s_nop 0
	global_load_lds_dwordx4 v130, s[22:23]
	s_nop 1
	s_add_i32 m0, s26, 0x2000
	s_nop 0
	global_load_lds_dwordx4 v134, s[22:23]
	s_waitcnt vmcnt(8) lgkmcnt(0)
	s_barrier
	v_mfma_f32_16x16x32_bf16 v[60:63], v[154:157], v[182:185], v[60:63]
	v_mfma_f32_16x16x32_bf16 v[56:59], v[166:169], v[182:185], v[56:59]
	v_mfma_f32_16x16x32_bf16 v[48:51], v[154:157], v[194:197], v[48:51]
	v_mfma_f32_16x16x32_bf16 v[40:43], v[166:169], v[194:197], v[40:43]
	v_mfma_f32_16x16x32_bf16 v[32:35], v[154:157], v[202:205], v[32:35]
	v_mfma_f32_16x16x32_bf16 v[24:27], v[166:169], v[202:205], v[24:27]
	v_mfma_f32_16x16x32_bf16 v[16:19], v[154:157], v[210:213], v[16:19]
	v_mfma_f32_16x16x32_bf16 v[8:11], v[166:169], v[210:213], v[8:11]
	v_mfma_f32_16x16x32_bf16 v[60:63], v[158:161], v[190:193], v[60:63]
	v_mfma_f32_16x16x32_bf16 v[56:59], v[170:173], v[190:193], v[56:59]
	v_mfma_f32_16x16x32_bf16 v[48:51], v[158:161], v[198:201], v[48:51]
	v_mfma_f32_16x16x32_bf16 v[40:43], v[170:173], v[198:201], v[40:43]
	v_mfma_f32_16x16x32_bf16 v[32:35], v[158:161], v[206:209], v[32:35]
	v_mfma_f32_16x16x32_bf16 v[24:27], v[170:173], v[206:209], v[24:27]
	v_mfma_f32_16x16x32_bf16 v[16:19], v[158:161], v[214:217], v[16:19]
	v_mfma_f32_16x16x32_bf16 v[8:11], v[170:173], v[214:217], v[8:11]
	v_mfma_f32_16x16x32_bf16 v[52:55], v[218:221], v[182:185], v[52:55]
	v_mfma_f32_16x16x32_bf16 v[44:47], v[226:229], v[182:185], v[44:47]
	v_mfma_f32_16x16x32_bf16 v[36:39], v[218:221], v[194:197], v[36:39]
	v_mfma_f32_16x16x32_bf16 v[28:31], v[226:229], v[194:197], v[28:31]
	v_mfma_f32_16x16x32_bf16 v[20:23], v[218:221], v[202:205], v[20:23]
	v_mfma_f32_16x16x32_bf16 v[12:15], v[226:229], v[202:205], v[12:15]
	v_mfma_f32_16x16x32_bf16 v[4:7], v[218:221], v[210:213], v[4:7]
	v_mfma_f32_16x16x32_bf16 v[0:3], v[226:229], v[210:213], v[0:3]
	v_mfma_f32_16x16x32_bf16 v[52:55], v[222:225], v[190:193], v[52:55]
	v_mfma_f32_16x16x32_bf16 v[44:47], v[230:233], v[190:193], v[44:47]
	v_mfma_f32_16x16x32_bf16 v[36:39], v[222:225], v[198:201], v[36:39]
	v_mfma_f32_16x16x32_bf16 v[28:31], v[230:233], v[198:201], v[28:31]
	v_mfma_f32_16x16x32_bf16 v[20:23], v[222:225], v[206:209], v[20:23]
	v_mfma_f32_16x16x32_bf16 v[12:15], v[230:233], v[206:209], v[12:15]
	v_mfma_f32_16x16x32_bf16 v[4:7], v[222:225], v[214:217], v[4:7]
	v_mfma_f32_16x16x32_bf16 v[0:3], v[230:233], v[214:217], v[0:3]
	s_barrier
; __device__ __forceinline__ unsigned cvt_pk_bf16(float lo, float hi) { unsigned r; asm volatile("v_cvt_pk_bf16_f32 %0, %1, %2" : "=v"(r) : "v"(lo), "v"(hi)); return r; }
; __device__ __forceinline__ float flogsig16(float x) { return (fminf(x, 0.f) - __logf(1.0f + __expf(-fabsf(x)))) * 0.0625f; }
; #define PG8_WAIT_V(n) asm volatile("s_waitcnt vmcnt(" #n ")" ::: "memory")
; #define PG8_BAR __builtin_amdgcn_s_barrier()
;     __device__ __forceinline__ void operator()(const f32x4 (&acc)[2][2][4][2], const Unit& u, int wr, int wc, int fr, int fq) const {
;     ...
;         const int row0 = u.pm * BM + wr * 64 + fr, col0 = u.pn * BM + wc * 32 + 8 * fq, bcol0 = wc * 32 + 8 * fq;
;         f32x4 bv[2][2];
; #pragma unroll
;         for (int bj = 0; bj < 2; ++bj)
; #pragma unroll
;             for (int n = 0; n < 2; ++n) bv[bj][n] = bias ? *(const f32x4*)(bias + bcol0 + bj * HALF + 4 * n) : (f32x4){0.f, 0.f, 0.f, 0.f};
; #pragma unroll
;         for (int ai = 0; ai < 2; ++ai)
; #pragma unroll
;             for (int m = 0; m < 4; ++m) { bf16_t* rowp = O + (size_t)(row0 + ai * HALF + m * 16) * ldc + col0;
; #pragma unroll
;                 for (int bj = 0; bj < 2; ++bj) { f32x4 v0 = acc[ai][bj][m][0] + bv[bj][0], v1 = acc[ai][bj][m][1] + bv[bj][1];
;                     if (act == 1) {
; #pragma unroll
;                         for (int j = 0; j < 1; ++j) { v0 = v0 * sigmoid4(v0); v1 = v1 * sigmoid4(v1); } }
;                     else if (act == 2) {
; #pragma unroll
;                         for (int j = 0; j < 1; ++j) { v0 = sigmoid4(v0); v1 = sigmoid4(v1); } }
;                     else if (act == 3) {
; #pragma unroll
;                         for (int j = 0; j < 4; ++j) { v0[j] = flogsig16(v0[j]); v1[j] = flogsig16(v1[j]); } }
;                     u32x4 w; w.x = cvt_pk_bf16(v0[0], v0[1]); w.y = cvt_pk_bf16(v0[2], v0[3]); w.z = cvt_pk_bf16(v1[0], v1[1]); w.w = cvt_pk_bf16(v1[2], v1[3]);
;                     *(u32x4*)(rowp + bj * HALF) = w; } }
; template <class Epi, class Sched>
; __device__ __forceinline__ void gemm_phase(PG8_LAS unsigned char* lds, const Gemm g, const Sched& S, const Epi& E) {
;     ...
;             PG8_WAIT_V(6); PG8_BAR; PG8_MMA(1, 1, At, B1); PG8_BAR;
;         }
;         if constexpr (!Epi::AFTER_DRAIN) { E(acc, cur, wr, wc, fr, fq); S.done(cur); }
	s_add_i32 s57, s57, 2
	s_add_u32 s55, s55, 0x100
	s_addc_u32 s56, s56, 0
	s_cmp_gt_u32 s57, 41
	s_mov_b64 s[22:23], s[24:25]
	s_cbranch_scc0 .LBB0_286
	v_lshl_add_u32 v154, s53, 8, v146
	v_lshl_or_b32 v144, s54, 8, v148
	v_ashrrev_i32_e32 v155, 31, v154
	v_ashrrev_i32_e32 v145, 31, v144
	v_lshlrev_b64 v[156:157], 11, v[154:155]
	v_lshl_add_u64 v[156:157], s[10:11], 0, v[156:157]
	v_lshlrev_b64 v[158:159], 1, v[144:145]
	v_lshl_add_u64 v[144:145], v[156:157], 0, v[158:159]
	v_pk_add_f32 v[126:127], v[126:127], 0 op_sel_hi:[1,0]
	v_pk_add_f32 v[124:125], v[124:125], 0 op_sel_hi:[1,0]
	v_pk_add_f32 v[156:157], v[122:123], 0 op_sel_hi:[1,0]
	v_pk_add_f32 v[122:123], v[120:121], 0 op_sel_hi:[1,0]
	v_cvt_pk_bf16_f32 v120, v124, v125
	v_cvt_pk_bf16_f32 v121, v126, v127
	v_pk_add_f32 v[116:117], v[116:117], 0 op_sel_hi:[1,0]
	v_cvt_pk_bf16_f32 v122, v122, v123
	v_cvt_pk_bf16_f32 v123, v156, v157
	global_store_dwordx4 v[144:145], v[120:123], off
	v_pk_add_f32 v[118:119], v[118:119], 0 op_sel_hi:[1,0]
	v_pk_add_f32 v[110:111], v[110:111], 0 op_sel_hi:[1,0]
	v_pk_add_f32 v[120:121], v[114:115], 0 op_sel_hi:[1,0]
	v_pk_add_f32 v[114:115], v[112:113], 0 op_sel_hi:[1,0]
	v_cvt_pk_bf16_f32 v112, v116, v117
	v_cvt_pk_bf16_f32 v113, v118, v119
	v_pk_add_f32 v[108:109], v[108:109], 0 op_sel_hi:[1,0]
	v_cvt_pk_bf16_f32 v114, v114, v115
	v_cvt_pk_bf16_f32 v115, v120, v121
	global_store_dwordx4 v[144:145], v[112:115], off offset:256
	v_pk_add_f32 v[100:101], v[100:101], 0 op_sel_hi:[1,0]
	v_pk_add_f32 v[102:103], v[102:103], 0 op_sel_hi:[1,0]
	v_or_b32_e32 v112, 16, v154
	v_ashrrev_i32_e32 v113, 31, v112
	v_lshlrev_b64 v[112:113], 11, v[112:113]
	v_lshl_add_u64 v[112:113], s[10:11], 0, v[112:113]
	v_lshl_add_u64 v[112:113], v[112:113], 0, v[158:159]
	v_pk_add_f32 v[114:115], v[106:107], 0 op_sel_hi:[1,0]
	v_pk_add_f32 v[106:107], v[104:105], 0 op_sel_hi:[1,0]
	v_cvt_pk_bf16_f32 v104, v108, v109
	v_cvt_pk_bf16_f32 v105, v110, v111
	v_pk_add_f32 v[94:95], v[94:95], 0 op_sel_hi:[1,0]
	v_cvt_pk_bf16_f32 v106, v106, v107
	v_cvt_pk_bf16_f32 v107, v114, v115
	global_store_dwordx4 v[112:113], v[104:107], off
	v_pk_add_f32 v[92:93], v[92:93], 0 op_sel_hi:[1,0]
	v_pk_add_f32 v[84:85], v[84:85], 0 op_sel_hi:[1,0]
	v_pk_add_f32 v[104:105], v[98:99], 0 op_sel_hi:[1,0]
	v_pk_add_f32 v[98:99], v[96:97], 0 op_sel_hi:[1,0]
	v_cvt_pk_bf16_f32 v96, v100, v101
	v_cvt_pk_bf16_f32 v97, v102, v103
	v_pk_add_f32 v[86:87], v[86:87], 0 op_sel_hi:[1,0]
	v_cvt_pk_bf16_f32 v98, v98, v99
	v_cvt_pk_bf16_f32 v99, v104, v105
	global_store_dwordx4 v[112:113], v[96:99], off offset:256
	v_pk_add_f32 v[78:79], v[78:79], 0 op_sel_hi:[1,0]
	v_pk_add_f32 v[76:77], v[76:77], 0 op_sel_hi:[1,0]
	v_or_b32_e32 v96, 32, v154
	v_ashrrev_i32_e32 v97, 31, v96
	v_lshlrev_b64 v[96:97], 11, v[96:97]
	v_lshl_add_u64 v[96:97], s[10:11], 0, v[96:97]
	v_lshl_add_u64 v[96:97], v[96:97], 0, v[158:159]
	v_pk_add_f32 v[98:99], v[90:91], 0 op_sel_hi:[1,0]
	v_pk_add_f32 v[90:91], v[88:89], 0 op_sel_hi:[1,0]
	v_cvt_pk_bf16_f32 v88, v92, v93
	v_cvt_pk_bf16_f32 v89, v94, v95
	v_pk_add_f32 v[70:71], v[70:71], 0 op_sel_hi:[1,0]
	v_cvt_pk_bf16_f32 v90, v90, v91
	v_cvt_pk_bf16_f32 v91, v98, v99
	global_store_dwordx4 v[96:97], v[88:91], off
	v_pk_add_f32 v[68:69], v[68:69], 0 op_sel_hi:[1,0]
	s_mov_b64 s[22:23], 0x40000
	v_pk_add_f32 v[88:89], v[82:83], 0 op_sel_hi:[1,0]
	v_pk_add_f32 v[82:83], v[80:81], 0 op_sel_hi:[1,0]
	v_cvt_pk_bf16_f32 v80, v84, v85
	v_cvt_pk_bf16_f32 v81, v86, v87
	v_pk_add_f32 v[60:61], v[60:61], 0 op_sel_hi:[1,0]
	v_cvt_pk_bf16_f32 v82, v82, v83
	v_cvt_pk_bf16_f32 v83, v88, v89
	global_store_dwordx4 v[96:97], v[80:83], off offset:256
	v_pk_add_f32 v[62:63], v[62:63], 0 op_sel_hi:[1,0]
	v_pk_add_f32 v[54:55], v[54:55], 0 op_sel_hi:[1,0]
	v_or_b32_e32 v80, 48, v154
	v_ashrrev_i32_e32 v81, 31, v80
	v_lshlrev_b64 v[80:81], 11, v[80:81]
	v_lshl_add_u64 v[80:81], s[10:11], 0, v[80:81]
	v_lshl_add_u64 v[80:81], v[80:81], 0, v[158:159]
	v_pk_add_f32 v[82:83], v[74:75], 0 op_sel_hi:[1,0]
	v_pk_add_f32 v[74:75], v[72:73], 0 op_sel_hi:[1,0]
	v_cvt_pk_bf16_f32 v72, v76, v77
	v_cvt_pk_bf16_f32 v73, v78, v79
	v_pk_add_f32 v[52:53], v[52:53], 0 op_sel_hi:[1,0]
; __device__ __forceinline__ unsigned cvt_pk_bf16(float lo, float hi) { unsigned r; asm volatile("v_cvt_pk_bf16_f32 %0, %1, %2" : "=v"(r) : "v"(lo), "v"(hi)); return r; }
; __device__ __forceinline__ float flogsig16(float x) { return (fminf(x, 0.f) - __logf(1.0f + __expf(-fabsf(x)))) * 0.0625f; }
; #define PG8_WAIT_V(n) asm volatile("s_waitcnt vmcnt(" #n ")" ::: "memory")
; #define PG8_BAR __builtin_amdgcn_s_barrier()
;     __device__ __forceinline__ void operator()(const f32x4 (&acc)[2][2][4][2], const Unit& u, int wr, int wc, int fr, int fq) const {
;     ...
;         for (int ai = 0; ai < 2; ++ai)
; #pragma unroll
;             for (int m = 0; m < 4; ++m) { bf16_t* rowp = O + (size_t)(row0 + ai * HALF + m * 16) * ldc + col0;
; #pragma unroll
;                 for (int bj = 0; bj < 2; ++bj) { f32x4 v0 = acc[ai][bj][m][0] + bv[bj][0], v1 = acc[ai][bj][m][1] + bv[bj][1];
;                     if (act == 1) {
; #pragma unroll
;                         for (int j = 0; j < 1; ++j) { v0 = v0 * sigmoid4(v0); v1 = v1 * sigmoid4(v1); } }
;                     else if (act == 2) {
; #pragma unroll
;                         for (int j = 0; j < 1; ++j) { v0 = sigmoid4(v0); v1 = sigmoid4(v1); } }
;                     else if (act == 3) {
; #pragma unroll
;                         for (int j = 0; j < 4; ++j) { v0[j] = flogsig16(v0[j]); v1[j] = flogsig16(v1[j]); } }
;                     u32x4 w; w.x = cvt_pk_bf16(v0[0], v0[1]); w.y = cvt_pk_bf16(v0[2], v0[3]); w.z = cvt_pk_bf16(v1[0], v1[1]); w.w = cvt_pk_bf16(v1[2], v1[3]);
;                     *(u32x4*)(rowp + bj * HALF) = w; } }
; template <class Epi, class Sched>
; __device__ __forceinline__ void gemm_phase(PG8_LAS unsigned char* lds, const Gemm g, const Sched& S, const Epi& E) {
;     ...
;         if (!has_next) break;
; #pragma unroll
;         for (int a = 0; a < 2; ++a)
; #pragma unroll
;             for (int b = 0; b < 2; ++b)
; #pragma unroll
;                 for (int m = 0; m < 4; ++m)
; #pragma unroll
;                     for (int n = 0; n < 2; ++n) acc[a][b][m][n] = (f32x4){0.f, 0.f, 0.f, 0.f};
;         cur = nxt; cA = nA; cB = nB; ++ui;
;     }
;     PG8_WAIT_V(0);
;     if (wr == 0) PG8_BAR;
;     PG8_BAR;
	v_cvt_pk_bf16_f32 v74, v74, v75
	v_cvt_pk_bf16_f32 v75, v82, v83
	global_store_dwordx4 v[80:81], v[72:75], off
	v_pk_add_f32 v[48:49], v[48:49], 0 op_sel_hi:[1,0]
	v_pk_add_f32 v[38:39], v[38:39], 0 op_sel_hi:[1,0]
	v_pk_add_f32 v[72:73], v[66:67], 0 op_sel_hi:[1,0]
	v_pk_add_f32 v[66:67], v[64:65], 0 op_sel_hi:[1,0]
	v_cvt_pk_bf16_f32 v64, v68, v69
	v_cvt_pk_bf16_f32 v65, v70, v71
	v_pk_add_f32 v[36:37], v[36:37], 0 op_sel_hi:[1,0]
	v_cvt_pk_bf16_f32 v66, v66, v67
	v_cvt_pk_bf16_f32 v67, v72, v73
	global_store_dwordx4 v[80:81], v[64:67], off offset:256
	v_pk_add_f32 v[32:33], v[32:33], 0 op_sel_hi:[1,0]
	v_pk_add_f32 v[22:23], v[22:23], 0 op_sel_hi:[1,0]
	v_lshl_add_u64 v[64:65], v[144:145], 0, s[22:23]
	s_mov_b32 s22, 0x40000
	v_pk_add_f32 v[66:67], v[58:59], 0 op_sel_hi:[1,0]
	v_pk_add_f32 v[58:59], v[56:57], 0 op_sel_hi:[1,0]
	v_cvt_pk_bf16_f32 v56, v60, v61
	v_add_co_u32_e32 v60, vcc, s22, v144
	v_cvt_pk_bf16_f32 v57, v62, v63
	v_cvt_pk_bf16_f32 v58, v58, v59
	v_cvt_pk_bf16_f32 v59, v66, v67
	s_mov_b64 s[22:23], 0x48000
	s_nop 0
	v_addc_co_u32_e32 v61, vcc, 0, v145, vcc
	global_store_dwordx4 v[60:61], v[56:59], off
	v_pk_add_f32 v[20:21], v[20:21], 0 op_sel_hi:[1,0]
	v_pk_add_f32 v[16:17], v[16:17], 0 op_sel_hi:[1,0]
	v_pk_add_f32 v[56:57], v[46:47], 0 op_sel_hi:[1,0]
	v_pk_add_f32 v[46:47], v[44:45], 0 op_sel_hi:[1,0]
	v_cvt_pk_bf16_f32 v44, v52, v53
	v_cvt_pk_bf16_f32 v45, v54, v55
	s_mov_b32 s54, s51
	v_cvt_pk_bf16_f32 v46, v46, v47
	v_cvt_pk_bf16_f32 v47, v56, v57
	global_store_dwordx4 v[64:65], v[44:47], off offset:256
	s_mov_b32 s53, s52
	s_mov_b64 s[24:25], s[4:5]
	v_pk_add_f32 v[46:47], v[50:51], 0 op_sel_hi:[1,0]
	v_pk_add_f32 v[50:51], v[42:43], 0 op_sel_hi:[1,0]
	v_pk_add_f32 v[42:43], v[40:41], 0 op_sel_hi:[1,0]
	v_cvt_pk_bf16_f32 v40, v48, v49
	v_cvt_pk_bf16_f32 v41, v46, v47
	v_add_co_u32_e32 v46, vcc, s48, v144
	v_cvt_pk_bf16_f32 v42, v42, v43
	v_cvt_pk_bf16_f32 v43, v50, v51
	v_lshl_add_u64 v[44:45], v[144:145], 0, s[22:23]
	s_nop 0
	v_addc_co_u32_e32 v47, vcc, 0, v145, vcc
	global_store_dwordx4 v[46:47], v[40:43], off
	s_mov_b64 s[22:23], s[0:1]
	v_pk_add_f32 v[6:7], v[6:7], 0 op_sel_hi:[1,0]
	v_pk_add_f32 v[40:41], v[30:31], 0 op_sel_hi:[1,0]
	v_pk_add_f32 v[30:31], v[28:29], 0 op_sel_hi:[1,0]
	v_cvt_pk_bf16_f32 v28, v36, v37
	v_cvt_pk_bf16_f32 v29, v38, v39
	v_pk_add_f32 v[4:5], v[4:5], 0 op_sel_hi:[1,0]
	v_cvt_pk_bf16_f32 v30, v30, v31
	v_cvt_pk_bf16_f32 v31, v40, v41
	global_store_dwordx4 v[44:45], v[28:31], off offset:256
	s_nop 1
	v_pk_add_f32 v[30:31], v[34:35], 0 op_sel_hi:[1,0]
	v_pk_add_f32 v[34:35], v[26:27], 0 op_sel_hi:[1,0]
	v_pk_add_f32 v[26:27], v[24:25], 0 op_sel_hi:[1,0]
	v_cvt_pk_bf16_f32 v24, v32, v33
	v_cvt_pk_bf16_f32 v25, v30, v31
	v_add_co_u32_e32 v30, vcc, s49, v144
	v_cvt_pk_bf16_f32 v26, v26, v27
	v_cvt_pk_bf16_f32 v27, v34, v35
	v_lshl_add_u64 v[28:29], v[144:145], 0, s[16:17]
	s_nop 0
	v_addc_co_u32_e32 v31, vcc, 0, v145, vcc
	global_store_dwordx4 v[30:31], v[24:27], off
	s_nop 1
	v_pk_add_f32 v[24:25], v[14:15], 0 op_sel_hi:[1,0]
	v_pk_add_f32 v[14:15], v[12:13], 0 op_sel_hi:[1,0]
	v_cvt_pk_bf16_f32 v12, v20, v21
	v_cvt_pk_bf16_f32 v13, v22, v23
	s_nop 0
	v_cvt_pk_bf16_f32 v14, v14, v15
	v_cvt_pk_bf16_f32 v15, v24, v25
	global_store_dwordx4 v[28:29], v[12:15], off offset:256
	s_nop 1
	v_pk_add_f32 v[14:15], v[18:19], 0 op_sel_hi:[1,0]
	v_pk_add_f32 v[18:19], v[10:11], 0 op_sel_hi:[1,0]
	v_pk_add_f32 v[10:11], v[8:9], 0 op_sel_hi:[1,0]
	v_cvt_pk_bf16_f32 v8, v16, v17
	v_cvt_pk_bf16_f32 v9, v14, v15
	v_add_co_u32_e32 v14, vcc, s50, v144
	v_lshl_add_u64 v[12:13], v[144:145], 0, s[18:19]
	s_nop 0
	v_addc_co_u32_e32 v15, vcc, 0, v145, vcc
	v_cvt_pk_bf16_f32 v10, v10, v11
	v_cvt_pk_bf16_f32 v11, v18, v19
	global_store_dwordx4 v[14:15], v[8:11], off
	s_and_b64 vcc, exec, s[2:3]
	s_nop 0
	v_pk_add_f32 v[8:9], v[2:3], 0 op_sel_hi:[1,0]
	v_pk_add_f32 v[2:3], v[0:1], 0 op_sel_hi:[1,0]
	v_cvt_pk_bf16_f32 v0, v4, v5
	v_cvt_pk_bf16_f32 v1, v6, v7
	s_nop 0
	v_cvt_pk_bf16_f32 v2, v2, v3
	v_cvt_pk_bf16_f32 v3, v8, v9
	global_store_dwordx4 v[12:13], v[0:3], off offset:256
	s_cbranch_vccz .LBB0_275
	s_waitcnt vmcnt(0)
	s_cmpk_gt_u32 s31, 0xff
	s_cbranch_scc1 .LBB0_290
	s_barrier

; #define PG8_STAGE(bufoff, gbase, voff) do { _Pragma("unroll") for (int _i = 0; _i < 2; ++_i) \
;         __builtin_amdgcn_global_load_lds((const unsigned*)((const char*)(gbase) + (voff)[_i]), (PG8_LAS unsigned*)(lds + (bufoff) + ldsw + _i * 8192), 16, 0, 0); } while (0)
; #define PG8_LDA(dst, b, h) do { _Pragma("unroll") for (int m = 0; m < 4; ++m) _Pragma("unroll") for (int k = 0; k < 2; ++k) dst[m][k] = *(const PG8_LAS bf16x8*)(lds + PG8_SA(b, h) + aoff + m * 2048 + k * 1024); } while (0)
; #define PG8_LDB(dst, b, h) do { _Pragma("unroll") for (int n = 0; n < 2; ++n) _Pragma("unroll") for (int k = 0; k < 2; ++k) dst[n][k] = *(const PG8_LAS bf16x8*)(lds + PG8_SB(b, h) + boff + n * 2048 + k * 1024); } while (0)
; #define PG8_WAIT_V(n) asm volatile("s_waitcnt vmcnt(" #n ")" ::: "memory")
; #define PG8_WAIT_L(n) asm volatile("s_waitcnt lgkmcnt(" #n ")" ::: "memory")
; #define PG8_BAR __builtin_amdgcn_s_barrier()
; #define PG8_SCHED __builtin_amdgcn_sched_barrier(0)
; template <class Epi, class Sched>
; __device__ __forceinline__ void gemm_phase(PG8_LAS unsigned char* lds, const Gemm g, const Sched& S, const Epi& E) {
;     ...
;         const bool has_next = S.next(ui + 1, nxt);
;         const char* nA = has_next ? (const char*)g.A + (size_t)nxt.pm * tstep : cA; const char* nB = has_next ? (const char*)g.Bt + (size_t)nxt.pn * tstep : cB;
;         for (int t = 0; t < nt; t += 2) {
;             const bool last = (t == nt - 2);
;             const char* a1 = cA + (size_t)(t + 1) * kstep;
;             const char* a2 = last ? nA : cA + (size_t)(t + 2) * kstep; const char* b2 = last ? nB : cB + (size_t)(t + 2) * kstep;
;             const char* a3 = a2 + kstep; const char* b3 = b2 + kstep;
;             if (last && has_next) S.a_ready(nxt);
;             PG8_LDB(B0, 0, 0); PG8_SCHED; PG8_LDA(At, 0, 0); PG8_STAGE(PG8_SA(1, 1), a1 + hstep, voffA);
;             PG8_WAIT_L(8); PG8_BAR; PG8_WAIT_L(0); PG8_MMA(0, 0, At, B0); PG8_BAR; PG8_SCHED;
;             PG8_LDB(B1, 0, 1); PG8_STAGE(PG8_SB(0, 0), b2, voffB);
;             PG8_BAR; PG8_WAIT_L(0); PG8_MMA(0, 1, At, B1); PG8_BAR;
;             PG8_LDA(At, 0, 1); PG8_STAGE(PG8_SA(0, 0), a2, voffA);
;             PG8_BAR; PG8_WAIT_L(0); PG8_MMA(1, 0, At, B0); PG8_BAR; PG8_SCHED;
;             PG8_STAGE(PG8_SB(0, 1), b2 + hstep, voffB);
;             PG8_WAIT_V(6); PG8_BAR; PG8_MMA(1, 1, At, B1); PG8_BAR;
.LBB0_415:
	s_ashr_i32 s21, s20, 31
	v_cmp_lt_i64_e32 vcc, s[22:23], v[170:171]
	s_lshl_b64 s[22:23], s[20:21], 19
	s_add_u32 s22, s31, s22
	s_addc_u32 s23, s34, s23
	s_and_b64 s[24:25], vcc, exec
	s_cselect_b32 s7, s23, s1
	s_cselect_b32 s10, s22, s0
	s_ashr_i32 s19, s18, 31
	s_lshl_b64 s[24:25], s[18:19], 19
	s_add_u32 s24, s8, s24
	s_addc_u32 s25, s9, s25
	s_and_b64 s[28:29], vcc, exec
	s_cselect_b32 s19, s25, s5
	s_cselect_b32 s21, s24, s4
	s_add_u32 s0, s0, 0x40080
	s_addc_u32 s1, s1, 0
	s_add_u32 s51, s4, 0x100
	s_addc_u32 s52, s5, 0
	s_mov_b32 s53, -2
	ds_read_b128 v[24:27], v186
	ds_read_b128 v[28:31], v186 offset:1024
	ds_read_b128 v[40:43], v186 offset:2048
	ds_read_b128 v[44:47], v186 offset:3072
	s_add_u32 s4, s0, 0xfffc0080
	s_addc_u32 s5, s1, -1
	s_cmp_eq_u32 s53, 12
	s_cselect_b32 s29, s7, s5
	s_cselect_b32 s28, s10, s4
	s_cselect_b32 s5, s19, s52
	s_cselect_b32 s4, s21, s51
	s_add_i32 m0, s27, 0xc000
	ds_read_b128 v[144:147], v187
	ds_read_b128 v[148:151], v187 offset:1024
	ds_read_b128 v[182:185], v187 offset:2048
	ds_read_b128 v[192:195], v187 offset:3072
	ds_read_b128 v[196:199], v187 offset:4096
	ds_read_b128 v[200:203], v187 offset:5120
	ds_read_b128 v[204:207], v187 offset:6144
	ds_read_b128 v[208:211], v187 offset:7168
	global_load_lds_dwordx4 v166, s[0:1]
	s_nop 1
	s_add_i32 m0, s27, 0xe000
	s_nop 0
	global_load_lds_dwordx4 v168, s[0:1]
	s_waitcnt lgkmcnt(12)
	ds_read_b128 v[212:215], v189
	ds_read_b128 v[216:219], v189 offset:1024
	ds_read_b128 v[220:223], v189 offset:2048
	ds_read_b128 v[224:227], v189 offset:3072
	s_waitcnt vmcnt(8) lgkmcnt(0)
	s_barrier
	v_mfma_f32_16x16x32_bf16 v[140:143], v[24:27], v[144:147], 0
	v_mfma_f32_16x16x32_bf16 v[136:139], v[40:43], v[144:147], 0
	v_mfma_f32_16x16x32_bf16 v[124:127], v[24:27], v[182:185], 0
	v_mfma_f32_16x16x32_bf16 v[120:123], v[40:43], v[182:185], 0
	v_mfma_f32_16x16x32_bf16 v[108:111], v[24:27], v[196:199], 0
	v_mfma_f32_16x16x32_bf16 v[104:107], v[40:43], v[196:199], 0
	v_mfma_f32_16x16x32_bf16 v[92:95], v[24:27], v[204:207], 0
	v_mfma_f32_16x16x32_bf16 v[88:91], v[40:43], v[204:207], 0
	v_mfma_f32_16x16x32_bf16 v[140:143], v[28:31], v[148:151], v[140:143]
	v_mfma_f32_16x16x32_bf16 v[136:139], v[44:47], v[148:151], v[136:139]
	v_mfma_f32_16x16x32_bf16 v[124:127], v[28:31], v[192:195], v[124:127]
	v_mfma_f32_16x16x32_bf16 v[120:123], v[44:47], v[192:195], v[120:123]
	v_mfma_f32_16x16x32_bf16 v[108:111], v[28:31], v[200:203], v[108:111]
	v_mfma_f32_16x16x32_bf16 v[104:107], v[44:47], v[200:203], v[104:107]
	v_mfma_f32_16x16x32_bf16 v[92:95], v[28:31], v[208:211], v[92:95]
	v_mfma_f32_16x16x32_bf16 v[88:91], v[44:47], v[208:211], v[88:91]
	v_mfma_f32_16x16x32_bf16 v[132:135], v[212:215], v[144:147], 0
	v_mfma_f32_16x16x32_bf16 v[128:131], v[220:223], v[144:147], 0
	v_mfma_f32_16x16x32_bf16 v[116:119], v[212:215], v[182:185], 0
	v_mfma_f32_16x16x32_bf16 v[112:115], v[220:223], v[182:185], 0
	v_mfma_f32_16x16x32_bf16 v[100:103], v[212:215], v[196:199], 0
	v_mfma_f32_16x16x32_bf16 v[96:99], v[220:223], v[196:199], 0
	v_mfma_f32_16x16x32_bf16 v[84:87], v[212:215], v[204:207], 0
	v_mfma_f32_16x16x32_bf16 v[80:83], v[220:223], v[204:207], 0
	v_mfma_f32_16x16x32_bf16 v[132:135], v[216:219], v[148:151], v[132:135]
	v_mfma_f32_16x16x32_bf16 v[128:131], v[224:227], v[148:151], v[128:131]
	v_mfma_f32_16x16x32_bf16 v[116:119], v[216:219], v[192:195], v[116:119]
	v_mfma_f32_16x16x32_bf16 v[112:115], v[224:227], v[192:195], v[112:115]
	v_mfma_f32_16x16x32_bf16 v[100:103], v[216:219], v[200:203], v[100:103]
	v_mfma_f32_16x16x32_bf16 v[96:99], v[224:227], v[200:203], v[96:99]
	v_mfma_f32_16x16x32_bf16 v[84:87], v[216:219], v[208:211], v[84:87]
	v_mfma_f32_16x16x32_bf16 v[80:83], v[224:227], v[208:211], v[80:83]
	s_barrier
	ds_read_b128 v[144:147], v187 offset:16384
	ds_read_b128 v[148:151], v187 offset:17408
	ds_read_b128 v[182:185], v187 offset:18432
	ds_read_b128 v[192:195], v187 offset:19456
	ds_read_b128 v[196:199], v187 offset:20480
	ds_read_b128 v[200:203], v187 offset:21504
	ds_read_b128 v[204:207], v187 offset:22528
	ds_read_b128 v[208:211], v187 offset:23552
	s_add_i32 s54, s43, s35
	s_add_u32 s98, s4, s14
	s_addc_u32 s99, s5, s15
	s_mov_b32 m0, s54
	s_nop 0
	global_load_lds_dwordx4 v156, s[4:5]
	s_nop 1
	s_add_i32 m0, s54, 0x2000
	s_nop 0
	global_load_lds_dwordx4 v160, s[4:5]
	s_nop 1
	s_mov_b32 m0, s27
	s_add_u32 s100, s28, s14
	s_addc_u32 s101, s29, s15
	global_load_lds_dwordx4 v154, s[28:29]
	s_nop 1
	s_mov_b32 m0, s36
	s_nop 0
	global_load_lds_dwordx4 v158, s[28:29]
	s_add_u32 s54, s4, 0x40000
	s_addc_u32 s55, s5, 0
	s_add_i32 s56, s44, s35
	s_mov_b32 m0, s56
	s_nop 0
	global_load_lds_dwordx4 v156, s[54:55]
	s_nop 1
	s_add_i32 m0, s56, 0x2000
	s_nop 0
	global_load_lds_dwordx4 v160, s[54:55]
	s_waitcnt vmcnt(8) lgkmcnt(0)
	s_barrier
; #define PG8_STAGE(bufoff, gbase, voff) do { _Pragma("unroll") for (int _i = 0; _i < 2; ++_i) \
;         __builtin_amdgcn_global_load_lds((const unsigned*)((const char*)(gbase) + (voff)[_i]), (PG8_LAS unsigned*)(lds + (bufoff) + ldsw + _i * 8192), 16, 0, 0); } while (0)
; #define PG8_LDA(dst, b, h) do { _Pragma("unroll") for (int m = 0; m < 4; ++m) _Pragma("unroll") for (int k = 0; k < 2; ++k) dst[m][k] = *(const PG8_LAS bf16x8*)(lds + PG8_SA(b, h) + aoff + m * 2048 + k * 1024); } while (0)
; #define PG8_LDB(dst, b, h) do { _Pragma("unroll") for (int n = 0; n < 2; ++n) _Pragma("unroll") for (int k = 0; k < 2; ++k) dst[n][k] = *(const PG8_LAS bf16x8*)(lds + PG8_SB(b, h) + boff + n * 2048 + k * 1024); } while (0)
; #define PG8_MMA(ai, bj, At, Bt) do { __builtin_amdgcn_s_setprio(1); _Pragma("unroll") for (int m = 0; m < 4; ++m) _Pragma("unroll") for (int n = 0; n < 2; ++n) _Pragma("unroll") for (int k = 0; k < 2; ++k) \
;         acc[ai][bj][m][n] = __builtin_amdgcn_mfma_f32_16x16x32_bf16(Bt[n][k], At[m][k], acc[ai][bj][m][n], 0, 0, 0); __builtin_amdgcn_s_setprio(0); } while (0)
; #define PG8_WAIT_V(n) asm volatile("s_waitcnt vmcnt(" #n ")" ::: "memory")
; #define PG8_WAIT_L(n) asm volatile("s_waitcnt lgkmcnt(" #n ")" ::: "memory")
; #define PG8_BAR __builtin_amdgcn_s_barrier()
; #define PG8_SCHED __builtin_amdgcn_sched_barrier(0)
; template <class Epi, class Sched>
; __device__ __forceinline__ void gemm_phase(PG8_LAS unsigned char* lds, const Gemm g, const Sched& S, const Epi& E) {
;     ...
;             PG8_LDA(At, 0, 1); PG8_STAGE(PG8_SA(0, 0), a2, voffA);
;             PG8_BAR; PG8_WAIT_L(0); PG8_MMA(1, 0, At, B0); PG8_BAR; PG8_SCHED;
;             PG8_STAGE(PG8_SB(0, 1), b2 + hstep, voffB);
;             PG8_WAIT_V(6); PG8_BAR; PG8_MMA(1, 1, At, B1); PG8_BAR;
;             PG8_LDB(B0, 1, 0); PG8_SCHED; PG8_LDA(At, 1, 0); PG8_STAGE(PG8_SA(0, 1), a2 + hstep, voffA);
;             PG8_WAIT_L(8); PG8_BAR; PG8_WAIT_L(0); PG8_MMA(0, 0, At, B0); PG8_BAR; PG8_SCHED;
;             PG8_LDB(B1, 1, 1); PG8_STAGE(PG8_SB(1, 0), b3, voffB);
;             PG8_BAR; PG8_WAIT_L(0); PG8_MMA(0, 1, At, B1); PG8_BAR;
;             PG8_LDA(At, 1, 1); PG8_STAGE(PG8_SA(1, 0), a3, voffA);
;             PG8_BAR; PG8_WAIT_L(0); PG8_MMA(1, 0, At, B0); PG8_BAR; PG8_SCHED;
	v_mfma_f32_16x16x32_bf16 v[76:79], v[24:27], v[144:147], 0
	v_mfma_f32_16x16x32_bf16 v[72:75], v[40:43], v[144:147], 0
	v_mfma_f32_16x16x32_bf16 v[60:63], v[24:27], v[182:185], 0
	v_mfma_f32_16x16x32_bf16 v[56:59], v[40:43], v[182:185], 0
	v_mfma_f32_16x16x32_bf16 v[36:39], v[24:27], v[196:199], 0
	v_mfma_f32_16x16x32_bf16 v[32:35], v[40:43], v[196:199], 0
	v_mfma_f32_16x16x32_bf16 v[12:15], v[24:27], v[204:207], 0
	v_mfma_f32_16x16x32_bf16 v[8:11], v[40:43], v[204:207], 0
	v_mfma_f32_16x16x32_bf16 v[76:79], v[28:31], v[148:151], v[76:79]
	v_mfma_f32_16x16x32_bf16 v[72:75], v[44:47], v[148:151], v[72:75]
	v_mfma_f32_16x16x32_bf16 v[60:63], v[28:31], v[192:195], v[60:63]
	v_mfma_f32_16x16x32_bf16 v[56:59], v[44:47], v[192:195], v[56:59]
	v_mfma_f32_16x16x32_bf16 v[36:39], v[28:31], v[200:203], v[36:39]
	v_mfma_f32_16x16x32_bf16 v[32:35], v[44:47], v[200:203], v[32:35]
	v_mfma_f32_16x16x32_bf16 v[12:15], v[28:31], v[208:211], v[12:15]
	v_mfma_f32_16x16x32_bf16 v[8:11], v[44:47], v[208:211], v[8:11]
	v_mfma_f32_16x16x32_bf16 v[20:23], v[212:215], v[196:199], 0
	v_mfma_f32_16x16x32_bf16 v[16:19], v[220:223], v[196:199], 0
	v_mfma_f32_16x16x32_bf16 v[4:7], v[212:215], v[204:207], 0
	v_mfma_f32_16x16x32_bf16 v[0:3], v[220:223], v[204:207], 0
	v_mfma_f32_16x16x32_bf16 v[24:27], v[212:215], v[144:147], 0
	v_mfma_f32_16x16x32_bf16 v[28:31], v[220:223], v[144:147], 0
	v_mfma_f32_16x16x32_bf16 v[40:43], v[212:215], v[182:185], 0
	v_mfma_f32_16x16x32_bf16 v[44:47], v[220:223], v[182:185], 0
	v_mfma_f32_16x16x32_bf16 v[20:23], v[216:219], v[200:203], v[20:23]
	v_mfma_f32_16x16x32_bf16 v[16:19], v[224:227], v[200:203], v[16:19]
	v_mfma_f32_16x16x32_bf16 v[4:7], v[216:219], v[208:211], v[4:7]
	v_mfma_f32_16x16x32_bf16 v[0:3], v[224:227], v[208:211], v[0:3]
	v_mfma_f32_16x16x32_bf16 v[24:27], v[216:219], v[148:151], v[24:27]
	v_mfma_f32_16x16x32_bf16 v[28:31], v[224:227], v[148:151], v[28:31]
	v_mfma_f32_16x16x32_bf16 v[40:43], v[216:219], v[192:195], v[40:43]
	v_mfma_f32_16x16x32_bf16 v[44:47], v[224:227], v[192:195], v[44:47]
	s_barrier
	s_add_i32 s54, 0, 0x18000
	v_add_u32_e32 v68, s54, v179
	ds_read_b128 v[48:51], v68
	ds_read_b128 v[52:55], v68 offset:1024
	ds_read_b128 v[64:67], v68 offset:2048
	ds_read_b128 v[68:71], v68 offset:3072
	s_add_u32 s28, s28, 0x40000
	s_addc_u32 s29, s29, 0
	s_mov_b32 m0, s37
	ds_read_b128 v[144:147], v187 offset:32768
	ds_read_b128 v[148:151], v187 offset:33792
	ds_read_b128 v[182:185], v187 offset:34816
	ds_read_b128 v[192:195], v187 offset:35840
	ds_read_b128 v[196:199], v187 offset:36864
	ds_read_b128 v[200:203], v187 offset:37888
	ds_read_b128 v[204:207], v187 offset:38912
	ds_read_b128 v[208:211], v187 offset:39936
	global_load_lds_dwordx4 v154, s[28:29]
	s_nop 1
	s_mov_b32 m0, s38
	s_nop 0
	global_load_lds_dwordx4 v158, s[28:29]
	s_add_i32 s28, 0, 0x1c000
	v_add_u32_e32 v162, s28, v179
	s_waitcnt lgkmcnt(12)
	ds_read_b128 v[212:215], v162
	ds_read_b128 v[216:219], v162 offset:1024
	ds_read_b128 v[220:223], v162 offset:2048
	ds_read_b128 v[224:227], v162 offset:3072
	s_waitcnt vmcnt(8) lgkmcnt(0)
	s_barrier
	v_mfma_f32_16x16x32_bf16 v[140:143], v[48:51], v[144:147], v[140:143]
	v_mfma_f32_16x16x32_bf16 v[136:139], v[64:67], v[144:147], v[136:139]
	v_mfma_f32_16x16x32_bf16 v[124:127], v[48:51], v[182:185], v[124:127]
	v_mfma_f32_16x16x32_bf16 v[120:123], v[64:67], v[182:185], v[120:123]
	v_mfma_f32_16x16x32_bf16 v[108:111], v[48:51], v[196:199], v[108:111]
	v_mfma_f32_16x16x32_bf16 v[104:107], v[64:67], v[196:199], v[104:107]
	v_mfma_f32_16x16x32_bf16 v[92:95], v[48:51], v[204:207], v[92:95]
	v_mfma_f32_16x16x32_bf16 v[88:91], v[64:67], v[204:207], v[88:91]
	v_mfma_f32_16x16x32_bf16 v[140:143], v[52:55], v[148:151], v[140:143]
	v_mfma_f32_16x16x32_bf16 v[136:139], v[68:71], v[148:151], v[136:139]
	v_mfma_f32_16x16x32_bf16 v[124:127], v[52:55], v[192:195], v[124:127]
	v_mfma_f32_16x16x32_bf16 v[120:123], v[68:71], v[192:195], v[120:123]
	v_mfma_f32_16x16x32_bf16 v[108:111], v[52:55], v[200:203], v[108:111]
	v_mfma_f32_16x16x32_bf16 v[104:107], v[68:71], v[200:203], v[104:107]
	v_mfma_f32_16x16x32_bf16 v[92:95], v[52:55], v[208:211], v[92:95]
	v_mfma_f32_16x16x32_bf16 v[88:91], v[68:71], v[208:211], v[88:91]
	v_mfma_f32_16x16x32_bf16 v[132:135], v[212:215], v[144:147], v[132:135]
	v_mfma_f32_16x16x32_bf16 v[128:131], v[220:223], v[144:147], v[128:131]
	v_mfma_f32_16x16x32_bf16 v[116:119], v[212:215], v[182:185], v[116:119]
	v_mfma_f32_16x16x32_bf16 v[112:115], v[220:223], v[182:185], v[112:115]
	v_mfma_f32_16x16x32_bf16 v[100:103], v[212:215], v[196:199], v[100:103]
	v_mfma_f32_16x16x32_bf16 v[96:99], v[220:223], v[196:199], v[96:99]
	v_mfma_f32_16x16x32_bf16 v[84:87], v[212:215], v[204:207], v[84:87]
	v_mfma_f32_16x16x32_bf16 v[80:83], v[220:223], v[204:207], v[80:83]
	v_mfma_f32_16x16x32_bf16 v[132:135], v[216:219], v[148:151], v[132:135]
	v_mfma_f32_16x16x32_bf16 v[128:131], v[224:227], v[148:151], v[128:131]
	v_mfma_f32_16x16x32_bf16 v[116:119], v[216:219], v[192:195], v[116:119]
	v_mfma_f32_16x16x32_bf16 v[112:115], v[224:227], v[192:195], v[112:115]
	v_mfma_f32_16x16x32_bf16 v[100:103], v[216:219], v[200:203], v[100:103]
	v_mfma_f32_16x16x32_bf16 v[96:99], v[224:227], v[200:203], v[96:99]
	v_mfma_f32_16x16x32_bf16 v[84:87], v[216:219], v[208:211], v[84:87]
	v_mfma_f32_16x16x32_bf16 v[80:83], v[224:227], v[208:211], v[80:83]
	s_barrier
; #define PG8_STAGE(bufoff, gbase, voff) do { _Pragma("unroll") for (int _i = 0; _i < 2; ++_i) \
;         __builtin_amdgcn_global_load_lds((const unsigned*)((const char*)(gbase) + (voff)[_i]), (PG8_LAS unsigned*)(lds + (bufoff) + ldsw + _i * 8192), 16, 0, 0); } while (0)
; #define PG8_LDA(dst, b, h) do { _Pragma("unroll") for (int m = 0; m < 4; ++m) _Pragma("unroll") for (int k = 0; k < 2; ++k) dst[m][k] = *(const PG8_LAS bf16x8*)(lds + PG8_SA(b, h) + aoff + m * 2048 + k * 1024); } while (0)
; #define PG8_WAIT_V(n) asm volatile("s_waitcnt vmcnt(" #n ")" ::: "memory")
; #define PG8_BAR __builtin_amdgcn_s_barrier()
; template <class Epi, class Sched>
; __device__ __forceinline__ void gemm_phase(PG8_LAS unsigned char* lds, const Gemm g, const Sched& S, const Epi& E) {
;     ...
;             const bool last = (t == nt - 2);
;             const char* a1 = cA + (size_t)(t + 1) * kstep;
;             const char* a2 = last ? nA : cA + (size_t)(t + 2) * kstep; const char* b2 = last ? nB : cB + (size_t)(t + 2) * kstep;
;             const char* a3 = a2 + kstep; const char* b3 = b2 + kstep;
;             if (last && has_next) S.a_ready(nxt);
;             PG8_LDB(B0, 0, 0); PG8_SCHED; PG8_LDA(At, 0, 0); PG8_STAGE(PG8_SA(1, 1), a1 + hstep, voffA);
;             PG8_WAIT_L(8); PG8_BAR; PG8_WAIT_L(0); PG8_MMA(0, 0, At, B0); PG8_BAR; PG8_SCHED;
;             PG8_LDB(B1, 0, 1); PG8_STAGE(PG8_SB(0, 0), b2, voffB);
;             PG8_BAR; PG8_WAIT_L(0); PG8_MMA(0, 1, At, B1); PG8_BAR;
;             PG8_LDA(At, 0, 1); PG8_STAGE(PG8_SA(0, 0), a2, voffA);
;             PG8_BAR; PG8_WAIT_L(0); PG8_MMA(1, 0, At, B0); PG8_BAR; PG8_SCHED;
;             PG8_STAGE(PG8_SB(0, 1), b2 + hstep, voffB);
;             PG8_WAIT_V(6); PG8_BAR; PG8_MMA(1, 1, At, B1); PG8_BAR;
;             PG8_LDB(B0, 1, 0); PG8_SCHED; PG8_LDA(At, 1, 0); PG8_STAGE(PG8_SA(0, 1), a2 + hstep, voffA);
;             PG8_WAIT_L(8); PG8_BAR; PG8_WAIT_L(0); PG8_MMA(0, 0, At, B0); PG8_BAR; PG8_SCHED;
;             PG8_LDB(B1, 1, 1); PG8_STAGE(PG8_SB(1, 0), b3, voffB);
;             PG8_BAR; PG8_WAIT_L(0); PG8_MMA(0, 1, At, B1); PG8_BAR;
;             PG8_LDA(At, 1, 1); PG8_STAGE(PG8_SA(1, 0), a3, voffA);
;             PG8_BAR; PG8_WAIT_L(0); PG8_MMA(1, 0, At, B0); PG8_BAR; PG8_SCHED;
;             PG8_STAGE(PG8_SB(1, 1), b3 + hstep, voffB);
;             PG8_WAIT_V(6); PG8_BAR; PG8_MMA(1, 1, At, B1); PG8_BAR;
	ds_read_b128 v[144:147], v187 offset:49152
	ds_read_b128 v[148:151], v187 offset:50176
	ds_read_b128 v[182:185], v187 offset:51200
	ds_read_b128 v[192:195], v187 offset:52224
	ds_read_b128 v[196:199], v187 offset:53248
	ds_read_b128 v[200:203], v187 offset:54272
	ds_read_b128 v[204:207], v187 offset:55296
	ds_read_b128 v[208:211], v187 offset:56320
	s_add_i32 s29, s54, s35
	s_mov_b32 m0, s29
	s_nop 0
	global_load_lds_dwordx4 v156, s[98:99]
	s_nop 1
	s_add_i32 m0, s29, 0x2000
	s_nop 0
	global_load_lds_dwordx4 v160, s[98:99]
	s_nop 1
	s_mov_b32 m0, s39
	s_nop 0
	global_load_lds_dwordx4 v154, s[100:101]
	s_nop 1
	s_mov_b32 m0, s40
	s_nop 0
	global_load_lds_dwordx4 v158, s[100:101]
	s_add_u32 s4, s4, 0x40080
	s_addc_u32 s5, s5, 0
	s_add_i32 s28, s28, s35
	s_mov_b32 m0, s28
	s_nop 0
	global_load_lds_dwordx4 v156, s[4:5]
	s_nop 1
	s_add_i32 m0, s28, 0x2000
	s_nop 0
	global_load_lds_dwordx4 v160, s[4:5]
	s_waitcnt vmcnt(8) lgkmcnt(0)
	s_barrier
	v_mfma_f32_16x16x32_bf16 v[76:79], v[48:51], v[144:147], v[76:79]
	v_mfma_f32_16x16x32_bf16 v[72:75], v[64:67], v[144:147], v[72:75]
	v_mfma_f32_16x16x32_bf16 v[60:63], v[48:51], v[182:185], v[60:63]
	v_mfma_f32_16x16x32_bf16 v[56:59], v[64:67], v[182:185], v[56:59]
	v_mfma_f32_16x16x32_bf16 v[36:39], v[48:51], v[196:199], v[36:39]
	v_mfma_f32_16x16x32_bf16 v[32:35], v[64:67], v[196:199], v[32:35]
	v_mfma_f32_16x16x32_bf16 v[12:15], v[48:51], v[204:207], v[12:15]
	v_mfma_f32_16x16x32_bf16 v[8:11], v[64:67], v[204:207], v[8:11]
	v_mfma_f32_16x16x32_bf16 v[76:79], v[52:55], v[148:151], v[76:79]
	v_mfma_f32_16x16x32_bf16 v[72:75], v[68:71], v[148:151], v[72:75]
	v_mfma_f32_16x16x32_bf16 v[60:63], v[52:55], v[192:195], v[60:63]
	v_mfma_f32_16x16x32_bf16 v[56:59], v[68:71], v[192:195], v[56:59]
	v_mfma_f32_16x16x32_bf16 v[36:39], v[52:55], v[200:203], v[36:39]
	v_mfma_f32_16x16x32_bf16 v[32:35], v[68:71], v[200:203], v[32:35]
	v_mfma_f32_16x16x32_bf16 v[12:15], v[52:55], v[208:211], v[12:15]
	v_mfma_f32_16x16x32_bf16 v[8:11], v[68:71], v[208:211], v[8:11]
	v_mfma_f32_16x16x32_bf16 v[24:27], v[212:215], v[144:147], v[24:27]
	v_mfma_f32_16x16x32_bf16 v[68:71], v[216:219], v[148:151], v[24:27]
	v_mfma_f32_16x16x32_bf16 v[24:27], v[220:223], v[144:147], v[28:31]
	v_mfma_f32_16x16x32_bf16 v[64:67], v[224:227], v[148:151], v[24:27]
	v_mfma_f32_16x16x32_bf16 v[24:27], v[212:215], v[182:185], v[40:43]
	v_mfma_f32_16x16x32_bf16 v[52:55], v[216:219], v[192:195], v[24:27]
	v_mfma_f32_16x16x32_bf16 v[24:27], v[220:223], v[182:185], v[44:47]
	v_mfma_f32_16x16x32_bf16 v[20:23], v[212:215], v[196:199], v[20:23]
	v_mfma_f32_16x16x32_bf16 v[16:19], v[220:223], v[196:199], v[16:19]
	v_mfma_f32_16x16x32_bf16 v[4:7], v[212:215], v[204:207], v[4:7]
	v_mfma_f32_16x16x32_bf16 v[0:3], v[220:223], v[204:207], v[0:3]
	v_mfma_f32_16x16x32_bf16 v[48:51], v[224:227], v[192:195], v[24:27]
	v_mfma_f32_16x16x32_bf16 v[20:23], v[216:219], v[200:203], v[20:23]
	v_mfma_f32_16x16x32_bf16 v[16:19], v[224:227], v[200:203], v[16:19]
	v_mfma_f32_16x16x32_bf16 v[4:7], v[216:219], v[208:211], v[4:7]
	v_mfma_f32_16x16x32_bf16 v[0:3], v[224:227], v[208:211], v[0:3]
	s_barrier
	s_add_i32 s53, s53, 2
	s_add_u32 s0, s0, 0x100
	s_addc_u32 s1, s1, 0
	s_add_u32 s51, s51, 0x100
	s_addc_u32 s52, s52, 0
	s_cmp_gt_u32 s53, 13
.LBB0_416:
	ds_read_b128 v[24:27], v186
	ds_read_b128 v[28:31], v186 offset:1024
	ds_read_b128 v[40:43], v186 offset:2048
	ds_read_b128 v[44:47], v186 offset:3072
	s_add_u32 s4, s0, 0xfffc0080
	s_addc_u32 s5, s1, -1
	s_cmp_eq_u32 s53, 12
	s_cselect_b32 s29, s7, s5
	s_cselect_b32 s28, s10, s4
	s_cselect_b32 s5, s19, s52
	s_cselect_b32 s4, s21, s51
	s_add_i32 m0, s27, 0xc000
	ds_read_b128 v[144:147], v187
	ds_read_b128 v[148:151], v187 offset:1024
	ds_read_b128 v[182:185], v187 offset:2048
	ds_read_b128 v[192:195], v187 offset:3072
	ds_read_b128 v[196:199], v187 offset:4096
	ds_read_b128 v[200:203], v187 offset:5120
	ds_read_b128 v[204:207], v187 offset:6144
	ds_read_b128 v[208:211], v187 offset:7168
	global_load_lds_dwordx4 v166, s[0:1]
	s_nop 1
	s_add_i32 m0, s27, 0xe000
	s_nop 0
	global_load_lds_dwordx4 v168, s[0:1]
	s_waitcnt lgkmcnt(12)
	ds_read_b128 v[212:215], v189
	ds_read_b128 v[216:219], v189 offset:1024
	ds_read_b128 v[220:223], v189 offset:2048
	ds_read_b128 v[224:227], v189 offset:3072
	s_waitcnt vmcnt(8) lgkmcnt(0)
	s_barrier
	v_mfma_f32_16x16x32_bf16 v[140:143], v[24:27], v[144:147], v[140:143]
	v_mfma_f32_16x16x32_bf16 v[136:139], v[40:43], v[144:147], v[136:139]
	v_mfma_f32_16x16x32_bf16 v[124:127], v[24:27], v[182:185], v[124:127]
	v_mfma_f32_16x16x32_bf16 v[120:123], v[40:43], v[182:185], v[120:123]
	v_mfma_f32_16x16x32_bf16 v[108:111], v[24:27], v[196:199], v[108:111]
	v_mfma_f32_16x16x32_bf16 v[104:107], v[40:43], v[196:199], v[104:107]
	v_mfma_f32_16x16x32_bf16 v[92:95], v[24:27], v[204:207], v[92:95]
	v_mfma_f32_16x16x32_bf16 v[88:91], v[40:43], v[204:207], v[88:91]
	v_mfma_f32_16x16x32_bf16 v[140:143], v[28:31], v[148:151], v[140:143]
	v_mfma_f32_16x16x32_bf16 v[136:139], v[44:47], v[148:151], v[136:139]
	v_mfma_f32_16x16x32_bf16 v[124:127], v[28:31], v[192:195], v[124:127]
	v_mfma_f32_16x16x32_bf16 v[120:123], v[44:47], v[192:195], v[120:123]
	v_mfma_f32_16x16x32_bf16 v[108:111], v[28:31], v[200:203], v[108:111]
	v_mfma_f32_16x16x32_bf16 v[104:107], v[44:47], v[200:203], v[104:107]
	v_mfma_f32_16x16x32_bf16 v[92:95], v[28:31], v[208:211], v[92:95]
	v_mfma_f32_16x16x32_bf16 v[88:91], v[44:47], v[208:211], v[88:91]
	v_mfma_f32_16x16x32_bf16 v[132:135], v[212:215], v[144:147], v[132:135]
	v_mfma_f32_16x16x32_bf16 v[128:131], v[220:223], v[144:147], v[128:131]
	v_mfma_f32_16x16x32_bf16 v[116:119], v[212:215], v[182:185], v[116:119]
	v_mfma_f32_16x16x32_bf16 v[112:115], v[220:223], v[182:185], v[112:115]
	v_mfma_f32_16x16x32_bf16 v[100:103], v[212:215], v[196:199], v[100:103]
	v_mfma_f32_16x16x32_bf16 v[96:99], v[220:223], v[196:199], v[96:99]
	v_mfma_f32_16x16x32_bf16 v[84:87], v[212:215], v[204:207], v[84:87]
	v_mfma_f32_16x16x32_bf16 v[80:83], v[220:223], v[204:207], v[80:83]
	v_mfma_f32_16x16x32_bf16 v[132:135], v[216:219], v[148:151], v[132:135]
	v_mfma_f32_16x16x32_bf16 v[128:131], v[224:227], v[148:151], v[128:131]
	v_mfma_f32_16x16x32_bf16 v[116:119], v[216:219], v[192:195], v[116:119]
	v_mfma_f32_16x16x32_bf16 v[112:115], v[224:227], v[192:195], v[112:115]
	v_mfma_f32_16x16x32_bf16 v[100:103], v[216:219], v[200:203], v[100:103]
	v_mfma_f32_16x16x32_bf16 v[96:99], v[224:227], v[200:203], v[96:99]
	v_mfma_f32_16x16x32_bf16 v[84:87], v[216:219], v[208:211], v[84:87]
	v_mfma_f32_16x16x32_bf16 v[80:83], v[224:227], v[208:211], v[80:83]
	s_barrier
; #define PG8_STAGE(bufoff, gbase, voff) do { _Pragma("unroll") for (int _i = 0; _i < 2; ++_i) \
;         __builtin_amdgcn_global_load_lds((const unsigned*)((const char*)(gbase) + (voff)[_i]), (PG8_LAS unsigned*)(lds + (bufoff) + ldsw + _i * 8192), 16, 0, 0); } while (0)
; #define PG8_LDA(dst, b, h) do { _Pragma("unroll") for (int m = 0; m < 4; ++m) _Pragma("unroll") for (int k = 0; k < 2; ++k) dst[m][k] = *(const PG8_LAS bf16x8*)(lds + PG8_SA(b, h) + aoff + m * 2048 + k * 1024); } while (0)
; #define PG8_LDB(dst, b, h) do { _Pragma("unroll") for (int n = 0; n < 2; ++n) _Pragma("unroll") for (int k = 0; k < 2; ++k) dst[n][k] = *(const PG8_LAS bf16x8*)(lds + PG8_SB(b, h) + boff + n * 2048 + k * 1024); } while (0)
; #define PG8_MMA(ai, bj, At, Bt) do { __builtin_amdgcn_s_setprio(1); _Pragma("unroll") for (int m = 0; m < 4; ++m) _Pragma("unroll") for (int n = 0; n < 2; ++n) _Pragma("unroll") for (int k = 0; k < 2; ++k) \
;         acc[ai][bj][m][n] = __builtin_amdgcn_mfma_f32_16x16x32_bf16(Bt[n][k], At[m][k], acc[ai][bj][m][n], 0, 0, 0); __builtin_amdgcn_s_setprio(0); } while (0)
; #define PG8_WAIT_V(n) asm volatile("s_waitcnt vmcnt(" #n ")" ::: "memory")
; #define PG8_WAIT_L(n) asm volatile("s_waitcnt lgkmcnt(" #n ")" ::: "memory")
; #define PG8_BAR __builtin_amdgcn_s_barrier()
; #define PG8_SCHED __builtin_amdgcn_sched_barrier(0)
; template <class Epi, class Sched>
; __device__ __forceinline__ void gemm_phase(PG8_LAS unsigned char* lds, const Gemm g, const Sched& S, const Epi& E) {
;     ...
;             PG8_LDA(At, 0, 1); PG8_STAGE(PG8_SA(0, 0), a2, voffA);
;             PG8_BAR; PG8_WAIT_L(0); PG8_MMA(1, 0, At, B0); PG8_BAR; PG8_SCHED;
;             PG8_STAGE(PG8_SB(0, 1), b2 + hstep, voffB);
;             PG8_WAIT_V(6); PG8_BAR; PG8_MMA(1, 1, At, B1); PG8_BAR;
;             PG8_LDB(B0, 1, 0); PG8_SCHED; PG8_LDA(At, 1, 0); PG8_STAGE(PG8_SA(0, 1), a2 + hstep, voffA);
;             PG8_WAIT_L(8); PG8_BAR; PG8_WAIT_L(0); PG8_MMA(0, 0, At, B0); PG8_BAR; PG8_SCHED;
;             PG8_LDB(B1, 1, 1); PG8_STAGE(PG8_SB(1, 0), b3, voffB);
;             PG8_BAR; PG8_WAIT_L(0); PG8_MMA(0, 1, At, B1); PG8_BAR;
	ds_read_b128 v[144:147], v187 offset:16384
	ds_read_b128 v[148:151], v187 offset:17408
	ds_read_b128 v[182:185], v187 offset:18432
	ds_read_b128 v[192:195], v187 offset:19456
	ds_read_b128 v[196:199], v187 offset:20480
	ds_read_b128 v[200:203], v187 offset:21504
	ds_read_b128 v[204:207], v187 offset:22528
	ds_read_b128 v[208:211], v187 offset:23552
	s_add_i32 s54, s43, s35
	s_add_u32 s98, s4, s14
	s_addc_u32 s99, s5, s15
	s_mov_b32 m0, s54
	s_nop 0
	global_load_lds_dwordx4 v156, s[4:5]
	s_nop 1
	s_add_i32 m0, s54, 0x2000
	s_nop 0
	global_load_lds_dwordx4 v160, s[4:5]
	s_nop 1
	s_mov_b32 m0, s27
	s_add_u32 s100, s28, s14
	s_addc_u32 s101, s29, s15
	global_load_lds_dwordx4 v154, s[28:29]
	s_nop 1
	s_mov_b32 m0, s36
	s_nop 0
	global_load_lds_dwordx4 v158, s[28:29]
	s_add_u32 s54, s4, 0x40000
	s_addc_u32 s55, s5, 0
	s_add_i32 s56, s44, s35
	s_mov_b32 m0, s56
	s_nop 0
	global_load_lds_dwordx4 v156, s[54:55]
	s_nop 1
	s_add_i32 m0, s56, 0x2000
	s_nop 0
	global_load_lds_dwordx4 v160, s[54:55]
	s_waitcnt vmcnt(8) lgkmcnt(0)
	s_barrier
	v_mfma_f32_16x16x32_bf16 v[76:79], v[24:27], v[144:147], v[76:79]
	v_mfma_f32_16x16x32_bf16 v[72:75], v[40:43], v[144:147], v[72:75]
	v_mfma_f32_16x16x32_bf16 v[60:63], v[24:27], v[182:185], v[60:63]
	v_mfma_f32_16x16x32_bf16 v[56:59], v[40:43], v[182:185], v[56:59]
	v_mfma_f32_16x16x32_bf16 v[36:39], v[24:27], v[196:199], v[36:39]
	v_mfma_f32_16x16x32_bf16 v[32:35], v[40:43], v[196:199], v[32:35]
	v_mfma_f32_16x16x32_bf16 v[12:15], v[24:27], v[204:207], v[12:15]
	v_mfma_f32_16x16x32_bf16 v[8:11], v[40:43], v[204:207], v[8:11]
	v_mfma_f32_16x16x32_bf16 v[76:79], v[28:31], v[148:151], v[76:79]
	v_mfma_f32_16x16x32_bf16 v[72:75], v[44:47], v[148:151], v[72:75]
	v_mfma_f32_16x16x32_bf16 v[60:63], v[28:31], v[192:195], v[60:63]
	v_mfma_f32_16x16x32_bf16 v[56:59], v[44:47], v[192:195], v[56:59]
	v_mfma_f32_16x16x32_bf16 v[36:39], v[28:31], v[200:203], v[36:39]
	v_mfma_f32_16x16x32_bf16 v[32:35], v[44:47], v[200:203], v[32:35]
	v_mfma_f32_16x16x32_bf16 v[12:15], v[28:31], v[208:211], v[12:15]
	v_mfma_f32_16x16x32_bf16 v[8:11], v[44:47], v[208:211], v[8:11]
	v_mfma_f32_16x16x32_bf16 v[20:23], v[212:215], v[196:199], v[20:23]
	v_mfma_f32_16x16x32_bf16 v[16:19], v[220:223], v[196:199], v[16:19]
	v_mfma_f32_16x16x32_bf16 v[4:7], v[212:215], v[204:207], v[4:7]
	v_mfma_f32_16x16x32_bf16 v[0:3], v[220:223], v[204:207], v[0:3]
	v_mfma_f32_16x16x32_bf16 v[24:27], v[212:215], v[144:147], v[68:71]
	v_mfma_f32_16x16x32_bf16 v[28:31], v[220:223], v[144:147], v[64:67]
	v_mfma_f32_16x16x32_bf16 v[40:43], v[212:215], v[182:185], v[52:55]
	v_mfma_f32_16x16x32_bf16 v[44:47], v[220:223], v[182:185], v[48:51]
	v_mfma_f32_16x16x32_bf16 v[20:23], v[216:219], v[200:203], v[20:23]
	v_mfma_f32_16x16x32_bf16 v[16:19], v[224:227], v[200:203], v[16:19]
	v_mfma_f32_16x16x32_bf16 v[4:7], v[216:219], v[208:211], v[4:7]
	v_mfma_f32_16x16x32_bf16 v[0:3], v[224:227], v[208:211], v[0:3]
	v_mfma_f32_16x16x32_bf16 v[24:27], v[216:219], v[148:151], v[24:27]
	v_mfma_f32_16x16x32_bf16 v[28:31], v[224:227], v[148:151], v[28:31]
	v_mfma_f32_16x16x32_bf16 v[40:43], v[216:219], v[192:195], v[40:43]
	v_mfma_f32_16x16x32_bf16 v[44:47], v[224:227], v[192:195], v[44:47]
	s_barrier
	s_add_i32 s54, 0, 0x18000
	v_add_u32_e32 v68, s54, v179
	ds_read_b128 v[48:51], v68
	ds_read_b128 v[52:55], v68 offset:1024
	ds_read_b128 v[64:67], v68 offset:2048
	ds_read_b128 v[68:71], v68 offset:3072
	s_add_u32 s28, s28, 0x40000
	s_addc_u32 s29, s29, 0
	s_mov_b32 m0, s37
	ds_read_b128 v[144:147], v187 offset:32768
	ds_read_b128 v[148:151], v187 offset:33792
	ds_read_b128 v[182:185], v187 offset:34816
	ds_read_b128 v[192:195], v187 offset:35840
	ds_read_b128 v[196:199], v187 offset:36864
	ds_read_b128 v[200:203], v187 offset:37888
	ds_read_b128 v[204:207], v187 offset:38912
	ds_read_b128 v[208:211], v187 offset:39936
	global_load_lds_dwordx4 v154, s[28:29]
	s_nop 1
	s_mov_b32 m0, s38
	s_nop 0
	global_load_lds_dwordx4 v158, s[28:29]
	s_add_i32 s28, 0, 0x1c000
	v_add_u32_e32 v162, s28, v179
	s_waitcnt lgkmcnt(12)
	ds_read_b128 v[212:215], v162
	ds_read_b128 v[216:219], v162 offset:1024
	ds_read_b128 v[220:223], v162 offset:2048
	ds_read_b128 v[224:227], v162 offset:3072
	s_waitcnt vmcnt(8) lgkmcnt(0)
	s_barrier
; #define PG8_STAGE(bufoff, gbase, voff) do { _Pragma("unroll") for (int _i = 0; _i < 2; ++_i) \
;         __builtin_amdgcn_global_load_lds((const unsigned*)((const char*)(gbase) + (voff)[_i]), (PG8_LAS unsigned*)(lds + (bufoff) + ldsw + _i * 8192), 16, 0, 0); } while (0)
; #define PG8_LDA(dst, b, h) do { _Pragma("unroll") for (int m = 0; m < 4; ++m) _Pragma("unroll") for (int k = 0; k < 2; ++k) dst[m][k] = *(const PG8_LAS bf16x8*)(lds + PG8_SA(b, h) + aoff + m * 2048 + k * 1024); } while (0)
; #define PG8_LDB(dst, b, h) do { _Pragma("unroll") for (int n = 0; n < 2; ++n) _Pragma("unroll") for (int k = 0; k < 2; ++k) dst[n][k] = *(const PG8_LAS bf16x8*)(lds + PG8_SB(b, h) + boff + n * 2048 + k * 1024); } while (0)
; #define PG8_WAIT_V(n) asm volatile("s_waitcnt vmcnt(" #n ")" ::: "memory")
; #define PG8_WAIT_L(n) asm volatile("s_waitcnt lgkmcnt(" #n ")" ::: "memory")
; #define PG8_BAR __builtin_amdgcn_s_barrier()
; #define PG8_SCHED __builtin_amdgcn_sched_barrier(0)
;     __device__ __forceinline__ void operator()(const f32x4 (&acc)[2][2][4][2], const Unit& u, int wr, int wc, int fr, int fq) const {
;     ...
;         if (mode == 1) { if (u.pn >= 8 && u.pn < 12) act = 1; else if (u.pn >= 12) { act = 3; bias = (u.pn >= 14) ? bias_b + (u.pn - 14) * 256 : bias_f + (u.pn - 12) * 256; } }
;         else if (mode == 2) { if (u.pn >= 6) act = 2; }
;         const int row0 = u.pm * BM + wr * 64 + fr, col0 = u.pn * BM + wc * 32 + 8 * fq, bcol0 = wc * 32 + 8 * fq;
;         f32x4 bv[2][2];
; #pragma unroll
;         for (int bj = 0; bj < 2; ++bj)
; #pragma unroll
;             for (int n = 0; n < 2; ++n) bv[bj][n] = bias ? *(const f32x4*)(bias + bcol0 + bj * HALF + 4 * n) : (f32x4){0.f, 0.f, 0.f, 0.f};
; template <class Epi, class Sched>
; __device__ __forceinline__ void gemm_phase(PG8_LAS unsigned char* lds, const Gemm g, const Sched& S, const Epi& E) {
;     ...
;             PG8_WAIT_L(8); PG8_BAR; PG8_WAIT_L(0); PG8_MMA(0, 0, At, B0); PG8_BAR; PG8_SCHED;
;             PG8_LDB(B1, 1, 1); PG8_STAGE(PG8_SB(1, 0), b3, voffB);
;             PG8_BAR; PG8_WAIT_L(0); PG8_MMA(0, 1, At, B1); PG8_BAR;
;             PG8_LDA(At, 1, 1); PG8_STAGE(PG8_SA(1, 0), a3, voffA);
;             PG8_BAR; PG8_WAIT_L(0); PG8_MMA(1, 0, At, B0); PG8_BAR; PG8_SCHED;
;             PG8_STAGE(PG8_SB(1, 1), b3 + hstep, voffB);
;             PG8_WAIT_V(6); PG8_BAR; PG8_MMA(1, 1, At, B1); PG8_BAR;
	v_mfma_f32_16x16x32_bf16 v[140:143], v[48:51], v[144:147], v[140:143]
	v_mfma_f32_16x16x32_bf16 v[136:139], v[64:67], v[144:147], v[136:139]
	v_mfma_f32_16x16x32_bf16 v[124:127], v[48:51], v[182:185], v[124:127]
	v_mfma_f32_16x16x32_bf16 v[120:123], v[64:67], v[182:185], v[120:123]
	v_mfma_f32_16x16x32_bf16 v[108:111], v[48:51], v[196:199], v[108:111]
	v_mfma_f32_16x16x32_bf16 v[104:107], v[64:67], v[196:199], v[104:107]
	v_mfma_f32_16x16x32_bf16 v[92:95], v[48:51], v[204:207], v[92:95]
	v_mfma_f32_16x16x32_bf16 v[88:91], v[64:67], v[204:207], v[88:91]
	v_mfma_f32_16x16x32_bf16 v[140:143], v[52:55], v[148:151], v[140:143]
	v_mfma_f32_16x16x32_bf16 v[136:139], v[68:71], v[148:151], v[136:139]
	v_mfma_f32_16x16x32_bf16 v[124:127], v[52:55], v[192:195], v[124:127]
	v_mfma_f32_16x16x32_bf16 v[120:123], v[68:71], v[192:195], v[120:123]
	v_mfma_f32_16x16x32_bf16 v[108:111], v[52:55], v[200:203], v[108:111]
	v_mfma_f32_16x16x32_bf16 v[104:107], v[68:71], v[200:203], v[104:107]
	v_mfma_f32_16x16x32_bf16 v[92:95], v[52:55], v[208:211], v[92:95]
	v_mfma_f32_16x16x32_bf16 v[88:91], v[68:71], v[208:211], v[88:91]
	v_mfma_f32_16x16x32_bf16 v[132:135], v[212:215], v[144:147], v[132:135]
	v_mfma_f32_16x16x32_bf16 v[128:131], v[220:223], v[144:147], v[128:131]
	v_mfma_f32_16x16x32_bf16 v[116:119], v[212:215], v[182:185], v[116:119]
	v_mfma_f32_16x16x32_bf16 v[112:115], v[220:223], v[182:185], v[112:115]
	v_mfma_f32_16x16x32_bf16 v[100:103], v[212:215], v[196:199], v[100:103]
	v_mfma_f32_16x16x32_bf16 v[96:99], v[220:223], v[196:199], v[96:99]
	v_mfma_f32_16x16x32_bf16 v[84:87], v[212:215], v[204:207], v[84:87]
	v_mfma_f32_16x16x32_bf16 v[80:83], v[220:223], v[204:207], v[80:83]
	v_mfma_f32_16x16x32_bf16 v[132:135], v[216:219], v[148:151], v[132:135]
	v_mfma_f32_16x16x32_bf16 v[128:131], v[224:227], v[148:151], v[128:131]
	v_mfma_f32_16x16x32_bf16 v[116:119], v[216:219], v[192:195], v[116:119]
	v_mfma_f32_16x16x32_bf16 v[112:115], v[224:227], v[192:195], v[112:115]
	v_mfma_f32_16x16x32_bf16 v[100:103], v[216:219], v[200:203], v[100:103]
	v_mfma_f32_16x16x32_bf16 v[96:99], v[224:227], v[200:203], v[96:99]
	v_mfma_f32_16x16x32_bf16 v[84:87], v[216:219], v[208:211], v[84:87]
	v_mfma_f32_16x16x32_bf16 v[80:83], v[224:227], v[208:211], v[80:83]
	s_barrier
	ds_read_b128 v[144:147], v187 offset:49152
	ds_read_b128 v[148:151], v187 offset:50176
	ds_read_b128 v[182:185], v187 offset:51200
	ds_read_b128 v[192:195], v187 offset:52224
	ds_read_b128 v[196:199], v187 offset:53248
	ds_read_b128 v[200:203], v187 offset:54272
	ds_read_b128 v[204:207], v187 offset:55296
	ds_read_b128 v[208:211], v187 offset:56320
	s_add_i32 s29, s54, s35
	s_mov_b32 m0, s29
	s_nop 0
	global_load_lds_dwordx4 v156, s[98:99]
	s_nop 1
	s_add_i32 m0, s29, 0x2000
	s_nop 0
	global_load_lds_dwordx4 v160, s[98:99]
	s_nop 1
	s_mov_b32 m0, s39
	s_nop 0
	global_load_lds_dwordx4 v154, s[100:101]
	s_nop 1
	s_mov_b32 m0, s40
	s_nop 0
	global_load_lds_dwordx4 v158, s[100:101]
	s_add_u32 s4, s4, 0x40080
	s_addc_u32 s5, s5, 0
	s_add_i32 s28, s28, s35
	s_mov_b32 m0, s28
	s_nop 0
	global_load_lds_dwordx4 v156, s[4:5]
	s_nop 1
	s_add_i32 m0, s28, 0x2000
	s_nop 0
	global_load_lds_dwordx4 v160, s[4:5]
	s_waitcnt vmcnt(8) lgkmcnt(0)
	s_barrier
	v_mfma_f32_16x16x32_bf16 v[76:79], v[48:51], v[144:147], v[76:79]
	v_mfma_f32_16x16x32_bf16 v[72:75], v[64:67], v[144:147], v[72:75]
	v_mfma_f32_16x16x32_bf16 v[60:63], v[48:51], v[182:185], v[60:63]
	v_mfma_f32_16x16x32_bf16 v[56:59], v[64:67], v[182:185], v[56:59]
	v_mfma_f32_16x16x32_bf16 v[36:39], v[48:51], v[196:199], v[36:39]
	v_mfma_f32_16x16x32_bf16 v[32:35], v[64:67], v[196:199], v[32:35]
	v_mfma_f32_16x16x32_bf16 v[12:15], v[48:51], v[204:207], v[12:15]
	v_mfma_f32_16x16x32_bf16 v[8:11], v[64:67], v[204:207], v[8:11]
	v_mfma_f32_16x16x32_bf16 v[76:79], v[52:55], v[148:151], v[76:79]
	v_mfma_f32_16x16x32_bf16 v[72:75], v[68:71], v[148:151], v[72:75]
	v_mfma_f32_16x16x32_bf16 v[60:63], v[52:55], v[192:195], v[60:63]
	v_mfma_f32_16x16x32_bf16 v[56:59], v[68:71], v[192:195], v[56:59]
	v_mfma_f32_16x16x32_bf16 v[36:39], v[52:55], v[200:203], v[36:39]
	v_mfma_f32_16x16x32_bf16 v[32:35], v[68:71], v[200:203], v[32:35]
	v_mfma_f32_16x16x32_bf16 v[12:15], v[52:55], v[208:211], v[12:15]
	v_mfma_f32_16x16x32_bf16 v[8:11], v[68:71], v[208:211], v[8:11]
	v_mfma_f32_16x16x32_bf16 v[24:27], v[212:215], v[144:147], v[24:27]
	v_mfma_f32_16x16x32_bf16 v[68:71], v[216:219], v[148:151], v[24:27]
	v_mfma_f32_16x16x32_bf16 v[24:27], v[220:223], v[144:147], v[28:31]
	v_mfma_f32_16x16x32_bf16 v[64:67], v[224:227], v[148:151], v[24:27]
	v_mfma_f32_16x16x32_bf16 v[24:27], v[212:215], v[182:185], v[40:43]
	v_mfma_f32_16x16x32_bf16 v[52:55], v[216:219], v[192:195], v[24:27]
	v_mfma_f32_16x16x32_bf16 v[24:27], v[220:223], v[182:185], v[44:47]
	v_mfma_f32_16x16x32_bf16 v[20:23], v[212:215], v[196:199], v[20:23]
	v_mfma_f32_16x16x32_bf16 v[16:19], v[220:223], v[196:199], v[16:19]
	v_mfma_f32_16x16x32_bf16 v[4:7], v[212:215], v[204:207], v[4:7]
	v_mfma_f32_16x16x32_bf16 v[0:3], v[220:223], v[204:207], v[0:3]
	v_mfma_f32_16x16x32_bf16 v[48:51], v[224:227], v[192:195], v[24:27]
	v_mfma_f32_16x16x32_bf16 v[20:23], v[216:219], v[200:203], v[20:23]
	v_mfma_f32_16x16x32_bf16 v[16:19], v[224:227], v[200:203], v[16:19]
	v_mfma_f32_16x16x32_bf16 v[4:7], v[216:219], v[208:211], v[4:7]
	v_mfma_f32_16x16x32_bf16 v[0:3], v[224:227], v[208:211], v[0:3]
	s_barrier
	s_add_i32 s53, s53, 2
	s_add_u32 s0, s0, 0x100
	s_addc_u32 s1, s1, 0
	s_add_u32 s51, s51, 0x100
	s_addc_u32 s52, s52, 0
	s_cmp_gt_u32 s53, 13
	s_cbranch_scc0 .LBB0_416
	s_cmp_gt_i32 s26, 11
	s_cselect_b64 s[4:5], -1, 0
	s_cmp_lt_i32 s26, 12
	s_mov_b64 s[0:1], 0
	s_cbranch_scc1 .LBB0_422
	s_lshl_b32 s10, s26, 8
	s_cmp_lt_u32 s26, 14
	s_mov_b64 s[28:29], -1
	s_cbranch_scc0 .LBB0_420
	s_lshl_b64 s[0:1], s[10:11], 2
	v_readlane_b32 s52, v245, 0
	v_readlane_b32 s53, v245, 1
	s_add_u32 s0, s52, s0
	s_addc_u32 s1, s53, s1
	s_add_u32 s0, s0, 0xffffd000
	v_readlane_b32 s54, v245, 2
	v_readlane_b32 s55, v245, 3
	v_readlane_b32 s56, v245, 4
	v_readlane_b32 s57, v245, 5
	v_readlane_b32 s58, v245, 6
	v_readlane_b32 s59, v245, 7
	v_readlane_b32 s60, v245, 8
	v_readlane_b32 s61, v245, 9
	v_readlane_b32 s62, v245, 10
	v_readlane_b32 s63, v245, 11
	v_readlane_b32 s64, v245, 12
	v_readlane_b32 s65, v245, 13
	v_readlane_b32 s66, v245, 14
	v_readlane_b32 s67, v245, 15
	s_addc_u32 s1, s1, -1
	s_mov_b64 s[28:29], 0

; #define PG8_STAGE(bufoff, gbase, voff) do { _Pragma("unroll") for (int _i = 0; _i < 2; ++_i) \
;         __builtin_amdgcn_global_load_lds((const unsigned*)((const char*)(gbase) + (voff)[_i]), (PG8_LAS unsigned*)(lds + (bufoff) + ldsw + _i * 8192), 16, 0, 0); } while (0)
; #define PG8_LDA(dst, b, h) do { _Pragma("unroll") for (int m = 0; m < 4; ++m) _Pragma("unroll") for (int k = 0; k < 2; ++k) dst[m][k] = *(const PG8_LAS bf16x8*)(lds + PG8_SA(b, h) + aoff + m * 2048 + k * 1024); } while (0)
; #define PG8_LDB(dst, b, h) do { _Pragma("unroll") for (int n = 0; n < 2; ++n) _Pragma("unroll") for (int k = 0; k < 2; ++k) dst[n][k] = *(const PG8_LAS bf16x8*)(lds + PG8_SB(b, h) + boff + n * 2048 + k * 1024); } while (0)
; #define PG8_MMA(ai, bj, At, Bt) do { __builtin_amdgcn_s_setprio(1); _Pragma("unroll") for (int m = 0; m < 4; ++m) _Pragma("unroll") for (int n = 0; n < 2; ++n) _Pragma("unroll") for (int k = 0; k < 2; ++k) \
;         acc[ai][bj][m][n] = __builtin_amdgcn_mfma_f32_16x16x32_bf16(Bt[n][k], At[m][k], acc[ai][bj][m][n], 0, 0, 0); __builtin_amdgcn_s_setprio(0); } while (0)
; #define PG8_WAIT_L(n) asm volatile("s_waitcnt lgkmcnt(" #n ")" ::: "memory")
; #define PG8_BAR __builtin_amdgcn_s_barrier()
; #define PG8_SCHED __builtin_amdgcn_sched_barrier(0)
; template <class Epi, class Sched>
; __device__ __forceinline__ void gemm_phase(PG8_LAS unsigned char* lds, const Gemm g, const Sched& S, const Epi& E) {
;     ...
;         const bool has_next = S.next(ui + 1, nxt);
;         const char* nA = has_next ? (const char*)g.A + (size_t)nxt.pm * tstep : cA; const char* nB = has_next ? (const char*)g.Bt + (size_t)nxt.pn * tstep : cB;
;         for (int t = 0; t < nt; t += 2) {
;             const bool last = (t == nt - 2);
;             const char* a1 = cA + (size_t)(t + 1) * kstep;
;             const char* a2 = last ? nA : cA + (size_t)(t + 2) * kstep; const char* b2 = last ? nB : cB + (size_t)(t + 2) * kstep;
;             const char* a3 = a2 + kstep; const char* b3 = b2 + kstep;
;             if (last && has_next) S.a_ready(nxt);
;             PG8_LDB(B0, 0, 0); PG8_SCHED; PG8_LDA(At, 0, 0); PG8_STAGE(PG8_SA(1, 1), a1 + hstep, voffA);
;             PG8_WAIT_L(8); PG8_BAR; PG8_WAIT_L(0); PG8_MMA(0, 0, At, B0); PG8_BAR; PG8_SCHED;
;             PG8_LDB(B1, 0, 1); PG8_STAGE(PG8_SB(0, 0), b2, voffB);
;             PG8_BAR; PG8_WAIT_L(0); PG8_MMA(0, 1, At, B1); PG8_BAR;
.LBB0_723:
	s_ashr_i32 s11, s10, 31
	v_cmp_lt_i64_e32 vcc, s[12:13], v[140:141]
	s_lshl_b64 s[12:13], s[10:11], 19
	s_add_u32 s12, s26, s12
	s_addc_u32 s13, s27, s13
	s_and_b64 s[14:15], vcc, exec
	s_cselect_b32 s5, s13, s19
	s_cselect_b32 s11, s12, s18
	s_ashr_i32 s9, s8, 31
	s_lshl_b64 s[14:15], s[8:9], 19
	s_add_u32 s14, s28, s14
	s_addc_u32 s15, s29, s15
	s_and_b64 s[22:23], vcc, exec
	s_cselect_b32 s9, s15, s21
	s_cselect_b32 s45, s14, s20
	s_add_u32 s18, s18, 0x40080
	s_addc_u32 s19, s19, 0
	s_add_u32 s46, s20, 0x100
	s_addc_u32 s47, s21, 0
	s_mov_b32 s48, -2
	ds_read_b128 v[144:147], v151
	ds_read_b128 v[156:159], v151 offset:1024
	ds_read_b128 v[160:163], v151 offset:2048
	ds_read_b128 v[166:169], v151 offset:3072
	s_add_u32 s20, s18, 0xfffc0080
	s_addc_u32 s21, s19, -1
	s_cmp_eq_u32 s48, 12
	s_cselect_b32 s23, s5, s21
	s_cselect_b32 s22, s11, s20
	s_cselect_b32 s21, s9, s47
	s_cselect_b32 s20, s45, s46
	s_add_i32 m0, s17, 0xc000
	ds_read_b128 v[170:173], v153
	ds_read_b128 v[182:185], v153 offset:1024
	ds_read_b128 v[190:193], v153 offset:2048
	ds_read_b128 v[194:197], v153 offset:3072
	ds_read_b128 v[198:201], v153 offset:4096
	ds_read_b128 v[202:205], v153 offset:5120
	ds_read_b128 v[206:209], v153 offset:6144
	ds_read_b128 v[210:213], v153 offset:7168
	global_load_lds_dwordx4 v136, s[18:19]
	s_nop 1
	s_add_i32 m0, s17, 0xe000
	s_nop 0
	global_load_lds_dwordx4 v138, s[18:19]
	s_waitcnt lgkmcnt(12)
	ds_read_b128 v[214:217], v154
	ds_read_b128 v[218:221], v154 offset:1024
	ds_read_b128 v[222:225], v154 offset:2048
	ds_read_b128 v[226:229], v154 offset:3072
	s_waitcnt vmcnt(8) lgkmcnt(0)
	s_barrier
	v_mfma_f32_16x16x32_bf16 v[124:127], v[144:147], v[170:173], 0
	v_mfma_f32_16x16x32_bf16 v[120:123], v[160:163], v[170:173], 0
	v_mfma_f32_16x16x32_bf16 v[108:111], v[144:147], v[190:193], 0
	v_mfma_f32_16x16x32_bf16 v[104:107], v[160:163], v[190:193], 0
	v_mfma_f32_16x16x32_bf16 v[92:95], v[144:147], v[198:201], 0
	v_mfma_f32_16x16x32_bf16 v[88:91], v[160:163], v[198:201], 0
	v_mfma_f32_16x16x32_bf16 v[76:79], v[144:147], v[206:209], 0
	v_mfma_f32_16x16x32_bf16 v[72:75], v[160:163], v[206:209], 0
	v_mfma_f32_16x16x32_bf16 v[124:127], v[156:159], v[182:185], v[124:127]
	v_mfma_f32_16x16x32_bf16 v[120:123], v[166:169], v[182:185], v[120:123]
	v_mfma_f32_16x16x32_bf16 v[108:111], v[156:159], v[194:197], v[108:111]
	v_mfma_f32_16x16x32_bf16 v[104:107], v[166:169], v[194:197], v[104:107]
	v_mfma_f32_16x16x32_bf16 v[92:95], v[156:159], v[202:205], v[92:95]
	v_mfma_f32_16x16x32_bf16 v[88:91], v[166:169], v[202:205], v[88:91]
	v_mfma_f32_16x16x32_bf16 v[76:79], v[156:159], v[210:213], v[76:79]
	v_mfma_f32_16x16x32_bf16 v[72:75], v[166:169], v[210:213], v[72:75]
	v_mfma_f32_16x16x32_bf16 v[116:119], v[214:217], v[170:173], 0
	v_mfma_f32_16x16x32_bf16 v[112:115], v[222:225], v[170:173], 0
	v_mfma_f32_16x16x32_bf16 v[100:103], v[214:217], v[190:193], 0
	v_mfma_f32_16x16x32_bf16 v[96:99], v[222:225], v[190:193], 0
	v_mfma_f32_16x16x32_bf16 v[84:87], v[214:217], v[198:201], 0
	v_mfma_f32_16x16x32_bf16 v[80:83], v[222:225], v[198:201], 0
	v_mfma_f32_16x16x32_bf16 v[68:71], v[214:217], v[206:209], 0
	v_mfma_f32_16x16x32_bf16 v[64:67], v[222:225], v[206:209], 0
	v_mfma_f32_16x16x32_bf16 v[116:119], v[218:221], v[182:185], v[116:119]
	v_mfma_f32_16x16x32_bf16 v[112:115], v[226:229], v[182:185], v[112:115]
	v_mfma_f32_16x16x32_bf16 v[100:103], v[218:221], v[194:197], v[100:103]
	v_mfma_f32_16x16x32_bf16 v[96:99], v[226:229], v[194:197], v[96:99]
	v_mfma_f32_16x16x32_bf16 v[84:87], v[218:221], v[202:205], v[84:87]
	v_mfma_f32_16x16x32_bf16 v[80:83], v[226:229], v[202:205], v[80:83]
	v_mfma_f32_16x16x32_bf16 v[68:71], v[218:221], v[210:213], v[68:71]
	v_mfma_f32_16x16x32_bf16 v[64:67], v[226:229], v[210:213], v[64:67]
	s_barrier
	ds_read_b128 v[170:173], v153 offset:16384
	ds_read_b128 v[182:185], v153 offset:17408
	ds_read_b128 v[190:193], v153 offset:18432
	ds_read_b128 v[194:197], v153 offset:19456
	ds_read_b128 v[198:201], v153 offset:20480
	ds_read_b128 v[202:205], v153 offset:21504
	ds_read_b128 v[206:209], v153 offset:22528
	ds_read_b128 v[210:213], v153 offset:23552
	s_add_i32 s49, s42, s30
	s_add_u32 s98, s20, s6
	s_addc_u32 s99, s21, s7
	s_mov_b32 m0, s49
	s_nop 0
	global_load_lds_dwordx4 v130, s[20:21]
	s_nop 1
	s_add_i32 m0, s49, 0x2000
	s_nop 0
	global_load_lds_dwordx4 v134, s[20:21]
	s_nop 1
	s_mov_b32 m0, s17
	s_add_u32 s100, s22, s6
	s_addc_u32 s101, s23, s7
	global_load_lds_dwordx4 v128, s[22:23]
	s_nop 1
	s_mov_b32 m0, s31
	s_nop 0
	global_load_lds_dwordx4 v132, s[22:23]
	s_add_u32 s50, s20, 0x40000
	s_addc_u32 s51, s21, 0
	s_add_i32 s49, s43, s30
	s_mov_b32 m0, s49
	s_nop 0
	global_load_lds_dwordx4 v130, s[50:51]
	s_nop 1
	s_add_i32 m0, s49, 0x2000
	s_nop 0
	global_load_lds_dwordx4 v134, s[50:51]
	s_waitcnt vmcnt(8) lgkmcnt(0)
	s_barrier
; #define PG8_STAGE(bufoff, gbase, voff) do { _Pragma("unroll") for (int _i = 0; _i < 2; ++_i) \
;         __builtin_amdgcn_global_load_lds((const unsigned*)((const char*)(gbase) + (voff)[_i]), (PG8_LAS unsigned*)(lds + (bufoff) + ldsw + _i * 8192), 16, 0, 0); } while (0)
; #define PG8_LDA(dst, b, h) do { _Pragma("unroll") for (int m = 0; m < 4; ++m) _Pragma("unroll") for (int k = 0; k < 2; ++k) dst[m][k] = *(const PG8_LAS bf16x8*)(lds + PG8_SA(b, h) + aoff + m * 2048 + k * 1024); } while (0)
; #define PG8_LDB(dst, b, h) do { _Pragma("unroll") for (int n = 0; n < 2; ++n) _Pragma("unroll") for (int k = 0; k < 2; ++k) dst[n][k] = *(const PG8_LAS bf16x8*)(lds + PG8_SB(b, h) + boff + n * 2048 + k * 1024); } while (0)
; #define PG8_MMA(ai, bj, At, Bt) do { __builtin_amdgcn_s_setprio(1); _Pragma("unroll") for (int m = 0; m < 4; ++m) _Pragma("unroll") for (int n = 0; n < 2; ++n) _Pragma("unroll") for (int k = 0; k < 2; ++k) \
;         acc[ai][bj][m][n] = __builtin_amdgcn_mfma_f32_16x16x32_bf16(Bt[n][k], At[m][k], acc[ai][bj][m][n], 0, 0, 0); __builtin_amdgcn_s_setprio(0); } while (0)
; #define PG8_WAIT_V(n) asm volatile("s_waitcnt vmcnt(" #n ")" ::: "memory")
; #define PG8_WAIT_L(n) asm volatile("s_waitcnt lgkmcnt(" #n ")" ::: "memory")
; #define PG8_BAR __builtin_amdgcn_s_barrier()
; #define PG8_SCHED __builtin_amdgcn_sched_barrier(0)
; template <class Epi, class Sched>
; __device__ __forceinline__ void gemm_phase(PG8_LAS unsigned char* lds, const Gemm g, const Sched& S, const Epi& E) {
;     ...
;             PG8_LDA(At, 0, 1); PG8_STAGE(PG8_SA(0, 0), a2, voffA);
;             PG8_BAR; PG8_WAIT_L(0); PG8_MMA(1, 0, At, B0); PG8_BAR; PG8_SCHED;
;             PG8_STAGE(PG8_SB(0, 1), b2 + hstep, voffB);
;             PG8_WAIT_V(6); PG8_BAR; PG8_MMA(1, 1, At, B1); PG8_BAR;
;             PG8_LDB(B0, 1, 0); PG8_SCHED; PG8_LDA(At, 1, 0); PG8_STAGE(PG8_SA(0, 1), a2 + hstep, voffA);
;             PG8_WAIT_L(8); PG8_BAR; PG8_WAIT_L(0); PG8_MMA(0, 0, At, B0); PG8_BAR; PG8_SCHED;
;             PG8_LDB(B1, 1, 1); PG8_STAGE(PG8_SB(1, 0), b3, voffB);
;             PG8_BAR; PG8_WAIT_L(0); PG8_MMA(0, 1, At, B1); PG8_BAR;
	v_mfma_f32_16x16x32_bf16 v[60:63], v[144:147], v[170:173], 0
	v_mfma_f32_16x16x32_bf16 v[56:59], v[160:163], v[170:173], 0
	v_mfma_f32_16x16x32_bf16 v[44:47], v[144:147], v[190:193], 0
	v_mfma_f32_16x16x32_bf16 v[40:43], v[160:163], v[190:193], 0
	v_mfma_f32_16x16x32_bf16 v[28:31], v[144:147], v[198:201], 0
	v_mfma_f32_16x16x32_bf16 v[24:27], v[160:163], v[198:201], 0
	v_mfma_f32_16x16x32_bf16 v[12:15], v[144:147], v[206:209], 0
	v_mfma_f32_16x16x32_bf16 v[8:11], v[160:163], v[206:209], 0
	v_mfma_f32_16x16x32_bf16 v[60:63], v[156:159], v[182:185], v[60:63]
	v_mfma_f32_16x16x32_bf16 v[56:59], v[166:169], v[182:185], v[56:59]
	v_mfma_f32_16x16x32_bf16 v[44:47], v[156:159], v[194:197], v[44:47]
	v_mfma_f32_16x16x32_bf16 v[40:43], v[166:169], v[194:197], v[40:43]
	v_mfma_f32_16x16x32_bf16 v[28:31], v[156:159], v[202:205], v[28:31]
	v_mfma_f32_16x16x32_bf16 v[24:27], v[166:169], v[202:205], v[24:27]
	v_mfma_f32_16x16x32_bf16 v[12:15], v[156:159], v[210:213], v[12:15]
	v_mfma_f32_16x16x32_bf16 v[8:11], v[166:169], v[210:213], v[8:11]
	v_mfma_f32_16x16x32_bf16 v[52:55], v[214:217], v[170:173], 0
	v_mfma_f32_16x16x32_bf16 v[48:51], v[222:225], v[170:173], 0
	v_mfma_f32_16x16x32_bf16 v[36:39], v[214:217], v[190:193], 0
	v_mfma_f32_16x16x32_bf16 v[32:35], v[222:225], v[190:193], 0
	v_mfma_f32_16x16x32_bf16 v[20:23], v[214:217], v[198:201], 0
	v_mfma_f32_16x16x32_bf16 v[16:19], v[222:225], v[198:201], 0
	v_mfma_f32_16x16x32_bf16 v[4:7], v[214:217], v[206:209], 0
	v_mfma_f32_16x16x32_bf16 v[0:3], v[222:225], v[206:209], 0
	v_mfma_f32_16x16x32_bf16 v[52:55], v[218:221], v[182:185], v[52:55]
	v_mfma_f32_16x16x32_bf16 v[48:51], v[226:229], v[182:185], v[48:51]
	v_mfma_f32_16x16x32_bf16 v[36:39], v[218:221], v[194:197], v[36:39]
	v_mfma_f32_16x16x32_bf16 v[32:35], v[226:229], v[194:197], v[32:35]
	v_mfma_f32_16x16x32_bf16 v[20:23], v[218:221], v[202:205], v[20:23]
	v_mfma_f32_16x16x32_bf16 v[16:19], v[226:229], v[202:205], v[16:19]
	v_mfma_f32_16x16x32_bf16 v[4:7], v[218:221], v[210:213], v[4:7]
	v_mfma_f32_16x16x32_bf16 v[0:3], v[226:229], v[210:213], v[0:3]
	s_barrier
	s_add_i32 s49, 0, 0x18000
	v_add_u32_e32 v155, s49, v149
	ds_read_b128 v[144:147], v155
	ds_read_b128 v[156:159], v155 offset:1024
	ds_read_b128 v[160:163], v155 offset:2048
	ds_read_b128 v[166:169], v155 offset:3072
	s_add_u32 s22, s22, 0x40000
	s_addc_u32 s23, s23, 0
	s_mov_b32 m0, s34
	ds_read_b128 v[170:173], v153 offset:32768
	ds_read_b128 v[182:185], v153 offset:33792
	ds_read_b128 v[190:193], v153 offset:34816
	ds_read_b128 v[194:197], v153 offset:35840
	ds_read_b128 v[198:201], v153 offset:36864
	ds_read_b128 v[202:205], v153 offset:37888
	ds_read_b128 v[206:209], v153 offset:38912
	ds_read_b128 v[210:213], v153 offset:39936
	global_load_lds_dwordx4 v128, s[22:23]
	s_nop 1
	s_mov_b32 m0, s35
	s_nop 0
	global_load_lds_dwordx4 v132, s[22:23]
	s_add_i32 s22, 0, 0x1c000
	v_add_u32_e32 v155, s22, v149
	s_waitcnt lgkmcnt(12)
	ds_read_b128 v[214:217], v155
	ds_read_b128 v[218:221], v155 offset:1024
	ds_read_b128 v[222:225], v155 offset:2048
	ds_read_b128 v[226:229], v155 offset:3072
	s_waitcnt vmcnt(8) lgkmcnt(0)
	s_barrier
	v_mfma_f32_16x16x32_bf16 v[124:127], v[144:147], v[170:173], v[124:127]
	v_mfma_f32_16x16x32_bf16 v[120:123], v[160:163], v[170:173], v[120:123]
	v_mfma_f32_16x16x32_bf16 v[108:111], v[144:147], v[190:193], v[108:111]
	v_mfma_f32_16x16x32_bf16 v[104:107], v[160:163], v[190:193], v[104:107]
	v_mfma_f32_16x16x32_bf16 v[92:95], v[144:147], v[198:201], v[92:95]
	v_mfma_f32_16x16x32_bf16 v[88:91], v[160:163], v[198:201], v[88:91]
	v_mfma_f32_16x16x32_bf16 v[76:79], v[144:147], v[206:209], v[76:79]
	v_mfma_f32_16x16x32_bf16 v[72:75], v[160:163], v[206:209], v[72:75]
	v_mfma_f32_16x16x32_bf16 v[124:127], v[156:159], v[182:185], v[124:127]
	v_mfma_f32_16x16x32_bf16 v[120:123], v[166:169], v[182:185], v[120:123]
	v_mfma_f32_16x16x32_bf16 v[108:111], v[156:159], v[194:197], v[108:111]
	v_mfma_f32_16x16x32_bf16 v[104:107], v[166:169], v[194:197], v[104:107]
	v_mfma_f32_16x16x32_bf16 v[92:95], v[156:159], v[202:205], v[92:95]
	v_mfma_f32_16x16x32_bf16 v[88:91], v[166:169], v[202:205], v[88:91]
	v_mfma_f32_16x16x32_bf16 v[76:79], v[156:159], v[210:213], v[76:79]
	v_mfma_f32_16x16x32_bf16 v[72:75], v[166:169], v[210:213], v[72:75]
	v_mfma_f32_16x16x32_bf16 v[116:119], v[214:217], v[170:173], v[116:119]
	v_mfma_f32_16x16x32_bf16 v[112:115], v[222:225], v[170:173], v[112:115]
	v_mfma_f32_16x16x32_bf16 v[100:103], v[214:217], v[190:193], v[100:103]
	v_mfma_f32_16x16x32_bf16 v[96:99], v[222:225], v[190:193], v[96:99]
	v_mfma_f32_16x16x32_bf16 v[84:87], v[214:217], v[198:201], v[84:87]
	v_mfma_f32_16x16x32_bf16 v[80:83], v[222:225], v[198:201], v[80:83]
	v_mfma_f32_16x16x32_bf16 v[68:71], v[214:217], v[206:209], v[68:71]
	v_mfma_f32_16x16x32_bf16 v[64:67], v[222:225], v[206:209], v[64:67]
	v_mfma_f32_16x16x32_bf16 v[116:119], v[218:221], v[182:185], v[116:119]
	v_mfma_f32_16x16x32_bf16 v[112:115], v[226:229], v[182:185], v[112:115]
	v_mfma_f32_16x16x32_bf16 v[100:103], v[218:221], v[194:197], v[100:103]
	v_mfma_f32_16x16x32_bf16 v[96:99], v[226:229], v[194:197], v[96:99]
	v_mfma_f32_16x16x32_bf16 v[84:87], v[218:221], v[202:205], v[84:87]
	v_mfma_f32_16x16x32_bf16 v[80:83], v[226:229], v[202:205], v[80:83]
	v_mfma_f32_16x16x32_bf16 v[68:71], v[218:221], v[210:213], v[68:71]
	v_mfma_f32_16x16x32_bf16 v[64:67], v[226:229], v[210:213], v[64:67]
	s_barrier
; #define PG8_STAGE(bufoff, gbase, voff) do { _Pragma("unroll") for (int _i = 0; _i < 2; ++_i) \
;         __builtin_amdgcn_global_load_lds((const unsigned*)((const char*)(gbase) + (voff)[_i]), (PG8_LAS unsigned*)(lds + (bufoff) + ldsw + _i * 8192), 16, 0, 0); } while (0)
; #define PG8_LDA(dst, b, h) do { _Pragma("unroll") for (int m = 0; m < 4; ++m) _Pragma("unroll") for (int k = 0; k < 2; ++k) dst[m][k] = *(const PG8_LAS bf16x8*)(lds + PG8_SA(b, h) + aoff + m * 2048 + k * 1024); } while (0)
; #define PG8_WAIT_V(n) asm volatile("s_waitcnt vmcnt(" #n ")" ::: "memory")
; #define PG8_BAR __builtin_amdgcn_s_barrier()
; template <class Epi, class Sched>
; __device__ __forceinline__ void gemm_phase(PG8_LAS unsigned char* lds, const Gemm g, const Sched& S, const Epi& E) {
;     ...
;             const bool last = (t == nt - 2);
;             const char* a1 = cA + (size_t)(t + 1) * kstep;
;             const char* a2 = last ? nA : cA + (size_t)(t + 2) * kstep; const char* b2 = last ? nB : cB + (size_t)(t + 2) * kstep;
;             const char* a3 = a2 + kstep; const char* b3 = b2 + kstep;
;             if (last && has_next) S.a_ready(nxt);
;             PG8_LDB(B0, 0, 0); PG8_SCHED; PG8_LDA(At, 0, 0); PG8_STAGE(PG8_SA(1, 1), a1 + hstep, voffA);
;             PG8_WAIT_L(8); PG8_BAR; PG8_WAIT_L(0); PG8_MMA(0, 0, At, B0); PG8_BAR; PG8_SCHED;
;             PG8_LDB(B1, 0, 1); PG8_STAGE(PG8_SB(0, 0), b2, voffB);
;             PG8_BAR; PG8_WAIT_L(0); PG8_MMA(0, 1, At, B1); PG8_BAR;
;             PG8_LDA(At, 0, 1); PG8_STAGE(PG8_SA(0, 0), a2, voffA);
;             PG8_BAR; PG8_WAIT_L(0); PG8_MMA(1, 0, At, B0); PG8_BAR; PG8_SCHED;
;             PG8_STAGE(PG8_SB(0, 1), b2 + hstep, voffB);
;             PG8_WAIT_V(6); PG8_BAR; PG8_MMA(1, 1, At, B1); PG8_BAR;
;             PG8_LDB(B0, 1, 0); PG8_SCHED; PG8_LDA(At, 1, 0); PG8_STAGE(PG8_SA(0, 1), a2 + hstep, voffA);
;             PG8_WAIT_L(8); PG8_BAR; PG8_WAIT_L(0); PG8_MMA(0, 0, At, B0); PG8_BAR; PG8_SCHED;
;             PG8_LDB(B1, 1, 1); PG8_STAGE(PG8_SB(1, 0), b3, voffB);
;             PG8_BAR; PG8_WAIT_L(0); PG8_MMA(0, 1, At, B1); PG8_BAR;
;             PG8_LDA(At, 1, 1); PG8_STAGE(PG8_SA(1, 0), a3, voffA);
;             PG8_BAR; PG8_WAIT_L(0); PG8_MMA(1, 0, At, B0); PG8_BAR; PG8_SCHED;
;             PG8_STAGE(PG8_SB(1, 1), b3 + hstep, voffB);
;             PG8_WAIT_V(6); PG8_BAR; PG8_MMA(1, 1, At, B1); PG8_BAR;
	ds_read_b128 v[170:173], v153 offset:49152
	ds_read_b128 v[182:185], v153 offset:50176
	ds_read_b128 v[190:193], v153 offset:51200
	ds_read_b128 v[194:197], v153 offset:52224
	ds_read_b128 v[198:201], v153 offset:53248
	ds_read_b128 v[202:205], v153 offset:54272
	ds_read_b128 v[206:209], v153 offset:55296
	ds_read_b128 v[210:213], v153 offset:56320
	s_add_i32 s23, s49, s30
	s_mov_b32 m0, s23
	s_nop 0
	global_load_lds_dwordx4 v130, s[98:99]
	s_nop 1
	s_add_i32 m0, s23, 0x2000
	s_nop 0
	global_load_lds_dwordx4 v134, s[98:99]
	s_nop 1
	s_mov_b32 m0, s37
	s_nop 0
	global_load_lds_dwordx4 v128, s[100:101]
	s_nop 1
	s_mov_b32 m0, s38
	s_nop 0
	global_load_lds_dwordx4 v132, s[100:101]
	s_add_u32 s20, s20, 0x40080
	s_addc_u32 s21, s21, 0
	s_add_i32 s22, s22, s30
	s_mov_b32 m0, s22
	s_nop 0
	global_load_lds_dwordx4 v130, s[20:21]
	s_nop 1
	s_add_i32 m0, s22, 0x2000
	s_nop 0
	global_load_lds_dwordx4 v134, s[20:21]
	s_waitcnt vmcnt(8) lgkmcnt(0)
	s_barrier
	v_mfma_f32_16x16x32_bf16 v[60:63], v[144:147], v[170:173], v[60:63]
	v_mfma_f32_16x16x32_bf16 v[56:59], v[160:163], v[170:173], v[56:59]
	v_mfma_f32_16x16x32_bf16 v[44:47], v[144:147], v[190:193], v[44:47]
	v_mfma_f32_16x16x32_bf16 v[40:43], v[160:163], v[190:193], v[40:43]
	v_mfma_f32_16x16x32_bf16 v[28:31], v[144:147], v[198:201], v[28:31]
	v_mfma_f32_16x16x32_bf16 v[24:27], v[160:163], v[198:201], v[24:27]
	v_mfma_f32_16x16x32_bf16 v[12:15], v[144:147], v[206:209], v[12:15]
	v_mfma_f32_16x16x32_bf16 v[8:11], v[160:163], v[206:209], v[8:11]
	v_mfma_f32_16x16x32_bf16 v[60:63], v[156:159], v[182:185], v[60:63]
	v_mfma_f32_16x16x32_bf16 v[56:59], v[166:169], v[182:185], v[56:59]
	v_mfma_f32_16x16x32_bf16 v[44:47], v[156:159], v[194:197], v[44:47]
	v_mfma_f32_16x16x32_bf16 v[40:43], v[166:169], v[194:197], v[40:43]
	v_mfma_f32_16x16x32_bf16 v[28:31], v[156:159], v[202:205], v[28:31]
	v_mfma_f32_16x16x32_bf16 v[24:27], v[166:169], v[202:205], v[24:27]
	v_mfma_f32_16x16x32_bf16 v[12:15], v[156:159], v[210:213], v[12:15]
	v_mfma_f32_16x16x32_bf16 v[8:11], v[166:169], v[210:213], v[8:11]
	v_mfma_f32_16x16x32_bf16 v[52:55], v[214:217], v[170:173], v[52:55]
	v_mfma_f32_16x16x32_bf16 v[48:51], v[222:225], v[170:173], v[48:51]
	v_mfma_f32_16x16x32_bf16 v[36:39], v[214:217], v[190:193], v[36:39]
	v_mfma_f32_16x16x32_bf16 v[32:35], v[222:225], v[190:193], v[32:35]
	v_mfma_f32_16x16x32_bf16 v[20:23], v[214:217], v[198:201], v[20:23]
	v_mfma_f32_16x16x32_bf16 v[16:19], v[222:225], v[198:201], v[16:19]
	v_mfma_f32_16x16x32_bf16 v[4:7], v[214:217], v[206:209], v[4:7]
	v_mfma_f32_16x16x32_bf16 v[0:3], v[222:225], v[206:209], v[0:3]
	v_mfma_f32_16x16x32_bf16 v[52:55], v[218:221], v[182:185], v[52:55]
	v_mfma_f32_16x16x32_bf16 v[48:51], v[226:229], v[182:185], v[48:51]
	v_mfma_f32_16x16x32_bf16 v[36:39], v[218:221], v[194:197], v[36:39]
	v_mfma_f32_16x16x32_bf16 v[32:35], v[226:229], v[194:197], v[32:35]
	v_mfma_f32_16x16x32_bf16 v[20:23], v[218:221], v[202:205], v[20:23]
	v_mfma_f32_16x16x32_bf16 v[16:19], v[226:229], v[202:205], v[16:19]
	v_mfma_f32_16x16x32_bf16 v[4:7], v[218:221], v[210:213], v[4:7]
	v_mfma_f32_16x16x32_bf16 v[0:3], v[226:229], v[210:213], v[0:3]
	s_barrier
	s_add_i32 s48, s48, 2
	s_add_u32 s18, s18, 0x100
	s_addc_u32 s19, s19, 0
	s_add_u32 s46, s46, 0x100
	s_addc_u32 s47, s47, 0
	s_cmp_gt_u32 s48, 13
.LBB0_724:
	ds_read_b128 v[144:147], v151
	ds_read_b128 v[156:159], v151 offset:1024
	ds_read_b128 v[160:163], v151 offset:2048
	ds_read_b128 v[166:169], v151 offset:3072
	s_add_u32 s20, s18, 0xfffc0080
	s_addc_u32 s21, s19, -1
	s_cmp_eq_u32 s48, 12
	s_cselect_b32 s23, s5, s21
	s_cselect_b32 s22, s11, s20
	s_cselect_b32 s21, s9, s47
	s_cselect_b32 s20, s45, s46
	s_add_i32 m0, s17, 0xc000
	ds_read_b128 v[170:173], v153
	ds_read_b128 v[182:185], v153 offset:1024
	ds_read_b128 v[190:193], v153 offset:2048
	ds_read_b128 v[194:197], v153 offset:3072
	ds_read_b128 v[198:201], v153 offset:4096
	ds_read_b128 v[202:205], v153 offset:5120
	ds_read_b128 v[206:209], v153 offset:6144
	ds_read_b128 v[210:213], v153 offset:7168
	global_load_lds_dwordx4 v136, s[18:19]
	s_nop 1
	s_add_i32 m0, s17, 0xe000
	s_nop 0
	global_load_lds_dwordx4 v138, s[18:19]
	s_waitcnt lgkmcnt(12)
	ds_read_b128 v[214:217], v154
	ds_read_b128 v[218:221], v154 offset:1024
	ds_read_b128 v[222:225], v154 offset:2048
	ds_read_b128 v[226:229], v154 offset:3072
	s_waitcnt vmcnt(8) lgkmcnt(0)
	s_barrier
	v_mfma_f32_16x16x32_bf16 v[124:127], v[144:147], v[170:173], v[124:127]
	v_mfma_f32_16x16x32_bf16 v[120:123], v[160:163], v[170:173], v[120:123]
	v_mfma_f32_16x16x32_bf16 v[108:111], v[144:147], v[190:193], v[108:111]
	v_mfma_f32_16x16x32_bf16 v[104:107], v[160:163], v[190:193], v[104:107]
	v_mfma_f32_16x16x32_bf16 v[92:95], v[144:147], v[198:201], v[92:95]
	v_mfma_f32_16x16x32_bf16 v[88:91], v[160:163], v[198:201], v[88:91]
	v_mfma_f32_16x16x32_bf16 v[76:79], v[144:147], v[206:209], v[76:79]
	v_mfma_f32_16x16x32_bf16 v[72:75], v[160:163], v[206:209], v[72:75]
	v_mfma_f32_16x16x32_bf16 v[124:127], v[156:159], v[182:185], v[124:127]
	v_mfma_f32_16x16x32_bf16 v[120:123], v[166:169], v[182:185], v[120:123]
	v_mfma_f32_16x16x32_bf16 v[108:111], v[156:159], v[194:197], v[108:111]
	v_mfma_f32_16x16x32_bf16 v[104:107], v[166:169], v[194:197], v[104:107]
	v_mfma_f32_16x16x32_bf16 v[92:95], v[156:159], v[202:205], v[92:95]
	v_mfma_f32_16x16x32_bf16 v[88:91], v[166:169], v[202:205], v[88:91]
	v_mfma_f32_16x16x32_bf16 v[76:79], v[156:159], v[210:213], v[76:79]
	v_mfma_f32_16x16x32_bf16 v[72:75], v[166:169], v[210:213], v[72:75]
	v_mfma_f32_16x16x32_bf16 v[116:119], v[214:217], v[170:173], v[116:119]
	v_mfma_f32_16x16x32_bf16 v[112:115], v[222:225], v[170:173], v[112:115]
	v_mfma_f32_16x16x32_bf16 v[100:103], v[214:217], v[190:193], v[100:103]
	v_mfma_f32_16x16x32_bf16 v[96:99], v[222:225], v[190:193], v[96:99]
	v_mfma_f32_16x16x32_bf16 v[84:87], v[214:217], v[198:201], v[84:87]
	v_mfma_f32_16x16x32_bf16 v[80:83], v[222:225], v[198:201], v[80:83]
	v_mfma_f32_16x16x32_bf16 v[68:71], v[214:217], v[206:209], v[68:71]
	v_mfma_f32_16x16x32_bf16 v[64:67], v[222:225], v[206:209], v[64:67]
	v_mfma_f32_16x16x32_bf16 v[116:119], v[218:221], v[182:185], v[116:119]
	v_mfma_f32_16x16x32_bf16 v[112:115], v[226:229], v[182:185], v[112:115]
	v_mfma_f32_16x16x32_bf16 v[100:103], v[218:221], v[194:197], v[100:103]
	v_mfma_f32_16x16x32_bf16 v[96:99], v[226:229], v[194:197], v[96:99]
	v_mfma_f32_16x16x32_bf16 v[84:87], v[218:221], v[202:205], v[84:87]
	v_mfma_f32_16x16x32_bf16 v[80:83], v[226:229], v[202:205], v[80:83]
	v_mfma_f32_16x16x32_bf16 v[68:71], v[218:221], v[210:213], v[68:71]
	v_mfma_f32_16x16x32_bf16 v[64:67], v[226:229], v[210:213], v[64:67]
	s_barrier
; #define PG8_STAGE(bufoff, gbase, voff) do { _Pragma("unroll") for (int _i = 0; _i < 2; ++_i) \
;         __builtin_amdgcn_global_load_lds((const unsigned*)((const char*)(gbase) + (voff)[_i]), (PG8_LAS unsigned*)(lds + (bufoff) + ldsw + _i * 8192), 16, 0, 0); } while (0)
; #define PG8_LDA(dst, b, h) do { _Pragma("unroll") for (int m = 0; m < 4; ++m) _Pragma("unroll") for (int k = 0; k < 2; ++k) dst[m][k] = *(const PG8_LAS bf16x8*)(lds + PG8_SA(b, h) + aoff + m * 2048 + k * 1024); } while (0)
; #define PG8_LDB(dst, b, h) do { _Pragma("unroll") for (int n = 0; n < 2; ++n) _Pragma("unroll") for (int k = 0; k < 2; ++k) dst[n][k] = *(const PG8_LAS bf16x8*)(lds + PG8_SB(b, h) + boff + n * 2048 + k * 1024); } while (0)
; #define PG8_MMA(ai, bj, At, Bt) do { __builtin_amdgcn_s_setprio(1); _Pragma("unroll") for (int m = 0; m < 4; ++m) _Pragma("unroll") for (int n = 0; n < 2; ++n) _Pragma("unroll") for (int k = 0; k < 2; ++k) \
;         acc[ai][bj][m][n] = __builtin_amdgcn_mfma_f32_16x16x32_bf16(Bt[n][k], At[m][k], acc[ai][bj][m][n], 0, 0, 0); __builtin_amdgcn_s_setprio(0); } while (0)
; #define PG8_WAIT_V(n) asm volatile("s_waitcnt vmcnt(" #n ")" ::: "memory")
; #define PG8_WAIT_L(n) asm volatile("s_waitcnt lgkmcnt(" #n ")" ::: "memory")
; #define PG8_BAR __builtin_amdgcn_s_barrier()
; #define PG8_SCHED __builtin_amdgcn_sched_barrier(0)
; template <class Epi, class Sched>
; __device__ __forceinline__ void gemm_phase(PG8_LAS unsigned char* lds, const Gemm g, const Sched& S, const Epi& E) {
;     ...
;             PG8_LDA(At, 0, 1); PG8_STAGE(PG8_SA(0, 0), a2, voffA);
;             PG8_BAR; PG8_WAIT_L(0); PG8_MMA(1, 0, At, B0); PG8_BAR; PG8_SCHED;
;             PG8_STAGE(PG8_SB(0, 1), b2 + hstep, voffB);
;             PG8_WAIT_V(6); PG8_BAR; PG8_MMA(1, 1, At, B1); PG8_BAR;
;             PG8_LDB(B0, 1, 0); PG8_SCHED; PG8_LDA(At, 1, 0); PG8_STAGE(PG8_SA(0, 1), a2 + hstep, voffA);
;             PG8_WAIT_L(8); PG8_BAR; PG8_WAIT_L(0); PG8_MMA(0, 0, At, B0); PG8_BAR; PG8_SCHED;
;             PG8_LDB(B1, 1, 1); PG8_STAGE(PG8_SB(1, 0), b3, voffB);
;             PG8_BAR; PG8_WAIT_L(0); PG8_MMA(0, 1, At, B1); PG8_BAR;
	ds_read_b128 v[170:173], v153 offset:16384
	ds_read_b128 v[182:185], v153 offset:17408
	ds_read_b128 v[190:193], v153 offset:18432
	ds_read_b128 v[194:197], v153 offset:19456
	ds_read_b128 v[198:201], v153 offset:20480
	ds_read_b128 v[202:205], v153 offset:21504
	ds_read_b128 v[206:209], v153 offset:22528
	ds_read_b128 v[210:213], v153 offset:23552
	s_add_i32 s49, s42, s30
	s_add_u32 s98, s20, s6
	s_addc_u32 s99, s21, s7
	s_mov_b32 m0, s49
	s_nop 0
	global_load_lds_dwordx4 v130, s[20:21]
	s_nop 1
	s_add_i32 m0, s49, 0x2000
	s_nop 0
	global_load_lds_dwordx4 v134, s[20:21]
	s_nop 1
	s_mov_b32 m0, s17
	s_add_u32 s100, s22, s6
	s_addc_u32 s101, s23, s7
	global_load_lds_dwordx4 v128, s[22:23]
	s_nop 1
	s_mov_b32 m0, s31
	s_nop 0
	global_load_lds_dwordx4 v132, s[22:23]
	s_add_u32 s50, s20, 0x40000
	s_addc_u32 s51, s21, 0
	s_add_i32 s49, s43, s30
	s_mov_b32 m0, s49
	s_nop 0
	global_load_lds_dwordx4 v130, s[50:51]
	s_nop 1
	s_add_i32 m0, s49, 0x2000
	s_nop 0
	global_load_lds_dwordx4 v134, s[50:51]
	s_waitcnt vmcnt(8) lgkmcnt(0)
	s_barrier
	v_mfma_f32_16x16x32_bf16 v[60:63], v[144:147], v[170:173], v[60:63]
	v_mfma_f32_16x16x32_bf16 v[56:59], v[160:163], v[170:173], v[56:59]
	v_mfma_f32_16x16x32_bf16 v[44:47], v[144:147], v[190:193], v[44:47]
	v_mfma_f32_16x16x32_bf16 v[40:43], v[160:163], v[190:193], v[40:43]
	v_mfma_f32_16x16x32_bf16 v[28:31], v[144:147], v[198:201], v[28:31]
	v_mfma_f32_16x16x32_bf16 v[24:27], v[160:163], v[198:201], v[24:27]
	v_mfma_f32_16x16x32_bf16 v[12:15], v[144:147], v[206:209], v[12:15]
	v_mfma_f32_16x16x32_bf16 v[8:11], v[160:163], v[206:209], v[8:11]
	v_mfma_f32_16x16x32_bf16 v[60:63], v[156:159], v[182:185], v[60:63]
	v_mfma_f32_16x16x32_bf16 v[56:59], v[166:169], v[182:185], v[56:59]
	v_mfma_f32_16x16x32_bf16 v[44:47], v[156:159], v[194:197], v[44:47]
	v_mfma_f32_16x16x32_bf16 v[40:43], v[166:169], v[194:197], v[40:43]
	v_mfma_f32_16x16x32_bf16 v[28:31], v[156:159], v[202:205], v[28:31]
	v_mfma_f32_16x16x32_bf16 v[24:27], v[166:169], v[202:205], v[24:27]
	v_mfma_f32_16x16x32_bf16 v[12:15], v[156:159], v[210:213], v[12:15]
	v_mfma_f32_16x16x32_bf16 v[8:11], v[166:169], v[210:213], v[8:11]
	v_mfma_f32_16x16x32_bf16 v[52:55], v[214:217], v[170:173], v[52:55]
	v_mfma_f32_16x16x32_bf16 v[48:51], v[222:225], v[170:173], v[48:51]
	v_mfma_f32_16x16x32_bf16 v[36:39], v[214:217], v[190:193], v[36:39]
	v_mfma_f32_16x16x32_bf16 v[32:35], v[222:225], v[190:193], v[32:35]
	v_mfma_f32_16x16x32_bf16 v[20:23], v[214:217], v[198:201], v[20:23]
	v_mfma_f32_16x16x32_bf16 v[16:19], v[222:225], v[198:201], v[16:19]
	v_mfma_f32_16x16x32_bf16 v[4:7], v[214:217], v[206:209], v[4:7]
	v_mfma_f32_16x16x32_bf16 v[0:3], v[222:225], v[206:209], v[0:3]
	v_mfma_f32_16x16x32_bf16 v[52:55], v[218:221], v[182:185], v[52:55]
	v_mfma_f32_16x16x32_bf16 v[48:51], v[226:229], v[182:185], v[48:51]
	v_mfma_f32_16x16x32_bf16 v[36:39], v[218:221], v[194:197], v[36:39]
	v_mfma_f32_16x16x32_bf16 v[32:35], v[226:229], v[194:197], v[32:35]
	v_mfma_f32_16x16x32_bf16 v[20:23], v[218:221], v[202:205], v[20:23]
	v_mfma_f32_16x16x32_bf16 v[16:19], v[226:229], v[202:205], v[16:19]
	v_mfma_f32_16x16x32_bf16 v[4:7], v[218:221], v[210:213], v[4:7]
	v_mfma_f32_16x16x32_bf16 v[0:3], v[226:229], v[210:213], v[0:3]
	s_barrier
	s_add_i32 s49, 0, 0x18000
	v_add_u32_e32 v155, s49, v149
	ds_read_b128 v[144:147], v155
	ds_read_b128 v[156:159], v155 offset:1024
	ds_read_b128 v[160:163], v155 offset:2048
	ds_read_b128 v[166:169], v155 offset:3072
	s_add_u32 s22, s22, 0x40000
	s_addc_u32 s23, s23, 0
	s_mov_b32 m0, s34
	ds_read_b128 v[170:173], v153 offset:32768
	ds_read_b128 v[182:185], v153 offset:33792
	ds_read_b128 v[190:193], v153 offset:34816
	ds_read_b128 v[194:197], v153 offset:35840
	ds_read_b128 v[198:201], v153 offset:36864
	ds_read_b128 v[202:205], v153 offset:37888
	ds_read_b128 v[206:209], v153 offset:38912
	ds_read_b128 v[210:213], v153 offset:39936
	global_load_lds_dwordx4 v128, s[22:23]
	s_nop 1
	s_mov_b32 m0, s35
	s_nop 0
	global_load_lds_dwordx4 v132, s[22:23]
	s_add_i32 s22, 0, 0x1c000
	v_add_u32_e32 v155, s22, v149
	s_waitcnt lgkmcnt(12)
	ds_read_b128 v[214:217], v155
	ds_read_b128 v[218:221], v155 offset:1024
	ds_read_b128 v[222:225], v155 offset:2048
	ds_read_b128 v[226:229], v155 offset:3072
	s_waitcnt vmcnt(8) lgkmcnt(0)
	s_barrier
	v_mfma_f32_16x16x32_bf16 v[124:127], v[144:147], v[170:173], v[124:127]
	v_mfma_f32_16x16x32_bf16 v[120:123], v[160:163], v[170:173], v[120:123]
	v_mfma_f32_16x16x32_bf16 v[108:111], v[144:147], v[190:193], v[108:111]
	v_mfma_f32_16x16x32_bf16 v[104:107], v[160:163], v[190:193], v[104:107]
	v_mfma_f32_16x16x32_bf16 v[92:95], v[144:147], v[198:201], v[92:95]
	v_mfma_f32_16x16x32_bf16 v[88:91], v[160:163], v[198:201], v[88:91]
	v_mfma_f32_16x16x32_bf16 v[76:79], v[144:147], v[206:209], v[76:79]
	v_mfma_f32_16x16x32_bf16 v[72:75], v[160:163], v[206:209], v[72:75]
	v_mfma_f32_16x16x32_bf16 v[124:127], v[156:159], v[182:185], v[124:127]
	v_mfma_f32_16x16x32_bf16 v[120:123], v[166:169], v[182:185], v[120:123]
	v_mfma_f32_16x16x32_bf16 v[108:111], v[156:159], v[194:197], v[108:111]
	v_mfma_f32_16x16x32_bf16 v[104:107], v[166:169], v[194:197], v[104:107]
	v_mfma_f32_16x16x32_bf16 v[92:95], v[156:159], v[202:205], v[92:95]
	v_mfma_f32_16x16x32_bf16 v[88:91], v[166:169], v[202:205], v[88:91]
	v_mfma_f32_16x16x32_bf16 v[76:79], v[156:159], v[210:213], v[76:79]
	v_mfma_f32_16x16x32_bf16 v[72:75], v[166:169], v[210:213], v[72:75]
	v_mfma_f32_16x16x32_bf16 v[116:119], v[214:217], v[170:173], v[116:119]
	v_mfma_f32_16x16x32_bf16 v[112:115], v[222:225], v[170:173], v[112:115]
	v_mfma_f32_16x16x32_bf16 v[100:103], v[214:217], v[190:193], v[100:103]
	v_mfma_f32_16x16x32_bf16 v[96:99], v[222:225], v[190:193], v[96:99]
	v_mfma_f32_16x16x32_bf16 v[84:87], v[214:217], v[198:201], v[84:87]
	v_mfma_f32_16x16x32_bf16 v[80:83], v[222:225], v[198:201], v[80:83]
	v_mfma_f32_16x16x32_bf16 v[68:71], v[214:217], v[206:209], v[68:71]
	v_mfma_f32_16x16x32_bf16 v[64:67], v[222:225], v[206:209], v[64:67]
	v_mfma_f32_16x16x32_bf16 v[116:119], v[218:221], v[182:185], v[116:119]
	v_mfma_f32_16x16x32_bf16 v[112:115], v[226:229], v[182:185], v[112:115]
	v_mfma_f32_16x16x32_bf16 v[100:103], v[218:221], v[194:197], v[100:103]
	v_mfma_f32_16x16x32_bf16 v[96:99], v[226:229], v[194:197], v[96:99]
	v_mfma_f32_16x16x32_bf16 v[84:87], v[218:221], v[202:205], v[84:87]
	v_mfma_f32_16x16x32_bf16 v[80:83], v[226:229], v[202:205], v[80:83]
	v_mfma_f32_16x16x32_bf16 v[68:71], v[218:221], v[210:213], v[68:71]
	v_mfma_f32_16x16x32_bf16 v[64:67], v[226:229], v[210:213], v[64:67]
	s_barrier
; #define PG8_STAGE(bufoff, gbase, voff) do { _Pragma("unroll") for (int _i = 0; _i < 2; ++_i) \
;         __builtin_amdgcn_global_load_lds((const unsigned*)((const char*)(gbase) + (voff)[_i]), (PG8_LAS unsigned*)(lds + (bufoff) + ldsw + _i * 8192), 16, 0, 0); } while (0)
; #define PG8_LDA(dst, b, h) do { _Pragma("unroll") for (int m = 0; m < 4; ++m) _Pragma("unroll") for (int k = 0; k < 2; ++k) dst[m][k] = *(const PG8_LAS bf16x8*)(lds + PG8_SA(b, h) + aoff + m * 2048 + k * 1024); } while (0)
; #define PG8_MMA(ai, bj, At, Bt) do { __builtin_amdgcn_s_setprio(1); _Pragma("unroll") for (int m = 0; m < 4; ++m) _Pragma("unroll") for (int n = 0; n < 2; ++n) _Pragma("unroll") for (int k = 0; k < 2; ++k) \
;         acc[ai][bj][m][n] = __builtin_amdgcn_mfma_f32_16x16x32_bf16(Bt[n][k], At[m][k], acc[ai][bj][m][n], 0, 0, 0); __builtin_amdgcn_s_setprio(0); } while (0)
; #define PG8_WAIT_V(n) asm volatile("s_waitcnt vmcnt(" #n ")" ::: "memory")
; #define PG8_WAIT_L(n) asm volatile("s_waitcnt lgkmcnt(" #n ")" ::: "memory")
; #define PG8_BAR __builtin_amdgcn_s_barrier()
; #define PG8_SCHED __builtin_amdgcn_sched_barrier(0)
; __device__ __forceinline__ f32x4 sigmoid4(f32x4 x) {
;     f32x4 d;
; #pragma unroll
;     for (int j = 0; j < 4; ++j) d[j] = 1.0f + __expf(-fmaxf(x[j], -20.0f));
;     const float p01 = d[0] * d[1], p23 = d[2] * d[3], r = __builtin_amdgcn_rcpf(p01 * p23), r01 = r * p23, r23 = r * p01;
;     return (f32x4){r01 * d[1], r01 * d[0], r23 * d[3], r23 * d[2]};
; }
; template <class Epi, class Sched>
; __device__ __forceinline__ void gemm_phase(PG8_LAS unsigned char* lds, const Gemm g, const Sched& S, const Epi& E) {
;     ...
;             PG8_LDA(At, 1, 1); PG8_STAGE(PG8_SA(1, 0), a3, voffA);
;             PG8_BAR; PG8_WAIT_L(0); PG8_MMA(1, 0, At, B0); PG8_BAR; PG8_SCHED;
;             PG8_STAGE(PG8_SB(1, 1), b3 + hstep, voffB);
;             PG8_WAIT_V(6); PG8_BAR; PG8_MMA(1, 1, At, B1); PG8_BAR;
	ds_read_b128 v[170:173], v153 offset:49152
	ds_read_b128 v[182:185], v153 offset:50176
	ds_read_b128 v[190:193], v153 offset:51200
	ds_read_b128 v[194:197], v153 offset:52224
	ds_read_b128 v[198:201], v153 offset:53248
	ds_read_b128 v[202:205], v153 offset:54272
	ds_read_b128 v[206:209], v153 offset:55296
	ds_read_b128 v[210:213], v153 offset:56320
	s_add_i32 s23, s49, s30
	s_mov_b32 m0, s23
	s_nop 0
	global_load_lds_dwordx4 v130, s[98:99]
	s_nop 1
	s_add_i32 m0, s23, 0x2000
	s_nop 0
	global_load_lds_dwordx4 v134, s[98:99]
	s_nop 1
	s_mov_b32 m0, s37
	s_nop 0
	global_load_lds_dwordx4 v128, s[100:101]
	s_nop 1
	s_mov_b32 m0, s38
	s_nop 0
	global_load_lds_dwordx4 v132, s[100:101]
	s_add_u32 s20, s20, 0x40080
	s_addc_u32 s21, s21, 0
	s_add_i32 s22, s22, s30
	s_mov_b32 m0, s22
	s_nop 0
	global_load_lds_dwordx4 v130, s[20:21]
	s_nop 1
	s_add_i32 m0, s22, 0x2000
	s_nop 0
	global_load_lds_dwordx4 v134, s[20:21]
	s_waitcnt vmcnt(8) lgkmcnt(0)
	s_barrier
	v_mfma_f32_16x16x32_bf16 v[60:63], v[144:147], v[170:173], v[60:63]
	v_mfma_f32_16x16x32_bf16 v[56:59], v[160:163], v[170:173], v[56:59]
	v_mfma_f32_16x16x32_bf16 v[44:47], v[144:147], v[190:193], v[44:47]
	v_mfma_f32_16x16x32_bf16 v[40:43], v[160:163], v[190:193], v[40:43]
	v_mfma_f32_16x16x32_bf16 v[28:31], v[144:147], v[198:201], v[28:31]
	v_mfma_f32_16x16x32_bf16 v[24:27], v[160:163], v[198:201], v[24:27]
	v_mfma_f32_16x16x32_bf16 v[12:15], v[144:147], v[206:209], v[12:15]
	v_mfma_f32_16x16x32_bf16 v[8:11], v[160:163], v[206:209], v[8:11]
	v_mfma_f32_16x16x32_bf16 v[60:63], v[156:159], v[182:185], v[60:63]
	v_mfma_f32_16x16x32_bf16 v[56:59], v[166:169], v[182:185], v[56:59]
	v_mfma_f32_16x16x32_bf16 v[44:47], v[156:159], v[194:197], v[44:47]
	v_mfma_f32_16x16x32_bf16 v[40:43], v[166:169], v[194:197], v[40:43]
	v_mfma_f32_16x16x32_bf16 v[28:31], v[156:159], v[202:205], v[28:31]
	v_mfma_f32_16x16x32_bf16 v[24:27], v[166:169], v[202:205], v[24:27]
	v_mfma_f32_16x16x32_bf16 v[12:15], v[156:159], v[210:213], v[12:15]
	v_mfma_f32_16x16x32_bf16 v[8:11], v[166:169], v[210:213], v[8:11]
	v_mfma_f32_16x16x32_bf16 v[52:55], v[214:217], v[170:173], v[52:55]
	v_mfma_f32_16x16x32_bf16 v[48:51], v[222:225], v[170:173], v[48:51]
	v_mfma_f32_16x16x32_bf16 v[36:39], v[214:217], v[190:193], v[36:39]
	v_mfma_f32_16x16x32_bf16 v[32:35], v[222:225], v[190:193], v[32:35]
	v_mfma_f32_16x16x32_bf16 v[20:23], v[214:217], v[198:201], v[20:23]
	v_mfma_f32_16x16x32_bf16 v[16:19], v[222:225], v[198:201], v[16:19]
	v_mfma_f32_16x16x32_bf16 v[4:7], v[214:217], v[206:209], v[4:7]
	v_mfma_f32_16x16x32_bf16 v[0:3], v[222:225], v[206:209], v[0:3]
	v_mfma_f32_16x16x32_bf16 v[52:55], v[218:221], v[182:185], v[52:55]
	v_mfma_f32_16x16x32_bf16 v[48:51], v[226:229], v[182:185], v[48:51]
	v_mfma_f32_16x16x32_bf16 v[36:39], v[218:221], v[194:197], v[36:39]
	v_mfma_f32_16x16x32_bf16 v[32:35], v[226:229], v[194:197], v[32:35]
	v_mfma_f32_16x16x32_bf16 v[20:23], v[218:221], v[202:205], v[20:23]
	v_mfma_f32_16x16x32_bf16 v[16:19], v[226:229], v[202:205], v[16:19]
	v_mfma_f32_16x16x32_bf16 v[4:7], v[218:221], v[210:213], v[4:7]
	v_mfma_f32_16x16x32_bf16 v[0:3], v[226:229], v[210:213], v[0:3]
	s_barrier
	s_add_i32 s48, s48, 2
	s_add_u32 s18, s18, 0x100
	s_addc_u32 s19, s19, 0
	s_add_u32 s46, s46, 0x100
	s_addc_u32 s47, s47, 0
	s_cmp_gt_u32 s48, 13
	s_cbranch_scc0 .LBB0_724
	s_cmp_gt_i32 s4, 5
	s_cselect_b64 s[18:19], -1, 0
	s_cmp_lt_i32 s4, 6
	v_pk_add_f32 v[144:145], v[126:127], 0 op_sel_hi:[1,0]
	v_pk_add_f32 v[146:147], v[124:125], 0 op_sel_hi:[1,0]
	v_pk_add_f32 v[124:125], v[122:123], 0 op_sel_hi:[1,0]
	v_pk_add_f32 v[126:127], v[120:121], 0 op_sel_hi:[1,0]
	s_cbranch_scc1 .LBB0_727
	v_max_f32_e32 v122, 0xc1a00000, v144
	v_mul_f32_e32 v122, 0xbfb8aa3b, v122
	v_exp_f32_e32 v123, v122
	v_max_f32_e32 v120, 0xc1a00000, v146
	v_max_f32_e32 v121, 0xc1a00000, v147
	v_max_f32_e32 v122, 0xc1a00000, v145
	v_mul_f32_e32 v120, 0xbfb8aa3b, v120
	v_mul_f32_e32 v121, 0xbfb8aa3b, v121
	v_mul_f32_e32 v122, 0xbfb8aa3b, v122
	v_exp_f32_e32 v120, v120
	v_exp_f32_e32 v121, v121
	v_exp_f32_e32 v122, v122
	v_max_f32_e32 v124, 0xc1a00000, v124
	v_pk_add_f32 v[120:121], v[120:121], 1.0 op_sel_hi:[1,0]
	v_pk_add_f32 v[122:123], v[122:123], 1.0 op_sel_hi:[1,0]
	v_mov_b32_e32 v144, v120
	v_mov_b32_e32 v145, v123
	v_pk_mov_b32 v[146:147], v[120:121], v[122:123] op_sel:[1,0]
	v_mul_f32_e32 v124, 0xbfb8aa3b, v124
	v_pk_mul_f32 v[144:145], v[144:145], v[146:147]
	v_exp_f32_e32 v147, v124
	v_max_f32_e32 v126, 0xc1a00000, v126
	v_max_f32_e32 v127, 0xc1a00000, v127
	v_max_f32_e32 v124, 0xc1a00000, v125
	v_mul_f32_e32 v146, v144, v145
	v_mul_f32_e32 v126, 0xbfb8aa3b, v126
	v_mul_f32_e32 v127, 0xbfb8aa3b, v127
	v_mul_f32_e32 v124, 0xbfb8aa3b, v124
	v_rcp_f32_e32 v155, v146
	v_exp_f32_e32 v126, v126
	v_exp_f32_e32 v127, v127
	v_exp_f32_e32 v146, v124
	v_mul_f32_e32 v124, v145, v155
	v_mul_f32_e32 v144, v144, v155
	v_pk_add_f32 v[126:127], v[126:127], 1.0 op_sel_hi:[1,0]
	v_pk_add_f32 v[156:157], v[146:147], 1.0 op_sel_hi:[1,0]
	v_mov_b32_e32 v146, v126
	v_mov_b32_e32 v147, v157
	v_pk_mov_b32 v[158:159], v[126:127], v[156:157] op_sel:[1,0]
	v_pk_mul_f32 v[144:145], v[122:123], v[144:145] op_sel_hi:[1,0]
	v_pk_mul_f32 v[158:159], v[146:147], v[158:159]
	s_nop 0
	v_mul_f32_e32 v125, v158, v159
	v_rcp_f32_e32 v125, v125
	s_nop 0
	v_pk_mul_f32 v[146:147], v[120:121], v[124:125] op_sel:[1,0] op_sel_hi:[0,0]
	v_mul_f32_e32 v120, v159, v125
	v_mul_f32_e32 v122, v158, v125
	v_pk_mul_f32 v[124:125], v[156:157], v[122:123] op_sel_hi:[1,0]
	v_pk_mul_f32 v[126:127], v[126:127], v[120:121] op_sel:[1,0] op_sel_hi:[0,0]

; #define PG8_STAGE(bufoff, gbase, voff) do { _Pragma("unroll") for (int _i = 0; _i < 2; ++_i) \
;         __builtin_amdgcn_global_load_lds((const unsigned*)((const char*)(gbase) + (voff)[_i]), (PG8_LAS unsigned*)(lds + (bufoff) + ldsw + _i * 8192), 16, 0, 0); } while (0)
; #define PG8_LDA(dst, b, h) do { _Pragma("unroll") for (int m = 0; m < 4; ++m) _Pragma("unroll") for (int k = 0; k < 2; ++k) dst[m][k] = *(const PG8_LAS bf16x8*)(lds + PG8_SA(b, h) + aoff + m * 2048 + k * 1024); } while (0)
; #define PG8_LDB(dst, b, h) do { _Pragma("unroll") for (int n = 0; n < 2; ++n) _Pragma("unroll") for (int k = 0; k < 2; ++k) dst[n][k] = *(const PG8_LAS bf16x8*)(lds + PG8_SB(b, h) + boff + n * 2048 + k * 1024); } while (0)
; #define PG8_MMA(ai, bj, At, Bt) do { __builtin_amdgcn_s_setprio(1); _Pragma("unroll") for (int m = 0; m < 4; ++m) _Pragma("unroll") for (int n = 0; n < 2; ++n) _Pragma("unroll") for (int k = 0; k < 2; ++k) \
;         acc[ai][bj][m][n] = __builtin_amdgcn_mfma_f32_16x16x32_bf16(Bt[n][k], At[m][k], acc[ai][bj][m][n], 0, 0, 0); __builtin_amdgcn_s_setprio(0); } while (0)
; #define PG8_WAIT_L(n) asm volatile("s_waitcnt lgkmcnt(" #n ")" ::: "memory")
; #define PG8_BAR __builtin_amdgcn_s_barrier()
; #define PG8_SCHED __builtin_amdgcn_sched_barrier(0)
; template <class Epi, class Sched>
; __device__ __forceinline__ void gemm_phase(PG8_LAS unsigned char* lds, const Gemm g, const Sched& S, const Epi& E) {
;     ...
;         const bool has_next = S.next(ui + 1, nxt);
;         const char* nA = has_next ? (const char*)g.A + (size_t)nxt.pm * tstep : cA; const char* nB = has_next ? (const char*)g.Bt + (size_t)nxt.pn * tstep : cB;
;         for (int t = 0; t < nt; t += 2) {
;             const bool last = (t == nt - 2);
;             const char* a1 = cA + (size_t)(t + 1) * kstep;
;             const char* a2 = last ? nA : cA + (size_t)(t + 2) * kstep; const char* b2 = last ? nB : cB + (size_t)(t + 2) * kstep;
;             const char* a3 = a2 + kstep; const char* b3 = b2 + kstep;
;             if (last && has_next) S.a_ready(nxt);
;             PG8_LDB(B0, 0, 0); PG8_SCHED; PG8_LDA(At, 0, 0); PG8_STAGE(PG8_SA(1, 1), a1 + hstep, voffA);
;             PG8_WAIT_L(8); PG8_BAR; PG8_WAIT_L(0); PG8_MMA(0, 0, At, B0); PG8_BAR; PG8_SCHED;
;             PG8_LDB(B1, 0, 1); PG8_STAGE(PG8_SB(0, 0), b2, voffB);
;             PG8_BAR; PG8_WAIT_L(0); PG8_MMA(0, 1, At, B1); PG8_BAR;
.LBB0_990:
	s_ashr_i32 s11, s10, 31
	v_cmp_lt_i64_e32 vcc, s[12:13], v[140:141]
	s_lshl_b64 s[12:13], s[10:11], 19
	s_add_u32 s12, s27, s12
	s_addc_u32 s13, s28, s13
	s_and_b64 s[14:15], vcc, exec
	s_cselect_b32 s11, s13, s19
	s_cselect_b32 s43, s12, s18
	s_ashr_i32 s9, s8, 31
	s_lshl_b64 s[14:15], s[8:9], 19
	s_add_u32 s14, s96, s14
	s_addc_u32 s15, s97, s15
	s_and_b64 s[22:23], vcc, exec
	s_cselect_b32 s9, s15, s21
	s_cselect_b32 s44, s14, s20
	s_add_u32 s18, s18, 0x40080
	s_addc_u32 s19, s19, 0
	s_add_u32 s45, s20, 0x100
	s_addc_u32 s46, s21, 0
	s_mov_b32 s47, -2
	ds_read_b128 v[144:147], v153
	ds_read_b128 v[156:159], v153 offset:1024
	ds_read_b128 v[160:163], v153 offset:2048
	ds_read_b128 v[164:167], v153 offset:3072
	s_add_u32 s20, s18, 0xfffc0080
	s_addc_u32 s21, s19, -1
	s_cmp_eq_u32 s47, 12
	s_cselect_b32 s23, s11, s21
	s_cselect_b32 s22, s43, s20
	s_cselect_b32 s21, s9, s46
	s_cselect_b32 s20, s44, s45
	s_add_i32 m0, s17, 0xc000
	ds_read_b128 v[168:171], v154
	ds_read_b128 v[172:175], v154 offset:1024
	ds_read_b128 v[182:185], v154 offset:2048
	ds_read_b128 v[190:193], v154 offset:3072
	ds_read_b128 v[194:197], v154 offset:4096
	ds_read_b128 v[198:201], v154 offset:5120
	ds_read_b128 v[202:205], v154 offset:6144
	ds_read_b128 v[206:209], v154 offset:7168
	global_load_lds_dwordx4 v136, s[18:19]
	s_nop 1
	s_add_i32 m0, s17, 0xe000
	s_nop 0
	global_load_lds_dwordx4 v138, s[18:19]
	s_waitcnt lgkmcnt(12)
	ds_read_b128 v[210:213], v155
	ds_read_b128 v[214:217], v155 offset:1024
	ds_read_b128 v[218:221], v155 offset:2048
	ds_read_b128 v[222:225], v155 offset:3072
	s_waitcnt vmcnt(8) lgkmcnt(0)
	s_barrier
	v_mfma_f32_16x16x32_bf16 v[124:127], v[144:147], v[168:171], 0
	v_mfma_f32_16x16x32_bf16 v[120:123], v[160:163], v[168:171], 0
	v_mfma_f32_16x16x32_bf16 v[112:115], v[144:147], v[182:185], 0
	v_mfma_f32_16x16x32_bf16 v[104:107], v[160:163], v[182:185], 0
	v_mfma_f32_16x16x32_bf16 v[96:99], v[144:147], v[194:197], 0
	v_mfma_f32_16x16x32_bf16 v[88:91], v[160:163], v[194:197], 0
	v_mfma_f32_16x16x32_bf16 v[80:83], v[144:147], v[202:205], 0
	v_mfma_f32_16x16x32_bf16 v[72:75], v[160:163], v[202:205], 0
	v_mfma_f32_16x16x32_bf16 v[124:127], v[156:159], v[172:175], v[124:127]
	v_mfma_f32_16x16x32_bf16 v[120:123], v[164:167], v[172:175], v[120:123]
	v_mfma_f32_16x16x32_bf16 v[112:115], v[156:159], v[190:193], v[112:115]
	v_mfma_f32_16x16x32_bf16 v[104:107], v[164:167], v[190:193], v[104:107]
	v_mfma_f32_16x16x32_bf16 v[96:99], v[156:159], v[198:201], v[96:99]
	v_mfma_f32_16x16x32_bf16 v[88:91], v[164:167], v[198:201], v[88:91]
	v_mfma_f32_16x16x32_bf16 v[80:83], v[156:159], v[206:209], v[80:83]
	v_mfma_f32_16x16x32_bf16 v[72:75], v[164:167], v[206:209], v[72:75]
	v_mfma_f32_16x16x32_bf16 v[116:119], v[210:213], v[168:171], 0
	v_mfma_f32_16x16x32_bf16 v[108:111], v[218:221], v[168:171], 0
	v_mfma_f32_16x16x32_bf16 v[100:103], v[210:213], v[182:185], 0
	v_mfma_f32_16x16x32_bf16 v[92:95], v[218:221], v[182:185], 0
	v_mfma_f32_16x16x32_bf16 v[84:87], v[210:213], v[194:197], 0
	v_mfma_f32_16x16x32_bf16 v[76:79], v[218:221], v[194:197], 0
	v_mfma_f32_16x16x32_bf16 v[68:71], v[210:213], v[202:205], 0
	v_mfma_f32_16x16x32_bf16 v[64:67], v[218:221], v[202:205], 0
	v_mfma_f32_16x16x32_bf16 v[116:119], v[214:217], v[172:175], v[116:119]
	v_mfma_f32_16x16x32_bf16 v[108:111], v[222:225], v[172:175], v[108:111]
	v_mfma_f32_16x16x32_bf16 v[100:103], v[214:217], v[190:193], v[100:103]
	v_mfma_f32_16x16x32_bf16 v[92:95], v[222:225], v[190:193], v[92:95]
	v_mfma_f32_16x16x32_bf16 v[84:87], v[214:217], v[198:201], v[84:87]
	v_mfma_f32_16x16x32_bf16 v[76:79], v[222:225], v[198:201], v[76:79]
	v_mfma_f32_16x16x32_bf16 v[68:71], v[214:217], v[206:209], v[68:71]
	v_mfma_f32_16x16x32_bf16 v[64:67], v[222:225], v[206:209], v[64:67]
	s_barrier
	ds_read_b128 v[168:171], v154 offset:16384
	ds_read_b128 v[172:175], v154 offset:17408
	ds_read_b128 v[182:185], v154 offset:18432
	ds_read_b128 v[190:193], v154 offset:19456
	ds_read_b128 v[194:197], v154 offset:20480
	ds_read_b128 v[198:201], v154 offset:21504
	ds_read_b128 v[202:205], v154 offset:22528
	ds_read_b128 v[206:209], v154 offset:23552
	s_add_i32 s48, s39, s29
	s_add_u32 s98, s20, s6
	s_addc_u32 s99, s21, s7
	s_mov_b32 m0, s48
	s_nop 0
	global_load_lds_dwordx4 v130, s[20:21]
	s_nop 1
	s_add_i32 m0, s48, 0x2000
	s_nop 0
	global_load_lds_dwordx4 v134, s[20:21]
	s_nop 1
	s_mov_b32 m0, s17
	s_add_u32 s100, s22, s6
	s_addc_u32 s101, s23, s7
	global_load_lds_dwordx4 v128, s[22:23]
	s_nop 1
	s_mov_b32 m0, s30
	s_nop 0
	global_load_lds_dwordx4 v132, s[22:23]
	s_add_u32 s48, s20, 0x40000
	s_addc_u32 s49, s21, 0
	s_add_i32 s50, s40, s29
	s_mov_b32 m0, s50
	s_nop 0
	global_load_lds_dwordx4 v130, s[48:49]
	s_nop 1
	s_add_i32 m0, s50, 0x2000
	s_nop 0
	global_load_lds_dwordx4 v134, s[48:49]
	s_waitcnt vmcnt(8) lgkmcnt(0)
	s_barrier
; #define PG8_STAGE(bufoff, gbase, voff) do { _Pragma("unroll") for (int _i = 0; _i < 2; ++_i) \
;         __builtin_amdgcn_global_load_lds((const unsigned*)((const char*)(gbase) + (voff)[_i]), (PG8_LAS unsigned*)(lds + (bufoff) + ldsw + _i * 8192), 16, 0, 0); } while (0)
; #define PG8_LDA(dst, b, h) do { _Pragma("unroll") for (int m = 0; m < 4; ++m) _Pragma("unroll") for (int k = 0; k < 2; ++k) dst[m][k] = *(const PG8_LAS bf16x8*)(lds + PG8_SA(b, h) + aoff + m * 2048 + k * 1024); } while (0)
; #define PG8_LDB(dst, b, h) do { _Pragma("unroll") for (int n = 0; n < 2; ++n) _Pragma("unroll") for (int k = 0; k < 2; ++k) dst[n][k] = *(const PG8_LAS bf16x8*)(lds + PG8_SB(b, h) + boff + n * 2048 + k * 1024); } while (0)
; #define PG8_MMA(ai, bj, At, Bt) do { __builtin_amdgcn_s_setprio(1); _Pragma("unroll") for (int m = 0; m < 4; ++m) _Pragma("unroll") for (int n = 0; n < 2; ++n) _Pragma("unroll") for (int k = 0; k < 2; ++k) \
;         acc[ai][bj][m][n] = __builtin_amdgcn_mfma_f32_16x16x32_bf16(Bt[n][k], At[m][k], acc[ai][bj][m][n], 0, 0, 0); __builtin_amdgcn_s_setprio(0); } while (0)
; #define PG8_WAIT_V(n) asm volatile("s_waitcnt vmcnt(" #n ")" ::: "memory")
; #define PG8_WAIT_L(n) asm volatile("s_waitcnt lgkmcnt(" #n ")" ::: "memory")
; #define PG8_BAR __builtin_amdgcn_s_barrier()
; #define PG8_SCHED __builtin_amdgcn_sched_barrier(0)
; template <class Epi, class Sched>
; __device__ __forceinline__ void gemm_phase(PG8_LAS unsigned char* lds, const Gemm g, const Sched& S, const Epi& E) {
;     ...
;             PG8_LDA(At, 0, 1); PG8_STAGE(PG8_SA(0, 0), a2, voffA);
;             PG8_BAR; PG8_WAIT_L(0); PG8_MMA(1, 0, At, B0); PG8_BAR; PG8_SCHED;
;             PG8_STAGE(PG8_SB(0, 1), b2 + hstep, voffB);
;             PG8_WAIT_V(6); PG8_BAR; PG8_MMA(1, 1, At, B1); PG8_BAR;
;             PG8_LDB(B0, 1, 0); PG8_SCHED; PG8_LDA(At, 1, 0); PG8_STAGE(PG8_SA(0, 1), a2 + hstep, voffA);
;             PG8_WAIT_L(8); PG8_BAR; PG8_WAIT_L(0); PG8_MMA(0, 0, At, B0); PG8_BAR; PG8_SCHED;
;             PG8_LDB(B1, 1, 1); PG8_STAGE(PG8_SB(1, 0), b3, voffB);
;             PG8_BAR; PG8_WAIT_L(0); PG8_MMA(0, 1, At, B1); PG8_BAR;
	v_mfma_f32_16x16x32_bf16 v[60:63], v[144:147], v[168:171], 0
	v_mfma_f32_16x16x32_bf16 v[56:59], v[160:163], v[168:171], 0
	v_mfma_f32_16x16x32_bf16 v[48:51], v[144:147], v[182:185], 0
	v_mfma_f32_16x16x32_bf16 v[40:43], v[160:163], v[182:185], 0
	v_mfma_f32_16x16x32_bf16 v[32:35], v[144:147], v[194:197], 0
	v_mfma_f32_16x16x32_bf16 v[24:27], v[160:163], v[194:197], 0
	v_mfma_f32_16x16x32_bf16 v[16:19], v[144:147], v[202:205], 0
	v_mfma_f32_16x16x32_bf16 v[8:11], v[160:163], v[202:205], 0
	v_mfma_f32_16x16x32_bf16 v[60:63], v[156:159], v[172:175], v[60:63]
	v_mfma_f32_16x16x32_bf16 v[56:59], v[164:167], v[172:175], v[56:59]
	v_mfma_f32_16x16x32_bf16 v[48:51], v[156:159], v[190:193], v[48:51]
	v_mfma_f32_16x16x32_bf16 v[40:43], v[164:167], v[190:193], v[40:43]
	v_mfma_f32_16x16x32_bf16 v[32:35], v[156:159], v[198:201], v[32:35]
	v_mfma_f32_16x16x32_bf16 v[24:27], v[164:167], v[198:201], v[24:27]
	v_mfma_f32_16x16x32_bf16 v[16:19], v[156:159], v[206:209], v[16:19]
	v_mfma_f32_16x16x32_bf16 v[8:11], v[164:167], v[206:209], v[8:11]
	v_mfma_f32_16x16x32_bf16 v[52:55], v[210:213], v[168:171], 0
	v_mfma_f32_16x16x32_bf16 v[44:47], v[218:221], v[168:171], 0
	v_mfma_f32_16x16x32_bf16 v[36:39], v[210:213], v[182:185], 0
	v_mfma_f32_16x16x32_bf16 v[28:31], v[218:221], v[182:185], 0
	v_mfma_f32_16x16x32_bf16 v[20:23], v[210:213], v[194:197], 0
	v_mfma_f32_16x16x32_bf16 v[12:15], v[218:221], v[194:197], 0
	v_mfma_f32_16x16x32_bf16 v[4:7], v[210:213], v[202:205], 0
	v_mfma_f32_16x16x32_bf16 v[0:3], v[218:221], v[202:205], 0
	v_mfma_f32_16x16x32_bf16 v[52:55], v[214:217], v[172:175], v[52:55]
	v_mfma_f32_16x16x32_bf16 v[44:47], v[222:225], v[172:175], v[44:47]
	v_mfma_f32_16x16x32_bf16 v[36:39], v[214:217], v[190:193], v[36:39]
	v_mfma_f32_16x16x32_bf16 v[28:31], v[222:225], v[190:193], v[28:31]
	v_mfma_f32_16x16x32_bf16 v[20:23], v[214:217], v[198:201], v[20:23]
	v_mfma_f32_16x16x32_bf16 v[12:15], v[222:225], v[198:201], v[12:15]
	v_mfma_f32_16x16x32_bf16 v[4:7], v[214:217], v[206:209], v[4:7]
	v_mfma_f32_16x16x32_bf16 v[0:3], v[222:225], v[206:209], v[0:3]
	s_barrier
	s_add_i32 s48, 0, 0x18000
	v_add_u32_e32 v164, s48, v151
	ds_read_b128 v[144:147], v164
	ds_read_b128 v[156:159], v164 offset:1024
	ds_read_b128 v[160:163], v164 offset:2048
	ds_read_b128 v[164:167], v164 offset:3072
	s_add_u32 s22, s22, 0x40000
	s_addc_u32 s23, s23, 0
	s_mov_b32 m0, s31
	ds_read_b128 v[168:171], v154 offset:32768
	ds_read_b128 v[172:175], v154 offset:33792
	ds_read_b128 v[182:185], v154 offset:34816
	ds_read_b128 v[190:193], v154 offset:35840
	ds_read_b128 v[194:197], v154 offset:36864
	ds_read_b128 v[198:201], v154 offset:37888
	ds_read_b128 v[202:205], v154 offset:38912
	ds_read_b128 v[206:209], v154 offset:39936
	global_load_lds_dwordx4 v128, s[22:23]
	s_nop 1
	s_mov_b32 m0, s34
	s_nop 0
	global_load_lds_dwordx4 v132, s[22:23]
	s_add_i32 s22, 0, 0x1c000
	v_add_u32_e32 v179, s22, v151
	s_waitcnt lgkmcnt(12)
	ds_read_b128 v[210:213], v179
	ds_read_b128 v[214:217], v179 offset:1024
	ds_read_b128 v[218:221], v179 offset:2048
	ds_read_b128 v[222:225], v179 offset:3072
	s_waitcnt vmcnt(8) lgkmcnt(0)
	s_barrier
	v_mfma_f32_16x16x32_bf16 v[124:127], v[144:147], v[168:171], v[124:127]
	v_mfma_f32_16x16x32_bf16 v[120:123], v[160:163], v[168:171], v[120:123]
	v_mfma_f32_16x16x32_bf16 v[112:115], v[144:147], v[182:185], v[112:115]
	v_mfma_f32_16x16x32_bf16 v[104:107], v[160:163], v[182:185], v[104:107]
	v_mfma_f32_16x16x32_bf16 v[96:99], v[144:147], v[194:197], v[96:99]
	v_mfma_f32_16x16x32_bf16 v[88:91], v[160:163], v[194:197], v[88:91]
	v_mfma_f32_16x16x32_bf16 v[80:83], v[144:147], v[202:205], v[80:83]
	v_mfma_f32_16x16x32_bf16 v[72:75], v[160:163], v[202:205], v[72:75]
	v_mfma_f32_16x16x32_bf16 v[124:127], v[156:159], v[172:175], v[124:127]
	v_mfma_f32_16x16x32_bf16 v[120:123], v[164:167], v[172:175], v[120:123]
	v_mfma_f32_16x16x32_bf16 v[112:115], v[156:159], v[190:193], v[112:115]
	v_mfma_f32_16x16x32_bf16 v[104:107], v[164:167], v[190:193], v[104:107]
	v_mfma_f32_16x16x32_bf16 v[96:99], v[156:159], v[198:201], v[96:99]
	v_mfma_f32_16x16x32_bf16 v[88:91], v[164:167], v[198:201], v[88:91]
	v_mfma_f32_16x16x32_bf16 v[80:83], v[156:159], v[206:209], v[80:83]
	v_mfma_f32_16x16x32_bf16 v[72:75], v[164:167], v[206:209], v[72:75]
	v_mfma_f32_16x16x32_bf16 v[116:119], v[210:213], v[168:171], v[116:119]
	v_mfma_f32_16x16x32_bf16 v[108:111], v[218:221], v[168:171], v[108:111]
	v_mfma_f32_16x16x32_bf16 v[100:103], v[210:213], v[182:185], v[100:103]
	v_mfma_f32_16x16x32_bf16 v[92:95], v[218:221], v[182:185], v[92:95]
	v_mfma_f32_16x16x32_bf16 v[84:87], v[210:213], v[194:197], v[84:87]
	v_mfma_f32_16x16x32_bf16 v[76:79], v[218:221], v[194:197], v[76:79]
	v_mfma_f32_16x16x32_bf16 v[68:71], v[210:213], v[202:205], v[68:71]
	v_mfma_f32_16x16x32_bf16 v[64:67], v[218:221], v[202:205], v[64:67]
	v_mfma_f32_16x16x32_bf16 v[116:119], v[214:217], v[172:175], v[116:119]
	v_mfma_f32_16x16x32_bf16 v[108:111], v[222:225], v[172:175], v[108:111]
	v_mfma_f32_16x16x32_bf16 v[100:103], v[214:217], v[190:193], v[100:103]
	v_mfma_f32_16x16x32_bf16 v[92:95], v[222:225], v[190:193], v[92:95]
	v_mfma_f32_16x16x32_bf16 v[84:87], v[214:217], v[198:201], v[84:87]
	v_mfma_f32_16x16x32_bf16 v[76:79], v[222:225], v[198:201], v[76:79]
	v_mfma_f32_16x16x32_bf16 v[68:71], v[214:217], v[206:209], v[68:71]
	v_mfma_f32_16x16x32_bf16 v[64:67], v[222:225], v[206:209], v[64:67]
	s_barrier
; #define PG8_STAGE(bufoff, gbase, voff) do { _Pragma("unroll") for (int _i = 0; _i < 2; ++_i) \
;         __builtin_amdgcn_global_load_lds((const unsigned*)((const char*)(gbase) + (voff)[_i]), (PG8_LAS unsigned*)(lds + (bufoff) + ldsw + _i * 8192), 16, 0, 0); } while (0)
; #define PG8_LDA(dst, b, h) do { _Pragma("unroll") for (int m = 0; m < 4; ++m) _Pragma("unroll") for (int k = 0; k < 2; ++k) dst[m][k] = *(const PG8_LAS bf16x8*)(lds + PG8_SA(b, h) + aoff + m * 2048 + k * 1024); } while (0)
; #define PG8_WAIT_V(n) asm volatile("s_waitcnt vmcnt(" #n ")" ::: "memory")
; #define PG8_BAR __builtin_amdgcn_s_barrier()
; template <class Epi, class Sched>
; __device__ __forceinline__ void gemm_phase(PG8_LAS unsigned char* lds, const Gemm g, const Sched& S, const Epi& E) {
;     ...
;             const bool last = (t == nt - 2);
;             const char* a1 = cA + (size_t)(t + 1) * kstep;
;             const char* a2 = last ? nA : cA + (size_t)(t + 2) * kstep; const char* b2 = last ? nB : cB + (size_t)(t + 2) * kstep;
;             const char* a3 = a2 + kstep; const char* b3 = b2 + kstep;
;             if (last && has_next) S.a_ready(nxt);
;             PG8_LDB(B0, 0, 0); PG8_SCHED; PG8_LDA(At, 0, 0); PG8_STAGE(PG8_SA(1, 1), a1 + hstep, voffA);
;             PG8_WAIT_L(8); PG8_BAR; PG8_WAIT_L(0); PG8_MMA(0, 0, At, B0); PG8_BAR; PG8_SCHED;
;             PG8_LDB(B1, 0, 1); PG8_STAGE(PG8_SB(0, 0), b2, voffB);
;             PG8_BAR; PG8_WAIT_L(0); PG8_MMA(0, 1, At, B1); PG8_BAR;
;             PG8_LDA(At, 0, 1); PG8_STAGE(PG8_SA(0, 0), a2, voffA);
;             PG8_BAR; PG8_WAIT_L(0); PG8_MMA(1, 0, At, B0); PG8_BAR; PG8_SCHED;
;             PG8_STAGE(PG8_SB(0, 1), b2 + hstep, voffB);
;             PG8_WAIT_V(6); PG8_BAR; PG8_MMA(1, 1, At, B1); PG8_BAR;
;             PG8_LDB(B0, 1, 0); PG8_SCHED; PG8_LDA(At, 1, 0); PG8_STAGE(PG8_SA(0, 1), a2 + hstep, voffA);
;             PG8_WAIT_L(8); PG8_BAR; PG8_WAIT_L(0); PG8_MMA(0, 0, At, B0); PG8_BAR; PG8_SCHED;
;             PG8_LDB(B1, 1, 1); PG8_STAGE(PG8_SB(1, 0), b3, voffB);
;             PG8_BAR; PG8_WAIT_L(0); PG8_MMA(0, 1, At, B1); PG8_BAR;
;             PG8_LDA(At, 1, 1); PG8_STAGE(PG8_SA(1, 0), a3, voffA);
;             PG8_BAR; PG8_WAIT_L(0); PG8_MMA(1, 0, At, B0); PG8_BAR; PG8_SCHED;
;             PG8_STAGE(PG8_SB(1, 1), b3 + hstep, voffB);
;             PG8_WAIT_V(6); PG8_BAR; PG8_MMA(1, 1, At, B1); PG8_BAR;
	ds_read_b128 v[168:171], v154 offset:49152
	ds_read_b128 v[172:175], v154 offset:50176
	ds_read_b128 v[182:185], v154 offset:51200
	ds_read_b128 v[190:193], v154 offset:52224
	ds_read_b128 v[194:197], v154 offset:53248
	ds_read_b128 v[198:201], v154 offset:54272
	ds_read_b128 v[202:205], v154 offset:55296
	ds_read_b128 v[206:209], v154 offset:56320
	s_add_i32 s23, s48, s29
	s_mov_b32 m0, s23
	s_nop 0
	global_load_lds_dwordx4 v130, s[98:99]
	s_nop 1
	s_add_i32 m0, s23, 0x2000
	s_nop 0
	global_load_lds_dwordx4 v134, s[98:99]
	s_nop 1
	s_mov_b32 m0, s36
	s_nop 0
	global_load_lds_dwordx4 v128, s[100:101]
	s_nop 1
	s_mov_b32 m0, s37
	s_nop 0
	global_load_lds_dwordx4 v132, s[100:101]
	s_add_u32 s20, s20, 0x40080
	s_addc_u32 s21, s21, 0
	s_add_i32 s22, s22, s29
	s_mov_b32 m0, s22
	s_nop 0
	global_load_lds_dwordx4 v130, s[20:21]
	s_nop 1
	s_add_i32 m0, s22, 0x2000
	s_nop 0
	global_load_lds_dwordx4 v134, s[20:21]
	s_waitcnt vmcnt(8) lgkmcnt(0)
	s_barrier
	v_mfma_f32_16x16x32_bf16 v[60:63], v[144:147], v[168:171], v[60:63]
	v_mfma_f32_16x16x32_bf16 v[56:59], v[160:163], v[168:171], v[56:59]
	v_mfma_f32_16x16x32_bf16 v[48:51], v[144:147], v[182:185], v[48:51]
	v_mfma_f32_16x16x32_bf16 v[40:43], v[160:163], v[182:185], v[40:43]
	v_mfma_f32_16x16x32_bf16 v[32:35], v[144:147], v[194:197], v[32:35]
	v_mfma_f32_16x16x32_bf16 v[24:27], v[160:163], v[194:197], v[24:27]
	v_mfma_f32_16x16x32_bf16 v[16:19], v[144:147], v[202:205], v[16:19]
	v_mfma_f32_16x16x32_bf16 v[8:11], v[160:163], v[202:205], v[8:11]
	v_mfma_f32_16x16x32_bf16 v[60:63], v[156:159], v[172:175], v[60:63]
	v_mfma_f32_16x16x32_bf16 v[56:59], v[164:167], v[172:175], v[56:59]
	v_mfma_f32_16x16x32_bf16 v[48:51], v[156:159], v[190:193], v[48:51]
	v_mfma_f32_16x16x32_bf16 v[40:43], v[164:167], v[190:193], v[40:43]
	v_mfma_f32_16x16x32_bf16 v[32:35], v[156:159], v[198:201], v[32:35]
	v_mfma_f32_16x16x32_bf16 v[24:27], v[164:167], v[198:201], v[24:27]
	v_mfma_f32_16x16x32_bf16 v[16:19], v[156:159], v[206:209], v[16:19]
	v_mfma_f32_16x16x32_bf16 v[8:11], v[164:167], v[206:209], v[8:11]
	v_mfma_f32_16x16x32_bf16 v[52:55], v[210:213], v[168:171], v[52:55]
	v_mfma_f32_16x16x32_bf16 v[44:47], v[218:221], v[168:171], v[44:47]
	v_mfma_f32_16x16x32_bf16 v[36:39], v[210:213], v[182:185], v[36:39]
	v_mfma_f32_16x16x32_bf16 v[28:31], v[218:221], v[182:185], v[28:31]
	v_mfma_f32_16x16x32_bf16 v[20:23], v[210:213], v[194:197], v[20:23]
	v_mfma_f32_16x16x32_bf16 v[12:15], v[218:221], v[194:197], v[12:15]
	v_mfma_f32_16x16x32_bf16 v[4:7], v[210:213], v[202:205], v[4:7]
	v_mfma_f32_16x16x32_bf16 v[0:3], v[218:221], v[202:205], v[0:3]
	v_mfma_f32_16x16x32_bf16 v[52:55], v[214:217], v[172:175], v[52:55]
	v_mfma_f32_16x16x32_bf16 v[44:47], v[222:225], v[172:175], v[44:47]
	v_mfma_f32_16x16x32_bf16 v[36:39], v[214:217], v[190:193], v[36:39]
	v_mfma_f32_16x16x32_bf16 v[28:31], v[222:225], v[190:193], v[28:31]
	v_mfma_f32_16x16x32_bf16 v[20:23], v[214:217], v[198:201], v[20:23]
	v_mfma_f32_16x16x32_bf16 v[12:15], v[222:225], v[198:201], v[12:15]
	v_mfma_f32_16x16x32_bf16 v[4:7], v[214:217], v[206:209], v[4:7]
	v_mfma_f32_16x16x32_bf16 v[0:3], v[222:225], v[206:209], v[0:3]
	s_barrier
	s_add_i32 s47, s47, 2
	s_add_u32 s18, s18, 0x100
	s_addc_u32 s19, s19, 0
	s_add_u32 s45, s45, 0x100
	s_addc_u32 s46, s46, 0
	s_cmp_gt_u32 s47, 13
.LBB0_991:
	ds_read_b128 v[144:147], v153
	ds_read_b128 v[156:159], v153 offset:1024
	ds_read_b128 v[160:163], v153 offset:2048
	ds_read_b128 v[164:167], v153 offset:3072
	s_add_u32 s20, s18, 0xfffc0080
	s_addc_u32 s21, s19, -1
	s_cmp_eq_u32 s47, 12
	s_cselect_b32 s23, s11, s21
	s_cselect_b32 s22, s43, s20
	s_cselect_b32 s21, s9, s46
	s_cselect_b32 s20, s44, s45
	s_add_i32 m0, s17, 0xc000
	ds_read_b128 v[168:171], v154
	ds_read_b128 v[172:175], v154 offset:1024
	ds_read_b128 v[182:185], v154 offset:2048
	ds_read_b128 v[190:193], v154 offset:3072
	ds_read_b128 v[194:197], v154 offset:4096
	ds_read_b128 v[198:201], v154 offset:5120
	ds_read_b128 v[202:205], v154 offset:6144
	ds_read_b128 v[206:209], v154 offset:7168
	global_load_lds_dwordx4 v136, s[18:19]
	s_nop 1
	s_add_i32 m0, s17, 0xe000
	s_nop 0
	global_load_lds_dwordx4 v138, s[18:19]
	s_waitcnt lgkmcnt(12)
	ds_read_b128 v[210:213], v155
	ds_read_b128 v[214:217], v155 offset:1024
	ds_read_b128 v[218:221], v155 offset:2048
	ds_read_b128 v[222:225], v155 offset:3072
	s_waitcnt vmcnt(8) lgkmcnt(0)
	s_barrier
	v_mfma_f32_16x16x32_bf16 v[124:127], v[144:147], v[168:171], v[124:127]
	v_mfma_f32_16x16x32_bf16 v[120:123], v[160:163], v[168:171], v[120:123]
	v_mfma_f32_16x16x32_bf16 v[112:115], v[144:147], v[182:185], v[112:115]
	v_mfma_f32_16x16x32_bf16 v[104:107], v[160:163], v[182:185], v[104:107]
	v_mfma_f32_16x16x32_bf16 v[96:99], v[144:147], v[194:197], v[96:99]
	v_mfma_f32_16x16x32_bf16 v[88:91], v[160:163], v[194:197], v[88:91]
	v_mfma_f32_16x16x32_bf16 v[80:83], v[144:147], v[202:205], v[80:83]
	v_mfma_f32_16x16x32_bf16 v[72:75], v[160:163], v[202:205], v[72:75]
	v_mfma_f32_16x16x32_bf16 v[124:127], v[156:159], v[172:175], v[124:127]
	v_mfma_f32_16x16x32_bf16 v[120:123], v[164:167], v[172:175], v[120:123]
	v_mfma_f32_16x16x32_bf16 v[112:115], v[156:159], v[190:193], v[112:115]
	v_mfma_f32_16x16x32_bf16 v[104:107], v[164:167], v[190:193], v[104:107]
	v_mfma_f32_16x16x32_bf16 v[96:99], v[156:159], v[198:201], v[96:99]
	v_mfma_f32_16x16x32_bf16 v[88:91], v[164:167], v[198:201], v[88:91]
	v_mfma_f32_16x16x32_bf16 v[80:83], v[156:159], v[206:209], v[80:83]
	v_mfma_f32_16x16x32_bf16 v[72:75], v[164:167], v[206:209], v[72:75]
	v_mfma_f32_16x16x32_bf16 v[116:119], v[210:213], v[168:171], v[116:119]
	v_mfma_f32_16x16x32_bf16 v[108:111], v[218:221], v[168:171], v[108:111]
	v_mfma_f32_16x16x32_bf16 v[100:103], v[210:213], v[182:185], v[100:103]
	v_mfma_f32_16x16x32_bf16 v[92:95], v[218:221], v[182:185], v[92:95]
	v_mfma_f32_16x16x32_bf16 v[84:87], v[210:213], v[194:197], v[84:87]
	v_mfma_f32_16x16x32_bf16 v[76:79], v[218:221], v[194:197], v[76:79]
	v_mfma_f32_16x16x32_bf16 v[68:71], v[210:213], v[202:205], v[68:71]
	v_mfma_f32_16x16x32_bf16 v[64:67], v[218:221], v[202:205], v[64:67]
	v_mfma_f32_16x16x32_bf16 v[116:119], v[214:217], v[172:175], v[116:119]
	v_mfma_f32_16x16x32_bf16 v[108:111], v[222:225], v[172:175], v[108:111]
	v_mfma_f32_16x16x32_bf16 v[100:103], v[214:217], v[190:193], v[100:103]
	v_mfma_f32_16x16x32_bf16 v[92:95], v[222:225], v[190:193], v[92:95]
	v_mfma_f32_16x16x32_bf16 v[84:87], v[214:217], v[198:201], v[84:87]
	v_mfma_f32_16x16x32_bf16 v[76:79], v[222:225], v[198:201], v[76:79]
	v_mfma_f32_16x16x32_bf16 v[68:71], v[214:217], v[206:209], v[68:71]
	v_mfma_f32_16x16x32_bf16 v[64:67], v[222:225], v[206:209], v[64:67]
	s_barrier
; #define PG8_STAGE(bufoff, gbase, voff) do { _Pragma("unroll") for (int _i = 0; _i < 2; ++_i) \
;         __builtin_amdgcn_global_load_lds((const unsigned*)((const char*)(gbase) + (voff)[_i]), (PG8_LAS unsigned*)(lds + (bufoff) + ldsw + _i * 8192), 16, 0, 0); } while (0)
; #define PG8_LDA(dst, b, h) do { _Pragma("unroll") for (int m = 0; m < 4; ++m) _Pragma("unroll") for (int k = 0; k < 2; ++k) dst[m][k] = *(const PG8_LAS bf16x8*)(lds + PG8_SA(b, h) + aoff + m * 2048 + k * 1024); } while (0)
; #define PG8_LDB(dst, b, h) do { _Pragma("unroll") for (int n = 0; n < 2; ++n) _Pragma("unroll") for (int k = 0; k < 2; ++k) dst[n][k] = *(const PG8_LAS bf16x8*)(lds + PG8_SB(b, h) + boff + n * 2048 + k * 1024); } while (0)
; #define PG8_MMA(ai, bj, At, Bt) do { __builtin_amdgcn_s_setprio(1); _Pragma("unroll") for (int m = 0; m < 4; ++m) _Pragma("unroll") for (int n = 0; n < 2; ++n) _Pragma("unroll") for (int k = 0; k < 2; ++k) \
;         acc[ai][bj][m][n] = __builtin_amdgcn_mfma_f32_16x16x32_bf16(Bt[n][k], At[m][k], acc[ai][bj][m][n], 0, 0, 0); __builtin_amdgcn_s_setprio(0); } while (0)
; #define PG8_WAIT_V(n) asm volatile("s_waitcnt vmcnt(" #n ")" ::: "memory")
; #define PG8_WAIT_L(n) asm volatile("s_waitcnt lgkmcnt(" #n ")" ::: "memory")
; #define PG8_BAR __builtin_amdgcn_s_barrier()
; #define PG8_SCHED __builtin_amdgcn_sched_barrier(0)
; template <class Epi, class Sched>
; __device__ __forceinline__ void gemm_phase(PG8_LAS unsigned char* lds, const Gemm g, const Sched& S, const Epi& E) {
;     ...
;             PG8_LDA(At, 0, 1); PG8_STAGE(PG8_SA(0, 0), a2, voffA);
;             PG8_BAR; PG8_WAIT_L(0); PG8_MMA(1, 0, At, B0); PG8_BAR; PG8_SCHED;
;             PG8_STAGE(PG8_SB(0, 1), b2 + hstep, voffB);
;             PG8_WAIT_V(6); PG8_BAR; PG8_MMA(1, 1, At, B1); PG8_BAR;
;             PG8_LDB(B0, 1, 0); PG8_SCHED; PG8_LDA(At, 1, 0); PG8_STAGE(PG8_SA(0, 1), a2 + hstep, voffA);
;             PG8_WAIT_L(8); PG8_BAR; PG8_WAIT_L(0); PG8_MMA(0, 0, At, B0); PG8_BAR; PG8_SCHED;
;             PG8_LDB(B1, 1, 1); PG8_STAGE(PG8_SB(1, 0), b3, voffB);
;             PG8_BAR; PG8_WAIT_L(0); PG8_MMA(0, 1, At, B1); PG8_BAR;
	ds_read_b128 v[168:171], v154 offset:16384
	ds_read_b128 v[172:175], v154 offset:17408
	ds_read_b128 v[182:185], v154 offset:18432
	ds_read_b128 v[190:193], v154 offset:19456
	ds_read_b128 v[194:197], v154 offset:20480
	ds_read_b128 v[198:201], v154 offset:21504
	ds_read_b128 v[202:205], v154 offset:22528
	ds_read_b128 v[206:209], v154 offset:23552
	s_add_i32 s48, s39, s29
	s_add_u32 s98, s20, s6
	s_addc_u32 s99, s21, s7
	s_mov_b32 m0, s48
	s_nop 0
	global_load_lds_dwordx4 v130, s[20:21]
	s_nop 1
	s_add_i32 m0, s48, 0x2000
	s_nop 0
	global_load_lds_dwordx4 v134, s[20:21]
	s_nop 1
	s_mov_b32 m0, s17
	s_add_u32 s100, s22, s6
	s_addc_u32 s101, s23, s7
	global_load_lds_dwordx4 v128, s[22:23]
	s_nop 1
	s_mov_b32 m0, s30
	s_nop 0
	global_load_lds_dwordx4 v132, s[22:23]
	s_add_u32 s48, s20, 0x40000
	s_addc_u32 s49, s21, 0
	s_add_i32 s50, s40, s29
	s_mov_b32 m0, s50
	s_nop 0
	global_load_lds_dwordx4 v130, s[48:49]
	s_nop 1
	s_add_i32 m0, s50, 0x2000
	s_nop 0
	global_load_lds_dwordx4 v134, s[48:49]
	s_waitcnt vmcnt(8) lgkmcnt(0)
	s_barrier
	v_mfma_f32_16x16x32_bf16 v[60:63], v[144:147], v[168:171], v[60:63]
	v_mfma_f32_16x16x32_bf16 v[56:59], v[160:163], v[168:171], v[56:59]
	v_mfma_f32_16x16x32_bf16 v[48:51], v[144:147], v[182:185], v[48:51]
	v_mfma_f32_16x16x32_bf16 v[40:43], v[160:163], v[182:185], v[40:43]
	v_mfma_f32_16x16x32_bf16 v[32:35], v[144:147], v[194:197], v[32:35]
	v_mfma_f32_16x16x32_bf16 v[24:27], v[160:163], v[194:197], v[24:27]
	v_mfma_f32_16x16x32_bf16 v[16:19], v[144:147], v[202:205], v[16:19]
	v_mfma_f32_16x16x32_bf16 v[8:11], v[160:163], v[202:205], v[8:11]
	v_mfma_f32_16x16x32_bf16 v[60:63], v[156:159], v[172:175], v[60:63]
	v_mfma_f32_16x16x32_bf16 v[56:59], v[164:167], v[172:175], v[56:59]
	v_mfma_f32_16x16x32_bf16 v[48:51], v[156:159], v[190:193], v[48:51]
	v_mfma_f32_16x16x32_bf16 v[40:43], v[164:167], v[190:193], v[40:43]
	v_mfma_f32_16x16x32_bf16 v[32:35], v[156:159], v[198:201], v[32:35]
	v_mfma_f32_16x16x32_bf16 v[24:27], v[164:167], v[198:201], v[24:27]
	v_mfma_f32_16x16x32_bf16 v[16:19], v[156:159], v[206:209], v[16:19]
	v_mfma_f32_16x16x32_bf16 v[8:11], v[164:167], v[206:209], v[8:11]
	v_mfma_f32_16x16x32_bf16 v[52:55], v[210:213], v[168:171], v[52:55]
	v_mfma_f32_16x16x32_bf16 v[44:47], v[218:221], v[168:171], v[44:47]
	v_mfma_f32_16x16x32_bf16 v[36:39], v[210:213], v[182:185], v[36:39]
	v_mfma_f32_16x16x32_bf16 v[28:31], v[218:221], v[182:185], v[28:31]
	v_mfma_f32_16x16x32_bf16 v[20:23], v[210:213], v[194:197], v[20:23]
	v_mfma_f32_16x16x32_bf16 v[12:15], v[218:221], v[194:197], v[12:15]
	v_mfma_f32_16x16x32_bf16 v[4:7], v[210:213], v[202:205], v[4:7]
	v_mfma_f32_16x16x32_bf16 v[0:3], v[218:221], v[202:205], v[0:3]
	v_mfma_f32_16x16x32_bf16 v[52:55], v[214:217], v[172:175], v[52:55]
	v_mfma_f32_16x16x32_bf16 v[44:47], v[222:225], v[172:175], v[44:47]
	v_mfma_f32_16x16x32_bf16 v[36:39], v[214:217], v[190:193], v[36:39]
	v_mfma_f32_16x16x32_bf16 v[28:31], v[222:225], v[190:193], v[28:31]
	v_mfma_f32_16x16x32_bf16 v[20:23], v[214:217], v[198:201], v[20:23]
	v_mfma_f32_16x16x32_bf16 v[12:15], v[222:225], v[198:201], v[12:15]
	v_mfma_f32_16x16x32_bf16 v[4:7], v[214:217], v[206:209], v[4:7]
	v_mfma_f32_16x16x32_bf16 v[0:3], v[222:225], v[206:209], v[0:3]
	s_barrier
	s_add_i32 s48, 0, 0x18000
	v_add_u32_e32 v164, s48, v151
	ds_read_b128 v[144:147], v164
	ds_read_b128 v[156:159], v164 offset:1024
	ds_read_b128 v[160:163], v164 offset:2048
	ds_read_b128 v[164:167], v164 offset:3072
	s_add_u32 s22, s22, 0x40000
	s_addc_u32 s23, s23, 0
	s_mov_b32 m0, s31
	ds_read_b128 v[168:171], v154 offset:32768
	ds_read_b128 v[172:175], v154 offset:33792
	ds_read_b128 v[182:185], v154 offset:34816
	ds_read_b128 v[190:193], v154 offset:35840
	ds_read_b128 v[194:197], v154 offset:36864
	ds_read_b128 v[198:201], v154 offset:37888
	ds_read_b128 v[202:205], v154 offset:38912
	ds_read_b128 v[206:209], v154 offset:39936
	global_load_lds_dwordx4 v128, s[22:23]
	s_nop 1
	s_mov_b32 m0, s34
	s_nop 0
	global_load_lds_dwordx4 v132, s[22:23]
	s_add_i32 s22, 0, 0x1c000
	v_add_u32_e32 v179, s22, v151
	s_waitcnt lgkmcnt(12)
	ds_read_b128 v[210:213], v179
	ds_read_b128 v[214:217], v179 offset:1024
	ds_read_b128 v[218:221], v179 offset:2048
	ds_read_b128 v[222:225], v179 offset:3072
	s_waitcnt vmcnt(8) lgkmcnt(0)
	s_barrier
	v_mfma_f32_16x16x32_bf16 v[124:127], v[144:147], v[168:171], v[124:127]
	v_mfma_f32_16x16x32_bf16 v[120:123], v[160:163], v[168:171], v[120:123]
	v_mfma_f32_16x16x32_bf16 v[112:115], v[144:147], v[182:185], v[112:115]
	v_mfma_f32_16x16x32_bf16 v[104:107], v[160:163], v[182:185], v[104:107]
	v_mfma_f32_16x16x32_bf16 v[96:99], v[144:147], v[194:197], v[96:99]
	v_mfma_f32_16x16x32_bf16 v[88:91], v[160:163], v[194:197], v[88:91]
	v_mfma_f32_16x16x32_bf16 v[80:83], v[144:147], v[202:205], v[80:83]
	v_mfma_f32_16x16x32_bf16 v[72:75], v[160:163], v[202:205], v[72:75]
	v_mfma_f32_16x16x32_bf16 v[124:127], v[156:159], v[172:175], v[124:127]
	v_mfma_f32_16x16x32_bf16 v[120:123], v[164:167], v[172:175], v[120:123]
	v_mfma_f32_16x16x32_bf16 v[112:115], v[156:159], v[190:193], v[112:115]
	v_mfma_f32_16x16x32_bf16 v[104:107], v[164:167], v[190:193], v[104:107]
	v_mfma_f32_16x16x32_bf16 v[96:99], v[156:159], v[198:201], v[96:99]
	v_mfma_f32_16x16x32_bf16 v[88:91], v[164:167], v[198:201], v[88:91]
	v_mfma_f32_16x16x32_bf16 v[80:83], v[156:159], v[206:209], v[80:83]
	v_mfma_f32_16x16x32_bf16 v[72:75], v[164:167], v[206:209], v[72:75]
	v_mfma_f32_16x16x32_bf16 v[116:119], v[210:213], v[168:171], v[116:119]
	v_mfma_f32_16x16x32_bf16 v[108:111], v[218:221], v[168:171], v[108:111]
	v_mfma_f32_16x16x32_bf16 v[100:103], v[210:213], v[182:185], v[100:103]
	v_mfma_f32_16x16x32_bf16 v[92:95], v[218:221], v[182:185], v[92:95]
	v_mfma_f32_16x16x32_bf16 v[84:87], v[210:213], v[194:197], v[84:87]
	v_mfma_f32_16x16x32_bf16 v[76:79], v[218:221], v[194:197], v[76:79]
	v_mfma_f32_16x16x32_bf16 v[68:71], v[210:213], v[202:205], v[68:71]
	v_mfma_f32_16x16x32_bf16 v[64:67], v[218:221], v[202:205], v[64:67]
	v_mfma_f32_16x16x32_bf16 v[116:119], v[214:217], v[172:175], v[116:119]
	v_mfma_f32_16x16x32_bf16 v[108:111], v[222:225], v[172:175], v[108:111]
	v_mfma_f32_16x16x32_bf16 v[100:103], v[214:217], v[190:193], v[100:103]
	v_mfma_f32_16x16x32_bf16 v[92:95], v[222:225], v[190:193], v[92:95]
	v_mfma_f32_16x16x32_bf16 v[84:87], v[214:217], v[198:201], v[84:87]
	v_mfma_f32_16x16x32_bf16 v[76:79], v[222:225], v[198:201], v[76:79]
	v_mfma_f32_16x16x32_bf16 v[68:71], v[214:217], v[206:209], v[68:71]
	v_mfma_f32_16x16x32_bf16 v[64:67], v[222:225], v[206:209], v[64:67]
	s_barrier
; #define PG8_STAGE(bufoff, gbase, voff) do { _Pragma("unroll") for (int _i = 0; _i < 2; ++_i) \
;         __builtin_amdgcn_global_load_lds((const unsigned*)((const char*)(gbase) + (voff)[_i]), (PG8_LAS unsigned*)(lds + (bufoff) + ldsw + _i * 8192), 16, 0, 0); } while (0)
; #define PG8_LDA(dst, b, h) do { _Pragma("unroll") for (int m = 0; m < 4; ++m) _Pragma("unroll") for (int k = 0; k < 2; ++k) dst[m][k] = *(const PG8_LAS bf16x8*)(lds + PG8_SA(b, h) + aoff + m * 2048 + k * 1024); } while (0)
; #define PG8_MMA(ai, bj, At, Bt) do { __builtin_amdgcn_s_setprio(1); _Pragma("unroll") for (int m = 0; m < 4; ++m) _Pragma("unroll") for (int n = 0; n < 2; ++n) _Pragma("unroll") for (int k = 0; k < 2; ++k) \
;         acc[ai][bj][m][n] = __builtin_amdgcn_mfma_f32_16x16x32_bf16(Bt[n][k], At[m][k], acc[ai][bj][m][n], 0, 0, 0); __builtin_amdgcn_s_setprio(0); } while (0)
; #define PG8_WAIT_V(n) asm volatile("s_waitcnt vmcnt(" #n ")" ::: "memory")
; #define PG8_WAIT_L(n) asm volatile("s_waitcnt lgkmcnt(" #n ")" ::: "memory")
; #define PG8_BAR __builtin_amdgcn_s_barrier()
; #define PG8_SCHED __builtin_amdgcn_sched_barrier(0)
;     __device__ __forceinline__ void operator()(const f32x4 (&acc)[2][2][4][2], const Unit& u, int wr, int wc, int fr, int fq) const {
;         const int row0 = u.pm * BM + wr * 64 + fr, col0 = u.pn * BM + wc * 32 + 8 * fq;
; #pragma unroll
;         for (int ai = 0; ai < 2; ++ai)
; #pragma unroll
;             for (int m = 0; m < 4; ++m) { const size_t r = (size_t)(row0 + ai * HALF + m * 16); bf16_t* rowp = O + r * ldc + col0; const bf16_t* gp = G + r * ldg + col0;
; #pragma unroll
;                 for (int bj = 0; bj < 2; ++bj) { const u32x4 gw = *(const u32x4*)(gp + bj * HALF);
; template <class Epi, class Sched>
; __device__ __forceinline__ void gemm_phase(PG8_LAS unsigned char* lds, const Gemm g, const Sched& S, const Epi& E) {
;     ...
;             PG8_LDA(At, 1, 1); PG8_STAGE(PG8_SA(1, 0), a3, voffA);
;             PG8_BAR; PG8_WAIT_L(0); PG8_MMA(1, 0, At, B0); PG8_BAR; PG8_SCHED;
;             PG8_STAGE(PG8_SB(1, 1), b3 + hstep, voffB);
;             PG8_WAIT_V(6); PG8_BAR; PG8_MMA(1, 1, At, B1); PG8_BAR;
	ds_read_b128 v[168:171], v154 offset:49152
	ds_read_b128 v[172:175], v154 offset:50176
	ds_read_b128 v[182:185], v154 offset:51200
	ds_read_b128 v[190:193], v154 offset:52224
	ds_read_b128 v[194:197], v154 offset:53248
	ds_read_b128 v[198:201], v154 offset:54272
	ds_read_b128 v[202:205], v154 offset:55296
	ds_read_b128 v[206:209], v154 offset:56320
	s_add_i32 s23, s48, s29
	s_mov_b32 m0, s23
	s_nop 0
	global_load_lds_dwordx4 v130, s[98:99]
	s_nop 1
	s_add_i32 m0, s23, 0x2000
	s_nop 0
	global_load_lds_dwordx4 v134, s[98:99]
	s_nop 1
	s_mov_b32 m0, s36
	s_nop 0
	global_load_lds_dwordx4 v128, s[100:101]
	s_nop 1
	s_mov_b32 m0, s37
	s_nop 0
	global_load_lds_dwordx4 v132, s[100:101]
	s_add_u32 s20, s20, 0x40080
	s_addc_u32 s21, s21, 0
	s_add_i32 s22, s22, s29
	s_mov_b32 m0, s22
	s_nop 0
	global_load_lds_dwordx4 v130, s[20:21]
	s_nop 1
	s_add_i32 m0, s22, 0x2000
	s_nop 0
	global_load_lds_dwordx4 v134, s[20:21]
	s_waitcnt vmcnt(8) lgkmcnt(0)
	s_barrier
	v_mfma_f32_16x16x32_bf16 v[60:63], v[144:147], v[168:171], v[60:63]
	v_mfma_f32_16x16x32_bf16 v[56:59], v[160:163], v[168:171], v[56:59]
	v_mfma_f32_16x16x32_bf16 v[48:51], v[144:147], v[182:185], v[48:51]
	v_mfma_f32_16x16x32_bf16 v[40:43], v[160:163], v[182:185], v[40:43]
	v_mfma_f32_16x16x32_bf16 v[32:35], v[144:147], v[194:197], v[32:35]
	v_mfma_f32_16x16x32_bf16 v[24:27], v[160:163], v[194:197], v[24:27]
	v_mfma_f32_16x16x32_bf16 v[16:19], v[144:147], v[202:205], v[16:19]
	v_mfma_f32_16x16x32_bf16 v[8:11], v[160:163], v[202:205], v[8:11]
	v_mfma_f32_16x16x32_bf16 v[60:63], v[156:159], v[172:175], v[60:63]
	v_mfma_f32_16x16x32_bf16 v[56:59], v[164:167], v[172:175], v[56:59]
	v_mfma_f32_16x16x32_bf16 v[48:51], v[156:159], v[190:193], v[48:51]
	v_mfma_f32_16x16x32_bf16 v[40:43], v[164:167], v[190:193], v[40:43]
	v_mfma_f32_16x16x32_bf16 v[32:35], v[156:159], v[198:201], v[32:35]
	v_mfma_f32_16x16x32_bf16 v[24:27], v[164:167], v[198:201], v[24:27]
	v_mfma_f32_16x16x32_bf16 v[16:19], v[156:159], v[206:209], v[16:19]
	v_mfma_f32_16x16x32_bf16 v[8:11], v[164:167], v[206:209], v[8:11]
	v_mfma_f32_16x16x32_bf16 v[52:55], v[210:213], v[168:171], v[52:55]
	v_mfma_f32_16x16x32_bf16 v[44:47], v[218:221], v[168:171], v[44:47]
	v_mfma_f32_16x16x32_bf16 v[36:39], v[210:213], v[182:185], v[36:39]
	v_mfma_f32_16x16x32_bf16 v[28:31], v[218:221], v[182:185], v[28:31]
	v_mfma_f32_16x16x32_bf16 v[20:23], v[210:213], v[194:197], v[20:23]
	v_mfma_f32_16x16x32_bf16 v[12:15], v[218:221], v[194:197], v[12:15]
	v_mfma_f32_16x16x32_bf16 v[4:7], v[210:213], v[202:205], v[4:7]
	v_mfma_f32_16x16x32_bf16 v[0:3], v[218:221], v[202:205], v[0:3]
	v_mfma_f32_16x16x32_bf16 v[52:55], v[214:217], v[172:175], v[52:55]
	v_mfma_f32_16x16x32_bf16 v[44:47], v[222:225], v[172:175], v[44:47]
	v_mfma_f32_16x16x32_bf16 v[36:39], v[214:217], v[190:193], v[36:39]
	v_mfma_f32_16x16x32_bf16 v[28:31], v[222:225], v[190:193], v[28:31]
	v_mfma_f32_16x16x32_bf16 v[20:23], v[214:217], v[198:201], v[20:23]
	v_mfma_f32_16x16x32_bf16 v[12:15], v[222:225], v[198:201], v[12:15]
	v_mfma_f32_16x16x32_bf16 v[4:7], v[214:217], v[206:209], v[4:7]
	v_mfma_f32_16x16x32_bf16 v[0:3], v[222:225], v[206:209], v[0:3]
	s_barrier
	s_add_i32 s47, s47, 2
	s_add_u32 s18, s18, 0x100
	s_addc_u32 s19, s19, 0
	s_add_u32 s45, s45, 0x100
	s_addc_u32 s46, s46, 0
	s_cmp_gt_u32 s47, 13
	s_cbranch_scc0 .LBB0_991
	v_lshl_or_b32 v144, s42, 8, v152
	v_lshl_add_u32 v146, s16, 8, v150
	v_ashrrev_i32_e32 v145, 31, v144
	v_mov_b64_e32 v[148:149], s[4:5]
	v_lshlrev_b64 v[144:145], 1, v[144:145]
	v_mad_i64_i32 v[156:157], s[18:19], v146, s41, v[148:149]
	v_lshl_add_u64 v[160:161], v[156:157], 0, v[144:145]
	global_load_dwordx4 v[166:169], v[160:161], off offset:3072
	global_load_dwordx4 v[170:173], v[160:161], off offset:3328
	s_mul_i32 s98, s41, 16
	s_mov_b32 s99, 0
	v_lshl_add_u64 v[224:225], v[160:161], 0, s[98:99]
	global_load_dwordx4 v[182:185], v[224:225], off offset:3072
	global_load_dwordx4 v[190:193], v[224:225], off offset:3328
	s_mul_i32 s98, s41, 32
	s_mov_b32 s99, 0
	v_lshl_add_u64 v[174:175], v[160:161], 0, s[98:99]
	global_load_dwordx4 v[194:197], v[174:175], off offset:3072
	global_load_dwordx4 v[198:201], v[174:175], off offset:3328
	s_mul_i32 s98, s41, 48
	s_mov_b32 s99, 0
	v_lshl_add_u64 v[224:225], v[160:161], 0, s[98:99]
	global_load_dwordx4 v[202:205], v[224:225], off offset:3072
	global_load_dwordx4 v[206:209], v[224:225], off offset:3328
	s_mul_i32 s98, s41, 128
	s_mov_b32 s99, 0
	v_lshl_add_u64 v[174:175], v[160:161], 0, s[98:99]
	global_load_dwordx4 v[210:213], v[174:175], off offset:3072
	global_load_dwordx4 v[214:217], v[174:175], off offset:3328
	s_mul_i32 s98, s41, 144
	s_mov_b32 s99, 0
	v_lshl_add_u64 v[218:219], v[160:161], 0, s[98:99]
	s_mul_i32 s98, s41, 160
	s_mov_b32 s99, 0
	v_lshl_add_u64 v[220:221], v[160:161], 0, s[98:99]
	s_mul_i32 s98, s41, 176
	s_mov_b32 s99, 0
	v_lshl_add_u64 v[222:223], v[160:161], 0, s[98:99]
	s_and_b64 vcc, exec, s[2:3]
	s_mov_b32 s42, s8
	s_mov_b32 s16, s10
	s_mov_b64 s[20:21], s[14:15]
	s_waitcnt vmcnt(9)
; __device__ __forceinline__ unsigned cvt_pk_bf16(float lo, float hi) { unsigned r; asm volatile("v_cvt_pk_bf16_f32 %0, %1, %2" : "=v"(r) : "v"(lo), "v"(hi)); return r; }
; __device__ __forceinline__ float bf_lo(unsigned u) { return __uint_as_float(u << 16); }
; __device__ __forceinline__ float bf_hi(unsigned u) { return __uint_as_float(u & 0xffff0000u); }
;     __device__ __forceinline__ void operator()(const f32x4 (&acc)[2][2][4][2], const Unit& u, int wr, int wc, int fr, int fq) const {
;     ...
;             for (int m = 0; m < 4; ++m) { const size_t r = (size_t)(row0 + ai * HALF + m * 16); bf16_t* rowp = O + r * ldc + col0; const bf16_t* gp = G + r * ldg + col0;
; #pragma unroll
;                 for (int bj = 0; bj < 2; ++bj) { const u32x4 gw = *(const u32x4*)(gp + bj * HALF);
;                     f32x4 v0 = acc[ai][bj][m][0], v1 = acc[ai][bj][m][1];
;                     v0[0] *= bf_lo(gw.x); v0[1] *= bf_hi(gw.x); v0[2] *= bf_lo(gw.y); v0[3] *= bf_hi(gw.y);
;                     v1[0] *= bf_lo(gw.z); v1[1] *= bf_hi(gw.z); v1[2] *= bf_lo(gw.w); v1[3] *= bf_hi(gw.w);
;                     if (ACCUM) { const u32x4 pw = *(const u32x4*)(rowp + bj * HALF);
;                         v0[0] += bf_lo(pw.x); v0[1] += bf_hi(pw.x); v0[2] += bf_lo(pw.y); v0[3] += bf_hi(pw.y);
;                         v1[0] += bf_lo(pw.z); v1[1] += bf_hi(pw.z); v1[2] += bf_lo(pw.w); v1[3] += bf_hi(pw.w); }
;                     u32x4 w; w.x = cvt_pk_bf16(v0[0], v0[1]); w.y = cvt_pk_bf16(v0[2], v0[3]); w.z = cvt_pk_bf16(v1[0], v1[1]); w.w = cvt_pk_bf16(v1[2], v1[3]);
;                     *(u32x4*)(rowp + bj * HALF) = w; } }
	v_mov_b32_e32 v156, v166
	v_mov_b32_e32 v157, v167
	v_mov_b32_e32 v158, v168
	v_mov_b32_e32 v159, v169
	global_load_dwordx4 v[166:169], v[218:219], off offset:3072
	v_lshlrev_b32_e32 v147, 16, v156
	v_and_b32_e32 v156, 0xffff0000, v156
	v_lshlrev_b32_e32 v162, 16, v157
	v_and_b32_e32 v157, 0xffff0000, v157
	v_lshlrev_b32_e32 v164, 16, v159
	v_and_b32_e32 v159, 0xffff0000, v159
	v_lshlrev_b32_e32 v163, 16, v158
	v_and_b32_e32 v158, 0xffff0000, v158
	v_mul_f32_e32 v124, v124, v147
	v_mul_f32_e32 v125, v125, v156
	v_mul_f32_e32 v126, v126, v162
	v_mul_f32_e32 v127, v127, v157
	v_mul_f32_e32 v123, v123, v159
	v_mul_f32_e32 v147, v120, v163
	v_mul_f32_e32 v156, v121, v158
	v_mul_f32_e32 v157, v122, v164
	v_cvt_pk_bf16_f32 v120, v124, v125
	v_cvt_pk_bf16_f32 v121, v126, v127
	v_cvt_pk_bf16_f32 v122, v147, v156
	v_cvt_pk_bf16_f32 v123, v157, v123
	v_ashrrev_i32_e32 v147, 31, v146
	v_lshlrev_b64 v[158:159], 11, v[146:147]
	v_lshl_add_u64 v[158:159], s[0:1], 0, v[158:159]
	v_or_b32_e32 v156, 16, v146
	v_lshl_add_u64 v[158:159], v[158:159], 0, v[144:145]
	v_mad_i64_i32 v[160:161], s[18:19], v156, s41, v[148:149]
	global_store_dwordx4 v[158:159], v[120:123], off
	v_lshl_add_u64 v[160:161], v[160:161], 0, v[144:145]
	v_ashrrev_i32_e32 v157, 31, v156
	s_waitcnt vmcnt(10)
	v_mov_b32_e32 v124, v170
	v_mov_b32_e32 v125, v171
	v_mov_b32_e32 v126, v172
	v_mov_b32_e32 v127, v173
	global_load_dwordx4 v[170:173], v[218:219], off offset:3328
	v_lshlrev_b32_e32 v120, 16, v124
	v_and_b32_e32 v121, 0xffff0000, v124
	v_lshlrev_b32_e32 v122, 16, v125
	v_and_b32_e32 v123, 0xffff0000, v125
	v_lshlrev_b32_e32 v124, 16, v126
	v_and_b32_e32 v125, 0xffff0000, v126
	v_lshlrev_b32_e32 v126, 16, v127
	v_and_b32_e32 v127, 0xffff0000, v127
	v_mul_f32_e32 v116, v116, v120
	v_mul_f32_e32 v117, v117, v121
	v_mul_f32_e32 v118, v118, v122
	v_mul_f32_e32 v119, v119, v123
	v_mul_f32_e32 v111, v111, v127
	v_mul_f32_e32 v120, v108, v124
	v_mul_f32_e32 v121, v109, v125
	v_mul_f32_e32 v122, v110, v126
	v_cvt_pk_bf16_f32 v108, v116, v117
	v_cvt_pk_bf16_f32 v109, v118, v119
	v_cvt_pk_bf16_f32 v110, v120, v121
	v_cvt_pk_bf16_f32 v111, v122, v111
	s_nop 0
	global_store_dwordx4 v[158:159], v[108:111], off offset:256
	s_waitcnt vmcnt(11)
	v_mov_b32_e32 v116, v182
	v_mov_b32_e32 v117, v183
	v_mov_b32_e32 v118, v184
	v_mov_b32_e32 v119, v185
	global_load_dwordx4 v[182:185], v[220:221], off offset:3072
	s_nop 0
	v_lshlrev_b32_e32 v108, 16, v116
	v_and_b32_e32 v109, 0xffff0000, v116
	v_lshlrev_b32_e32 v110, 16, v117
	v_and_b32_e32 v111, 0xffff0000, v117
	v_lshlrev_b32_e32 v116, 16, v118
	v_and_b32_e32 v117, 0xffff0000, v118
	v_lshlrev_b32_e32 v118, 16, v119
	v_and_b32_e32 v119, 0xffff0000, v119
	v_mul_f32_e32 v108, v112, v108
	v_mul_f32_e32 v109, v113, v109
	v_mul_f32_e32 v110, v114, v110
	v_mul_f32_e32 v111, v115, v111
	v_mul_f32_e32 v107, v107, v119
	v_mul_f32_e32 v112, v104, v116
	v_mul_f32_e32 v113, v105, v117
	v_mul_f32_e32 v114, v106, v118
	v_cvt_pk_bf16_f32 v104, v108, v109
	v_cvt_pk_bf16_f32 v105, v110, v111
	v_cvt_pk_bf16_f32 v106, v112, v113
	v_cvt_pk_bf16_f32 v107, v114, v107
	v_lshlrev_b64 v[116:117], 11, v[156:157]
	v_lshl_add_u64 v[116:117], s[0:1], 0, v[116:117]
	v_or_b32_e32 v112, 32, v146
	v_lshl_add_u64 v[116:117], v[116:117], 0, v[144:145]
	v_mad_i64_i32 v[114:115], s[18:19], v112, s41, v[148:149]
	global_store_dwordx4 v[116:117], v[104:107], off
	v_lshl_add_u64 v[114:115], v[114:115], 0, v[144:145]
	v_ashrrev_i32_e32 v113, 31, v112
	s_waitcnt vmcnt(12)
	v_mov_b32_e32 v108, v190
	v_mov_b32_e32 v109, v191
	v_mov_b32_e32 v110, v192
	v_mov_b32_e32 v111, v193
	global_load_dwordx4 v[190:193], v[220:221], off offset:3328
	v_lshlrev_b32_e32 v104, 16, v108
	v_and_b32_e32 v105, 0xffff0000, v108
	v_lshlrev_b32_e32 v106, 16, v109
	v_and_b32_e32 v107, 0xffff0000, v109
	v_lshlrev_b32_e32 v108, 16, v110
	v_and_b32_e32 v109, 0xffff0000, v110
	v_lshlrev_b32_e32 v110, 16, v111
	v_and_b32_e32 v111, 0xffff0000, v111
	v_mul_f32_e32 v100, v100, v104
	v_mul_f32_e32 v101, v101, v105
	v_mul_f32_e32 v102, v102, v106
	v_mul_f32_e32 v103, v103, v107
	v_mul_f32_e32 v95, v95, v111
	v_mul_f32_e32 v104, v92, v108
	v_mul_f32_e32 v105, v93, v109
	v_mul_f32_e32 v106, v94, v110
	v_cvt_pk_bf16_f32 v92, v100, v101
	v_cvt_pk_bf16_f32 v93, v102, v103
	v_cvt_pk_bf16_f32 v94, v104, v105
	v_cvt_pk_bf16_f32 v95, v106, v95
	s_nop 0
	global_store_dwordx4 v[116:117], v[92:95], off offset:256
	s_waitcnt vmcnt(13)
	v_mov_b32_e32 v100, v194
	v_mov_b32_e32 v101, v195
	v_mov_b32_e32 v102, v196
	v_mov_b32_e32 v103, v197
	global_load_dwordx4 v[194:197], v[222:223], off offset:3072
	s_nop 0
	v_lshlrev_b32_e32 v92, 16, v100
	v_and_b32_e32 v93, 0xffff0000, v100
	v_lshlrev_b32_e32 v94, 16, v101
	v_and_b32_e32 v95, 0xffff0000, v101
	v_lshlrev_b32_e32 v100, 16, v102
	v_and_b32_e32 v101, 0xffff0000, v102
	v_lshlrev_b32_e32 v102, 16, v103
	v_and_b32_e32 v103, 0xffff0000, v103
	v_mul_f32_e32 v92, v96, v92
	v_mul_f32_e32 v93, v97, v93
	v_mul_f32_e32 v94, v98, v94
	v_mul_f32_e32 v95, v99, v95
	v_mul_f32_e32 v91, v91, v103
	v_mul_f32_e32 v96, v88, v100
	v_mul_f32_e32 v97, v89, v101
	v_mul_f32_e32 v98, v90, v102
	v_cvt_pk_bf16_f32 v88, v92, v93
	v_cvt_pk_bf16_f32 v89, v94, v95
	v_cvt_pk_bf16_f32 v90, v96, v97
	v_cvt_pk_bf16_f32 v91, v98, v91
	v_lshlrev_b64 v[100:101], 11, v[112:113]
	v_lshl_add_u64 v[100:101], s[0:1], 0, v[100:101]
	v_or_b32_e32 v96, 48, v146
	v_lshl_add_u64 v[100:101], v[100:101], 0, v[144:145]
	v_mad_i64_i32 v[98:99], s[18:19], v96, s41, v[148:149]
	global_store_dwordx4 v[100:101], v[88:91], off
	v_lshl_add_u64 v[98:99], v[98:99], 0, v[144:145]
	v_ashrrev_i32_e32 v97, 31, v96
	s_waitcnt vmcnt(14)
; __device__ __forceinline__ unsigned cvt_pk_bf16(float lo, float hi) { unsigned r; asm volatile("v_cvt_pk_bf16_f32 %0, %1, %2" : "=v"(r) : "v"(lo), "v"(hi)); return r; }
; __device__ __forceinline__ float bf_lo(unsigned u) { return __uint_as_float(u << 16); }
; __device__ __forceinline__ float bf_hi(unsigned u) { return __uint_as_float(u & 0xffff0000u); }
;     __device__ __forceinline__ void operator()(const f32x4 (&acc)[2][2][4][2], const Unit& u, int wr, int wc, int fr, int fq) const {
;     ...
;             for (int m = 0; m < 4; ++m) { const size_t r = (size_t)(row0 + ai * HALF + m * 16); bf16_t* rowp = O + r * ldc + col0; const bf16_t* gp = G + r * ldg + col0;
; #pragma unroll
;                 for (int bj = 0; bj < 2; ++bj) { const u32x4 gw = *(const u32x4*)(gp + bj * HALF);
;                     f32x4 v0 = acc[ai][bj][m][0], v1 = acc[ai][bj][m][1];
;                     v0[0] *= bf_lo(gw.x); v0[1] *= bf_hi(gw.x); v0[2] *= bf_lo(gw.y); v0[3] *= bf_hi(gw.y);
;                     v1[0] *= bf_lo(gw.z); v1[1] *= bf_hi(gw.z); v1[2] *= bf_lo(gw.w); v1[3] *= bf_hi(gw.w);
;                     if (ACCUM) { const u32x4 pw = *(const u32x4*)(rowp + bj * HALF);
;                         v0[0] += bf_lo(pw.x); v0[1] += bf_hi(pw.x); v0[2] += bf_lo(pw.y); v0[3] += bf_hi(pw.y);
;                         v1[0] += bf_lo(pw.z); v1[1] += bf_hi(pw.z); v1[2] += bf_lo(pw.w); v1[3] += bf_hi(pw.w); }
;                     u32x4 w; w.x = cvt_pk_bf16(v0[0], v0[1]); w.y = cvt_pk_bf16(v0[2], v0[3]); w.z = cvt_pk_bf16(v1[0], v1[1]); w.w = cvt_pk_bf16(v1[2], v1[3]);
;                     *(u32x4*)(rowp + bj * HALF) = w; } }
	v_mov_b32_e32 v92, v198
	v_mov_b32_e32 v93, v199
	v_mov_b32_e32 v94, v200
	v_mov_b32_e32 v95, v201
	global_load_dwordx4 v[198:201], v[222:223], off offset:3328
	v_lshlrev_b32_e32 v88, 16, v92
	v_and_b32_e32 v89, 0xffff0000, v92
	v_lshlrev_b32_e32 v90, 16, v93
	v_and_b32_e32 v91, 0xffff0000, v93
	v_lshlrev_b32_e32 v92, 16, v94
	v_and_b32_e32 v93, 0xffff0000, v94
	v_lshlrev_b32_e32 v94, 16, v95
	v_and_b32_e32 v95, 0xffff0000, v95
	v_mul_f32_e32 v84, v84, v88
	v_mul_f32_e32 v85, v85, v89
	v_mul_f32_e32 v86, v86, v90
	v_mul_f32_e32 v87, v87, v91
	v_mul_f32_e32 v79, v79, v95
	v_mul_f32_e32 v88, v76, v92
	v_mul_f32_e32 v89, v77, v93
	v_mul_f32_e32 v90, v78, v94
	v_cvt_pk_bf16_f32 v76, v84, v85
	v_cvt_pk_bf16_f32 v77, v86, v87
	v_cvt_pk_bf16_f32 v78, v88, v89
	v_cvt_pk_bf16_f32 v79, v90, v79
	s_nop 0
	global_store_dwordx4 v[100:101], v[76:79], off offset:256
	s_waitcnt vmcnt(15)
	v_mov_b32_e32 v84, v202
	v_mov_b32_e32 v85, v203
	v_mov_b32_e32 v86, v204
	v_mov_b32_e32 v87, v205
	s_nop 0
	v_lshlrev_b32_e32 v76, 16, v84
	v_and_b32_e32 v77, 0xffff0000, v84
	v_lshlrev_b32_e32 v78, 16, v85
	v_and_b32_e32 v79, 0xffff0000, v85
	v_lshlrev_b32_e32 v84, 16, v86
	v_and_b32_e32 v85, 0xffff0000, v86
	v_lshlrev_b32_e32 v86, 16, v87
	v_and_b32_e32 v87, 0xffff0000, v87
	v_mul_f32_e32 v76, v80, v76
	v_mul_f32_e32 v77, v81, v77
	v_mul_f32_e32 v78, v82, v78
	v_mul_f32_e32 v79, v83, v79
	v_mul_f32_e32 v75, v75, v87
	v_mul_f32_e32 v80, v72, v84
	v_mul_f32_e32 v81, v73, v85
	v_mul_f32_e32 v82, v74, v86
	v_cvt_pk_bf16_f32 v72, v76, v77
	v_cvt_pk_bf16_f32 v73, v78, v79
	v_cvt_pk_bf16_f32 v74, v80, v81
	v_cvt_pk_bf16_f32 v75, v82, v75
	v_lshlrev_b64 v[84:85], 11, v[96:97]
	v_lshl_add_u64 v[84:85], s[0:1], 0, v[84:85]
	v_add_u32_e32 v80, 0x80, v146
	v_lshl_add_u64 v[84:85], v[84:85], 0, v[144:145]
	v_mad_i64_i32 v[82:83], s[18:19], v80, s41, v[148:149]
	global_store_dwordx4 v[84:85], v[72:75], off
	v_lshl_add_u64 v[82:83], v[82:83], 0, v[144:145]
	v_ashrrev_i32_e32 v81, 31, v80
	s_waitcnt vmcnt(15)
	v_mov_b32_e32 v76, v206
	v_mov_b32_e32 v77, v207
	v_mov_b32_e32 v78, v208
	v_mov_b32_e32 v79, v209
	v_lshlrev_b32_e32 v72, 16, v76
	v_and_b32_e32 v73, 0xffff0000, v76
	v_lshlrev_b32_e32 v74, 16, v77
	v_and_b32_e32 v75, 0xffff0000, v77
	v_lshlrev_b32_e32 v76, 16, v78
	v_and_b32_e32 v77, 0xffff0000, v78
	v_lshlrev_b32_e32 v78, 16, v79
	v_and_b32_e32 v79, 0xffff0000, v79
	v_mul_f32_e32 v68, v68, v72
	v_mul_f32_e32 v69, v69, v73
	v_mul_f32_e32 v70, v70, v74
	v_mul_f32_e32 v71, v71, v75
	v_mul_f32_e32 v67, v67, v79
	v_mul_f32_e32 v72, v64, v76
	v_mul_f32_e32 v73, v65, v77
	v_mul_f32_e32 v74, v66, v78
	v_cvt_pk_bf16_f32 v64, v68, v69
	v_cvt_pk_bf16_f32 v65, v70, v71
	v_cvt_pk_bf16_f32 v66, v72, v73
	v_cvt_pk_bf16_f32 v67, v74, v67
	s_nop 0
	global_store_dwordx4 v[84:85], v[64:67], off offset:256
	s_waitcnt vmcnt(15)
	v_mov_b32_e32 v68, v210
	v_mov_b32_e32 v69, v211
	v_mov_b32_e32 v70, v212
	v_mov_b32_e32 v71, v213
	s_nop 0
	v_lshlrev_b32_e32 v64, 16, v68
	v_and_b32_e32 v65, 0xffff0000, v68
	v_lshlrev_b32_e32 v66, 16, v69
	v_and_b32_e32 v67, 0xffff0000, v69
	v_lshlrev_b32_e32 v68, 16, v70
	v_and_b32_e32 v69, 0xffff0000, v70
	v_lshlrev_b32_e32 v70, 16, v71
	v_and_b32_e32 v71, 0xffff0000, v71
	v_mul_f32_e32 v60, v60, v64
	v_mul_f32_e32 v61, v61, v65
	v_mul_f32_e32 v62, v62, v66
	v_mul_f32_e32 v63, v63, v67
	v_mul_f32_e32 v59, v59, v71
	v_mul_f32_e32 v64, v56, v68
	v_mul_f32_e32 v65, v57, v69
	v_mul_f32_e32 v66, v58, v70
	v_cvt_pk_bf16_f32 v56, v60, v61
	v_cvt_pk_bf16_f32 v57, v62, v63
	v_cvt_pk_bf16_f32 v58, v64, v65
	v_cvt_pk_bf16_f32 v59, v66, v59
	v_lshlrev_b64 v[68:69], 11, v[80:81]
	v_lshl_add_u64 v[68:69], s[0:1], 0, v[68:69]
	v_add_u32_e32 v64, 0x90, v146
	v_lshl_add_u64 v[68:69], v[68:69], 0, v[144:145]
	v_mad_i64_i32 v[66:67], s[18:19], v64, s41, v[148:149]
	global_store_dwordx4 v[68:69], v[56:59], off
	v_lshl_add_u64 v[66:67], v[66:67], 0, v[144:145]
	v_ashrrev_i32_e32 v65, 31, v64
	s_waitcnt vmcnt(15)
	v_mov_b32_e32 v60, v214
	v_mov_b32_e32 v61, v215
	v_mov_b32_e32 v62, v216
	v_mov_b32_e32 v63, v217
	v_lshlrev_b32_e32 v56, 16, v60
	v_and_b32_e32 v57, 0xffff0000, v60
	v_lshlrev_b32_e32 v58, 16, v61
	v_and_b32_e32 v59, 0xffff0000, v61
	v_lshlrev_b32_e32 v60, 16, v62
	v_and_b32_e32 v61, 0xffff0000, v62
	v_lshlrev_b32_e32 v62, 16, v63
	v_and_b32_e32 v63, 0xffff0000, v63
	v_mul_f32_e32 v52, v52, v56
	v_mul_f32_e32 v53, v53, v57
	v_mul_f32_e32 v54, v54, v58
	v_mul_f32_e32 v55, v55, v59
	v_mul_f32_e32 v47, v47, v63
	v_mul_f32_e32 v56, v44, v60
	v_mul_f32_e32 v57, v45, v61
	v_mul_f32_e32 v58, v46, v62
	v_cvt_pk_bf16_f32 v44, v52, v53
	v_cvt_pk_bf16_f32 v45, v54, v55
	v_cvt_pk_bf16_f32 v46, v56, v57
	v_cvt_pk_bf16_f32 v47, v58, v47
	s_nop 0
	global_store_dwordx4 v[68:69], v[44:47], off offset:256
	s_waitcnt vmcnt(15)
; __device__ __forceinline__ unsigned cvt_pk_bf16(float lo, float hi) { unsigned r; asm volatile("v_cvt_pk_bf16_f32 %0, %1, %2" : "=v"(r) : "v"(lo), "v"(hi)); return r; }
; __device__ __forceinline__ float bf_lo(unsigned u) { return __uint_as_float(u << 16); }
; __device__ __forceinline__ float bf_hi(unsigned u) { return __uint_as_float(u & 0xffff0000u); }
; #define PG8_WAIT_V(n) asm volatile("s_waitcnt vmcnt(" #n ")" ::: "memory")
; #define PG8_BAR __builtin_amdgcn_s_barrier()
;     __device__ __forceinline__ void operator()(const f32x4 (&acc)[2][2][4][2], const Unit& u, int wr, int wc, int fr, int fq) const {
;     ...
;                 for (int bj = 0; bj < 2; ++bj) { const u32x4 gw = *(const u32x4*)(gp + bj * HALF);
;                     f32x4 v0 = acc[ai][bj][m][0], v1 = acc[ai][bj][m][1];
;                     v0[0] *= bf_lo(gw.x); v0[1] *= bf_hi(gw.x); v0[2] *= bf_lo(gw.y); v0[3] *= bf_hi(gw.y);
;                     v1[0] *= bf_lo(gw.z); v1[1] *= bf_hi(gw.z); v1[2] *= bf_lo(gw.w); v1[3] *= bf_hi(gw.w);
;                     if (ACCUM) { const u32x4 pw = *(const u32x4*)(rowp + bj * HALF);
;                         v0[0] += bf_lo(pw.x); v0[1] += bf_hi(pw.x); v0[2] += bf_lo(pw.y); v0[3] += bf_hi(pw.y);
;                         v1[0] += bf_lo(pw.z); v1[1] += bf_hi(pw.z); v1[2] += bf_lo(pw.w); v1[3] += bf_hi(pw.w); }
;                     u32x4 w; w.x = cvt_pk_bf16(v0[0], v0[1]); w.y = cvt_pk_bf16(v0[2], v0[3]); w.z = cvt_pk_bf16(v1[0], v1[1]); w.w = cvt_pk_bf16(v1[2], v1[3]);
;                     *(u32x4*)(rowp + bj * HALF) = w; } }
; template <class Epi, class Sched>
; __device__ __forceinline__ void gemm_phase(PG8_LAS unsigned char* lds, const Gemm g, const Sched& S, const Epi& E) {
;     ...
;     PG8_WAIT_V(0);
;     if (wr == 0) PG8_BAR;
;     PG8_BAR;
	v_mov_b32_e32 v52, v166
	v_mov_b32_e32 v53, v167
	v_mov_b32_e32 v54, v168
	v_mov_b32_e32 v55, v169
	s_nop 0
	v_lshlrev_b32_e32 v44, 16, v52
	v_and_b32_e32 v45, 0xffff0000, v52
	v_lshlrev_b32_e32 v46, 16, v53
	v_and_b32_e32 v47, 0xffff0000, v53
	v_lshlrev_b32_e32 v52, 16, v54
	v_and_b32_e32 v53, 0xffff0000, v54
	v_lshlrev_b32_e32 v54, 16, v55
	v_and_b32_e32 v55, 0xffff0000, v55
	v_mul_f32_e32 v44, v48, v44
	v_mul_f32_e32 v45, v49, v45
	v_mul_f32_e32 v46, v50, v46
	v_mul_f32_e32 v47, v51, v47
	v_mul_f32_e32 v43, v43, v55
	v_mul_f32_e32 v48, v40, v52
	v_mul_f32_e32 v49, v41, v53
	v_mul_f32_e32 v50, v42, v54
	v_cvt_pk_bf16_f32 v40, v44, v45
	v_cvt_pk_bf16_f32 v41, v46, v47
	v_cvt_pk_bf16_f32 v42, v48, v49
	v_cvt_pk_bf16_f32 v43, v50, v43
	v_lshlrev_b64 v[52:53], 11, v[64:65]
	v_lshl_add_u64 v[52:53], s[0:1], 0, v[52:53]
	v_add_u32_e32 v48, 0xa0, v146
	v_lshl_add_u64 v[52:53], v[52:53], 0, v[144:145]
	v_mad_i64_i32 v[50:51], s[18:19], v48, s41, v[148:149]
	global_store_dwordx4 v[52:53], v[40:43], off
	v_lshl_add_u64 v[50:51], v[50:51], 0, v[144:145]
	v_ashrrev_i32_e32 v49, 31, v48
	s_waitcnt vmcnt(14)
	v_mov_b32_e32 v44, v170
	v_mov_b32_e32 v45, v171
	v_mov_b32_e32 v46, v172
	v_mov_b32_e32 v47, v173
	v_lshlrev_b32_e32 v40, 16, v44
	v_and_b32_e32 v41, 0xffff0000, v44
	v_lshlrev_b32_e32 v42, 16, v45
	v_and_b32_e32 v43, 0xffff0000, v45
	v_lshlrev_b32_e32 v44, 16, v46
	v_and_b32_e32 v45, 0xffff0000, v46
	v_lshlrev_b32_e32 v46, 16, v47
	v_and_b32_e32 v47, 0xffff0000, v47
	v_mul_f32_e32 v36, v36, v40
	v_mul_f32_e32 v37, v37, v41
	v_mul_f32_e32 v38, v38, v42
	v_mul_f32_e32 v39, v39, v43
	v_mul_f32_e32 v31, v31, v47
	v_mul_f32_e32 v40, v28, v44
	v_mul_f32_e32 v41, v29, v45
	v_mul_f32_e32 v42, v30, v46
	v_cvt_pk_bf16_f32 v28, v36, v37
	v_cvt_pk_bf16_f32 v29, v38, v39
	v_cvt_pk_bf16_f32 v30, v40, v41
	v_cvt_pk_bf16_f32 v31, v42, v31
	s_nop 0
	global_store_dwordx4 v[52:53], v[28:31], off offset:256
	s_waitcnt vmcnt(13)
	v_mov_b32_e32 v36, v182
	v_mov_b32_e32 v37, v183
	v_mov_b32_e32 v38, v184
	v_mov_b32_e32 v39, v185
	s_nop 0
	v_lshlrev_b32_e32 v28, 16, v36
	v_and_b32_e32 v29, 0xffff0000, v36
	v_lshlrev_b32_e32 v30, 16, v37
	v_and_b32_e32 v31, 0xffff0000, v37
	v_lshlrev_b32_e32 v36, 16, v38
	v_and_b32_e32 v37, 0xffff0000, v38
	v_lshlrev_b32_e32 v38, 16, v39
	v_and_b32_e32 v39, 0xffff0000, v39
	v_mul_f32_e32 v28, v32, v28
	v_mul_f32_e32 v29, v33, v29
	v_mul_f32_e32 v30, v34, v30
	v_mul_f32_e32 v31, v35, v31
	v_mul_f32_e32 v27, v27, v39
	v_mul_f32_e32 v32, v24, v36
	v_mul_f32_e32 v33, v25, v37
	v_mul_f32_e32 v34, v26, v38
	v_cvt_pk_bf16_f32 v24, v28, v29
	v_cvt_pk_bf16_f32 v25, v30, v31
	v_cvt_pk_bf16_f32 v26, v32, v33
	v_cvt_pk_bf16_f32 v27, v34, v27
	v_lshlrev_b64 v[36:37], 11, v[48:49]
	v_lshl_add_u64 v[36:37], s[0:1], 0, v[36:37]
	v_add_u32_e32 v32, 0xb0, v146
	v_lshl_add_u64 v[36:37], v[36:37], 0, v[144:145]
	v_mad_i64_i32 v[34:35], s[18:19], v32, s41, v[148:149]
	global_store_dwordx4 v[36:37], v[24:27], off
	v_lshl_add_u64 v[34:35], v[34:35], 0, v[144:145]
	v_ashrrev_i32_e32 v33, 31, v32
	s_mov_b64 s[18:19], s[12:13]
	s_waitcnt vmcnt(12)
	v_mov_b32_e32 v28, v190
	v_mov_b32_e32 v29, v191
	v_mov_b32_e32 v30, v192
	v_mov_b32_e32 v31, v193
	v_lshlrev_b32_e32 v24, 16, v28
	v_and_b32_e32 v25, 0xffff0000, v28
	v_lshlrev_b32_e32 v26, 16, v29
	v_and_b32_e32 v27, 0xffff0000, v29
	v_lshlrev_b32_e32 v28, 16, v30
	v_and_b32_e32 v29, 0xffff0000, v30
	v_lshlrev_b32_e32 v30, 16, v31
	v_and_b32_e32 v31, 0xffff0000, v31
	v_mul_f32_e32 v20, v20, v24
	v_mul_f32_e32 v21, v21, v25
	v_mul_f32_e32 v22, v22, v26
	v_mul_f32_e32 v23, v23, v27
	v_mul_f32_e32 v15, v15, v31
	v_mul_f32_e32 v24, v12, v28
	v_mul_f32_e32 v25, v13, v29
	v_mul_f32_e32 v26, v14, v30
	v_cvt_pk_bf16_f32 v12, v20, v21
	v_cvt_pk_bf16_f32 v13, v22, v23
	v_cvt_pk_bf16_f32 v14, v24, v25
	v_cvt_pk_bf16_f32 v15, v26, v15
	s_nop 0
	global_store_dwordx4 v[36:37], v[12:15], off offset:256
	s_waitcnt vmcnt(11)
	v_mov_b32_e32 v20, v194
	v_mov_b32_e32 v21, v195
	v_mov_b32_e32 v22, v196
	v_mov_b32_e32 v23, v197
	s_nop 0
	v_lshlrev_b32_e32 v12, 16, v20
	v_and_b32_e32 v13, 0xffff0000, v20
	v_lshlrev_b32_e32 v14, 16, v21
	v_and_b32_e32 v15, 0xffff0000, v21
	v_lshlrev_b32_e32 v20, 16, v22
	v_and_b32_e32 v21, 0xffff0000, v22
	v_lshlrev_b32_e32 v22, 16, v23
	v_and_b32_e32 v23, 0xffff0000, v23
	v_mul_f32_e32 v12, v16, v12
	v_mul_f32_e32 v13, v17, v13
	v_mul_f32_e32 v14, v18, v14
	v_mul_f32_e32 v15, v19, v15
	v_mul_f32_e32 v11, v11, v23
	v_mul_f32_e32 v16, v8, v20
	v_mul_f32_e32 v17, v9, v21
	v_mul_f32_e32 v18, v10, v22
	v_cvt_pk_bf16_f32 v8, v12, v13
	v_cvt_pk_bf16_f32 v9, v14, v15
	v_cvt_pk_bf16_f32 v10, v16, v17
	v_cvt_pk_bf16_f32 v11, v18, v11
	v_lshlrev_b64 v[16:17], 11, v[32:33]
	v_lshl_add_u64 v[16:17], s[0:1], 0, v[16:17]
	v_lshl_add_u64 v[16:17], v[16:17], 0, v[144:145]
	global_store_dwordx4 v[16:17], v[8:11], off
	s_waitcnt vmcnt(10)
	v_mov_b32_e32 v12, v198
	v_mov_b32_e32 v13, v199
	v_mov_b32_e32 v14, v200
	v_mov_b32_e32 v15, v201
	s_nop 0
	v_lshlrev_b32_e32 v8, 16, v12
	v_and_b32_e32 v9, 0xffff0000, v12
	v_lshlrev_b32_e32 v10, 16, v13
	v_and_b32_e32 v11, 0xffff0000, v13
	v_lshlrev_b32_e32 v12, 16, v14
	v_and_b32_e32 v13, 0xffff0000, v14
	v_lshlrev_b32_e32 v14, 16, v15
	v_and_b32_e32 v15, 0xffff0000, v15
	v_mul_f32_e32 v3, v3, v15
	v_mul_f32_e32 v4, v4, v8
	v_mul_f32_e32 v5, v5, v9
	v_mul_f32_e32 v6, v6, v10
	v_mul_f32_e32 v7, v7, v11
	v_mul_f32_e32 v8, v0, v12
	v_mul_f32_e32 v9, v1, v13
	v_mul_f32_e32 v10, v2, v14
	v_cvt_pk_bf16_f32 v0, v4, v5
	v_cvt_pk_bf16_f32 v1, v6, v7
	v_cvt_pk_bf16_f32 v2, v8, v9
	v_cvt_pk_bf16_f32 v3, v10, v3
	global_store_dwordx4 v[16:17], v[0:3], off offset:256
	s_cbranch_vccz .LBB0_984
	s_waitcnt vmcnt(0)
	s_cmpk_gt_u32 s25, 0xff
	s_cbranch_scc1 .LBB0_995
	s_barrier

; #define PG8_STAGE(bufoff, gbase, voff) do { _Pragma("unroll") for (int _i = 0; _i < 2; ++_i) \
;         __builtin_amdgcn_global_load_lds((const unsigned*)((const char*)(gbase) + (voff)[_i]), (PG8_LAS unsigned*)(lds + (bufoff) + ldsw + _i * 8192), 16, 0, 0); } while (0)
; #define PG8_LDA(dst, b, h) do { _Pragma("unroll") for (int m = 0; m < 4; ++m) _Pragma("unroll") for (int k = 0; k < 2; ++k) dst[m][k] = *(const PG8_LAS bf16x8*)(lds + PG8_SA(b, h) + aoff + m * 2048 + k * 1024); } while (0)
; #define PG8_LDB(dst, b, h) do { _Pragma("unroll") for (int n = 0; n < 2; ++n) _Pragma("unroll") for (int k = 0; k < 2; ++k) dst[n][k] = *(const PG8_LAS bf16x8*)(lds + PG8_SB(b, h) + boff + n * 2048 + k * 1024); } while (0)
; #define PG8_MMA(ai, bj, At, Bt) do { __builtin_amdgcn_s_setprio(1); _Pragma("unroll") for (int m = 0; m < 4; ++m) _Pragma("unroll") for (int n = 0; n < 2; ++n) _Pragma("unroll") for (int k = 0; k < 2; ++k) \
;         acc[ai][bj][m][n] = __builtin_amdgcn_mfma_f32_16x16x32_bf16(Bt[n][k], At[m][k], acc[ai][bj][m][n], 0, 0, 0); __builtin_amdgcn_s_setprio(0); } while (0)
; #define PG8_WAIT_L(n) asm volatile("s_waitcnt lgkmcnt(" #n ")" ::: "memory")
; #define PG8_BAR __builtin_amdgcn_s_barrier()
; #define PG8_SCHED __builtin_amdgcn_sched_barrier(0)
; template <class Epi, class Sched>
; __device__ __forceinline__ void gemm_phase(PG8_LAS unsigned char* lds, const Gemm g, const Sched& S, const Epi& E) {
;     ...
;         const bool has_next = S.next(ui + 1, nxt);
;         const char* nA = has_next ? (const char*)g.A + (size_t)nxt.pm * tstep : cA; const char* nB = has_next ? (const char*)g.Bt + (size_t)nxt.pn * tstep : cB;
;         for (int t = 0; t < nt; t += 2) {
;             const bool last = (t == nt - 2);
;             const char* a1 = cA + (size_t)(t + 1) * kstep;
;             const char* a2 = last ? nA : cA + (size_t)(t + 2) * kstep; const char* b2 = last ? nB : cB + (size_t)(t + 2) * kstep;
;             const char* a3 = a2 + kstep; const char* b3 = b2 + kstep;
;             if (last && has_next) S.a_ready(nxt);
;             PG8_LDB(B0, 0, 0); PG8_SCHED; PG8_LDA(At, 0, 0); PG8_STAGE(PG8_SA(1, 1), a1 + hstep, voffA);
;             PG8_WAIT_L(8); PG8_BAR; PG8_WAIT_L(0); PG8_MMA(0, 0, At, B0); PG8_BAR; PG8_SCHED;
;             PG8_LDB(B1, 0, 1); PG8_STAGE(PG8_SB(0, 0), b2, voffB);
;             PG8_BAR; PG8_WAIT_L(0); PG8_MMA(0, 1, At, B1); PG8_BAR;
.LBB0_1010:
	s_ashr_i32 s11, s10, 31
	v_cmp_lt_i64_e32 vcc, s[12:13], v[140:141]
	s_lshl_b64 s[12:13], s[10:11], 19
	s_add_u32 s12, s27, s12
	s_addc_u32 s13, s28, s13
	s_and_b64 s[14:15], vcc, exec
	s_cselect_b32 s11, s13, s19
	s_cselect_b32 s43, s12, s18
	s_ashr_i32 s9, s8, 31
	s_lshl_b64 s[14:15], s[8:9], 19
	s_add_u32 s14, s94, s14
	s_addc_u32 s15, s95, s15
	s_and_b64 s[22:23], vcc, exec
	s_cselect_b32 s9, s15, s21
	s_cselect_b32 s44, s14, s20
	s_add_u32 s18, s18, 0x40080
	s_addc_u32 s19, s19, 0
	s_add_u32 s45, s20, 0x100
	s_addc_u32 s46, s21, 0
	s_mov_b32 s47, -2
	ds_read_b128 v[144:147], v153
	ds_read_b128 v[156:159], v153 offset:1024
	ds_read_b128 v[160:163], v153 offset:2048
	ds_read_b128 v[164:167], v153 offset:3072
	s_add_u32 s20, s18, 0xfffc0080
	s_addc_u32 s21, s19, -1
	s_cmp_eq_u32 s47, 12
	s_cselect_b32 s23, s11, s21
	s_cselect_b32 s22, s43, s20
	s_cselect_b32 s21, s9, s46
	s_cselect_b32 s20, s44, s45
	s_add_i32 m0, s17, 0xc000
	ds_read_b128 v[168:171], v154
	ds_read_b128 v[172:175], v154 offset:1024
	ds_read_b128 v[182:185], v154 offset:2048
	ds_read_b128 v[190:193], v154 offset:3072
	ds_read_b128 v[194:197], v154 offset:4096
	ds_read_b128 v[198:201], v154 offset:5120
	ds_read_b128 v[202:205], v154 offset:6144
	ds_read_b128 v[206:209], v154 offset:7168
	global_load_lds_dwordx4 v136, s[18:19]
	s_nop 1
	s_add_i32 m0, s17, 0xe000
	s_nop 0
	global_load_lds_dwordx4 v138, s[18:19]
	s_waitcnt lgkmcnt(12)
	ds_read_b128 v[210:213], v155
	ds_read_b128 v[214:217], v155 offset:1024
	ds_read_b128 v[218:221], v155 offset:2048
	ds_read_b128 v[222:225], v155 offset:3072
	s_waitcnt vmcnt(8) lgkmcnt(0)
	s_barrier
	v_mfma_f32_16x16x32_bf16 v[124:127], v[144:147], v[168:171], 0
	v_mfma_f32_16x16x32_bf16 v[120:123], v[160:163], v[168:171], 0
	v_mfma_f32_16x16x32_bf16 v[108:111], v[144:147], v[182:185], 0
	v_mfma_f32_16x16x32_bf16 v[104:107], v[160:163], v[182:185], 0
	v_mfma_f32_16x16x32_bf16 v[92:95], v[144:147], v[194:197], 0
	v_mfma_f32_16x16x32_bf16 v[88:91], v[160:163], v[194:197], 0
	v_mfma_f32_16x16x32_bf16 v[76:79], v[144:147], v[202:205], 0
	v_mfma_f32_16x16x32_bf16 v[72:75], v[160:163], v[202:205], 0
	v_mfma_f32_16x16x32_bf16 v[124:127], v[156:159], v[172:175], v[124:127]
	v_mfma_f32_16x16x32_bf16 v[120:123], v[164:167], v[172:175], v[120:123]
	v_mfma_f32_16x16x32_bf16 v[108:111], v[156:159], v[190:193], v[108:111]
	v_mfma_f32_16x16x32_bf16 v[104:107], v[164:167], v[190:193], v[104:107]
	v_mfma_f32_16x16x32_bf16 v[92:95], v[156:159], v[198:201], v[92:95]
	v_mfma_f32_16x16x32_bf16 v[88:91], v[164:167], v[198:201], v[88:91]
	v_mfma_f32_16x16x32_bf16 v[76:79], v[156:159], v[206:209], v[76:79]
	v_mfma_f32_16x16x32_bf16 v[72:75], v[164:167], v[206:209], v[72:75]
	v_mfma_f32_16x16x32_bf16 v[116:119], v[210:213], v[168:171], 0
	v_mfma_f32_16x16x32_bf16 v[112:115], v[218:221], v[168:171], 0
	v_mfma_f32_16x16x32_bf16 v[100:103], v[210:213], v[182:185], 0
	v_mfma_f32_16x16x32_bf16 v[96:99], v[218:221], v[182:185], 0
	v_mfma_f32_16x16x32_bf16 v[84:87], v[210:213], v[194:197], 0
	v_mfma_f32_16x16x32_bf16 v[80:83], v[218:221], v[194:197], 0
	v_mfma_f32_16x16x32_bf16 v[68:71], v[210:213], v[202:205], 0
	v_mfma_f32_16x16x32_bf16 v[64:67], v[218:221], v[202:205], 0
	v_mfma_f32_16x16x32_bf16 v[116:119], v[214:217], v[172:175], v[116:119]
	v_mfma_f32_16x16x32_bf16 v[112:115], v[222:225], v[172:175], v[112:115]
	v_mfma_f32_16x16x32_bf16 v[100:103], v[214:217], v[190:193], v[100:103]
	v_mfma_f32_16x16x32_bf16 v[96:99], v[222:225], v[190:193], v[96:99]
	v_mfma_f32_16x16x32_bf16 v[84:87], v[214:217], v[198:201], v[84:87]
	v_mfma_f32_16x16x32_bf16 v[80:83], v[222:225], v[198:201], v[80:83]
	v_mfma_f32_16x16x32_bf16 v[68:71], v[214:217], v[206:209], v[68:71]
	v_mfma_f32_16x16x32_bf16 v[64:67], v[222:225], v[206:209], v[64:67]
	s_barrier
	ds_read_b128 v[168:171], v154 offset:16384
	ds_read_b128 v[172:175], v154 offset:17408
	ds_read_b128 v[182:185], v154 offset:18432
	ds_read_b128 v[190:193], v154 offset:19456
	ds_read_b128 v[194:197], v154 offset:20480
	ds_read_b128 v[198:201], v154 offset:21504
	ds_read_b128 v[202:205], v154 offset:22528
	ds_read_b128 v[206:209], v154 offset:23552
	s_add_i32 s48, s39, s29
	s_add_u32 s98, s20, s6
	s_addc_u32 s99, s21, s7
	s_mov_b32 m0, s48
	s_nop 0
	global_load_lds_dwordx4 v130, s[20:21]
	s_nop 1
	s_add_i32 m0, s48, 0x2000
	s_nop 0
	global_load_lds_dwordx4 v134, s[20:21]
	s_nop 1
	s_mov_b32 m0, s17
	s_add_u32 s100, s22, s6
	s_addc_u32 s101, s23, s7
	global_load_lds_dwordx4 v128, s[22:23]
	s_nop 1
	s_mov_b32 m0, s30
	s_nop 0
	global_load_lds_dwordx4 v132, s[22:23]
	s_add_u32 s48, s20, 0x40000
	s_addc_u32 s49, s21, 0
	s_add_i32 s50, s40, s29
	s_mov_b32 m0, s50
	s_nop 0
	global_load_lds_dwordx4 v130, s[48:49]
	s_nop 1
	s_add_i32 m0, s50, 0x2000
	s_nop 0
	global_load_lds_dwordx4 v134, s[48:49]
	s_waitcnt vmcnt(8) lgkmcnt(0)
	s_barrier
; #define PG8_STAGE(bufoff, gbase, voff) do { _Pragma("unroll") for (int _i = 0; _i < 2; ++_i) \
;         __builtin_amdgcn_global_load_lds((const unsigned*)((const char*)(gbase) + (voff)[_i]), (PG8_LAS unsigned*)(lds + (bufoff) + ldsw + _i * 8192), 16, 0, 0); } while (0)
; #define PG8_LDA(dst, b, h) do { _Pragma("unroll") for (int m = 0; m < 4; ++m) _Pragma("unroll") for (int k = 0; k < 2; ++k) dst[m][k] = *(const PG8_LAS bf16x8*)(lds + PG8_SA(b, h) + aoff + m * 2048 + k * 1024); } while (0)
; #define PG8_LDB(dst, b, h) do { _Pragma("unroll") for (int n = 0; n < 2; ++n) _Pragma("unroll") for (int k = 0; k < 2; ++k) dst[n][k] = *(const PG8_LAS bf16x8*)(lds + PG8_SB(b, h) + boff + n * 2048 + k * 1024); } while (0)
; #define PG8_MMA(ai, bj, At, Bt) do { __builtin_amdgcn_s_setprio(1); _Pragma("unroll") for (int m = 0; m < 4; ++m) _Pragma("unroll") for (int n = 0; n < 2; ++n) _Pragma("unroll") for (int k = 0; k < 2; ++k) \
;         acc[ai][bj][m][n] = __builtin_amdgcn_mfma_f32_16x16x32_bf16(Bt[n][k], At[m][k], acc[ai][bj][m][n], 0, 0, 0); __builtin_amdgcn_s_setprio(0); } while (0)
; #define PG8_WAIT_V(n) asm volatile("s_waitcnt vmcnt(" #n ")" ::: "memory")
; #define PG8_WAIT_L(n) asm volatile("s_waitcnt lgkmcnt(" #n ")" ::: "memory")
; #define PG8_BAR __builtin_amdgcn_s_barrier()
; #define PG8_SCHED __builtin_amdgcn_sched_barrier(0)
; template <class Epi, class Sched>
; __device__ __forceinline__ void gemm_phase(PG8_LAS unsigned char* lds, const Gemm g, const Sched& S, const Epi& E) {
;     ...
;             PG8_LDA(At, 0, 1); PG8_STAGE(PG8_SA(0, 0), a2, voffA);
;             PG8_BAR; PG8_WAIT_L(0); PG8_MMA(1, 0, At, B0); PG8_BAR; PG8_SCHED;
;             PG8_STAGE(PG8_SB(0, 1), b2 + hstep, voffB);
;             PG8_WAIT_V(6); PG8_BAR; PG8_MMA(1, 1, At, B1); PG8_BAR;
;             PG8_LDB(B0, 1, 0); PG8_SCHED; PG8_LDA(At, 1, 0); PG8_STAGE(PG8_SA(0, 1), a2 + hstep, voffA);
;             PG8_WAIT_L(8); PG8_BAR; PG8_WAIT_L(0); PG8_MMA(0, 0, At, B0); PG8_BAR; PG8_SCHED;
;             PG8_LDB(B1, 1, 1); PG8_STAGE(PG8_SB(1, 0), b3, voffB);
;             PG8_BAR; PG8_WAIT_L(0); PG8_MMA(0, 1, At, B1); PG8_BAR;
	v_mfma_f32_16x16x32_bf16 v[60:63], v[144:147], v[168:171], 0
	v_mfma_f32_16x16x32_bf16 v[56:59], v[160:163], v[168:171], 0
	v_mfma_f32_16x16x32_bf16 v[44:47], v[144:147], v[182:185], 0
	v_mfma_f32_16x16x32_bf16 v[40:43], v[160:163], v[182:185], 0
	v_mfma_f32_16x16x32_bf16 v[28:31], v[144:147], v[194:197], 0
	v_mfma_f32_16x16x32_bf16 v[24:27], v[160:163], v[194:197], 0
	v_mfma_f32_16x16x32_bf16 v[12:15], v[144:147], v[202:205], 0
	v_mfma_f32_16x16x32_bf16 v[8:11], v[160:163], v[202:205], 0
	v_mfma_f32_16x16x32_bf16 v[60:63], v[156:159], v[172:175], v[60:63]
	v_mfma_f32_16x16x32_bf16 v[56:59], v[164:167], v[172:175], v[56:59]
	v_mfma_f32_16x16x32_bf16 v[44:47], v[156:159], v[190:193], v[44:47]
	v_mfma_f32_16x16x32_bf16 v[40:43], v[164:167], v[190:193], v[40:43]
	v_mfma_f32_16x16x32_bf16 v[28:31], v[156:159], v[198:201], v[28:31]
	v_mfma_f32_16x16x32_bf16 v[24:27], v[164:167], v[198:201], v[24:27]
	v_mfma_f32_16x16x32_bf16 v[12:15], v[156:159], v[206:209], v[12:15]
	v_mfma_f32_16x16x32_bf16 v[8:11], v[164:167], v[206:209], v[8:11]
	v_mfma_f32_16x16x32_bf16 v[52:55], v[210:213], v[168:171], 0
	v_mfma_f32_16x16x32_bf16 v[48:51], v[218:221], v[168:171], 0
	v_mfma_f32_16x16x32_bf16 v[36:39], v[210:213], v[182:185], 0
	v_mfma_f32_16x16x32_bf16 v[32:35], v[218:221], v[182:185], 0
	v_mfma_f32_16x16x32_bf16 v[20:23], v[210:213], v[194:197], 0
	v_mfma_f32_16x16x32_bf16 v[16:19], v[218:221], v[194:197], 0
	v_mfma_f32_16x16x32_bf16 v[4:7], v[210:213], v[202:205], 0
	v_mfma_f32_16x16x32_bf16 v[0:3], v[218:221], v[202:205], 0
	v_mfma_f32_16x16x32_bf16 v[52:55], v[214:217], v[172:175], v[52:55]
	v_mfma_f32_16x16x32_bf16 v[48:51], v[222:225], v[172:175], v[48:51]
	v_mfma_f32_16x16x32_bf16 v[36:39], v[214:217], v[190:193], v[36:39]
	v_mfma_f32_16x16x32_bf16 v[32:35], v[222:225], v[190:193], v[32:35]
	v_mfma_f32_16x16x32_bf16 v[20:23], v[214:217], v[198:201], v[20:23]
	v_mfma_f32_16x16x32_bf16 v[16:19], v[222:225], v[198:201], v[16:19]
	v_mfma_f32_16x16x32_bf16 v[4:7], v[214:217], v[206:209], v[4:7]
	v_mfma_f32_16x16x32_bf16 v[0:3], v[222:225], v[206:209], v[0:3]
	s_barrier
	s_add_i32 s48, 0, 0x18000
	v_add_u32_e32 v164, s48, v151
	ds_read_b128 v[144:147], v164
	ds_read_b128 v[156:159], v164 offset:1024
	ds_read_b128 v[160:163], v164 offset:2048
	ds_read_b128 v[164:167], v164 offset:3072
	s_add_u32 s22, s22, 0x40000
	s_addc_u32 s23, s23, 0
	s_mov_b32 m0, s31
	ds_read_b128 v[168:171], v154 offset:32768
	ds_read_b128 v[172:175], v154 offset:33792
	ds_read_b128 v[182:185], v154 offset:34816
	ds_read_b128 v[190:193], v154 offset:35840
	ds_read_b128 v[194:197], v154 offset:36864
	ds_read_b128 v[198:201], v154 offset:37888
	ds_read_b128 v[202:205], v154 offset:38912
	ds_read_b128 v[206:209], v154 offset:39936
	global_load_lds_dwordx4 v128, s[22:23]
	s_nop 1
	s_mov_b32 m0, s34
	s_nop 0
	global_load_lds_dwordx4 v132, s[22:23]
	s_add_i32 s22, 0, 0x1c000
	v_add_u32_e32 v179, s22, v151
	s_waitcnt lgkmcnt(12)
	ds_read_b128 v[210:213], v179
	ds_read_b128 v[214:217], v179 offset:1024
	ds_read_b128 v[218:221], v179 offset:2048
	ds_read_b128 v[222:225], v179 offset:3072
	s_waitcnt vmcnt(8) lgkmcnt(0)
	s_barrier
	v_mfma_f32_16x16x32_bf16 v[124:127], v[144:147], v[168:171], v[124:127]
	v_mfma_f32_16x16x32_bf16 v[120:123], v[160:163], v[168:171], v[120:123]
	v_mfma_f32_16x16x32_bf16 v[108:111], v[144:147], v[182:185], v[108:111]
	v_mfma_f32_16x16x32_bf16 v[104:107], v[160:163], v[182:185], v[104:107]
	v_mfma_f32_16x16x32_bf16 v[92:95], v[144:147], v[194:197], v[92:95]
	v_mfma_f32_16x16x32_bf16 v[88:91], v[160:163], v[194:197], v[88:91]
	v_mfma_f32_16x16x32_bf16 v[76:79], v[144:147], v[202:205], v[76:79]
	v_mfma_f32_16x16x32_bf16 v[72:75], v[160:163], v[202:205], v[72:75]
	v_mfma_f32_16x16x32_bf16 v[124:127], v[156:159], v[172:175], v[124:127]
	v_mfma_f32_16x16x32_bf16 v[120:123], v[164:167], v[172:175], v[120:123]
	v_mfma_f32_16x16x32_bf16 v[108:111], v[156:159], v[190:193], v[108:111]
	v_mfma_f32_16x16x32_bf16 v[104:107], v[164:167], v[190:193], v[104:107]
	v_mfma_f32_16x16x32_bf16 v[92:95], v[156:159], v[198:201], v[92:95]
	v_mfma_f32_16x16x32_bf16 v[88:91], v[164:167], v[198:201], v[88:91]
	v_mfma_f32_16x16x32_bf16 v[76:79], v[156:159], v[206:209], v[76:79]
	v_mfma_f32_16x16x32_bf16 v[72:75], v[164:167], v[206:209], v[72:75]
	v_mfma_f32_16x16x32_bf16 v[116:119], v[210:213], v[168:171], v[116:119]
	v_mfma_f32_16x16x32_bf16 v[112:115], v[218:221], v[168:171], v[112:115]
	v_mfma_f32_16x16x32_bf16 v[100:103], v[210:213], v[182:185], v[100:103]
	v_mfma_f32_16x16x32_bf16 v[96:99], v[218:221], v[182:185], v[96:99]
	v_mfma_f32_16x16x32_bf16 v[84:87], v[210:213], v[194:197], v[84:87]
	v_mfma_f32_16x16x32_bf16 v[80:83], v[218:221], v[194:197], v[80:83]
	v_mfma_f32_16x16x32_bf16 v[68:71], v[210:213], v[202:205], v[68:71]
	v_mfma_f32_16x16x32_bf16 v[64:67], v[218:221], v[202:205], v[64:67]
	v_mfma_f32_16x16x32_bf16 v[116:119], v[214:217], v[172:175], v[116:119]
	v_mfma_f32_16x16x32_bf16 v[112:115], v[222:225], v[172:175], v[112:115]
	v_mfma_f32_16x16x32_bf16 v[100:103], v[214:217], v[190:193], v[100:103]
	v_mfma_f32_16x16x32_bf16 v[96:99], v[222:225], v[190:193], v[96:99]
	v_mfma_f32_16x16x32_bf16 v[84:87], v[214:217], v[198:201], v[84:87]
	v_mfma_f32_16x16x32_bf16 v[80:83], v[222:225], v[198:201], v[80:83]
	v_mfma_f32_16x16x32_bf16 v[68:71], v[214:217], v[206:209], v[68:71]
	v_mfma_f32_16x16x32_bf16 v[64:67], v[222:225], v[206:209], v[64:67]
	s_barrier
; #define PG8_STAGE(bufoff, gbase, voff) do { _Pragma("unroll") for (int _i = 0; _i < 2; ++_i) \
;         __builtin_amdgcn_global_load_lds((const unsigned*)((const char*)(gbase) + (voff)[_i]), (PG8_LAS unsigned*)(lds + (bufoff) + ldsw + _i * 8192), 16, 0, 0); } while (0)
; #define PG8_LDA(dst, b, h) do { _Pragma("unroll") for (int m = 0; m < 4; ++m) _Pragma("unroll") for (int k = 0; k < 2; ++k) dst[m][k] = *(const PG8_LAS bf16x8*)(lds + PG8_SA(b, h) + aoff + m * 2048 + k * 1024); } while (0)
; #define PG8_WAIT_V(n) asm volatile("s_waitcnt vmcnt(" #n ")" ::: "memory")
; #define PG8_BAR __builtin_amdgcn_s_barrier()
; template <class Epi, class Sched>
; __device__ __forceinline__ void gemm_phase(PG8_LAS unsigned char* lds, const Gemm g, const Sched& S, const Epi& E) {
;     ...
;             const bool last = (t == nt - 2);
;             const char* a1 = cA + (size_t)(t + 1) * kstep;
;             const char* a2 = last ? nA : cA + (size_t)(t + 2) * kstep; const char* b2 = last ? nB : cB + (size_t)(t + 2) * kstep;
;             const char* a3 = a2 + kstep; const char* b3 = b2 + kstep;
;             if (last && has_next) S.a_ready(nxt);
;             PG8_LDB(B0, 0, 0); PG8_SCHED; PG8_LDA(At, 0, 0); PG8_STAGE(PG8_SA(1, 1), a1 + hstep, voffA);
;             PG8_WAIT_L(8); PG8_BAR; PG8_WAIT_L(0); PG8_MMA(0, 0, At, B0); PG8_BAR; PG8_SCHED;
;             PG8_LDB(B1, 0, 1); PG8_STAGE(PG8_SB(0, 0), b2, voffB);
;             PG8_BAR; PG8_WAIT_L(0); PG8_MMA(0, 1, At, B1); PG8_BAR;
;             PG8_LDA(At, 0, 1); PG8_STAGE(PG8_SA(0, 0), a2, voffA);
;             PG8_BAR; PG8_WAIT_L(0); PG8_MMA(1, 0, At, B0); PG8_BAR; PG8_SCHED;
;             PG8_STAGE(PG8_SB(0, 1), b2 + hstep, voffB);
;             PG8_WAIT_V(6); PG8_BAR; PG8_MMA(1, 1, At, B1); PG8_BAR;
;             PG8_LDB(B0, 1, 0); PG8_SCHED; PG8_LDA(At, 1, 0); PG8_STAGE(PG8_SA(0, 1), a2 + hstep, voffA);
;             PG8_WAIT_L(8); PG8_BAR; PG8_WAIT_L(0); PG8_MMA(0, 0, At, B0); PG8_BAR; PG8_SCHED;
;             PG8_LDB(B1, 1, 1); PG8_STAGE(PG8_SB(1, 0), b3, voffB);
;             PG8_BAR; PG8_WAIT_L(0); PG8_MMA(0, 1, At, B1); PG8_BAR;
;             PG8_LDA(At, 1, 1); PG8_STAGE(PG8_SA(1, 0), a3, voffA);
;             PG8_BAR; PG8_WAIT_L(0); PG8_MMA(1, 0, At, B0); PG8_BAR; PG8_SCHED;
;             PG8_STAGE(PG8_SB(1, 1), b3 + hstep, voffB);
;             PG8_WAIT_V(6); PG8_BAR; PG8_MMA(1, 1, At, B1); PG8_BAR;
	ds_read_b128 v[168:171], v154 offset:49152
	ds_read_b128 v[172:175], v154 offset:50176
	ds_read_b128 v[182:185], v154 offset:51200
	ds_read_b128 v[190:193], v154 offset:52224
	ds_read_b128 v[194:197], v154 offset:53248
	ds_read_b128 v[198:201], v154 offset:54272
	ds_read_b128 v[202:205], v154 offset:55296
	ds_read_b128 v[206:209], v154 offset:56320
	s_add_i32 s23, s48, s29
	s_mov_b32 m0, s23
	s_nop 0
	global_load_lds_dwordx4 v130, s[98:99]
	s_nop 1
	s_add_i32 m0, s23, 0x2000
	s_nop 0
	global_load_lds_dwordx4 v134, s[98:99]
	s_nop 1
	s_mov_b32 m0, s36
	s_nop 0
	global_load_lds_dwordx4 v128, s[100:101]
	s_nop 1
	s_mov_b32 m0, s37
	s_nop 0
	global_load_lds_dwordx4 v132, s[100:101]
	s_add_u32 s20, s20, 0x40080
	s_addc_u32 s21, s21, 0
	s_add_i32 s22, s22, s29
	s_mov_b32 m0, s22
	s_nop 0
	global_load_lds_dwordx4 v130, s[20:21]
	s_nop 1
	s_add_i32 m0, s22, 0x2000
	s_nop 0
	global_load_lds_dwordx4 v134, s[20:21]
	s_waitcnt vmcnt(8) lgkmcnt(0)
	s_barrier
	v_mfma_f32_16x16x32_bf16 v[60:63], v[144:147], v[168:171], v[60:63]
	v_mfma_f32_16x16x32_bf16 v[56:59], v[160:163], v[168:171], v[56:59]
	v_mfma_f32_16x16x32_bf16 v[44:47], v[144:147], v[182:185], v[44:47]
	v_mfma_f32_16x16x32_bf16 v[40:43], v[160:163], v[182:185], v[40:43]
	v_mfma_f32_16x16x32_bf16 v[28:31], v[144:147], v[194:197], v[28:31]
	v_mfma_f32_16x16x32_bf16 v[24:27], v[160:163], v[194:197], v[24:27]
	v_mfma_f32_16x16x32_bf16 v[12:15], v[144:147], v[202:205], v[12:15]
	v_mfma_f32_16x16x32_bf16 v[8:11], v[160:163], v[202:205], v[8:11]
	v_mfma_f32_16x16x32_bf16 v[60:63], v[156:159], v[172:175], v[60:63]
	v_mfma_f32_16x16x32_bf16 v[56:59], v[164:167], v[172:175], v[56:59]
	v_mfma_f32_16x16x32_bf16 v[44:47], v[156:159], v[190:193], v[44:47]
	v_mfma_f32_16x16x32_bf16 v[40:43], v[164:167], v[190:193], v[40:43]
	v_mfma_f32_16x16x32_bf16 v[28:31], v[156:159], v[198:201], v[28:31]
	v_mfma_f32_16x16x32_bf16 v[24:27], v[164:167], v[198:201], v[24:27]
	v_mfma_f32_16x16x32_bf16 v[12:15], v[156:159], v[206:209], v[12:15]
	v_mfma_f32_16x16x32_bf16 v[8:11], v[164:167], v[206:209], v[8:11]
	v_mfma_f32_16x16x32_bf16 v[52:55], v[210:213], v[168:171], v[52:55]
	v_mfma_f32_16x16x32_bf16 v[48:51], v[218:221], v[168:171], v[48:51]
	v_mfma_f32_16x16x32_bf16 v[36:39], v[210:213], v[182:185], v[36:39]
	v_mfma_f32_16x16x32_bf16 v[32:35], v[218:221], v[182:185], v[32:35]
	v_mfma_f32_16x16x32_bf16 v[20:23], v[210:213], v[194:197], v[20:23]
	v_mfma_f32_16x16x32_bf16 v[16:19], v[218:221], v[194:197], v[16:19]
	v_mfma_f32_16x16x32_bf16 v[4:7], v[210:213], v[202:205], v[4:7]
	v_mfma_f32_16x16x32_bf16 v[0:3], v[218:221], v[202:205], v[0:3]
	v_mfma_f32_16x16x32_bf16 v[52:55], v[214:217], v[172:175], v[52:55]
	v_mfma_f32_16x16x32_bf16 v[48:51], v[222:225], v[172:175], v[48:51]
	v_mfma_f32_16x16x32_bf16 v[36:39], v[214:217], v[190:193], v[36:39]
	v_mfma_f32_16x16x32_bf16 v[32:35], v[222:225], v[190:193], v[32:35]
	v_mfma_f32_16x16x32_bf16 v[20:23], v[214:217], v[198:201], v[20:23]
	v_mfma_f32_16x16x32_bf16 v[16:19], v[222:225], v[198:201], v[16:19]
	v_mfma_f32_16x16x32_bf16 v[4:7], v[214:217], v[206:209], v[4:7]
	v_mfma_f32_16x16x32_bf16 v[0:3], v[222:225], v[206:209], v[0:3]
	s_barrier
	s_add_i32 s47, s47, 2
	s_add_u32 s18, s18, 0x100
	s_addc_u32 s19, s19, 0
	s_add_u32 s45, s45, 0x100
	s_addc_u32 s46, s46, 0
	s_cmp_gt_u32 s47, 13
.LBB0_1011:
	ds_read_b128 v[144:147], v153
	ds_read_b128 v[156:159], v153 offset:1024
	ds_read_b128 v[160:163], v153 offset:2048
	ds_read_b128 v[164:167], v153 offset:3072
	s_add_u32 s20, s18, 0xfffc0080
	s_addc_u32 s21, s19, -1
	s_cmp_eq_u32 s47, 12
	s_cselect_b32 s23, s11, s21
	s_cselect_b32 s22, s43, s20
	s_cselect_b32 s21, s9, s46
	s_cselect_b32 s20, s44, s45
	s_add_i32 m0, s17, 0xc000
	ds_read_b128 v[168:171], v154
	ds_read_b128 v[172:175], v154 offset:1024
	ds_read_b128 v[182:185], v154 offset:2048
	ds_read_b128 v[190:193], v154 offset:3072
	ds_read_b128 v[194:197], v154 offset:4096
	ds_read_b128 v[198:201], v154 offset:5120
	ds_read_b128 v[202:205], v154 offset:6144
	ds_read_b128 v[206:209], v154 offset:7168
	global_load_lds_dwordx4 v136, s[18:19]
	s_nop 1
	s_add_i32 m0, s17, 0xe000
	s_nop 0
	global_load_lds_dwordx4 v138, s[18:19]
	s_waitcnt lgkmcnt(12)
	ds_read_b128 v[210:213], v155
	ds_read_b128 v[214:217], v155 offset:1024
	ds_read_b128 v[218:221], v155 offset:2048
	ds_read_b128 v[222:225], v155 offset:3072
	s_waitcnt vmcnt(8) lgkmcnt(0)
	s_barrier
	v_mfma_f32_16x16x32_bf16 v[124:127], v[144:147], v[168:171], v[124:127]
	v_mfma_f32_16x16x32_bf16 v[120:123], v[160:163], v[168:171], v[120:123]
	v_mfma_f32_16x16x32_bf16 v[108:111], v[144:147], v[182:185], v[108:111]
	v_mfma_f32_16x16x32_bf16 v[104:107], v[160:163], v[182:185], v[104:107]
	v_mfma_f32_16x16x32_bf16 v[92:95], v[144:147], v[194:197], v[92:95]
	v_mfma_f32_16x16x32_bf16 v[88:91], v[160:163], v[194:197], v[88:91]
	v_mfma_f32_16x16x32_bf16 v[76:79], v[144:147], v[202:205], v[76:79]
	v_mfma_f32_16x16x32_bf16 v[72:75], v[160:163], v[202:205], v[72:75]
	v_mfma_f32_16x16x32_bf16 v[124:127], v[156:159], v[172:175], v[124:127]
	v_mfma_f32_16x16x32_bf16 v[120:123], v[164:167], v[172:175], v[120:123]
	v_mfma_f32_16x16x32_bf16 v[108:111], v[156:159], v[190:193], v[108:111]
	v_mfma_f32_16x16x32_bf16 v[104:107], v[164:167], v[190:193], v[104:107]
	v_mfma_f32_16x16x32_bf16 v[92:95], v[156:159], v[198:201], v[92:95]
	v_mfma_f32_16x16x32_bf16 v[88:91], v[164:167], v[198:201], v[88:91]
	v_mfma_f32_16x16x32_bf16 v[76:79], v[156:159], v[206:209], v[76:79]
	v_mfma_f32_16x16x32_bf16 v[72:75], v[164:167], v[206:209], v[72:75]
	v_mfma_f32_16x16x32_bf16 v[116:119], v[210:213], v[168:171], v[116:119]
	v_mfma_f32_16x16x32_bf16 v[112:115], v[218:221], v[168:171], v[112:115]
	v_mfma_f32_16x16x32_bf16 v[100:103], v[210:213], v[182:185], v[100:103]
	v_mfma_f32_16x16x32_bf16 v[96:99], v[218:221], v[182:185], v[96:99]
	v_mfma_f32_16x16x32_bf16 v[84:87], v[210:213], v[194:197], v[84:87]
	v_mfma_f32_16x16x32_bf16 v[80:83], v[218:221], v[194:197], v[80:83]
	v_mfma_f32_16x16x32_bf16 v[68:71], v[210:213], v[202:205], v[68:71]
	v_mfma_f32_16x16x32_bf16 v[64:67], v[218:221], v[202:205], v[64:67]
	v_mfma_f32_16x16x32_bf16 v[116:119], v[214:217], v[172:175], v[116:119]
	v_mfma_f32_16x16x32_bf16 v[112:115], v[222:225], v[172:175], v[112:115]
	v_mfma_f32_16x16x32_bf16 v[100:103], v[214:217], v[190:193], v[100:103]
	v_mfma_f32_16x16x32_bf16 v[96:99], v[222:225], v[190:193], v[96:99]
	v_mfma_f32_16x16x32_bf16 v[84:87], v[214:217], v[198:201], v[84:87]
	v_mfma_f32_16x16x32_bf16 v[80:83], v[222:225], v[198:201], v[80:83]
	v_mfma_f32_16x16x32_bf16 v[68:71], v[214:217], v[206:209], v[68:71]
	v_mfma_f32_16x16x32_bf16 v[64:67], v[222:225], v[206:209], v[64:67]
	s_barrier
; #define PG8_STAGE(bufoff, gbase, voff) do { _Pragma("unroll") for (int _i = 0; _i < 2; ++_i) \
;         __builtin_amdgcn_global_load_lds((const unsigned*)((const char*)(gbase) + (voff)[_i]), (PG8_LAS unsigned*)(lds + (bufoff) + ldsw + _i * 8192), 16, 0, 0); } while (0)
; #define PG8_LDA(dst, b, h) do { _Pragma("unroll") for (int m = 0; m < 4; ++m) _Pragma("unroll") for (int k = 0; k < 2; ++k) dst[m][k] = *(const PG8_LAS bf16x8*)(lds + PG8_SA(b, h) + aoff + m * 2048 + k * 1024); } while (0)
; #define PG8_LDB(dst, b, h) do { _Pragma("unroll") for (int n = 0; n < 2; ++n) _Pragma("unroll") for (int k = 0; k < 2; ++k) dst[n][k] = *(const PG8_LAS bf16x8*)(lds + PG8_SB(b, h) + boff + n * 2048 + k * 1024); } while (0)
; #define PG8_MMA(ai, bj, At, Bt) do { __builtin_amdgcn_s_setprio(1); _Pragma("unroll") for (int m = 0; m < 4; ++m) _Pragma("unroll") for (int n = 0; n < 2; ++n) _Pragma("unroll") for (int k = 0; k < 2; ++k) \
;         acc[ai][bj][m][n] = __builtin_amdgcn_mfma_f32_16x16x32_bf16(Bt[n][k], At[m][k], acc[ai][bj][m][n], 0, 0, 0); __builtin_amdgcn_s_setprio(0); } while (0)
; #define PG8_WAIT_V(n) asm volatile("s_waitcnt vmcnt(" #n ")" ::: "memory")
; #define PG8_WAIT_L(n) asm volatile("s_waitcnt lgkmcnt(" #n ")" ::: "memory")
; #define PG8_BAR __builtin_amdgcn_s_barrier()
; #define PG8_SCHED __builtin_amdgcn_sched_barrier(0)
; template <class Epi, class Sched>
; __device__ __forceinline__ void gemm_phase(PG8_LAS unsigned char* lds, const Gemm g, const Sched& S, const Epi& E) {
;     ...
;             PG8_LDA(At, 0, 1); PG8_STAGE(PG8_SA(0, 0), a2, voffA);
;             PG8_BAR; PG8_WAIT_L(0); PG8_MMA(1, 0, At, B0); PG8_BAR; PG8_SCHED;
;             PG8_STAGE(PG8_SB(0, 1), b2 + hstep, voffB);
;             PG8_WAIT_V(6); PG8_BAR; PG8_MMA(1, 1, At, B1); PG8_BAR;
;             PG8_LDB(B0, 1, 0); PG8_SCHED; PG8_LDA(At, 1, 0); PG8_STAGE(PG8_SA(0, 1), a2 + hstep, voffA);
;             PG8_WAIT_L(8); PG8_BAR; PG8_WAIT_L(0); PG8_MMA(0, 0, At, B0); PG8_BAR; PG8_SCHED;
;             PG8_LDB(B1, 1, 1); PG8_STAGE(PG8_SB(1, 0), b3, voffB);
;             PG8_BAR; PG8_WAIT_L(0); PG8_MMA(0, 1, At, B1); PG8_BAR;
	ds_read_b128 v[168:171], v154 offset:16384
	ds_read_b128 v[172:175], v154 offset:17408
	ds_read_b128 v[182:185], v154 offset:18432
	ds_read_b128 v[190:193], v154 offset:19456
	ds_read_b128 v[194:197], v154 offset:20480
	ds_read_b128 v[198:201], v154 offset:21504
	ds_read_b128 v[202:205], v154 offset:22528
	ds_read_b128 v[206:209], v154 offset:23552
	s_add_i32 s48, s39, s29
	s_add_u32 s98, s20, s6
	s_addc_u32 s99, s21, s7
	s_mov_b32 m0, s48
	s_nop 0
	global_load_lds_dwordx4 v130, s[20:21]
	s_nop 1
	s_add_i32 m0, s48, 0x2000
	s_nop 0
	global_load_lds_dwordx4 v134, s[20:21]
	s_nop 1
	s_mov_b32 m0, s17
	s_add_u32 s100, s22, s6
	s_addc_u32 s101, s23, s7
	global_load_lds_dwordx4 v128, s[22:23]
	s_nop 1
	s_mov_b32 m0, s30
	s_nop 0
	global_load_lds_dwordx4 v132, s[22:23]
	s_add_u32 s48, s20, 0x40000
	s_addc_u32 s49, s21, 0
	s_add_i32 s50, s40, s29
	s_mov_b32 m0, s50
	s_nop 0
	global_load_lds_dwordx4 v130, s[48:49]
	s_nop 1
	s_add_i32 m0, s50, 0x2000
	s_nop 0
	global_load_lds_dwordx4 v134, s[48:49]
	s_waitcnt vmcnt(8) lgkmcnt(0)
	s_barrier
	v_mfma_f32_16x16x32_bf16 v[60:63], v[144:147], v[168:171], v[60:63]
	v_mfma_f32_16x16x32_bf16 v[56:59], v[160:163], v[168:171], v[56:59]
	v_mfma_f32_16x16x32_bf16 v[44:47], v[144:147], v[182:185], v[44:47]
	v_mfma_f32_16x16x32_bf16 v[40:43], v[160:163], v[182:185], v[40:43]
	v_mfma_f32_16x16x32_bf16 v[28:31], v[144:147], v[194:197], v[28:31]
	v_mfma_f32_16x16x32_bf16 v[24:27], v[160:163], v[194:197], v[24:27]
	v_mfma_f32_16x16x32_bf16 v[12:15], v[144:147], v[202:205], v[12:15]
	v_mfma_f32_16x16x32_bf16 v[8:11], v[160:163], v[202:205], v[8:11]
	v_mfma_f32_16x16x32_bf16 v[60:63], v[156:159], v[172:175], v[60:63]
	v_mfma_f32_16x16x32_bf16 v[56:59], v[164:167], v[172:175], v[56:59]
	v_mfma_f32_16x16x32_bf16 v[44:47], v[156:159], v[190:193], v[44:47]
	v_mfma_f32_16x16x32_bf16 v[40:43], v[164:167], v[190:193], v[40:43]
	v_mfma_f32_16x16x32_bf16 v[28:31], v[156:159], v[198:201], v[28:31]
	v_mfma_f32_16x16x32_bf16 v[24:27], v[164:167], v[198:201], v[24:27]
	v_mfma_f32_16x16x32_bf16 v[12:15], v[156:159], v[206:209], v[12:15]
	v_mfma_f32_16x16x32_bf16 v[8:11], v[164:167], v[206:209], v[8:11]
	v_mfma_f32_16x16x32_bf16 v[52:55], v[210:213], v[168:171], v[52:55]
	v_mfma_f32_16x16x32_bf16 v[48:51], v[218:221], v[168:171], v[48:51]
	v_mfma_f32_16x16x32_bf16 v[36:39], v[210:213], v[182:185], v[36:39]
	v_mfma_f32_16x16x32_bf16 v[32:35], v[218:221], v[182:185], v[32:35]
	v_mfma_f32_16x16x32_bf16 v[20:23], v[210:213], v[194:197], v[20:23]
	v_mfma_f32_16x16x32_bf16 v[16:19], v[218:221], v[194:197], v[16:19]
	v_mfma_f32_16x16x32_bf16 v[4:7], v[210:213], v[202:205], v[4:7]
	v_mfma_f32_16x16x32_bf16 v[0:3], v[218:221], v[202:205], v[0:3]
	v_mfma_f32_16x16x32_bf16 v[52:55], v[214:217], v[172:175], v[52:55]
	v_mfma_f32_16x16x32_bf16 v[48:51], v[222:225], v[172:175], v[48:51]
	v_mfma_f32_16x16x32_bf16 v[36:39], v[214:217], v[190:193], v[36:39]
	v_mfma_f32_16x16x32_bf16 v[32:35], v[222:225], v[190:193], v[32:35]
	v_mfma_f32_16x16x32_bf16 v[20:23], v[214:217], v[198:201], v[20:23]
	v_mfma_f32_16x16x32_bf16 v[16:19], v[222:225], v[198:201], v[16:19]
	v_mfma_f32_16x16x32_bf16 v[4:7], v[214:217], v[206:209], v[4:7]
	v_mfma_f32_16x16x32_bf16 v[0:3], v[222:225], v[206:209], v[0:3]
	s_barrier
	s_add_i32 s48, 0, 0x18000
	v_add_u32_e32 v164, s48, v151
	ds_read_b128 v[144:147], v164
	ds_read_b128 v[156:159], v164 offset:1024
	ds_read_b128 v[160:163], v164 offset:2048
	ds_read_b128 v[164:167], v164 offset:3072
	s_add_u32 s22, s22, 0x40000
	s_addc_u32 s23, s23, 0
	s_mov_b32 m0, s31
	ds_read_b128 v[168:171], v154 offset:32768
	ds_read_b128 v[172:175], v154 offset:33792
	ds_read_b128 v[182:185], v154 offset:34816
	ds_read_b128 v[190:193], v154 offset:35840
	ds_read_b128 v[194:197], v154 offset:36864
	ds_read_b128 v[198:201], v154 offset:37888
	ds_read_b128 v[202:205], v154 offset:38912
	ds_read_b128 v[206:209], v154 offset:39936
	global_load_lds_dwordx4 v128, s[22:23]
	s_nop 1
	s_mov_b32 m0, s34
	s_nop 0
	global_load_lds_dwordx4 v132, s[22:23]
	s_add_i32 s22, 0, 0x1c000
	v_add_u32_e32 v179, s22, v151
	s_waitcnt lgkmcnt(12)
	ds_read_b128 v[210:213], v179
	ds_read_b128 v[214:217], v179 offset:1024
	ds_read_b128 v[218:221], v179 offset:2048
	ds_read_b128 v[222:225], v179 offset:3072
	s_waitcnt vmcnt(8) lgkmcnt(0)
	s_barrier
	v_mfma_f32_16x16x32_bf16 v[124:127], v[144:147], v[168:171], v[124:127]
	v_mfma_f32_16x16x32_bf16 v[120:123], v[160:163], v[168:171], v[120:123]
	v_mfma_f32_16x16x32_bf16 v[108:111], v[144:147], v[182:185], v[108:111]
	v_mfma_f32_16x16x32_bf16 v[104:107], v[160:163], v[182:185], v[104:107]
	v_mfma_f32_16x16x32_bf16 v[92:95], v[144:147], v[194:197], v[92:95]
	v_mfma_f32_16x16x32_bf16 v[88:91], v[160:163], v[194:197], v[88:91]
	v_mfma_f32_16x16x32_bf16 v[76:79], v[144:147], v[202:205], v[76:79]
	v_mfma_f32_16x16x32_bf16 v[72:75], v[160:163], v[202:205], v[72:75]
	v_mfma_f32_16x16x32_bf16 v[124:127], v[156:159], v[172:175], v[124:127]
	v_mfma_f32_16x16x32_bf16 v[120:123], v[164:167], v[172:175], v[120:123]
	v_mfma_f32_16x16x32_bf16 v[108:111], v[156:159], v[190:193], v[108:111]
	v_mfma_f32_16x16x32_bf16 v[104:107], v[164:167], v[190:193], v[104:107]
	v_mfma_f32_16x16x32_bf16 v[92:95], v[156:159], v[198:201], v[92:95]
	v_mfma_f32_16x16x32_bf16 v[88:91], v[164:167], v[198:201], v[88:91]
	v_mfma_f32_16x16x32_bf16 v[76:79], v[156:159], v[206:209], v[76:79]
	v_mfma_f32_16x16x32_bf16 v[72:75], v[164:167], v[206:209], v[72:75]
	v_mfma_f32_16x16x32_bf16 v[116:119], v[210:213], v[168:171], v[116:119]
	v_mfma_f32_16x16x32_bf16 v[112:115], v[218:221], v[168:171], v[112:115]
	v_mfma_f32_16x16x32_bf16 v[100:103], v[210:213], v[182:185], v[100:103]
	v_mfma_f32_16x16x32_bf16 v[96:99], v[218:221], v[182:185], v[96:99]
	v_mfma_f32_16x16x32_bf16 v[84:87], v[210:213], v[194:197], v[84:87]
	v_mfma_f32_16x16x32_bf16 v[80:83], v[218:221], v[194:197], v[80:83]
	v_mfma_f32_16x16x32_bf16 v[68:71], v[210:213], v[202:205], v[68:71]
	v_mfma_f32_16x16x32_bf16 v[64:67], v[218:221], v[202:205], v[64:67]
	v_mfma_f32_16x16x32_bf16 v[116:119], v[214:217], v[172:175], v[116:119]
	v_mfma_f32_16x16x32_bf16 v[112:115], v[222:225], v[172:175], v[112:115]
	v_mfma_f32_16x16x32_bf16 v[100:103], v[214:217], v[190:193], v[100:103]
	v_mfma_f32_16x16x32_bf16 v[96:99], v[222:225], v[190:193], v[96:99]
	v_mfma_f32_16x16x32_bf16 v[84:87], v[214:217], v[198:201], v[84:87]
	v_mfma_f32_16x16x32_bf16 v[80:83], v[222:225], v[198:201], v[80:83]
	v_mfma_f32_16x16x32_bf16 v[68:71], v[214:217], v[206:209], v[68:71]
	v_mfma_f32_16x16x32_bf16 v[64:67], v[222:225], v[206:209], v[64:67]
	s_barrier
; __device__ __forceinline__ float bf_lo(unsigned u) { return __uint_as_float(u << 16); }
; __device__ __forceinline__ float bf_hi(unsigned u) { return __uint_as_float(u & 0xffff0000u); }
; #define PG8_STAGE(bufoff, gbase, voff) do { _Pragma("unroll") for (int _i = 0; _i < 2; ++_i) \
;         __builtin_amdgcn_global_load_lds((const unsigned*)((const char*)(gbase) + (voff)[_i]), (PG8_LAS unsigned*)(lds + (bufoff) + ldsw + _i * 8192), 16, 0, 0); } while (0)
; #define PG8_LDA(dst, b, h) do { _Pragma("unroll") for (int m = 0; m < 4; ++m) _Pragma("unroll") for (int k = 0; k < 2; ++k) dst[m][k] = *(const PG8_LAS bf16x8*)(lds + PG8_SA(b, h) + aoff + m * 2048 + k * 1024); } while (0)
; #define PG8_MMA(ai, bj, At, Bt) do { __builtin_amdgcn_s_setprio(1); _Pragma("unroll") for (int m = 0; m < 4; ++m) _Pragma("unroll") for (int n = 0; n < 2; ++n) _Pragma("unroll") for (int k = 0; k < 2; ++k) \
;         acc[ai][bj][m][n] = __builtin_amdgcn_mfma_f32_16x16x32_bf16(Bt[n][k], At[m][k], acc[ai][bj][m][n], 0, 0, 0); __builtin_amdgcn_s_setprio(0); } while (0)
; #define PG8_WAIT_V(n) asm volatile("s_waitcnt vmcnt(" #n ")" ::: "memory")
;     __device__ __forceinline__ void operator()(const f32x4 (&acc)[2][2][4][2], const Unit& u, int wr, int wc, int fr, int fq) const {
;     ...
;             for (int m = 0; m < 4; ++m) { const size_t r = (size_t)(row0 + ai * HALF + m * 16); bf16_t* rowp = O + r * ldc + col0; const bf16_t* gp = G + r * ldg + col0;
; #pragma unroll
;                 for (int bj = 0; bj < 2; ++bj) { const u32x4 gw = *(const u32x4*)(gp + bj * HALF);
;                     f32x4 v0 = acc[ai][bj][m][0], v1 = acc[ai][bj][m][1];
;                     v0[0] *= bf_lo(gw.x); v0[1] *= bf_hi(gw.x); v0[2] *= bf_lo(gw.y); v0[3] *= bf_hi(gw.y);
;                     v1[0] *= bf_lo(gw.z); v1[1] *= bf_hi(gw.z); v1[2] *= bf_lo(gw.w); v1[3] *= bf_hi(gw.w);
;                     if (ACCUM) { const u32x4 pw = *(const u32x4*)(rowp + bj * HALF);
; template <class Epi, class Sched>
; __device__ __forceinline__ void gemm_phase(PG8_LAS unsigned char* lds, const Gemm g, const Sched& S, const Epi& E) {
;     ...
;             PG8_LDA(At, 1, 1); PG8_STAGE(PG8_SA(1, 0), a3, voffA);
;             PG8_BAR; PG8_WAIT_L(0); PG8_MMA(1, 0, At, B0); PG8_BAR; PG8_SCHED;
;             PG8_STAGE(PG8_SB(1, 1), b3 + hstep, voffB);
;             PG8_WAIT_V(6); PG8_BAR; PG8_MMA(1, 1, At, B1); PG8_BAR;
	ds_read_b128 v[168:171], v154 offset:49152
	ds_read_b128 v[172:175], v154 offset:50176
	ds_read_b128 v[182:185], v154 offset:51200
	ds_read_b128 v[190:193], v154 offset:52224
	ds_read_b128 v[194:197], v154 offset:53248
	ds_read_b128 v[198:201], v154 offset:54272
	ds_read_b128 v[202:205], v154 offset:55296
	ds_read_b128 v[206:209], v154 offset:56320
	s_add_i32 s23, s48, s29
	s_mov_b32 m0, s23
	s_nop 0
	global_load_lds_dwordx4 v130, s[98:99]
	s_nop 1
	s_add_i32 m0, s23, 0x2000
	s_nop 0
	global_load_lds_dwordx4 v134, s[98:99]
	s_nop 1
	s_mov_b32 m0, s36
	s_nop 0
	global_load_lds_dwordx4 v128, s[100:101]
	s_nop 1
	s_mov_b32 m0, s37
	s_nop 0
	global_load_lds_dwordx4 v132, s[100:101]
	s_add_u32 s20, s20, 0x40080
	s_addc_u32 s21, s21, 0
	s_add_i32 s22, s22, s29
	s_mov_b32 m0, s22
	s_nop 0
	global_load_lds_dwordx4 v130, s[20:21]
	s_nop 1
	s_add_i32 m0, s22, 0x2000
	s_nop 0
	global_load_lds_dwordx4 v134, s[20:21]
	s_waitcnt vmcnt(8) lgkmcnt(0)
	s_barrier
	v_mfma_f32_16x16x32_bf16 v[60:63], v[144:147], v[168:171], v[60:63]
	v_mfma_f32_16x16x32_bf16 v[56:59], v[160:163], v[168:171], v[56:59]
	v_mfma_f32_16x16x32_bf16 v[44:47], v[144:147], v[182:185], v[44:47]
	v_mfma_f32_16x16x32_bf16 v[40:43], v[160:163], v[182:185], v[40:43]
	v_mfma_f32_16x16x32_bf16 v[28:31], v[144:147], v[194:197], v[28:31]
	v_mfma_f32_16x16x32_bf16 v[24:27], v[160:163], v[194:197], v[24:27]
	v_mfma_f32_16x16x32_bf16 v[12:15], v[144:147], v[202:205], v[12:15]
	v_mfma_f32_16x16x32_bf16 v[8:11], v[160:163], v[202:205], v[8:11]
	v_mfma_f32_16x16x32_bf16 v[60:63], v[156:159], v[172:175], v[60:63]
	v_mfma_f32_16x16x32_bf16 v[56:59], v[164:167], v[172:175], v[56:59]
	v_mfma_f32_16x16x32_bf16 v[44:47], v[156:159], v[190:193], v[44:47]
	v_mfma_f32_16x16x32_bf16 v[40:43], v[164:167], v[190:193], v[40:43]
	v_mfma_f32_16x16x32_bf16 v[28:31], v[156:159], v[198:201], v[28:31]
	v_mfma_f32_16x16x32_bf16 v[24:27], v[164:167], v[198:201], v[24:27]
	v_mfma_f32_16x16x32_bf16 v[12:15], v[156:159], v[206:209], v[12:15]
	v_mfma_f32_16x16x32_bf16 v[8:11], v[164:167], v[206:209], v[8:11]
	v_mfma_f32_16x16x32_bf16 v[52:55], v[210:213], v[168:171], v[52:55]
	v_mfma_f32_16x16x32_bf16 v[48:51], v[218:221], v[168:171], v[48:51]
	v_mfma_f32_16x16x32_bf16 v[36:39], v[210:213], v[182:185], v[36:39]
	v_mfma_f32_16x16x32_bf16 v[32:35], v[218:221], v[182:185], v[32:35]
	v_mfma_f32_16x16x32_bf16 v[20:23], v[210:213], v[194:197], v[20:23]
	v_mfma_f32_16x16x32_bf16 v[16:19], v[218:221], v[194:197], v[16:19]
	v_mfma_f32_16x16x32_bf16 v[4:7], v[210:213], v[202:205], v[4:7]
	v_mfma_f32_16x16x32_bf16 v[0:3], v[218:221], v[202:205], v[0:3]
	v_mfma_f32_16x16x32_bf16 v[52:55], v[214:217], v[172:175], v[52:55]
	v_mfma_f32_16x16x32_bf16 v[48:51], v[222:225], v[172:175], v[48:51]
	v_mfma_f32_16x16x32_bf16 v[36:39], v[214:217], v[190:193], v[36:39]
	v_mfma_f32_16x16x32_bf16 v[32:35], v[222:225], v[190:193], v[32:35]
	v_mfma_f32_16x16x32_bf16 v[20:23], v[214:217], v[198:201], v[20:23]
	v_mfma_f32_16x16x32_bf16 v[16:19], v[222:225], v[198:201], v[16:19]
	v_mfma_f32_16x16x32_bf16 v[4:7], v[214:217], v[206:209], v[4:7]
	v_mfma_f32_16x16x32_bf16 v[0:3], v[222:225], v[206:209], v[0:3]
	s_barrier
	s_add_i32 s47, s47, 2
	s_add_u32 s18, s18, 0x100
	s_addc_u32 s19, s19, 0
	s_add_u32 s45, s45, 0x100
	s_addc_u32 s46, s46, 0
	s_cmp_gt_u32 s47, 13
	s_cbranch_scc0 .LBB0_1011
	v_lshl_add_u32 v146, s16, 8, v150
	v_lshl_or_b32 v144, s42, 8, v152
	v_ashrrev_i32_e32 v147, 31, v146
	v_ashrrev_i32_e32 v145, 31, v144
	v_mov_b64_e32 v[148:149], s[4:5]
	v_lshlrev_b64 v[160:161], 11, v[146:147]
	v_lshlrev_b64 v[144:145], 1, v[144:145]
	v_mad_i64_i32 v[156:157], s[18:19], v146, s41, v[148:149]
	v_lshl_add_u64 v[160:161], s[0:1], 0, v[160:161]
	v_lshl_add_u64 v[164:165], v[156:157], 0, v[144:145]
	v_lshl_add_u64 v[166:167], v[160:161], 0, v[144:145]
	v_mov_b64_e32 v[218:219], v[164:165]
	v_mov_b64_e32 v[220:221], v[166:167]
	s_mul_i32 s98, s41, 0
	s_mov_b32 s99, 0
	v_lshl_add_u64 v[222:223], v[218:219], 0, s[98:99]
	global_load_dwordx4 v[182:185], v[222:223], off
	s_mov_b32 s98, 0
	v_lshl_add_u64 v[224:225], v[220:221], 0, s[98:99]
	global_load_dwordx4 v[190:193], v[224:225], off
	s_mul_i32 s98, s41, 0
	s_mov_b32 s99, 0
	v_lshl_add_u64 v[222:223], v[218:219], 0, s[98:99]
	global_load_dwordx4 v[194:197], v[222:223], off offset:256
	s_mov_b32 s98, 0
	v_lshl_add_u64 v[224:225], v[220:221], 0, s[98:99]
	global_load_dwordx4 v[198:201], v[224:225], off offset:256
	s_mul_i32 s98, s41, 16
	s_mov_b32 s99, 0
	v_lshl_add_u64 v[222:223], v[218:219], 0, s[98:99]
	global_load_dwordx4 v[202:205], v[222:223], off
	s_mov_b32 s98, 32768
	v_lshl_add_u64 v[224:225], v[220:221], 0, s[98:99]
	global_load_dwordx4 v[206:209], v[224:225], off
	s_mul_i32 s98, s41, 16
	s_mov_b32 s99, 0
	v_lshl_add_u64 v[222:223], v[218:219], 0, s[98:99]
	global_load_dwordx4 v[210:213], v[222:223], off offset:256
	s_mov_b32 s98, 32768
	v_lshl_add_u64 v[224:225], v[220:221], 0, s[98:99]
	global_load_dwordx4 v[214:217], v[224:225], off offset:256
	s_and_b64 vcc, exec, s[2:3]
	s_mov_b32 s42, s8
	s_mov_b32 s16, s10
	s_mov_b64 s[20:21], s[14:15]
	s_waitcnt vmcnt(6)
; __device__ __forceinline__ unsigned cvt_pk_bf16(float lo, float hi) { unsigned r; asm volatile("v_cvt_pk_bf16_f32 %0, %1, %2" : "=v"(r) : "v"(lo), "v"(hi)); return r; }
; __device__ __forceinline__ float bf_lo(unsigned u) { return __uint_as_float(u << 16); }
; __device__ __forceinline__ float bf_hi(unsigned u) { return __uint_as_float(u & 0xffff0000u); }
;     __device__ __forceinline__ void operator()(const f32x4 (&acc)[2][2][4][2], const Unit& u, int wr, int wc, int fr, int fq) const {
;     ...
;             for (int m = 0; m < 4; ++m) { const size_t r = (size_t)(row0 + ai * HALF + m * 16); bf16_t* rowp = O + r * ldc + col0; const bf16_t* gp = G + r * ldg + col0;
; #pragma unroll
;                 for (int bj = 0; bj < 2; ++bj) { const u32x4 gw = *(const u32x4*)(gp + bj * HALF);
;                     f32x4 v0 = acc[ai][bj][m][0], v1 = acc[ai][bj][m][1];
;                     v0[0] *= bf_lo(gw.x); v0[1] *= bf_hi(gw.x); v0[2] *= bf_lo(gw.y); v0[3] *= bf_hi(gw.y);
;                     v1[0] *= bf_lo(gw.z); v1[1] *= bf_hi(gw.z); v1[2] *= bf_lo(gw.w); v1[3] *= bf_hi(gw.w);
;                     if (ACCUM) { const u32x4 pw = *(const u32x4*)(rowp + bj * HALF);
;                         v0[0] += bf_lo(pw.x); v0[1] += bf_hi(pw.x); v0[2] += bf_lo(pw.y); v0[3] += bf_hi(pw.y);
;                         v1[0] += bf_lo(pw.z); v1[1] += bf_hi(pw.z); v1[2] += bf_lo(pw.w); v1[3] += bf_hi(pw.w); }
;                     u32x4 w; w.x = cvt_pk_bf16(v0[0], v0[1]); w.y = cvt_pk_bf16(v0[2], v0[3]); w.z = cvt_pk_bf16(v1[0], v1[1]); w.w = cvt_pk_bf16(v1[2], v1[3]);
;                     *(u32x4*)(rowp + bj * HALF) = w; } }
	v_mov_b32_e32 v156, v182
	v_mov_b32_e32 v157, v183
	v_mov_b32_e32 v158, v184
	v_mov_b32_e32 v159, v185
	v_mov_b32_e32 v160, v190
	v_mov_b32_e32 v161, v191
	v_mov_b32_e32 v162, v192
	v_mov_b32_e32 v163, v193
	s_mul_i32 s98, s41, 32
	s_mov_b32 s99, 0
	v_lshl_add_u64 v[222:223], v[218:219], 0, s[98:99]
	global_load_dwordx4 v[182:185], v[222:223], off
	s_mov_b32 s98, 65536
	v_lshl_add_u64 v[224:225], v[220:221], 0, s[98:99]
	global_load_dwordx4 v[190:193], v[224:225], off
	v_lshlrev_b32_e32 v147, 16, v156
	v_and_b32_e32 v156, 0xffff0000, v156
	v_lshlrev_b32_e32 v168, 16, v157
	v_and_b32_e32 v157, 0xffff0000, v157
	v_lshlrev_b32_e32 v169, 16, v158
	v_and_b32_e32 v158, 0xffff0000, v158
	v_lshlrev_b32_e32 v170, 16, v159
	v_and_b32_e32 v159, 0xffff0000, v159
	v_lshlrev_b32_e32 v171, 16, v160
	v_and_b32_e32 v160, 0xffff0000, v160
	v_lshlrev_b32_e32 v172, 16, v161
	v_and_b32_e32 v161, 0xffff0000, v161
	v_lshlrev_b32_e32 v173, 16, v162
	v_and_b32_e32 v162, 0xffff0000, v162
	v_lshlrev_b32_e32 v174, 16, v163
	v_and_b32_e32 v163, 0xffff0000, v163
	v_fmac_f32_e32 v171, v124, v147
	v_fmac_f32_e32 v160, v125, v156
	v_fmac_f32_e32 v172, v126, v168
	v_fmac_f32_e32 v161, v127, v157
	v_fmac_f32_e32 v173, v120, v169
	v_fmac_f32_e32 v162, v121, v158
	v_fmac_f32_e32 v174, v122, v170
	v_fmac_f32_e32 v163, v123, v159
	v_cvt_pk_bf16_f32 v120, v171, v160
	v_cvt_pk_bf16_f32 v121, v172, v161
	v_cvt_pk_bf16_f32 v122, v173, v162
	v_cvt_pk_bf16_f32 v123, v174, v163
	v_or_b32_e32 v160, 16, v146
	global_store_dwordx4 v[166:167], v[120:123], off
	v_mad_i64_i32 v[162:163], s[18:19], v160, s41, v[148:149]
	v_lshl_add_u64 v[162:163], v[162:163], 0, v[144:145]
	s_waitcnt vmcnt(7)
	v_mov_b32_e32 v124, v194
	v_mov_b32_e32 v125, v195
	v_mov_b32_e32 v126, v196
	v_mov_b32_e32 v127, v197
	v_mov_b32_e32 v156, v198
	v_mov_b32_e32 v157, v199
	v_mov_b32_e32 v158, v200
	v_mov_b32_e32 v159, v201
	s_mul_i32 s98, s41, 32
	s_mov_b32 s99, 0
	v_lshl_add_u64 v[222:223], v[218:219], 0, s[98:99]
	global_load_dwordx4 v[194:197], v[222:223], off offset:256
	s_mov_b32 s98, 65536
	v_lshl_add_u64 v[224:225], v[220:221], 0, s[98:99]
	global_load_dwordx4 v[198:201], v[224:225], off offset:256
	v_lshlrev_b32_e32 v122, 16, v125
	v_lshlrev_b32_e32 v161, 16, v157
	v_lshlrev_b32_e32 v120, 16, v124
	v_and_b32_e32 v121, 0xffff0000, v124
	v_and_b32_e32 v123, 0xffff0000, v125
	v_lshlrev_b32_e32 v124, 16, v126
	v_and_b32_e32 v125, 0xffff0000, v126
	v_lshlrev_b32_e32 v147, 16, v156
	v_and_b32_e32 v156, 0xffff0000, v156
	v_and_b32_e32 v157, 0xffff0000, v157
	v_lshlrev_b32_e32 v164, 16, v158
	v_and_b32_e32 v158, 0xffff0000, v158
	v_fmac_f32_e32 v161, v118, v122
	v_fmac_f32_e32 v147, v116, v120
	v_fmac_f32_e32 v156, v117, v121
	v_fmac_f32_e32 v157, v119, v123
	v_fmac_f32_e32 v164, v112, v124
	v_fmac_f32_e32 v158, v113, v125
	v_cvt_pk_bf16_f32 v112, v147, v156
	v_cvt_pk_bf16_f32 v113, v161, v157
	v_ashrrev_i32_e32 v161, 31, v160
	v_lshlrev_b64 v[120:121], 11, v[160:161]
	v_lshl_add_u64 v[120:121], s[0:1], 0, v[120:121]
	v_lshlrev_b32_e32 v126, 16, v127
	v_and_b32_e32 v127, 0xffff0000, v127
	v_lshlrev_b32_e32 v165, 16, v159
	v_and_b32_e32 v159, 0xffff0000, v159
	v_lshl_add_u64 v[124:125], v[120:121], 0, v[144:145]
	v_fmac_f32_e32 v165, v114, v126
	v_fmac_f32_e32 v159, v115, v127
	v_cvt_pk_bf16_f32 v114, v164, v158
	v_cvt_pk_bf16_f32 v115, v165, v159
	s_waitcnt vmcnt(7)
	v_mov_b32_e32 v116, v202
	v_mov_b32_e32 v117, v203
	v_mov_b32_e32 v118, v204
	v_mov_b32_e32 v119, v205
	v_mov_b32_e32 v120, v206
	v_mov_b32_e32 v121, v207
	v_mov_b32_e32 v122, v208
	v_mov_b32_e32 v123, v209
	s_mul_i32 s98, s41, 48
	s_mov_b32 s99, 0
	v_lshl_add_u64 v[222:223], v[218:219], 0, s[98:99]
	global_load_dwordx4 v[202:205], v[222:223], off
	s_mov_b32 s98, 98304
	v_lshl_add_u64 v[224:225], v[220:221], 0, s[98:99]
	global_load_dwordx4 v[206:209], v[224:225], off
	v_lshlrev_b32_e32 v126, 16, v120
	global_store_dwordx4 v[166:167], v[112:115], off offset:256
	v_and_b32_e32 v120, 0xffff0000, v120
	v_lshlrev_b32_e32 v127, 16, v121
	v_lshlrev_b32_e32 v112, 16, v116
	v_and_b32_e32 v113, 0xffff0000, v116
	v_lshlrev_b32_e32 v114, 16, v117
	v_and_b32_e32 v115, 0xffff0000, v117
	v_lshlrev_b32_e32 v116, 16, v118
	v_and_b32_e32 v117, 0xffff0000, v118
	v_lshlrev_b32_e32 v118, 16, v119
	v_and_b32_e32 v119, 0xffff0000, v119
	v_and_b32_e32 v121, 0xffff0000, v121
	v_lshlrev_b32_e32 v147, 16, v122
	v_and_b32_e32 v122, 0xffff0000, v122
	v_lshlrev_b32_e32 v156, 16, v123
	v_and_b32_e32 v123, 0xffff0000, v123
	v_fmac_f32_e32 v126, v108, v112
	v_fmac_f32_e32 v120, v109, v113
	v_fmac_f32_e32 v127, v110, v114
	v_fmac_f32_e32 v121, v111, v115
	v_fmac_f32_e32 v147, v104, v116
	v_fmac_f32_e32 v122, v105, v117
	v_fmac_f32_e32 v156, v106, v118
	v_fmac_f32_e32 v123, v107, v119
	v_cvt_pk_bf16_f32 v104, v126, v120
	v_cvt_pk_bf16_f32 v105, v127, v121
	v_cvt_pk_bf16_f32 v106, v147, v122
	v_cvt_pk_bf16_f32 v107, v156, v123
	v_or_b32_e32 v116, 32, v146
	global_store_dwordx4 v[124:125], v[104:107], off
	v_mad_i64_i32 v[118:119], s[18:19], v116, s41, v[148:149]
	v_lshl_add_u64 v[118:119], v[118:119], 0, v[144:145]
	s_waitcnt vmcnt(9)
; __device__ __forceinline__ unsigned cvt_pk_bf16(float lo, float hi) { unsigned r; asm volatile("v_cvt_pk_bf16_f32 %0, %1, %2" : "=v"(r) : "v"(lo), "v"(hi)); return r; }
; __device__ __forceinline__ float bf_lo(unsigned u) { return __uint_as_float(u << 16); }
; __device__ __forceinline__ float bf_hi(unsigned u) { return __uint_as_float(u & 0xffff0000u); }
;     __device__ __forceinline__ void operator()(const f32x4 (&acc)[2][2][4][2], const Unit& u, int wr, int wc, int fr, int fq) const {
;     ...
;             for (int m = 0; m < 4; ++m) { const size_t r = (size_t)(row0 + ai * HALF + m * 16); bf16_t* rowp = O + r * ldc + col0; const bf16_t* gp = G + r * ldg + col0;
; #pragma unroll
;                 for (int bj = 0; bj < 2; ++bj) { const u32x4 gw = *(const u32x4*)(gp + bj * HALF);
;                     f32x4 v0 = acc[ai][bj][m][0], v1 = acc[ai][bj][m][1];
;                     v0[0] *= bf_lo(gw.x); v0[1] *= bf_hi(gw.x); v0[2] *= bf_lo(gw.y); v0[3] *= bf_hi(gw.y);
;                     v1[0] *= bf_lo(gw.z); v1[1] *= bf_hi(gw.z); v1[2] *= bf_lo(gw.w); v1[3] *= bf_hi(gw.w);
;                     if (ACCUM) { const u32x4 pw = *(const u32x4*)(rowp + bj * HALF);
;                         v0[0] += bf_lo(pw.x); v0[1] += bf_hi(pw.x); v0[2] += bf_lo(pw.y); v0[3] += bf_hi(pw.y);
;                         v1[0] += bf_lo(pw.z); v1[1] += bf_hi(pw.z); v1[2] += bf_lo(pw.w); v1[3] += bf_hi(pw.w); }
;                     u32x4 w; w.x = cvt_pk_bf16(v0[0], v0[1]); w.y = cvt_pk_bf16(v0[2], v0[3]); w.z = cvt_pk_bf16(v1[0], v1[1]); w.w = cvt_pk_bf16(v1[2], v1[3]);
;                     *(u32x4*)(rowp + bj * HALF) = w; } }
	v_mov_b32_e32 v108, v210
	v_mov_b32_e32 v109, v211
	v_mov_b32_e32 v110, v212
	v_mov_b32_e32 v111, v213
	v_mov_b32_e32 v112, v214
	v_mov_b32_e32 v113, v215
	v_mov_b32_e32 v114, v216
	v_mov_b32_e32 v115, v217
	s_mul_i32 s98, s41, 48
	s_mov_b32 s99, 0
	v_lshl_add_u64 v[222:223], v[218:219], 0, s[98:99]
	global_load_dwordx4 v[210:213], v[222:223], off offset:256
	s_mov_b32 s98, 98304
	v_lshl_add_u64 v[224:225], v[220:221], 0, s[98:99]
	global_load_dwordx4 v[214:217], v[224:225], off offset:256
	v_lshlrev_b32_e32 v104, 16, v108
	v_lshlrev_b32_e32 v117, 16, v112
	v_and_b32_e32 v105, 0xffff0000, v108
	v_lshlrev_b32_e32 v108, 16, v110
	v_and_b32_e32 v112, 0xffff0000, v112
	v_lshlrev_b32_e32 v121, 16, v114
	v_fmac_f32_e32 v117, v100, v104
	v_fmac_f32_e32 v112, v101, v105
	v_fmac_f32_e32 v121, v96, v108
	v_cvt_pk_bf16_f32 v96, v117, v112
	v_ashrrev_i32_e32 v117, 31, v116
	v_lshlrev_b64 v[104:105], 11, v[116:117]
	v_lshlrev_b32_e32 v106, 16, v109
	v_and_b32_e32 v107, 0xffff0000, v109
	v_and_b32_e32 v109, 0xffff0000, v110
	v_and_b32_e32 v114, 0xffff0000, v114
	v_lshl_add_u64 v[104:105], s[0:1], 0, v[104:105]
	v_lshlrev_b32_e32 v110, 16, v111
	v_and_b32_e32 v111, 0xffff0000, v111
	v_lshlrev_b32_e32 v120, 16, v113
	v_and_b32_e32 v113, 0xffff0000, v113
	v_lshlrev_b32_e32 v122, 16, v115
	v_and_b32_e32 v115, 0xffff0000, v115
	v_fmac_f32_e32 v114, v97, v109
	v_lshl_add_u64 v[108:109], v[104:105], 0, v[144:145]
	v_fmac_f32_e32 v120, v102, v106
	v_fmac_f32_e32 v113, v103, v107
	v_fmac_f32_e32 v122, v98, v110
	v_fmac_f32_e32 v115, v99, v111
	v_cvt_pk_bf16_f32 v97, v120, v113
	v_cvt_pk_bf16_f32 v98, v121, v114
	v_cvt_pk_bf16_f32 v99, v122, v115
	s_waitcnt vmcnt(9)
	v_mov_b32_e32 v100, v182
	v_mov_b32_e32 v101, v183
	v_mov_b32_e32 v102, v184
	v_mov_b32_e32 v103, v185
	v_mov_b32_e32 v104, v190
	v_mov_b32_e32 v105, v191
	v_mov_b32_e32 v106, v192
	v_mov_b32_e32 v107, v193
	s_mul_i32 s98, s41, 128
	s_mov_b32 s99, 0
	v_lshl_add_u64 v[222:223], v[218:219], 0, s[98:99]
	global_load_dwordx4 v[182:185], v[222:223], off
	s_mov_b32 s98, 262144
	v_lshl_add_u64 v[224:225], v[220:221], 0, s[98:99]
	global_load_dwordx4 v[190:193], v[224:225], off
	v_lshlrev_b32_e32 v110, 16, v104
	global_store_dwordx4 v[124:125], v[96:99], off offset:256
	v_and_b32_e32 v104, 0xffff0000, v104
	v_lshlrev_b32_e32 v111, 16, v105
	v_lshlrev_b32_e32 v96, 16, v100
	v_and_b32_e32 v97, 0xffff0000, v100
	v_lshlrev_b32_e32 v98, 16, v101
	v_and_b32_e32 v99, 0xffff0000, v101
	v_lshlrev_b32_e32 v100, 16, v102
	v_and_b32_e32 v101, 0xffff0000, v102
	v_lshlrev_b32_e32 v102, 16, v103
	v_and_b32_e32 v103, 0xffff0000, v103
	v_and_b32_e32 v105, 0xffff0000, v105
	v_lshlrev_b32_e32 v112, 16, v106
	v_and_b32_e32 v106, 0xffff0000, v106
	v_lshlrev_b32_e32 v113, 16, v107
	v_and_b32_e32 v107, 0xffff0000, v107
	v_fmac_f32_e32 v110, v92, v96
	v_fmac_f32_e32 v104, v93, v97
	v_fmac_f32_e32 v111, v94, v98
	v_fmac_f32_e32 v105, v95, v99
	v_fmac_f32_e32 v112, v88, v100
	v_fmac_f32_e32 v106, v89, v101
	v_fmac_f32_e32 v113, v90, v102
	v_fmac_f32_e32 v107, v91, v103
	v_cvt_pk_bf16_f32 v88, v110, v104
	v_cvt_pk_bf16_f32 v89, v111, v105
	v_cvt_pk_bf16_f32 v90, v112, v106
	v_cvt_pk_bf16_f32 v91, v113, v107
	v_or_b32_e32 v100, 48, v146
	global_store_dwordx4 v[108:109], v[88:91], off
	v_mad_i64_i32 v[102:103], s[18:19], v100, s41, v[148:149]
	v_lshl_add_u64 v[102:103], v[102:103], 0, v[144:145]
	s_waitcnt vmcnt(10)
	v_mov_b32_e32 v92, v194
	v_mov_b32_e32 v93, v195
	v_mov_b32_e32 v94, v196
	v_mov_b32_e32 v95, v197
	v_mov_b32_e32 v96, v198
	v_mov_b32_e32 v97, v199
	v_mov_b32_e32 v98, v200
	v_mov_b32_e32 v99, v201
	s_mul_i32 s98, s41, 128
	s_mov_b32 s99, 0
	v_lshl_add_u64 v[222:223], v[218:219], 0, s[98:99]
	global_load_dwordx4 v[194:197], v[222:223], off offset:256
	s_mov_b32 s98, 262144
	v_lshl_add_u64 v[224:225], v[220:221], 0, s[98:99]
	global_load_dwordx4 v[198:201], v[224:225], off offset:256
	v_lshlrev_b32_e32 v88, 16, v92
	v_lshlrev_b32_e32 v101, 16, v96
	v_and_b32_e32 v89, 0xffff0000, v92
	v_lshlrev_b32_e32 v92, 16, v94
	v_and_b32_e32 v96, 0xffff0000, v96
	v_lshlrev_b32_e32 v105, 16, v98
	v_fmac_f32_e32 v101, v84, v88
	v_fmac_f32_e32 v96, v85, v89
	v_fmac_f32_e32 v105, v80, v92
	v_cvt_pk_bf16_f32 v80, v101, v96
	v_ashrrev_i32_e32 v101, 31, v100
	v_lshlrev_b64 v[88:89], 11, v[100:101]
	v_lshlrev_b32_e32 v90, 16, v93
	v_and_b32_e32 v91, 0xffff0000, v93
	v_and_b32_e32 v93, 0xffff0000, v94
	v_and_b32_e32 v98, 0xffff0000, v98
	v_lshl_add_u64 v[88:89], s[0:1], 0, v[88:89]
	v_lshlrev_b32_e32 v94, 16, v95
	v_and_b32_e32 v95, 0xffff0000, v95
	v_lshlrev_b32_e32 v104, 16, v97
	v_and_b32_e32 v97, 0xffff0000, v97
	v_lshlrev_b32_e32 v106, 16, v99
	v_and_b32_e32 v99, 0xffff0000, v99
	v_fmac_f32_e32 v98, v81, v93
	v_lshl_add_u64 v[92:93], v[88:89], 0, v[144:145]
	v_fmac_f32_e32 v104, v86, v90
	v_fmac_f32_e32 v97, v87, v91
	v_fmac_f32_e32 v106, v82, v94
	v_fmac_f32_e32 v99, v83, v95
	v_cvt_pk_bf16_f32 v81, v104, v97
	v_cvt_pk_bf16_f32 v82, v105, v98
	v_cvt_pk_bf16_f32 v83, v106, v99
	s_waitcnt vmcnt(10)
; __device__ __forceinline__ unsigned cvt_pk_bf16(float lo, float hi) { unsigned r; asm volatile("v_cvt_pk_bf16_f32 %0, %1, %2" : "=v"(r) : "v"(lo), "v"(hi)); return r; }
; __device__ __forceinline__ float bf_lo(unsigned u) { return __uint_as_float(u << 16); }
; __device__ __forceinline__ float bf_hi(unsigned u) { return __uint_as_float(u & 0xffff0000u); }
;     __device__ __forceinline__ void operator()(const f32x4 (&acc)[2][2][4][2], const Unit& u, int wr, int wc, int fr, int fq) const {
;     ...
;             for (int m = 0; m < 4; ++m) { const size_t r = (size_t)(row0 + ai * HALF + m * 16); bf16_t* rowp = O + r * ldc + col0; const bf16_t* gp = G + r * ldg + col0;
; #pragma unroll
;                 for (int bj = 0; bj < 2; ++bj) { const u32x4 gw = *(const u32x4*)(gp + bj * HALF);
;                     f32x4 v0 = acc[ai][bj][m][0], v1 = acc[ai][bj][m][1];
;                     v0[0] *= bf_lo(gw.x); v0[1] *= bf_hi(gw.x); v0[2] *= bf_lo(gw.y); v0[3] *= bf_hi(gw.y);
;                     v1[0] *= bf_lo(gw.z); v1[1] *= bf_hi(gw.z); v1[2] *= bf_lo(gw.w); v1[3] *= bf_hi(gw.w);
;                     if (ACCUM) { const u32x4 pw = *(const u32x4*)(rowp + bj * HALF);
;                         v0[0] += bf_lo(pw.x); v0[1] += bf_hi(pw.x); v0[2] += bf_lo(pw.y); v0[3] += bf_hi(pw.y);
;                         v1[0] += bf_lo(pw.z); v1[1] += bf_hi(pw.z); v1[2] += bf_lo(pw.w); v1[3] += bf_hi(pw.w); }
;                     u32x4 w; w.x = cvt_pk_bf16(v0[0], v0[1]); w.y = cvt_pk_bf16(v0[2], v0[3]); w.z = cvt_pk_bf16(v1[0], v1[1]); w.w = cvt_pk_bf16(v1[2], v1[3]);
;                     *(u32x4*)(rowp + bj * HALF) = w; } }
	v_mov_b32_e32 v84, v202
	v_mov_b32_e32 v85, v203
	v_mov_b32_e32 v86, v204
	v_mov_b32_e32 v87, v205
	v_mov_b32_e32 v88, v206
	v_mov_b32_e32 v89, v207
	v_mov_b32_e32 v90, v208
	v_mov_b32_e32 v91, v209
	s_mul_i32 s98, s41, 144
	s_mov_b32 s99, 0
	v_lshl_add_u64 v[222:223], v[218:219], 0, s[98:99]
	global_load_dwordx4 v[202:205], v[222:223], off
	s_mov_b32 s98, 294912
	v_lshl_add_u64 v[224:225], v[220:221], 0, s[98:99]
	global_load_dwordx4 v[206:209], v[224:225], off
	v_lshlrev_b32_e32 v94, 16, v88
	global_store_dwordx4 v[108:109], v[80:83], off offset:256
	v_and_b32_e32 v88, 0xffff0000, v88
	v_lshlrev_b32_e32 v95, 16, v89
	v_lshlrev_b32_e32 v80, 16, v84
	v_and_b32_e32 v81, 0xffff0000, v84
	v_lshlrev_b32_e32 v82, 16, v85
	v_and_b32_e32 v83, 0xffff0000, v85
	v_lshlrev_b32_e32 v84, 16, v86
	v_and_b32_e32 v85, 0xffff0000, v86
	v_lshlrev_b32_e32 v86, 16, v87
	v_and_b32_e32 v87, 0xffff0000, v87
	v_and_b32_e32 v89, 0xffff0000, v89
	v_lshlrev_b32_e32 v96, 16, v90
	v_and_b32_e32 v90, 0xffff0000, v90
	v_lshlrev_b32_e32 v97, 16, v91
	v_and_b32_e32 v91, 0xffff0000, v91
	v_fmac_f32_e32 v94, v76, v80
	v_fmac_f32_e32 v88, v77, v81
	v_fmac_f32_e32 v95, v78, v82
	v_fmac_f32_e32 v89, v79, v83
	v_fmac_f32_e32 v96, v72, v84
	v_fmac_f32_e32 v90, v73, v85
	v_fmac_f32_e32 v97, v74, v86
	v_fmac_f32_e32 v91, v75, v87
	v_cvt_pk_bf16_f32 v72, v94, v88
	v_cvt_pk_bf16_f32 v73, v95, v89
	v_cvt_pk_bf16_f32 v74, v96, v90
	v_cvt_pk_bf16_f32 v75, v97, v91
	v_add_u32_e32 v84, 0x80, v146
	global_store_dwordx4 v[92:93], v[72:75], off
	v_mad_i64_i32 v[86:87], s[18:19], v84, s41, v[148:149]
	v_lshl_add_u64 v[86:87], v[86:87], 0, v[144:145]
	s_waitcnt vmcnt(10)
	v_mov_b32_e32 v76, v210
	v_mov_b32_e32 v77, v211
	v_mov_b32_e32 v78, v212
	v_mov_b32_e32 v79, v213
	v_mov_b32_e32 v80, v214
	v_mov_b32_e32 v81, v215
	v_mov_b32_e32 v82, v216
	v_mov_b32_e32 v83, v217
	s_mul_i32 s98, s41, 144
	s_mov_b32 s99, 0
	v_lshl_add_u64 v[222:223], v[218:219], 0, s[98:99]
	global_load_dwordx4 v[210:213], v[222:223], off offset:256
	s_mov_b32 s98, 294912
	v_lshl_add_u64 v[224:225], v[220:221], 0, s[98:99]
	global_load_dwordx4 v[214:217], v[224:225], off offset:256
	v_lshlrev_b32_e32 v72, 16, v76
	v_lshlrev_b32_e32 v85, 16, v80
	v_and_b32_e32 v73, 0xffff0000, v76
	v_lshlrev_b32_e32 v76, 16, v78
	v_and_b32_e32 v80, 0xffff0000, v80
	v_lshlrev_b32_e32 v89, 16, v82
	v_fmac_f32_e32 v85, v68, v72
	v_fmac_f32_e32 v80, v69, v73
	v_fmac_f32_e32 v89, v64, v76
	v_cvt_pk_bf16_f32 v64, v85, v80
	v_ashrrev_i32_e32 v85, 31, v84
	v_lshlrev_b64 v[72:73], 11, v[84:85]
	v_lshlrev_b32_e32 v74, 16, v77
	v_and_b32_e32 v75, 0xffff0000, v77
	v_and_b32_e32 v77, 0xffff0000, v78
	v_and_b32_e32 v82, 0xffff0000, v82
	v_lshl_add_u64 v[72:73], s[0:1], 0, v[72:73]
	v_lshlrev_b32_e32 v78, 16, v79
	v_and_b32_e32 v79, 0xffff0000, v79
	v_lshlrev_b32_e32 v88, 16, v81
	v_and_b32_e32 v81, 0xffff0000, v81
	v_lshlrev_b32_e32 v90, 16, v83
	v_and_b32_e32 v83, 0xffff0000, v83
	v_fmac_f32_e32 v82, v65, v77
	v_lshl_add_u64 v[76:77], v[72:73], 0, v[144:145]
	v_fmac_f32_e32 v88, v70, v74
	v_fmac_f32_e32 v81, v71, v75
	v_fmac_f32_e32 v90, v66, v78
	v_fmac_f32_e32 v83, v67, v79
	v_cvt_pk_bf16_f32 v65, v88, v81
	v_cvt_pk_bf16_f32 v66, v89, v82
	v_cvt_pk_bf16_f32 v67, v90, v83
	s_waitcnt vmcnt(10)
	v_mov_b32_e32 v68, v182
	v_mov_b32_e32 v69, v183
	v_mov_b32_e32 v70, v184
	v_mov_b32_e32 v71, v185
	v_mov_b32_e32 v72, v190
	v_mov_b32_e32 v73, v191
	v_mov_b32_e32 v74, v192
	v_mov_b32_e32 v75, v193
	s_mul_i32 s98, s41, 160
	s_mov_b32 s99, 0
	v_lshl_add_u64 v[222:223], v[218:219], 0, s[98:99]
	global_load_dwordx4 v[182:185], v[222:223], off
	s_mov_b32 s98, 327680
	v_lshl_add_u64 v[224:225], v[220:221], 0, s[98:99]
	global_load_dwordx4 v[190:193], v[224:225], off
	v_lshlrev_b32_e32 v78, 16, v72
	global_store_dwordx4 v[92:93], v[64:67], off offset:256
	v_and_b32_e32 v72, 0xffff0000, v72
	v_lshlrev_b32_e32 v79, 16, v73
	v_lshlrev_b32_e32 v64, 16, v68
	v_and_b32_e32 v65, 0xffff0000, v68
	v_lshlrev_b32_e32 v66, 16, v69
	v_and_b32_e32 v67, 0xffff0000, v69
	v_lshlrev_b32_e32 v68, 16, v70
	v_and_b32_e32 v69, 0xffff0000, v70
	v_lshlrev_b32_e32 v70, 16, v71
	v_and_b32_e32 v71, 0xffff0000, v71
	v_and_b32_e32 v73, 0xffff0000, v73
	v_lshlrev_b32_e32 v80, 16, v74
	v_and_b32_e32 v74, 0xffff0000, v74
	v_lshlrev_b32_e32 v81, 16, v75
	v_and_b32_e32 v75, 0xffff0000, v75
	v_fmac_f32_e32 v78, v60, v64
	v_fmac_f32_e32 v72, v61, v65
	v_fmac_f32_e32 v79, v62, v66
	v_fmac_f32_e32 v73, v63, v67
	v_fmac_f32_e32 v80, v56, v68
	v_fmac_f32_e32 v74, v57, v69
	v_fmac_f32_e32 v81, v58, v70
	v_fmac_f32_e32 v75, v59, v71
	v_cvt_pk_bf16_f32 v56, v78, v72
	v_cvt_pk_bf16_f32 v57, v79, v73
	v_cvt_pk_bf16_f32 v58, v80, v74
	v_cvt_pk_bf16_f32 v59, v81, v75
	v_add_u32_e32 v68, 0x90, v146
	global_store_dwordx4 v[76:77], v[56:59], off
	v_mad_i64_i32 v[70:71], s[18:19], v68, s41, v[148:149]
	v_lshl_add_u64 v[70:71], v[70:71], 0, v[144:145]
	s_waitcnt vmcnt(10)
; __device__ __forceinline__ unsigned cvt_pk_bf16(float lo, float hi) { unsigned r; asm volatile("v_cvt_pk_bf16_f32 %0, %1, %2" : "=v"(r) : "v"(lo), "v"(hi)); return r; }
; __device__ __forceinline__ float bf_lo(unsigned u) { return __uint_as_float(u << 16); }
; __device__ __forceinline__ float bf_hi(unsigned u) { return __uint_as_float(u & 0xffff0000u); }
;     __device__ __forceinline__ void operator()(const f32x4 (&acc)[2][2][4][2], const Unit& u, int wr, int wc, int fr, int fq) const {
;     ...
;             for (int m = 0; m < 4; ++m) { const size_t r = (size_t)(row0 + ai * HALF + m * 16); bf16_t* rowp = O + r * ldc + col0; const bf16_t* gp = G + r * ldg + col0;
; #pragma unroll
;                 for (int bj = 0; bj < 2; ++bj) { const u32x4 gw = *(const u32x4*)(gp + bj * HALF);
;                     f32x4 v0 = acc[ai][bj][m][0], v1 = acc[ai][bj][m][1];
;                     v0[0] *= bf_lo(gw.x); v0[1] *= bf_hi(gw.x); v0[2] *= bf_lo(gw.y); v0[3] *= bf_hi(gw.y);
;                     v1[0] *= bf_lo(gw.z); v1[1] *= bf_hi(gw.z); v1[2] *= bf_lo(gw.w); v1[3] *= bf_hi(gw.w);
;                     if (ACCUM) { const u32x4 pw = *(const u32x4*)(rowp + bj * HALF);
;                         v0[0] += bf_lo(pw.x); v0[1] += bf_hi(pw.x); v0[2] += bf_lo(pw.y); v0[3] += bf_hi(pw.y);
;                         v1[0] += bf_lo(pw.z); v1[1] += bf_hi(pw.z); v1[2] += bf_lo(pw.w); v1[3] += bf_hi(pw.w); }
;                     u32x4 w; w.x = cvt_pk_bf16(v0[0], v0[1]); w.y = cvt_pk_bf16(v0[2], v0[3]); w.z = cvt_pk_bf16(v1[0], v1[1]); w.w = cvt_pk_bf16(v1[2], v1[3]);
;                     *(u32x4*)(rowp + bj * HALF) = w; } }
	v_mov_b32_e32 v60, v194
	v_mov_b32_e32 v61, v195
	v_mov_b32_e32 v62, v196
	v_mov_b32_e32 v63, v197
	v_mov_b32_e32 v64, v198
	v_mov_b32_e32 v65, v199
	v_mov_b32_e32 v66, v200
	v_mov_b32_e32 v67, v201
	s_mul_i32 s98, s41, 160
	s_mov_b32 s99, 0
	v_lshl_add_u64 v[222:223], v[218:219], 0, s[98:99]
	global_load_dwordx4 v[194:197], v[222:223], off offset:256
	s_mov_b32 s98, 327680
	v_lshl_add_u64 v[224:225], v[220:221], 0, s[98:99]
	global_load_dwordx4 v[198:201], v[224:225], off offset:256
	v_lshlrev_b32_e32 v56, 16, v60
	v_lshlrev_b32_e32 v69, 16, v64
	v_and_b32_e32 v57, 0xffff0000, v60
	v_lshlrev_b32_e32 v60, 16, v62
	v_and_b32_e32 v64, 0xffff0000, v64
	v_lshlrev_b32_e32 v73, 16, v66
	v_fmac_f32_e32 v69, v52, v56
	v_fmac_f32_e32 v64, v53, v57
	v_fmac_f32_e32 v73, v48, v60
	v_cvt_pk_bf16_f32 v48, v69, v64
	v_ashrrev_i32_e32 v69, 31, v68
	v_lshlrev_b64 v[56:57], 11, v[68:69]
	v_lshlrev_b32_e32 v58, 16, v61
	v_and_b32_e32 v59, 0xffff0000, v61
	v_and_b32_e32 v61, 0xffff0000, v62
	v_and_b32_e32 v66, 0xffff0000, v66
	v_lshl_add_u64 v[56:57], s[0:1], 0, v[56:57]
	v_lshlrev_b32_e32 v62, 16, v63
	v_and_b32_e32 v63, 0xffff0000, v63
	v_lshlrev_b32_e32 v72, 16, v65
	v_and_b32_e32 v65, 0xffff0000, v65
	v_lshlrev_b32_e32 v74, 16, v67
	v_and_b32_e32 v67, 0xffff0000, v67
	v_fmac_f32_e32 v66, v49, v61
	v_lshl_add_u64 v[60:61], v[56:57], 0, v[144:145]
	v_fmac_f32_e32 v72, v54, v58
	v_fmac_f32_e32 v65, v55, v59
	v_fmac_f32_e32 v74, v50, v62
	v_fmac_f32_e32 v67, v51, v63
	v_cvt_pk_bf16_f32 v49, v72, v65
	v_cvt_pk_bf16_f32 v50, v73, v66
	v_cvt_pk_bf16_f32 v51, v74, v67
	s_waitcnt vmcnt(10)
	v_mov_b32_e32 v52, v202
	v_mov_b32_e32 v53, v203
	v_mov_b32_e32 v54, v204
	v_mov_b32_e32 v55, v205
	v_mov_b32_e32 v56, v206
	v_mov_b32_e32 v57, v207
	v_mov_b32_e32 v58, v208
	v_mov_b32_e32 v59, v209
	s_mul_i32 s98, s41, 176
	s_mov_b32 s99, 0
	v_lshl_add_u64 v[222:223], v[218:219], 0, s[98:99]
	global_load_dwordx4 v[202:205], v[222:223], off
	s_mov_b32 s98, 360448
	v_lshl_add_u64 v[224:225], v[220:221], 0, s[98:99]
	global_load_dwordx4 v[206:209], v[224:225], off
	v_lshlrev_b32_e32 v62, 16, v56
	global_store_dwordx4 v[76:77], v[48:51], off offset:256
	v_and_b32_e32 v56, 0xffff0000, v56
	v_lshlrev_b32_e32 v63, 16, v57
	v_lshlrev_b32_e32 v48, 16, v52
	v_and_b32_e32 v49, 0xffff0000, v52
	v_lshlrev_b32_e32 v50, 16, v53
	v_and_b32_e32 v51, 0xffff0000, v53
	v_lshlrev_b32_e32 v52, 16, v54
	v_and_b32_e32 v53, 0xffff0000, v54
	v_lshlrev_b32_e32 v54, 16, v55
	v_and_b32_e32 v55, 0xffff0000, v55
	v_and_b32_e32 v57, 0xffff0000, v57
	v_lshlrev_b32_e32 v64, 16, v58
	v_and_b32_e32 v58, 0xffff0000, v58
	v_lshlrev_b32_e32 v65, 16, v59
	v_and_b32_e32 v59, 0xffff0000, v59
	v_fmac_f32_e32 v62, v44, v48
	v_fmac_f32_e32 v56, v45, v49
	v_fmac_f32_e32 v63, v46, v50
	v_fmac_f32_e32 v57, v47, v51
	v_fmac_f32_e32 v64, v40, v52
	v_fmac_f32_e32 v58, v41, v53
	v_fmac_f32_e32 v65, v42, v54
	v_fmac_f32_e32 v59, v43, v55
	v_cvt_pk_bf16_f32 v40, v62, v56
	v_cvt_pk_bf16_f32 v41, v63, v57
	v_cvt_pk_bf16_f32 v42, v64, v58
	v_cvt_pk_bf16_f32 v43, v65, v59
	v_add_u32_e32 v52, 0xa0, v146
	global_store_dwordx4 v[60:61], v[40:43], off
	v_mad_i64_i32 v[54:55], s[18:19], v52, s41, v[148:149]
	v_lshl_add_u64 v[54:55], v[54:55], 0, v[144:145]
	s_waitcnt vmcnt(10)
	v_mov_b32_e32 v44, v210
	v_mov_b32_e32 v45, v211
	v_mov_b32_e32 v46, v212
	v_mov_b32_e32 v47, v213
	v_mov_b32_e32 v48, v214
	v_mov_b32_e32 v49, v215
	v_mov_b32_e32 v50, v216
	v_mov_b32_e32 v51, v217
	s_mul_i32 s98, s41, 176
	s_mov_b32 s99, 0
	v_lshl_add_u64 v[222:223], v[218:219], 0, s[98:99]
	global_load_dwordx4 v[210:213], v[222:223], off offset:256
	s_mov_b32 s98, 360448
	v_lshl_add_u64 v[224:225], v[220:221], 0, s[98:99]
	global_load_dwordx4 v[214:217], v[224:225], off offset:256
	v_lshlrev_b32_e32 v40, 16, v44
	v_lshlrev_b32_e32 v53, 16, v48
	v_and_b32_e32 v41, 0xffff0000, v44
	v_lshlrev_b32_e32 v44, 16, v46
	v_and_b32_e32 v48, 0xffff0000, v48
	v_lshlrev_b32_e32 v57, 16, v50
	v_fmac_f32_e32 v53, v36, v40
	v_fmac_f32_e32 v48, v37, v41
	v_fmac_f32_e32 v57, v32, v44
	v_cvt_pk_bf16_f32 v32, v53, v48
	v_ashrrev_i32_e32 v53, 31, v52
	v_lshlrev_b64 v[40:41], 11, v[52:53]
	v_lshlrev_b32_e32 v42, 16, v45
	v_and_b32_e32 v43, 0xffff0000, v45
	v_and_b32_e32 v45, 0xffff0000, v46
	v_and_b32_e32 v50, 0xffff0000, v50
	v_lshl_add_u64 v[40:41], s[0:1], 0, v[40:41]
	v_lshlrev_b32_e32 v46, 16, v47
	v_and_b32_e32 v47, 0xffff0000, v47
	v_lshlrev_b32_e32 v56, 16, v49
	v_and_b32_e32 v49, 0xffff0000, v49
	v_lshlrev_b32_e32 v58, 16, v51
	v_and_b32_e32 v51, 0xffff0000, v51
	v_fmac_f32_e32 v50, v33, v45
	v_lshl_add_u64 v[44:45], v[40:41], 0, v[144:145]
	v_fmac_f32_e32 v56, v38, v42
	v_fmac_f32_e32 v49, v39, v43
	v_fmac_f32_e32 v58, v34, v46
	v_fmac_f32_e32 v51, v35, v47
	v_cvt_pk_bf16_f32 v33, v56, v49
	v_cvt_pk_bf16_f32 v34, v57, v50
	v_cvt_pk_bf16_f32 v35, v58, v51
	s_waitcnt vmcnt(10)
; __device__ __forceinline__ unsigned cvt_pk_bf16(float lo, float hi) { unsigned r; asm volatile("v_cvt_pk_bf16_f32 %0, %1, %2" : "=v"(r) : "v"(lo), "v"(hi)); return r; }
; __device__ __forceinline__ float bf_lo(unsigned u) { return __uint_as_float(u << 16); }
; __device__ __forceinline__ float bf_hi(unsigned u) { return __uint_as_float(u & 0xffff0000u); }
; #define PG8_WAIT_V(n) asm volatile("s_waitcnt vmcnt(" #n ")" ::: "memory")
; #define PG8_BAR __builtin_amdgcn_s_barrier()
;     __device__ __forceinline__ void operator()(const f32x4 (&acc)[2][2][4][2], const Unit& u, int wr, int wc, int fr, int fq) const {
;     ...
;             for (int m = 0; m < 4; ++m) { const size_t r = (size_t)(row0 + ai * HALF + m * 16); bf16_t* rowp = O + r * ldc + col0; const bf16_t* gp = G + r * ldg + col0;
; #pragma unroll
;                 for (int bj = 0; bj < 2; ++bj) { const u32x4 gw = *(const u32x4*)(gp + bj * HALF);
;                     f32x4 v0 = acc[ai][bj][m][0], v1 = acc[ai][bj][m][1];
;                     v0[0] *= bf_lo(gw.x); v0[1] *= bf_hi(gw.x); v0[2] *= bf_lo(gw.y); v0[3] *= bf_hi(gw.y);
;                     v1[0] *= bf_lo(gw.z); v1[1] *= bf_hi(gw.z); v1[2] *= bf_lo(gw.w); v1[3] *= bf_hi(gw.w);
;                     if (ACCUM) { const u32x4 pw = *(const u32x4*)(rowp + bj * HALF);
;                         v0[0] += bf_lo(pw.x); v0[1] += bf_hi(pw.x); v0[2] += bf_lo(pw.y); v0[3] += bf_hi(pw.y);
;                         v1[0] += bf_lo(pw.z); v1[1] += bf_hi(pw.z); v1[2] += bf_lo(pw.w); v1[3] += bf_hi(pw.w); }
;                     u32x4 w; w.x = cvt_pk_bf16(v0[0], v0[1]); w.y = cvt_pk_bf16(v0[2], v0[3]); w.z = cvt_pk_bf16(v1[0], v1[1]); w.w = cvt_pk_bf16(v1[2], v1[3]);
;                     *(u32x4*)(rowp + bj * HALF) = w; } }
; template <class Epi, class Sched>
; __device__ __forceinline__ void gemm_phase(PG8_LAS unsigned char* lds, const Gemm g, const Sched& S, const Epi& E) {
;     ...
;         if (!has_next) break;
; #pragma unroll
;         for (int a = 0; a < 2; ++a)
; #pragma unroll
;             for (int b = 0; b < 2; ++b)
; #pragma unroll
;                 for (int m = 0; m < 4; ++m)
; #pragma unroll
;                     for (int n = 0; n < 2; ++n) acc[a][b][m][n] = (f32x4){0.f, 0.f, 0.f, 0.f};
;         cur = nxt; cA = nA; cB = nB; ++ui;
;     }
;     PG8_WAIT_V(0);
;     if (wr == 0) PG8_BAR;
;     PG8_BAR;
	v_mov_b32_e32 v36, v182
	v_mov_b32_e32 v37, v183
	v_mov_b32_e32 v38, v184
	v_mov_b32_e32 v39, v185
	v_mov_b32_e32 v40, v190
	v_mov_b32_e32 v41, v191
	v_mov_b32_e32 v42, v192
	v_mov_b32_e32 v43, v193
	v_lshlrev_b32_e32 v46, 16, v40
	global_store_dwordx4 v[60:61], v[32:35], off offset:256
	v_and_b32_e32 v40, 0xffff0000, v40
	v_lshlrev_b32_e32 v47, 16, v41
	v_lshlrev_b32_e32 v32, 16, v36
	v_and_b32_e32 v33, 0xffff0000, v36
	v_lshlrev_b32_e32 v34, 16, v37
	v_and_b32_e32 v35, 0xffff0000, v37
	v_lshlrev_b32_e32 v36, 16, v38
	v_and_b32_e32 v37, 0xffff0000, v38
	v_lshlrev_b32_e32 v38, 16, v39
	v_and_b32_e32 v39, 0xffff0000, v39
	v_and_b32_e32 v41, 0xffff0000, v41
	v_lshlrev_b32_e32 v48, 16, v42
	v_and_b32_e32 v42, 0xffff0000, v42
	v_lshlrev_b32_e32 v49, 16, v43
	v_and_b32_e32 v43, 0xffff0000, v43
	v_fmac_f32_e32 v46, v28, v32
	v_fmac_f32_e32 v40, v29, v33
	v_fmac_f32_e32 v47, v30, v34
	v_fmac_f32_e32 v41, v31, v35
	v_fmac_f32_e32 v48, v24, v36
	v_fmac_f32_e32 v42, v25, v37
	v_fmac_f32_e32 v49, v26, v38
	v_fmac_f32_e32 v43, v27, v39
	v_cvt_pk_bf16_f32 v24, v46, v40
	v_cvt_pk_bf16_f32 v25, v47, v41
	v_cvt_pk_bf16_f32 v26, v48, v42
	v_cvt_pk_bf16_f32 v27, v49, v43
	v_add_u32_e32 v36, 0xb0, v146
	global_store_dwordx4 v[44:45], v[24:27], off
	v_mad_i64_i32 v[38:39], s[18:19], v36, s41, v[148:149]
	v_lshl_add_u64 v[38:39], v[38:39], 0, v[144:145]
	s_mov_b64 s[18:19], s[12:13]
	s_waitcnt vmcnt(8)
	v_mov_b32_e32 v28, v194
	v_mov_b32_e32 v29, v195
	v_mov_b32_e32 v30, v196
	v_mov_b32_e32 v31, v197
	v_mov_b32_e32 v32, v198
	v_mov_b32_e32 v33, v199
	v_mov_b32_e32 v34, v200
	v_mov_b32_e32 v35, v201
	v_lshlrev_b32_e32 v24, 16, v28
	v_lshlrev_b32_e32 v37, 16, v32
	v_and_b32_e32 v25, 0xffff0000, v28
	v_lshlrev_b32_e32 v28, 16, v30
	v_and_b32_e32 v32, 0xffff0000, v32
	v_lshlrev_b32_e32 v41, 16, v34
	v_fmac_f32_e32 v37, v20, v24
	v_fmac_f32_e32 v32, v21, v25
	v_fmac_f32_e32 v41, v16, v28
	v_cvt_pk_bf16_f32 v16, v37, v32
	v_ashrrev_i32_e32 v37, 31, v36
	v_lshlrev_b64 v[24:25], 11, v[36:37]
	v_lshlrev_b32_e32 v26, 16, v29
	v_and_b32_e32 v27, 0xffff0000, v29
	v_and_b32_e32 v29, 0xffff0000, v30
	v_and_b32_e32 v34, 0xffff0000, v34
	v_lshl_add_u64 v[24:25], s[0:1], 0, v[24:25]
	v_lshlrev_b32_e32 v30, 16, v31
	v_and_b32_e32 v31, 0xffff0000, v31
	v_lshlrev_b32_e32 v40, 16, v33
	v_and_b32_e32 v33, 0xffff0000, v33
	v_lshlrev_b32_e32 v42, 16, v35
	v_and_b32_e32 v35, 0xffff0000, v35
	v_fmac_f32_e32 v34, v17, v29
	v_lshl_add_u64 v[28:29], v[24:25], 0, v[144:145]
	v_fmac_f32_e32 v40, v22, v26
	v_fmac_f32_e32 v33, v23, v27
	v_fmac_f32_e32 v42, v18, v30
	v_fmac_f32_e32 v35, v19, v31
	v_cvt_pk_bf16_f32 v17, v40, v33
	v_cvt_pk_bf16_f32 v18, v41, v34
	v_cvt_pk_bf16_f32 v19, v42, v35
	s_waitcnt vmcnt(6)
	v_mov_b32_e32 v20, v202
	v_mov_b32_e32 v21, v203
	v_mov_b32_e32 v22, v204
	v_mov_b32_e32 v23, v205
	v_mov_b32_e32 v24, v206
	v_mov_b32_e32 v25, v207
	v_mov_b32_e32 v26, v208
	v_mov_b32_e32 v27, v209
	v_lshlrev_b32_e32 v30, 16, v24
	global_store_dwordx4 v[44:45], v[16:19], off offset:256
	v_and_b32_e32 v24, 0xffff0000, v24
	v_lshlrev_b32_e32 v31, 16, v25
	v_lshlrev_b32_e32 v16, 16, v20
	v_and_b32_e32 v17, 0xffff0000, v20
	v_lshlrev_b32_e32 v18, 16, v21
	v_and_b32_e32 v19, 0xffff0000, v21
	v_lshlrev_b32_e32 v20, 16, v22
	v_and_b32_e32 v21, 0xffff0000, v22
	v_lshlrev_b32_e32 v22, 16, v23
	v_and_b32_e32 v23, 0xffff0000, v23
	v_and_b32_e32 v25, 0xffff0000, v25
	v_lshlrev_b32_e32 v32, 16, v26
	v_and_b32_e32 v26, 0xffff0000, v26
	v_lshlrev_b32_e32 v33, 16, v27
	v_and_b32_e32 v27, 0xffff0000, v27
	v_fmac_f32_e32 v30, v12, v16
	v_fmac_f32_e32 v24, v13, v17
	v_fmac_f32_e32 v31, v14, v18
	v_fmac_f32_e32 v25, v15, v19
	v_fmac_f32_e32 v32, v8, v20
	v_fmac_f32_e32 v26, v9, v21
	v_fmac_f32_e32 v33, v10, v22
	v_fmac_f32_e32 v27, v11, v23
	v_cvt_pk_bf16_f32 v8, v30, v24
	v_cvt_pk_bf16_f32 v9, v31, v25
	v_cvt_pk_bf16_f32 v10, v32, v26
	v_cvt_pk_bf16_f32 v11, v33, v27
	s_waitcnt vmcnt(3)
	v_mov_b32_e32 v12, v210
	v_mov_b32_e32 v13, v211
	v_mov_b32_e32 v14, v212
	v_mov_b32_e32 v15, v213
	v_mov_b32_e32 v16, v214
	v_mov_b32_e32 v17, v215
	v_mov_b32_e32 v18, v216
	v_mov_b32_e32 v19, v217
	v_lshlrev_b32_e32 v20, 16, v16
	global_store_dwordx4 v[28:29], v[8:11], off
	v_and_b32_e32 v16, 0xffff0000, v16
	v_lshlrev_b32_e32 v21, 16, v17
	v_lshlrev_b32_e32 v8, 16, v12
	v_and_b32_e32 v9, 0xffff0000, v12
	v_lshlrev_b32_e32 v10, 16, v13
	v_and_b32_e32 v11, 0xffff0000, v13
	v_lshlrev_b32_e32 v12, 16, v14
	v_and_b32_e32 v13, 0xffff0000, v14
	v_lshlrev_b32_e32 v14, 16, v15
	v_and_b32_e32 v15, 0xffff0000, v15
	v_and_b32_e32 v17, 0xffff0000, v17
	v_lshlrev_b32_e32 v22, 16, v18
	v_and_b32_e32 v18, 0xffff0000, v18
	v_lshlrev_b32_e32 v23, 16, v19
	v_and_b32_e32 v19, 0xffff0000, v19
	v_fmac_f32_e32 v20, v4, v8
	v_fmac_f32_e32 v16, v5, v9
	v_fmac_f32_e32 v21, v6, v10
	v_fmac_f32_e32 v17, v7, v11
	v_fmac_f32_e32 v22, v0, v12
	v_fmac_f32_e32 v18, v1, v13
	v_fmac_f32_e32 v23, v2, v14
	v_fmac_f32_e32 v19, v3, v15
	v_cvt_pk_bf16_f32 v0, v20, v16
	v_cvt_pk_bf16_f32 v1, v21, v17
	v_cvt_pk_bf16_f32 v2, v22, v18
	v_cvt_pk_bf16_f32 v3, v23, v19
	global_store_dwordx4 v[28:29], v[0:3], off offset:256
	s_cbranch_vccz .LBB0_1004
	s_waitcnt vmcnt(0)
	s_cmpk_gt_u32 s25, 0xff
	s_cbranch_scc1 .LBB0_1015
	s_barrier

; #define PG8_STAGE(bufoff, gbase, voff) do { _Pragma("unroll") for (int _i = 0; _i < 2; ++_i) \
;         __builtin_amdgcn_global_load_lds((const unsigned*)((const char*)(gbase) + (voff)[_i]), (PG8_LAS unsigned*)(lds + (bufoff) + ldsw + _i * 8192), 16, 0, 0); } while (0)
; #define PG8_LDA(dst, b, h) do { _Pragma("unroll") for (int m = 0; m < 4; ++m) _Pragma("unroll") for (int k = 0; k < 2; ++k) dst[m][k] = *(const PG8_LAS bf16x8*)(lds + PG8_SA(b, h) + aoff + m * 2048 + k * 1024); } while (0)
; #define PG8_LDB(dst, b, h) do { _Pragma("unroll") for (int n = 0; n < 2; ++n) _Pragma("unroll") for (int k = 0; k < 2; ++k) dst[n][k] = *(const PG8_LAS bf16x8*)(lds + PG8_SB(b, h) + boff + n * 2048 + k * 1024); } while (0)
; #define PG8_MMA(ai, bj, At, Bt) do { __builtin_amdgcn_s_setprio(1); _Pragma("unroll") for (int m = 0; m < 4; ++m) _Pragma("unroll") for (int n = 0; n < 2; ++n) _Pragma("unroll") for (int k = 0; k < 2; ++k) \
;         acc[ai][bj][m][n] = __builtin_amdgcn_mfma_f32_16x16x32_bf16(Bt[n][k], At[m][k], acc[ai][bj][m][n], 0, 0, 0); __builtin_amdgcn_s_setprio(0); } while (0)
; template <class Epi, class Sched>
; __device__ __forceinline__ void gemm_phase(PG8_LAS unsigned char* lds, const Gemm g, const Sched& S, const Epi& E) {
;     ...
;         const bool has_next = S.next(ui + 1, nxt);
;         const char* nA = has_next ? (const char*)g.A + (size_t)nxt.pm * tstep : cA; const char* nB = has_next ? (const char*)g.Bt + (size_t)nxt.pn * tstep : cB;
;         for (int t = 0; t < nt; t += 2) {
;             const bool last = (t == nt - 2);
;             const char* a1 = cA + (size_t)(t + 1) * kstep;
;             const char* a2 = last ? nA : cA + (size_t)(t + 2) * kstep; const char* b2 = last ? nB : cB + (size_t)(t + 2) * kstep;
;             const char* a3 = a2 + kstep; const char* b3 = b2 + kstep;
;             if (last && has_next) S.a_ready(nxt);
;             PG8_LDB(B0, 0, 0); PG8_SCHED; PG8_LDA(At, 0, 0); PG8_STAGE(PG8_SA(1, 1), a1 + hstep, voffA);
;             PG8_WAIT_L(8); PG8_BAR; PG8_WAIT_L(0); PG8_MMA(0, 0, At, B0); PG8_BAR; PG8_SCHED;
;             PG8_LDB(B1, 0, 1); PG8_STAGE(PG8_SB(0, 0), b2, voffB);
;             PG8_BAR; PG8_WAIT_L(0); PG8_MMA(0, 1, At, B1); PG8_BAR;
;             PG8_LDA(At, 0, 1); PG8_STAGE(PG8_SA(0, 0), a2, voffA);
;             PG8_BAR; PG8_WAIT_L(0); PG8_MMA(1, 0, At, B0); PG8_BAR; PG8_SCHED;
.LBB0_1082:
	s_ashr_i32 s17, s16, 31
	v_cmp_lt_i64_e32 vcc, s[18:19], v[140:141]
	s_lshl_b64 s[18:19], s[16:17], 19
	s_add_u32 s18, s35, s18
	s_addc_u32 s19, s36, s19
	s_and_b64 s[20:21], vcc, exec
	s_cselect_b32 s17, s19, s25
	s_cselect_b32 s52, s18, s24
	s_ashr_i32 s15, s14, 31
	s_lshl_b64 s[20:21], s[14:15], 19
	s_add_u32 s20, s72, s20
	s_addc_u32 s21, s73, s21
	s_and_b64 s[28:29], vcc, exec
	s_cselect_b32 s15, s21, s27
	s_cselect_b32 s53, s20, s26
	s_add_u32 s24, s24, 0x40080
	s_addc_u32 s25, s25, 0
	s_add_u32 s54, s26, 0x100
	s_addc_u32 s55, s27, 0
	s_mov_b32 s56, -2
	ds_read_b128 v[152:155], v149
	ds_read_b128 v[156:159], v149 offset:1024
	ds_read_b128 v[160:163], v149 offset:2048
	ds_read_b128 v[164:167], v149 offset:3072
	s_add_u32 s26, s24, 0xfffc0080
	s_addc_u32 s27, s25, -1
	s_cmp_eq_u32 s56, 12
	s_cselect_b32 s29, s17, s27
	s_cselect_b32 s28, s52, s26
	s_cselect_b32 s27, s15, s55
	s_cselect_b32 s26, s53, s54
	s_add_i32 m0, s23, 0xc000
	ds_read_b128 v[168:171], v150
	ds_read_b128 v[172:175], v150 offset:1024
	ds_read_b128 v[182:185], v150 offset:2048
	ds_read_b128 v[190:193], v150 offset:3072
	ds_read_b128 v[194:197], v150 offset:4096
	ds_read_b128 v[198:201], v150 offset:5120
	ds_read_b128 v[202:205], v150 offset:6144
	ds_read_b128 v[206:209], v150 offset:7168
	global_load_lds_dwordx4 v136, s[24:25]
	s_nop 1
	s_add_i32 m0, s23, 0xe000
	s_nop 0
	global_load_lds_dwordx4 v138, s[24:25]
	s_waitcnt lgkmcnt(12)
	ds_read_b128 v[210:213], v151
	ds_read_b128 v[214:217], v151 offset:1024
	ds_read_b128 v[218:221], v151 offset:2048
	ds_read_b128 v[222:225], v151 offset:3072
	s_waitcnt vmcnt(8) lgkmcnt(0)
	s_barrier
	v_mfma_f32_16x16x32_bf16 v[124:127], v[152:155], v[168:171], 0
	v_mfma_f32_16x16x32_bf16 v[120:123], v[160:163], v[168:171], 0
	v_mfma_f32_16x16x32_bf16 v[108:111], v[152:155], v[182:185], 0
	v_mfma_f32_16x16x32_bf16 v[104:107], v[160:163], v[182:185], 0
	v_mfma_f32_16x16x32_bf16 v[92:95], v[152:155], v[194:197], 0
	v_mfma_f32_16x16x32_bf16 v[88:91], v[160:163], v[194:197], 0
	v_mfma_f32_16x16x32_bf16 v[76:79], v[152:155], v[202:205], 0
	v_mfma_f32_16x16x32_bf16 v[72:75], v[160:163], v[202:205], 0
	v_mfma_f32_16x16x32_bf16 v[124:127], v[156:159], v[172:175], v[124:127]
	v_mfma_f32_16x16x32_bf16 v[120:123], v[164:167], v[172:175], v[120:123]
	v_mfma_f32_16x16x32_bf16 v[108:111], v[156:159], v[190:193], v[108:111]
	v_mfma_f32_16x16x32_bf16 v[104:107], v[164:167], v[190:193], v[104:107]
	v_mfma_f32_16x16x32_bf16 v[92:95], v[156:159], v[198:201], v[92:95]
	v_mfma_f32_16x16x32_bf16 v[88:91], v[164:167], v[198:201], v[88:91]
	v_mfma_f32_16x16x32_bf16 v[76:79], v[156:159], v[206:209], v[76:79]
	v_mfma_f32_16x16x32_bf16 v[72:75], v[164:167], v[206:209], v[72:75]
	v_mfma_f32_16x16x32_bf16 v[116:119], v[210:213], v[168:171], 0
	v_mfma_f32_16x16x32_bf16 v[112:115], v[218:221], v[168:171], 0
	v_mfma_f32_16x16x32_bf16 v[100:103], v[210:213], v[182:185], 0
	v_mfma_f32_16x16x32_bf16 v[96:99], v[218:221], v[182:185], 0
	v_mfma_f32_16x16x32_bf16 v[84:87], v[210:213], v[194:197], 0
	v_mfma_f32_16x16x32_bf16 v[80:83], v[218:221], v[194:197], 0
	v_mfma_f32_16x16x32_bf16 v[68:71], v[210:213], v[202:205], 0
	v_mfma_f32_16x16x32_bf16 v[64:67], v[218:221], v[202:205], 0
	v_mfma_f32_16x16x32_bf16 v[116:119], v[214:217], v[172:175], v[116:119]
	v_mfma_f32_16x16x32_bf16 v[112:115], v[222:225], v[172:175], v[112:115]
	v_mfma_f32_16x16x32_bf16 v[100:103], v[214:217], v[190:193], v[100:103]
	v_mfma_f32_16x16x32_bf16 v[96:99], v[222:225], v[190:193], v[96:99]
	v_mfma_f32_16x16x32_bf16 v[84:87], v[214:217], v[198:201], v[84:87]
	v_mfma_f32_16x16x32_bf16 v[80:83], v[222:225], v[198:201], v[80:83]
	v_mfma_f32_16x16x32_bf16 v[68:71], v[214:217], v[206:209], v[68:71]
	v_mfma_f32_16x16x32_bf16 v[64:67], v[222:225], v[206:209], v[64:67]
	s_barrier
	ds_read_b128 v[168:171], v150 offset:16384
	ds_read_b128 v[172:175], v150 offset:17408
	ds_read_b128 v[182:185], v150 offset:18432
	ds_read_b128 v[190:193], v150 offset:19456
	ds_read_b128 v[194:197], v150 offset:20480
	ds_read_b128 v[198:201], v150 offset:21504
	ds_read_b128 v[202:205], v150 offset:22528
	ds_read_b128 v[206:209], v150 offset:23552
	s_add_i32 s57, s45, s37
	s_add_u32 s98, s26, s6
	s_addc_u32 s99, s27, s7
	s_mov_b32 m0, s57
	s_nop 0
	global_load_lds_dwordx4 v130, s[26:27]
	s_nop 1
	s_add_i32 m0, s57, 0x2000
	s_nop 0
	global_load_lds_dwordx4 v134, s[26:27]
	s_nop 1
	s_mov_b32 m0, s23
	s_add_u32 s100, s28, s6
	s_addc_u32 s101, s29, s7
	global_load_lds_dwordx4 v128, s[28:29]
	s_nop 1
	s_mov_b32 m0, s38
	s_nop 0
	global_load_lds_dwordx4 v132, s[28:29]
	s_add_u32 s58, s26, 0x40000
	s_addc_u32 s59, s27, 0
	s_add_i32 s57, s46, s37
	s_mov_b32 m0, s57
	s_nop 0
	global_load_lds_dwordx4 v130, s[58:59]
	s_nop 1
	s_add_i32 m0, s57, 0x2000
	s_nop 0
	global_load_lds_dwordx4 v134, s[58:59]
	s_waitcnt vmcnt(8) lgkmcnt(0)
	s_barrier
; #define PG8_STAGE(bufoff, gbase, voff) do { _Pragma("unroll") for (int _i = 0; _i < 2; ++_i) \
;         __builtin_amdgcn_global_load_lds((const unsigned*)((const char*)(gbase) + (voff)[_i]), (PG8_LAS unsigned*)(lds + (bufoff) + ldsw + _i * 8192), 16, 0, 0); } while (0)
; #define PG8_LDA(dst, b, h) do { _Pragma("unroll") for (int m = 0; m < 4; ++m) _Pragma("unroll") for (int k = 0; k < 2; ++k) dst[m][k] = *(const PG8_LAS bf16x8*)(lds + PG8_SA(b, h) + aoff + m * 2048 + k * 1024); } while (0)
; #define PG8_LDB(dst, b, h) do { _Pragma("unroll") for (int n = 0; n < 2; ++n) _Pragma("unroll") for (int k = 0; k < 2; ++k) dst[n][k] = *(const PG8_LAS bf16x8*)(lds + PG8_SB(b, h) + boff + n * 2048 + k * 1024); } while (0)
; #define PG8_MMA(ai, bj, At, Bt) do { __builtin_amdgcn_s_setprio(1); _Pragma("unroll") for (int m = 0; m < 4; ++m) _Pragma("unroll") for (int n = 0; n < 2; ++n) _Pragma("unroll") for (int k = 0; k < 2; ++k) \
;         acc[ai][bj][m][n] = __builtin_amdgcn_mfma_f32_16x16x32_bf16(Bt[n][k], At[m][k], acc[ai][bj][m][n], 0, 0, 0); __builtin_amdgcn_s_setprio(0); } while (0)
; #define PG8_WAIT_V(n) asm volatile("s_waitcnt vmcnt(" #n ")" ::: "memory")
; #define PG8_WAIT_L(n) asm volatile("s_waitcnt lgkmcnt(" #n ")" ::: "memory")
; #define PG8_BAR __builtin_amdgcn_s_barrier()
; #define PG8_SCHED __builtin_amdgcn_sched_barrier(0)
; template <class Epi, class Sched>
; __device__ __forceinline__ void gemm_phase(PG8_LAS unsigned char* lds, const Gemm g, const Sched& S, const Epi& E) {
;     ...
;             PG8_BAR; PG8_WAIT_L(0); PG8_MMA(1, 0, At, B0); PG8_BAR; PG8_SCHED;
;             PG8_STAGE(PG8_SB(0, 1), b2 + hstep, voffB);
;             PG8_WAIT_V(6); PG8_BAR; PG8_MMA(1, 1, At, B1); PG8_BAR;
;             PG8_LDB(B0, 1, 0); PG8_SCHED; PG8_LDA(At, 1, 0); PG8_STAGE(PG8_SA(0, 1), a2 + hstep, voffA);
;             PG8_WAIT_L(8); PG8_BAR; PG8_WAIT_L(0); PG8_MMA(0, 0, At, B0); PG8_BAR; PG8_SCHED;
;             PG8_LDB(B1, 1, 1); PG8_STAGE(PG8_SB(1, 0), b3, voffB);
;             PG8_BAR; PG8_WAIT_L(0); PG8_MMA(0, 1, At, B1); PG8_BAR;
;             PG8_LDA(At, 1, 1); PG8_STAGE(PG8_SA(1, 0), a3, voffA);
	v_mfma_f32_16x16x32_bf16 v[60:63], v[152:155], v[168:171], 0
	v_mfma_f32_16x16x32_bf16 v[56:59], v[160:163], v[168:171], 0
	v_mfma_f32_16x16x32_bf16 v[48:51], v[152:155], v[182:185], 0
	v_mfma_f32_16x16x32_bf16 v[40:43], v[160:163], v[182:185], 0
	v_mfma_f32_16x16x32_bf16 v[32:35], v[152:155], v[194:197], 0
	v_mfma_f32_16x16x32_bf16 v[24:27], v[160:163], v[194:197], 0
	v_mfma_f32_16x16x32_bf16 v[16:19], v[152:155], v[202:205], 0
	v_mfma_f32_16x16x32_bf16 v[8:11], v[160:163], v[202:205], 0
	v_mfma_f32_16x16x32_bf16 v[60:63], v[156:159], v[172:175], v[60:63]
	v_mfma_f32_16x16x32_bf16 v[56:59], v[164:167], v[172:175], v[56:59]
	v_mfma_f32_16x16x32_bf16 v[48:51], v[156:159], v[190:193], v[48:51]
	v_mfma_f32_16x16x32_bf16 v[40:43], v[164:167], v[190:193], v[40:43]
	v_mfma_f32_16x16x32_bf16 v[32:35], v[156:159], v[198:201], v[32:35]
	v_mfma_f32_16x16x32_bf16 v[24:27], v[164:167], v[198:201], v[24:27]
	v_mfma_f32_16x16x32_bf16 v[16:19], v[156:159], v[206:209], v[16:19]
	v_mfma_f32_16x16x32_bf16 v[8:11], v[164:167], v[206:209], v[8:11]
	v_mfma_f32_16x16x32_bf16 v[52:55], v[210:213], v[168:171], 0
	v_mfma_f32_16x16x32_bf16 v[44:47], v[218:221], v[168:171], 0
	v_mfma_f32_16x16x32_bf16 v[36:39], v[210:213], v[182:185], 0
	v_mfma_f32_16x16x32_bf16 v[28:31], v[218:221], v[182:185], 0
	v_mfma_f32_16x16x32_bf16 v[20:23], v[210:213], v[194:197], 0
	v_mfma_f32_16x16x32_bf16 v[12:15], v[218:221], v[194:197], 0
	v_mfma_f32_16x16x32_bf16 v[4:7], v[210:213], v[202:205], 0
	v_mfma_f32_16x16x32_bf16 v[0:3], v[218:221], v[202:205], 0
	v_mfma_f32_16x16x32_bf16 v[52:55], v[214:217], v[172:175], v[52:55]
	v_mfma_f32_16x16x32_bf16 v[44:47], v[222:225], v[172:175], v[44:47]
	v_mfma_f32_16x16x32_bf16 v[36:39], v[214:217], v[190:193], v[36:39]
	v_mfma_f32_16x16x32_bf16 v[28:31], v[222:225], v[190:193], v[28:31]
	v_mfma_f32_16x16x32_bf16 v[20:23], v[214:217], v[198:201], v[20:23]
	v_mfma_f32_16x16x32_bf16 v[12:15], v[222:225], v[198:201], v[12:15]
	v_mfma_f32_16x16x32_bf16 v[4:7], v[214:217], v[206:209], v[4:7]
	v_mfma_f32_16x16x32_bf16 v[0:3], v[222:225], v[206:209], v[0:3]
	s_barrier
	s_add_i32 s57, 0, 0x18000
	v_add_u32_e32 v164, s57, v147
	ds_read_b128 v[152:155], v164
	ds_read_b128 v[156:159], v164 offset:1024
	ds_read_b128 v[160:163], v164 offset:2048
	ds_read_b128 v[164:167], v164 offset:3072
	s_add_u32 s28, s28, 0x40000
	s_addc_u32 s29, s29, 0
	s_mov_b32 m0, s39
	ds_read_b128 v[168:171], v150 offset:32768
	ds_read_b128 v[172:175], v150 offset:33792
	ds_read_b128 v[182:185], v150 offset:34816
	ds_read_b128 v[190:193], v150 offset:35840
	ds_read_b128 v[194:197], v150 offset:36864
	ds_read_b128 v[198:201], v150 offset:37888
	ds_read_b128 v[202:205], v150 offset:38912
	ds_read_b128 v[206:209], v150 offset:39936
	global_load_lds_dwordx4 v128, s[28:29]
	s_nop 1
	s_mov_b32 m0, s40
	s_nop 0
	global_load_lds_dwordx4 v132, s[28:29]
	s_add_i32 s28, 0, 0x1c000
	v_add_u32_e32 v179, s28, v147
	s_waitcnt lgkmcnt(12)
	ds_read_b128 v[210:213], v179
	ds_read_b128 v[214:217], v179 offset:1024
	ds_read_b128 v[218:221], v179 offset:2048
	ds_read_b128 v[222:225], v179 offset:3072
	s_waitcnt vmcnt(8) lgkmcnt(0)
	s_barrier
	v_mfma_f32_16x16x32_bf16 v[124:127], v[152:155], v[168:171], v[124:127]
	v_mfma_f32_16x16x32_bf16 v[120:123], v[160:163], v[168:171], v[120:123]
	v_mfma_f32_16x16x32_bf16 v[108:111], v[152:155], v[182:185], v[108:111]
	v_mfma_f32_16x16x32_bf16 v[104:107], v[160:163], v[182:185], v[104:107]
	v_mfma_f32_16x16x32_bf16 v[92:95], v[152:155], v[194:197], v[92:95]
	v_mfma_f32_16x16x32_bf16 v[88:91], v[160:163], v[194:197], v[88:91]
	v_mfma_f32_16x16x32_bf16 v[76:79], v[152:155], v[202:205], v[76:79]
	v_mfma_f32_16x16x32_bf16 v[72:75], v[160:163], v[202:205], v[72:75]
	v_mfma_f32_16x16x32_bf16 v[124:127], v[156:159], v[172:175], v[124:127]
	v_mfma_f32_16x16x32_bf16 v[120:123], v[164:167], v[172:175], v[120:123]
	v_mfma_f32_16x16x32_bf16 v[108:111], v[156:159], v[190:193], v[108:111]
	v_mfma_f32_16x16x32_bf16 v[104:107], v[164:167], v[190:193], v[104:107]
	v_mfma_f32_16x16x32_bf16 v[92:95], v[156:159], v[198:201], v[92:95]
	v_mfma_f32_16x16x32_bf16 v[88:91], v[164:167], v[198:201], v[88:91]
	v_mfma_f32_16x16x32_bf16 v[76:79], v[156:159], v[206:209], v[76:79]
	v_mfma_f32_16x16x32_bf16 v[72:75], v[164:167], v[206:209], v[72:75]
	v_mfma_f32_16x16x32_bf16 v[116:119], v[210:213], v[168:171], v[116:119]
	v_mfma_f32_16x16x32_bf16 v[112:115], v[218:221], v[168:171], v[112:115]
	v_mfma_f32_16x16x32_bf16 v[100:103], v[210:213], v[182:185], v[100:103]
	v_mfma_f32_16x16x32_bf16 v[96:99], v[218:221], v[182:185], v[96:99]
	v_mfma_f32_16x16x32_bf16 v[84:87], v[210:213], v[194:197], v[84:87]
	v_mfma_f32_16x16x32_bf16 v[80:83], v[218:221], v[194:197], v[80:83]
	v_mfma_f32_16x16x32_bf16 v[68:71], v[210:213], v[202:205], v[68:71]
	v_mfma_f32_16x16x32_bf16 v[64:67], v[218:221], v[202:205], v[64:67]
	v_mfma_f32_16x16x32_bf16 v[116:119], v[214:217], v[172:175], v[116:119]
	v_mfma_f32_16x16x32_bf16 v[112:115], v[222:225], v[172:175], v[112:115]
	v_mfma_f32_16x16x32_bf16 v[100:103], v[214:217], v[190:193], v[100:103]
	v_mfma_f32_16x16x32_bf16 v[96:99], v[222:225], v[190:193], v[96:99]
	v_mfma_f32_16x16x32_bf16 v[84:87], v[214:217], v[198:201], v[84:87]
	v_mfma_f32_16x16x32_bf16 v[80:83], v[222:225], v[198:201], v[80:83]
	v_mfma_f32_16x16x32_bf16 v[68:71], v[214:217], v[206:209], v[68:71]
	v_mfma_f32_16x16x32_bf16 v[64:67], v[222:225], v[206:209], v[64:67]
	s_barrier
; #define PG8_STAGE(bufoff, gbase, voff) do { _Pragma("unroll") for (int _i = 0; _i < 2; ++_i) \
;         __builtin_amdgcn_global_load_lds((const unsigned*)((const char*)(gbase) + (voff)[_i]), (PG8_LAS unsigned*)(lds + (bufoff) + ldsw + _i * 8192), 16, 0, 0); } while (0)
; #define PG8_LDA(dst, b, h) do { _Pragma("unroll") for (int m = 0; m < 4; ++m) _Pragma("unroll") for (int k = 0; k < 2; ++k) dst[m][k] = *(const PG8_LAS bf16x8*)(lds + PG8_SA(b, h) + aoff + m * 2048 + k * 1024); } while (0)
; #define PG8_LDB(dst, b, h) do { _Pragma("unroll") for (int n = 0; n < 2; ++n) _Pragma("unroll") for (int k = 0; k < 2; ++k) dst[n][k] = *(const PG8_LAS bf16x8*)(lds + PG8_SB(b, h) + boff + n * 2048 + k * 1024); } while (0)
; #define PG8_MMA(ai, bj, At, Bt) do { __builtin_amdgcn_s_setprio(1); _Pragma("unroll") for (int m = 0; m < 4; ++m) _Pragma("unroll") for (int n = 0; n < 2; ++n) _Pragma("unroll") for (int k = 0; k < 2; ++k) \
;         acc[ai][bj][m][n] = __builtin_amdgcn_mfma_f32_16x16x32_bf16(Bt[n][k], At[m][k], acc[ai][bj][m][n], 0, 0, 0); __builtin_amdgcn_s_setprio(0); } while (0)
; #define PG8_WAIT_V(n) asm volatile("s_waitcnt vmcnt(" #n ")" ::: "memory")
; #define PG8_WAIT_L(n) asm volatile("s_waitcnt lgkmcnt(" #n ")" ::: "memory")
; #define PG8_BAR __builtin_amdgcn_s_barrier()
; #define PG8_SCHED __builtin_amdgcn_sched_barrier(0)
; template <class Epi, class Sched>
; __device__ __forceinline__ void gemm_phase(PG8_LAS unsigned char* lds, const Gemm g, const Sched& S, const Epi& E) {
;     ...
;             PG8_LDB(B0, 0, 0); PG8_SCHED; PG8_LDA(At, 0, 0); PG8_STAGE(PG8_SA(1, 1), a1 + hstep, voffA);
;             PG8_WAIT_L(8); PG8_BAR; PG8_WAIT_L(0); PG8_MMA(0, 0, At, B0); PG8_BAR; PG8_SCHED;
;     ...
;             PG8_LDB(B1, 1, 1); PG8_STAGE(PG8_SB(1, 0), b3, voffB);
;             PG8_BAR; PG8_WAIT_L(0); PG8_MMA(0, 1, At, B1); PG8_BAR;
;             PG8_LDA(At, 1, 1); PG8_STAGE(PG8_SA(1, 0), a3, voffA);
;             PG8_BAR; PG8_WAIT_L(0); PG8_MMA(1, 0, At, B0); PG8_BAR; PG8_SCHED;
;             PG8_STAGE(PG8_SB(1, 1), b3 + hstep, voffB);
;             PG8_WAIT_V(6); PG8_BAR; PG8_MMA(1, 1, At, B1); PG8_BAR;
	ds_read_b128 v[168:171], v150 offset:49152
	ds_read_b128 v[172:175], v150 offset:50176
	ds_read_b128 v[182:185], v150 offset:51200
	ds_read_b128 v[190:193], v150 offset:52224
	ds_read_b128 v[194:197], v150 offset:53248
	ds_read_b128 v[198:201], v150 offset:54272
	ds_read_b128 v[202:205], v150 offset:55296
	ds_read_b128 v[206:209], v150 offset:56320
	s_add_i32 s29, s57, s37
	s_mov_b32 m0, s29
	s_nop 0
	global_load_lds_dwordx4 v130, s[98:99]
	s_nop 1
	s_add_i32 m0, s29, 0x2000
	s_nop 0
	global_load_lds_dwordx4 v134, s[98:99]
	s_nop 1
	s_mov_b32 m0, s42
	s_nop 0
	global_load_lds_dwordx4 v128, s[100:101]
	s_nop 1
	s_mov_b32 m0, s43
	s_nop 0
	global_load_lds_dwordx4 v132, s[100:101]
	s_add_u32 s26, s26, 0x40080
	s_addc_u32 s27, s27, 0
	s_add_i32 s28, s28, s37
	s_mov_b32 m0, s28
	s_nop 0
	global_load_lds_dwordx4 v130, s[26:27]
	s_nop 1
	s_add_i32 m0, s28, 0x2000
	s_nop 0
	global_load_lds_dwordx4 v134, s[26:27]
	s_waitcnt vmcnt(8) lgkmcnt(0)
	s_barrier
	v_mfma_f32_16x16x32_bf16 v[60:63], v[152:155], v[168:171], v[60:63]
	v_mfma_f32_16x16x32_bf16 v[56:59], v[160:163], v[168:171], v[56:59]
	v_mfma_f32_16x16x32_bf16 v[48:51], v[152:155], v[182:185], v[48:51]
	v_mfma_f32_16x16x32_bf16 v[40:43], v[160:163], v[182:185], v[40:43]
	v_mfma_f32_16x16x32_bf16 v[32:35], v[152:155], v[194:197], v[32:35]
	v_mfma_f32_16x16x32_bf16 v[24:27], v[160:163], v[194:197], v[24:27]
	v_mfma_f32_16x16x32_bf16 v[16:19], v[152:155], v[202:205], v[16:19]
	v_mfma_f32_16x16x32_bf16 v[8:11], v[160:163], v[202:205], v[8:11]
	v_mfma_f32_16x16x32_bf16 v[60:63], v[156:159], v[172:175], v[60:63]
	v_mfma_f32_16x16x32_bf16 v[56:59], v[164:167], v[172:175], v[56:59]
	v_mfma_f32_16x16x32_bf16 v[48:51], v[156:159], v[190:193], v[48:51]
	v_mfma_f32_16x16x32_bf16 v[40:43], v[164:167], v[190:193], v[40:43]
	v_mfma_f32_16x16x32_bf16 v[32:35], v[156:159], v[198:201], v[32:35]
	v_mfma_f32_16x16x32_bf16 v[24:27], v[164:167], v[198:201], v[24:27]
	v_mfma_f32_16x16x32_bf16 v[16:19], v[156:159], v[206:209], v[16:19]
	v_mfma_f32_16x16x32_bf16 v[8:11], v[164:167], v[206:209], v[8:11]
	v_mfma_f32_16x16x32_bf16 v[52:55], v[210:213], v[168:171], v[52:55]
	v_mfma_f32_16x16x32_bf16 v[44:47], v[218:221], v[168:171], v[44:47]
	v_mfma_f32_16x16x32_bf16 v[36:39], v[210:213], v[182:185], v[36:39]
	v_mfma_f32_16x16x32_bf16 v[28:31], v[218:221], v[182:185], v[28:31]
	v_mfma_f32_16x16x32_bf16 v[20:23], v[210:213], v[194:197], v[20:23]
	v_mfma_f32_16x16x32_bf16 v[12:15], v[218:221], v[194:197], v[12:15]
	v_mfma_f32_16x16x32_bf16 v[4:7], v[210:213], v[202:205], v[4:7]
	v_mfma_f32_16x16x32_bf16 v[0:3], v[218:221], v[202:205], v[0:3]
	v_mfma_f32_16x16x32_bf16 v[52:55], v[214:217], v[172:175], v[52:55]
	v_mfma_f32_16x16x32_bf16 v[44:47], v[222:225], v[172:175], v[44:47]
	v_mfma_f32_16x16x32_bf16 v[36:39], v[214:217], v[190:193], v[36:39]
	v_mfma_f32_16x16x32_bf16 v[28:31], v[222:225], v[190:193], v[28:31]
	v_mfma_f32_16x16x32_bf16 v[20:23], v[214:217], v[198:201], v[20:23]
	v_mfma_f32_16x16x32_bf16 v[12:15], v[222:225], v[198:201], v[12:15]
	v_mfma_f32_16x16x32_bf16 v[4:7], v[214:217], v[206:209], v[4:7]
	v_mfma_f32_16x16x32_bf16 v[0:3], v[222:225], v[206:209], v[0:3]
	s_barrier
	s_add_i32 s56, s56, 2
	s_add_u32 s24, s24, 0x100
	s_addc_u32 s25, s25, 0
	s_add_u32 s54, s54, 0x100
	s_addc_u32 s55, s55, 0
	s_cmp_gt_u32 s56, 13
.LBB0_1083:
	ds_read_b128 v[152:155], v149
	ds_read_b128 v[156:159], v149 offset:1024
	ds_read_b128 v[160:163], v149 offset:2048
	ds_read_b128 v[164:167], v149 offset:3072
	s_add_u32 s26, s24, 0xfffc0080
	s_addc_u32 s27, s25, -1
	s_cmp_eq_u32 s56, 12
	s_cselect_b32 s29, s17, s27
	s_cselect_b32 s28, s52, s26
	s_cselect_b32 s27, s15, s55
	s_cselect_b32 s26, s53, s54
	s_add_i32 m0, s23, 0xc000
	ds_read_b128 v[168:171], v150
	ds_read_b128 v[172:175], v150 offset:1024
	ds_read_b128 v[182:185], v150 offset:2048
	ds_read_b128 v[190:193], v150 offset:3072
	ds_read_b128 v[194:197], v150 offset:4096
	ds_read_b128 v[198:201], v150 offset:5120
	ds_read_b128 v[202:205], v150 offset:6144
	ds_read_b128 v[206:209], v150 offset:7168
	global_load_lds_dwordx4 v136, s[24:25]
	s_nop 1
	s_add_i32 m0, s23, 0xe000
	s_nop 0
	global_load_lds_dwordx4 v138, s[24:25]
	s_waitcnt lgkmcnt(12)
	ds_read_b128 v[210:213], v151
	ds_read_b128 v[214:217], v151 offset:1024
	ds_read_b128 v[218:221], v151 offset:2048
	ds_read_b128 v[222:225], v151 offset:3072
	s_waitcnt vmcnt(8) lgkmcnt(0)
	s_barrier
	v_mfma_f32_16x16x32_bf16 v[124:127], v[152:155], v[168:171], v[124:127]
	v_mfma_f32_16x16x32_bf16 v[120:123], v[160:163], v[168:171], v[120:123]
	v_mfma_f32_16x16x32_bf16 v[108:111], v[152:155], v[182:185], v[108:111]
	v_mfma_f32_16x16x32_bf16 v[104:107], v[160:163], v[182:185], v[104:107]
	v_mfma_f32_16x16x32_bf16 v[92:95], v[152:155], v[194:197], v[92:95]
	v_mfma_f32_16x16x32_bf16 v[88:91], v[160:163], v[194:197], v[88:91]
	v_mfma_f32_16x16x32_bf16 v[76:79], v[152:155], v[202:205], v[76:79]
	v_mfma_f32_16x16x32_bf16 v[72:75], v[160:163], v[202:205], v[72:75]
	v_mfma_f32_16x16x32_bf16 v[124:127], v[156:159], v[172:175], v[124:127]
	v_mfma_f32_16x16x32_bf16 v[120:123], v[164:167], v[172:175], v[120:123]
	v_mfma_f32_16x16x32_bf16 v[108:111], v[156:159], v[190:193], v[108:111]
	v_mfma_f32_16x16x32_bf16 v[104:107], v[164:167], v[190:193], v[104:107]
	v_mfma_f32_16x16x32_bf16 v[92:95], v[156:159], v[198:201], v[92:95]
	v_mfma_f32_16x16x32_bf16 v[88:91], v[164:167], v[198:201], v[88:91]
	v_mfma_f32_16x16x32_bf16 v[76:79], v[156:159], v[206:209], v[76:79]
	v_mfma_f32_16x16x32_bf16 v[72:75], v[164:167], v[206:209], v[72:75]
	v_mfma_f32_16x16x32_bf16 v[116:119], v[210:213], v[168:171], v[116:119]
	v_mfma_f32_16x16x32_bf16 v[112:115], v[218:221], v[168:171], v[112:115]
	v_mfma_f32_16x16x32_bf16 v[100:103], v[210:213], v[182:185], v[100:103]
	v_mfma_f32_16x16x32_bf16 v[96:99], v[218:221], v[182:185], v[96:99]
	v_mfma_f32_16x16x32_bf16 v[84:87], v[210:213], v[194:197], v[84:87]
	v_mfma_f32_16x16x32_bf16 v[80:83], v[218:221], v[194:197], v[80:83]
	v_mfma_f32_16x16x32_bf16 v[68:71], v[210:213], v[202:205], v[68:71]
	v_mfma_f32_16x16x32_bf16 v[64:67], v[218:221], v[202:205], v[64:67]
	v_mfma_f32_16x16x32_bf16 v[116:119], v[214:217], v[172:175], v[116:119]
	v_mfma_f32_16x16x32_bf16 v[112:115], v[222:225], v[172:175], v[112:115]
	v_mfma_f32_16x16x32_bf16 v[100:103], v[214:217], v[190:193], v[100:103]
	v_mfma_f32_16x16x32_bf16 v[96:99], v[222:225], v[190:193], v[96:99]
	v_mfma_f32_16x16x32_bf16 v[84:87], v[214:217], v[198:201], v[84:87]
	v_mfma_f32_16x16x32_bf16 v[80:83], v[222:225], v[198:201], v[80:83]
	v_mfma_f32_16x16x32_bf16 v[68:71], v[214:217], v[206:209], v[68:71]
	v_mfma_f32_16x16x32_bf16 v[64:67], v[222:225], v[206:209], v[64:67]
	s_barrier
; #define PG8_STAGE(bufoff, gbase, voff) do { _Pragma("unroll") for (int _i = 0; _i < 2; ++_i) \
;         __builtin_amdgcn_global_load_lds((const unsigned*)((const char*)(gbase) + (voff)[_i]), (PG8_LAS unsigned*)(lds + (bufoff) + ldsw + _i * 8192), 16, 0, 0); } while (0)
; #define PG8_LDA(dst, b, h) do { _Pragma("unroll") for (int m = 0; m < 4; ++m) _Pragma("unroll") for (int k = 0; k < 2; ++k) dst[m][k] = *(const PG8_LAS bf16x8*)(lds + PG8_SA(b, h) + aoff + m * 2048 + k * 1024); } while (0)
; #define PG8_LDB(dst, b, h) do { _Pragma("unroll") for (int n = 0; n < 2; ++n) _Pragma("unroll") for (int k = 0; k < 2; ++k) dst[n][k] = *(const PG8_LAS bf16x8*)(lds + PG8_SB(b, h) + boff + n * 2048 + k * 1024); } while (0)
; #define PG8_MMA(ai, bj, At, Bt) do { __builtin_amdgcn_s_setprio(1); _Pragma("unroll") for (int m = 0; m < 4; ++m) _Pragma("unroll") for (int n = 0; n < 2; ++n) _Pragma("unroll") for (int k = 0; k < 2; ++k) \
;         acc[ai][bj][m][n] = __builtin_amdgcn_mfma_f32_16x16x32_bf16(Bt[n][k], At[m][k], acc[ai][bj][m][n], 0, 0, 0); __builtin_amdgcn_s_setprio(0); } while (0)
; #define PG8_WAIT_V(n) asm volatile("s_waitcnt vmcnt(" #n ")" ::: "memory")
; #define PG8_WAIT_L(n) asm volatile("s_waitcnt lgkmcnt(" #n ")" ::: "memory")
; #define PG8_BAR __builtin_amdgcn_s_barrier()
; #define PG8_SCHED __builtin_amdgcn_sched_barrier(0)
; template <class Epi, class Sched>
; __device__ __forceinline__ void gemm_phase(PG8_LAS unsigned char* lds, const Gemm g, const Sched& S, const Epi& E) {
;     ...
;             PG8_LDB(B1, 0, 1); PG8_STAGE(PG8_SB(0, 0), b2, voffB);
;             PG8_BAR; PG8_WAIT_L(0); PG8_MMA(0, 1, At, B1); PG8_BAR;
;             PG8_LDA(At, 0, 1); PG8_STAGE(PG8_SA(0, 0), a2, voffA);
;             PG8_BAR; PG8_WAIT_L(0); PG8_MMA(1, 0, At, B0); PG8_BAR; PG8_SCHED;
;             PG8_STAGE(PG8_SB(0, 1), b2 + hstep, voffB);
;             PG8_WAIT_V(6); PG8_BAR; PG8_MMA(1, 1, At, B1); PG8_BAR;
;             PG8_LDB(B0, 1, 0); PG8_SCHED; PG8_LDA(At, 1, 0); PG8_STAGE(PG8_SA(0, 1), a2 + hstep, voffA);
;             PG8_WAIT_L(8); PG8_BAR; PG8_WAIT_L(0); PG8_MMA(0, 0, At, B0); PG8_BAR; PG8_SCHED;
	ds_read_b128 v[168:171], v150 offset:16384
	ds_read_b128 v[172:175], v150 offset:17408
	ds_read_b128 v[182:185], v150 offset:18432
	ds_read_b128 v[190:193], v150 offset:19456
	ds_read_b128 v[194:197], v150 offset:20480
	ds_read_b128 v[198:201], v150 offset:21504
	ds_read_b128 v[202:205], v150 offset:22528
	ds_read_b128 v[206:209], v150 offset:23552
	s_add_i32 s57, s45, s37
	s_add_u32 s98, s26, s6
	s_addc_u32 s99, s27, s7
	s_mov_b32 m0, s57
	s_nop 0
	global_load_lds_dwordx4 v130, s[26:27]
	s_nop 1
	s_add_i32 m0, s57, 0x2000
	s_nop 0
	global_load_lds_dwordx4 v134, s[26:27]
	s_nop 1
	s_mov_b32 m0, s23
	s_add_u32 s100, s28, s6
	s_addc_u32 s101, s29, s7
	global_load_lds_dwordx4 v128, s[28:29]
	s_nop 1
	s_mov_b32 m0, s38
	s_nop 0
	global_load_lds_dwordx4 v132, s[28:29]
	s_add_u32 s58, s26, 0x40000
	s_addc_u32 s59, s27, 0
	s_add_i32 s57, s46, s37
	s_mov_b32 m0, s57
	s_nop 0
	global_load_lds_dwordx4 v130, s[58:59]
	s_nop 1
	s_add_i32 m0, s57, 0x2000
	s_nop 0
	global_load_lds_dwordx4 v134, s[58:59]
	s_waitcnt vmcnt(8) lgkmcnt(0)
	s_barrier
	v_mfma_f32_16x16x32_bf16 v[60:63], v[152:155], v[168:171], v[60:63]
	v_mfma_f32_16x16x32_bf16 v[56:59], v[160:163], v[168:171], v[56:59]
	v_mfma_f32_16x16x32_bf16 v[48:51], v[152:155], v[182:185], v[48:51]
	v_mfma_f32_16x16x32_bf16 v[40:43], v[160:163], v[182:185], v[40:43]
	v_mfma_f32_16x16x32_bf16 v[32:35], v[152:155], v[194:197], v[32:35]
	v_mfma_f32_16x16x32_bf16 v[24:27], v[160:163], v[194:197], v[24:27]
	v_mfma_f32_16x16x32_bf16 v[16:19], v[152:155], v[202:205], v[16:19]
	v_mfma_f32_16x16x32_bf16 v[8:11], v[160:163], v[202:205], v[8:11]
	v_mfma_f32_16x16x32_bf16 v[60:63], v[156:159], v[172:175], v[60:63]
	v_mfma_f32_16x16x32_bf16 v[56:59], v[164:167], v[172:175], v[56:59]
	v_mfma_f32_16x16x32_bf16 v[48:51], v[156:159], v[190:193], v[48:51]
	v_mfma_f32_16x16x32_bf16 v[40:43], v[164:167], v[190:193], v[40:43]
	v_mfma_f32_16x16x32_bf16 v[32:35], v[156:159], v[198:201], v[32:35]
	v_mfma_f32_16x16x32_bf16 v[24:27], v[164:167], v[198:201], v[24:27]
	v_mfma_f32_16x16x32_bf16 v[16:19], v[156:159], v[206:209], v[16:19]
	v_mfma_f32_16x16x32_bf16 v[8:11], v[164:167], v[206:209], v[8:11]
	v_mfma_f32_16x16x32_bf16 v[52:55], v[210:213], v[168:171], v[52:55]
	v_mfma_f32_16x16x32_bf16 v[44:47], v[218:221], v[168:171], v[44:47]
	v_mfma_f32_16x16x32_bf16 v[36:39], v[210:213], v[182:185], v[36:39]
	v_mfma_f32_16x16x32_bf16 v[28:31], v[218:221], v[182:185], v[28:31]
	v_mfma_f32_16x16x32_bf16 v[20:23], v[210:213], v[194:197], v[20:23]
	v_mfma_f32_16x16x32_bf16 v[12:15], v[218:221], v[194:197], v[12:15]
	v_mfma_f32_16x16x32_bf16 v[4:7], v[210:213], v[202:205], v[4:7]
	v_mfma_f32_16x16x32_bf16 v[0:3], v[218:221], v[202:205], v[0:3]
	v_mfma_f32_16x16x32_bf16 v[52:55], v[214:217], v[172:175], v[52:55]
	v_mfma_f32_16x16x32_bf16 v[44:47], v[222:225], v[172:175], v[44:47]
	v_mfma_f32_16x16x32_bf16 v[36:39], v[214:217], v[190:193], v[36:39]
	v_mfma_f32_16x16x32_bf16 v[28:31], v[222:225], v[190:193], v[28:31]
	v_mfma_f32_16x16x32_bf16 v[20:23], v[214:217], v[198:201], v[20:23]
	v_mfma_f32_16x16x32_bf16 v[12:15], v[222:225], v[198:201], v[12:15]
	v_mfma_f32_16x16x32_bf16 v[4:7], v[214:217], v[206:209], v[4:7]
	v_mfma_f32_16x16x32_bf16 v[0:3], v[222:225], v[206:209], v[0:3]
	s_barrier
	s_add_i32 s57, 0, 0x18000
	v_add_u32_e32 v164, s57, v147
	ds_read_b128 v[152:155], v164
	ds_read_b128 v[156:159], v164 offset:1024
	ds_read_b128 v[160:163], v164 offset:2048
	ds_read_b128 v[164:167], v164 offset:3072
	s_add_u32 s28, s28, 0x40000
	s_addc_u32 s29, s29, 0
	s_mov_b32 m0, s39
	ds_read_b128 v[168:171], v150 offset:32768
	ds_read_b128 v[172:175], v150 offset:33792
	ds_read_b128 v[182:185], v150 offset:34816
	ds_read_b128 v[190:193], v150 offset:35840
	ds_read_b128 v[194:197], v150 offset:36864
	ds_read_b128 v[198:201], v150 offset:37888
	ds_read_b128 v[202:205], v150 offset:38912
	ds_read_b128 v[206:209], v150 offset:39936
	global_load_lds_dwordx4 v128, s[28:29]
	s_nop 1
	s_mov_b32 m0, s40
	s_nop 0
	global_load_lds_dwordx4 v132, s[28:29]
	s_add_i32 s28, 0, 0x1c000
	v_add_u32_e32 v179, s28, v147
	s_waitcnt lgkmcnt(12)
	ds_read_b128 v[210:213], v179
	ds_read_b128 v[214:217], v179 offset:1024
	ds_read_b128 v[218:221], v179 offset:2048
	ds_read_b128 v[222:225], v179 offset:3072
	s_waitcnt vmcnt(8) lgkmcnt(0)
	s_barrier
	v_mfma_f32_16x16x32_bf16 v[124:127], v[152:155], v[168:171], v[124:127]
	v_mfma_f32_16x16x32_bf16 v[120:123], v[160:163], v[168:171], v[120:123]
	v_mfma_f32_16x16x32_bf16 v[108:111], v[152:155], v[182:185], v[108:111]
	v_mfma_f32_16x16x32_bf16 v[104:107], v[160:163], v[182:185], v[104:107]
	v_mfma_f32_16x16x32_bf16 v[92:95], v[152:155], v[194:197], v[92:95]
	v_mfma_f32_16x16x32_bf16 v[88:91], v[160:163], v[194:197], v[88:91]
	v_mfma_f32_16x16x32_bf16 v[76:79], v[152:155], v[202:205], v[76:79]
	v_mfma_f32_16x16x32_bf16 v[72:75], v[160:163], v[202:205], v[72:75]
	v_mfma_f32_16x16x32_bf16 v[124:127], v[156:159], v[172:175], v[124:127]
	v_mfma_f32_16x16x32_bf16 v[120:123], v[164:167], v[172:175], v[120:123]
	v_mfma_f32_16x16x32_bf16 v[108:111], v[156:159], v[190:193], v[108:111]
	v_mfma_f32_16x16x32_bf16 v[104:107], v[164:167], v[190:193], v[104:107]
	v_mfma_f32_16x16x32_bf16 v[92:95], v[156:159], v[198:201], v[92:95]
	v_mfma_f32_16x16x32_bf16 v[88:91], v[164:167], v[198:201], v[88:91]
	v_mfma_f32_16x16x32_bf16 v[76:79], v[156:159], v[206:209], v[76:79]
	v_mfma_f32_16x16x32_bf16 v[72:75], v[164:167], v[206:209], v[72:75]
	v_mfma_f32_16x16x32_bf16 v[116:119], v[210:213], v[168:171], v[116:119]
	v_mfma_f32_16x16x32_bf16 v[112:115], v[218:221], v[168:171], v[112:115]
	v_mfma_f32_16x16x32_bf16 v[100:103], v[210:213], v[182:185], v[100:103]
	v_mfma_f32_16x16x32_bf16 v[96:99], v[218:221], v[182:185], v[96:99]
	v_mfma_f32_16x16x32_bf16 v[84:87], v[210:213], v[194:197], v[84:87]
	v_mfma_f32_16x16x32_bf16 v[80:83], v[218:221], v[194:197], v[80:83]
	v_mfma_f32_16x16x32_bf16 v[68:71], v[210:213], v[202:205], v[68:71]
	v_mfma_f32_16x16x32_bf16 v[64:67], v[218:221], v[202:205], v[64:67]
	v_mfma_f32_16x16x32_bf16 v[116:119], v[214:217], v[172:175], v[116:119]
	v_mfma_f32_16x16x32_bf16 v[112:115], v[222:225], v[172:175], v[112:115]
	v_mfma_f32_16x16x32_bf16 v[100:103], v[214:217], v[190:193], v[100:103]
	v_mfma_f32_16x16x32_bf16 v[96:99], v[222:225], v[190:193], v[96:99]
	v_mfma_f32_16x16x32_bf16 v[84:87], v[214:217], v[198:201], v[84:87]
	v_mfma_f32_16x16x32_bf16 v[80:83], v[222:225], v[198:201], v[80:83]
	v_mfma_f32_16x16x32_bf16 v[68:71], v[214:217], v[206:209], v[68:71]
	v_mfma_f32_16x16x32_bf16 v[64:67], v[222:225], v[206:209], v[64:67]
	s_barrier
; __device__ __forceinline__ unsigned cvt_pk_bf16(float lo, float hi) { unsigned r; asm volatile("v_cvt_pk_bf16_f32 %0, %1, %2" : "=v"(r) : "v"(lo), "v"(hi)); return r; }
; __device__ __forceinline__ float flogsig16(float x) { return (fminf(x, 0.f) - __logf(1.0f + __expf(-fabsf(x)))) * 0.0625f; }
; #define PG8_STAGE(bufoff, gbase, voff) do { _Pragma("unroll") for (int _i = 0; _i < 2; ++_i) \
;         __builtin_amdgcn_global_load_lds((const unsigned*)((const char*)(gbase) + (voff)[_i]), (PG8_LAS unsigned*)(lds + (bufoff) + ldsw + _i * 8192), 16, 0, 0); } while (0)
; #define PG8_LDA(dst, b, h) do { _Pragma("unroll") for (int m = 0; m < 4; ++m) _Pragma("unroll") for (int k = 0; k < 2; ++k) dst[m][k] = *(const PG8_LAS bf16x8*)(lds + PG8_SA(b, h) + aoff + m * 2048 + k * 1024); } while (0)
;     __device__ __forceinline__ void operator()(const f32x4 (&acc)[2][2][4][2], const Unit& u, int wr, int wc, int fr, int fq) const {
;     ...
;         for (int ai = 0; ai < 2; ++ai)
; #pragma unroll
;             for (int m = 0; m < 4; ++m) { bf16_t* rowp = O + (size_t)(row0 + ai * HALF + m * 16) * ldc + col0;
; #pragma unroll
;                 for (int bj = 0; bj < 2; ++bj) { f32x4 v0 = acc[ai][bj][m][0] + bv[bj][0], v1 = acc[ai][bj][m][1] + bv[bj][1];
;                     if (act == 1) {
; #pragma unroll
;                         for (int j = 0; j < 1; ++j) { v0 = v0 * sigmoid4(v0); v1 = v1 * sigmoid4(v1); } }
;                     else if (act == 2) {
; #pragma unroll
;                         for (int j = 0; j < 1; ++j) { v0 = sigmoid4(v0); v1 = sigmoid4(v1); } }
;                     else if (act == 3) {
; #pragma unroll
;                         for (int j = 0; j < 4; ++j) { v0[j] = flogsig16(v0[j]); v1[j] = flogsig16(v1[j]); } }
;                     u32x4 w; w.x = cvt_pk_bf16(v0[0], v0[1]); w.y = cvt_pk_bf16(v0[2], v0[3]); w.z = cvt_pk_bf16(v1[0], v1[1]); w.w = cvt_pk_bf16(v1[2], v1[3]);
;                     *(u32x4*)(rowp + bj * HALF) = w; } }
; template <class Epi, class Sched>
; __device__ __forceinline__ void gemm_phase(PG8_LAS unsigned char* lds, const Gemm g, const Sched& S, const Epi& E) {
;     ...
;             PG8_LDA(At, 1, 1); PG8_STAGE(PG8_SA(1, 0), a3, voffA);
;             PG8_BAR; PG8_WAIT_L(0); PG8_MMA(1, 0, At, B0); PG8_BAR; PG8_SCHED;
;             PG8_STAGE(PG8_SB(1, 1), b3 + hstep, voffB);
;             PG8_WAIT_V(6); PG8_BAR; PG8_MMA(1, 1, At, B1); PG8_BAR;
	ds_read_b128 v[168:171], v150 offset:49152
	ds_read_b128 v[172:175], v150 offset:50176
	ds_read_b128 v[182:185], v150 offset:51200
	ds_read_b128 v[190:193], v150 offset:52224
	ds_read_b128 v[194:197], v150 offset:53248
	ds_read_b128 v[198:201], v150 offset:54272
	ds_read_b128 v[202:205], v150 offset:55296
	ds_read_b128 v[206:209], v150 offset:56320
	s_add_i32 s29, s57, s37
	s_mov_b32 m0, s29
	s_nop 0
	global_load_lds_dwordx4 v130, s[98:99]
	s_nop 1
	s_add_i32 m0, s29, 0x2000
	s_nop 0
	global_load_lds_dwordx4 v134, s[98:99]
	s_nop 1
	s_mov_b32 m0, s42
	s_nop 0
	global_load_lds_dwordx4 v128, s[100:101]
	s_nop 1
	s_mov_b32 m0, s43
	s_nop 0
	global_load_lds_dwordx4 v132, s[100:101]
	s_add_u32 s26, s26, 0x40080
	s_addc_u32 s27, s27, 0
	s_add_i32 s28, s28, s37
	s_mov_b32 m0, s28
	s_nop 0
	global_load_lds_dwordx4 v130, s[26:27]
	s_nop 1
	s_add_i32 m0, s28, 0x2000
	s_nop 0
	global_load_lds_dwordx4 v134, s[26:27]
	s_waitcnt vmcnt(8) lgkmcnt(0)
	s_barrier
	v_mfma_f32_16x16x32_bf16 v[60:63], v[152:155], v[168:171], v[60:63]
	v_mfma_f32_16x16x32_bf16 v[56:59], v[160:163], v[168:171], v[56:59]
	v_mfma_f32_16x16x32_bf16 v[48:51], v[152:155], v[182:185], v[48:51]
	v_mfma_f32_16x16x32_bf16 v[40:43], v[160:163], v[182:185], v[40:43]
	v_mfma_f32_16x16x32_bf16 v[32:35], v[152:155], v[194:197], v[32:35]
	v_mfma_f32_16x16x32_bf16 v[24:27], v[160:163], v[194:197], v[24:27]
	v_mfma_f32_16x16x32_bf16 v[16:19], v[152:155], v[202:205], v[16:19]
	v_mfma_f32_16x16x32_bf16 v[8:11], v[160:163], v[202:205], v[8:11]
	v_mfma_f32_16x16x32_bf16 v[60:63], v[156:159], v[172:175], v[60:63]
	v_mfma_f32_16x16x32_bf16 v[56:59], v[164:167], v[172:175], v[56:59]
	v_mfma_f32_16x16x32_bf16 v[48:51], v[156:159], v[190:193], v[48:51]
	v_mfma_f32_16x16x32_bf16 v[40:43], v[164:167], v[190:193], v[40:43]
	v_mfma_f32_16x16x32_bf16 v[32:35], v[156:159], v[198:201], v[32:35]
	v_mfma_f32_16x16x32_bf16 v[24:27], v[164:167], v[198:201], v[24:27]
	v_mfma_f32_16x16x32_bf16 v[16:19], v[156:159], v[206:209], v[16:19]
	v_mfma_f32_16x16x32_bf16 v[8:11], v[164:167], v[206:209], v[8:11]
	v_mfma_f32_16x16x32_bf16 v[52:55], v[210:213], v[168:171], v[52:55]
	v_mfma_f32_16x16x32_bf16 v[44:47], v[218:221], v[168:171], v[44:47]
	v_mfma_f32_16x16x32_bf16 v[36:39], v[210:213], v[182:185], v[36:39]
	v_mfma_f32_16x16x32_bf16 v[28:31], v[218:221], v[182:185], v[28:31]
	v_mfma_f32_16x16x32_bf16 v[20:23], v[210:213], v[194:197], v[20:23]
	v_mfma_f32_16x16x32_bf16 v[12:15], v[218:221], v[194:197], v[12:15]
	v_mfma_f32_16x16x32_bf16 v[4:7], v[210:213], v[202:205], v[4:7]
	v_mfma_f32_16x16x32_bf16 v[0:3], v[218:221], v[202:205], v[0:3]
	v_mfma_f32_16x16x32_bf16 v[52:55], v[214:217], v[172:175], v[52:55]
	v_mfma_f32_16x16x32_bf16 v[44:47], v[222:225], v[172:175], v[44:47]
	v_mfma_f32_16x16x32_bf16 v[36:39], v[214:217], v[190:193], v[36:39]
	v_mfma_f32_16x16x32_bf16 v[28:31], v[222:225], v[190:193], v[28:31]
	v_mfma_f32_16x16x32_bf16 v[20:23], v[214:217], v[198:201], v[20:23]
	v_mfma_f32_16x16x32_bf16 v[12:15], v[222:225], v[198:201], v[12:15]
	v_mfma_f32_16x16x32_bf16 v[4:7], v[214:217], v[206:209], v[4:7]
	v_mfma_f32_16x16x32_bf16 v[0:3], v[222:225], v[206:209], v[0:3]
	s_barrier
	s_add_i32 s56, s56, 2
	s_add_u32 s24, s24, 0x100
	s_addc_u32 s25, s25, 0
	s_add_u32 s54, s54, 0x100
	s_addc_u32 s55, s55, 0
	s_cmp_gt_u32 s56, 13
	s_cbranch_scc0 .LBB0_1083
	v_lshl_add_u32 v152, s22, 8, v146
	v_lshl_or_b32 v144, s51, 8, v148
	v_ashrrev_i32_e32 v153, 31, v152
	v_ashrrev_i32_e32 v145, 31, v144
	v_lshlrev_b64 v[154:155], 11, v[152:153]
	v_lshl_add_u64 v[154:155], s[4:5], 0, v[154:155]
	v_lshlrev_b64 v[156:157], 1, v[144:145]
	v_lshl_add_u64 v[144:145], v[154:155], 0, v[156:157]
	v_pk_add_f32 v[126:127], v[126:127], 0 op_sel_hi:[1,0]
	v_pk_add_f32 v[124:125], v[124:125], 0 op_sel_hi:[1,0]
	v_pk_add_f32 v[154:155], v[122:123], 0 op_sel_hi:[1,0]
	v_pk_add_f32 v[122:123], v[120:121], 0 op_sel_hi:[1,0]
	v_cvt_pk_bf16_f32 v120, v124, v125
	v_cvt_pk_bf16_f32 v121, v126, v127
	v_pk_add_f32 v[116:117], v[116:117], 0 op_sel_hi:[1,0]
	v_cvt_pk_bf16_f32 v122, v122, v123
	v_cvt_pk_bf16_f32 v123, v154, v155
	global_store_dwordx4 v[144:145], v[120:123], off
	v_pk_add_f32 v[118:119], v[118:119], 0 op_sel_hi:[1,0]
	v_pk_add_f32 v[110:111], v[110:111], 0 op_sel_hi:[1,0]
	v_pk_add_f32 v[120:121], v[114:115], 0 op_sel_hi:[1,0]
	v_pk_add_f32 v[114:115], v[112:113], 0 op_sel_hi:[1,0]
	v_cvt_pk_bf16_f32 v112, v116, v117
	v_cvt_pk_bf16_f32 v113, v118, v119
	v_pk_add_f32 v[108:109], v[108:109], 0 op_sel_hi:[1,0]
	v_cvt_pk_bf16_f32 v114, v114, v115
	v_cvt_pk_bf16_f32 v115, v120, v121
	global_store_dwordx4 v[144:145], v[112:115], off offset:256
	v_pk_add_f32 v[100:101], v[100:101], 0 op_sel_hi:[1,0]
	v_pk_add_f32 v[102:103], v[102:103], 0 op_sel_hi:[1,0]
	v_or_b32_e32 v112, 16, v152
	v_ashrrev_i32_e32 v113, 31, v112
	v_lshlrev_b64 v[112:113], 11, v[112:113]
	v_lshl_add_u64 v[112:113], s[4:5], 0, v[112:113]
	v_lshl_add_u64 v[112:113], v[112:113], 0, v[156:157]
	v_pk_add_f32 v[114:115], v[106:107], 0 op_sel_hi:[1,0]
	v_pk_add_f32 v[106:107], v[104:105], 0 op_sel_hi:[1,0]
	v_cvt_pk_bf16_f32 v104, v108, v109
	v_cvt_pk_bf16_f32 v105, v110, v111
	v_pk_add_f32 v[94:95], v[94:95], 0 op_sel_hi:[1,0]
	v_cvt_pk_bf16_f32 v106, v106, v107
	v_cvt_pk_bf16_f32 v107, v114, v115
	global_store_dwordx4 v[112:113], v[104:107], off
	v_pk_add_f32 v[92:93], v[92:93], 0 op_sel_hi:[1,0]
	v_pk_add_f32 v[84:85], v[84:85], 0 op_sel_hi:[1,0]
	v_pk_add_f32 v[104:105], v[98:99], 0 op_sel_hi:[1,0]
	v_pk_add_f32 v[98:99], v[96:97], 0 op_sel_hi:[1,0]
	v_cvt_pk_bf16_f32 v96, v100, v101
	v_cvt_pk_bf16_f32 v97, v102, v103
	v_pk_add_f32 v[86:87], v[86:87], 0 op_sel_hi:[1,0]
; __device__ __forceinline__ unsigned cvt_pk_bf16(float lo, float hi) { unsigned r; asm volatile("v_cvt_pk_bf16_f32 %0, %1, %2" : "=v"(r) : "v"(lo), "v"(hi)); return r; }
; __device__ __forceinline__ float flogsig16(float x) { return (fminf(x, 0.f) - __logf(1.0f + __expf(-fabsf(x)))) * 0.0625f; }
; #define PG8_WAIT_V(n) asm volatile("s_waitcnt vmcnt(" #n ")" ::: "memory")
; #define PG8_BAR __builtin_amdgcn_s_barrier()
;     __device__ __forceinline__ void operator()(const f32x4 (&acc)[2][2][4][2], const Unit& u, int wr, int wc, int fr, int fq) const {
;     ...
;             for (int m = 0; m < 4; ++m) { bf16_t* rowp = O + (size_t)(row0 + ai * HALF + m * 16) * ldc + col0;
; #pragma unroll
;                 for (int bj = 0; bj < 2; ++bj) { f32x4 v0 = acc[ai][bj][m][0] + bv[bj][0], v1 = acc[ai][bj][m][1] + bv[bj][1];
;                     if (act == 1) {
; #pragma unroll
;                         for (int j = 0; j < 1; ++j) { v0 = v0 * sigmoid4(v0); v1 = v1 * sigmoid4(v1); } }
;                     else if (act == 2) {
; #pragma unroll
;                         for (int j = 0; j < 1; ++j) { v0 = sigmoid4(v0); v1 = sigmoid4(v1); } }
;                     else if (act == 3) {
; #pragma unroll
;                         for (int j = 0; j < 4; ++j) { v0[j] = flogsig16(v0[j]); v1[j] = flogsig16(v1[j]); } }
;                     u32x4 w; w.x = cvt_pk_bf16(v0[0], v0[1]); w.y = cvt_pk_bf16(v0[2], v0[3]); w.z = cvt_pk_bf16(v1[0], v1[1]); w.w = cvt_pk_bf16(v1[2], v1[3]);
;                     *(u32x4*)(rowp + bj * HALF) = w; } }
; template <class Epi, class Sched>
; __device__ __forceinline__ void gemm_phase(PG8_LAS unsigned char* lds, const Gemm g, const Sched& S, const Epi& E) {
;     ...
;         if (!has_next) break;
; #pragma unroll
;         for (int a = 0; a < 2; ++a)
; #pragma unroll
;             for (int b = 0; b < 2; ++b)
; #pragma unroll
;                 for (int m = 0; m < 4; ++m)
; #pragma unroll
;                     for (int n = 0; n < 2; ++n) acc[a][b][m][n] = (f32x4){0.f, 0.f, 0.f, 0.f};
;         cur = nxt; cA = nA; cB = nB; ++ui;
;     }
;     PG8_WAIT_V(0);
;     if (wr == 0) PG8_BAR;
;     PG8_BAR;
	v_cvt_pk_bf16_f32 v98, v98, v99
	v_cvt_pk_bf16_f32 v99, v104, v105
	global_store_dwordx4 v[112:113], v[96:99], off offset:256
	v_pk_add_f32 v[78:79], v[78:79], 0 op_sel_hi:[1,0]
	v_pk_add_f32 v[76:77], v[76:77], 0 op_sel_hi:[1,0]
	v_or_b32_e32 v96, 32, v152
	v_ashrrev_i32_e32 v97, 31, v96
	v_lshlrev_b64 v[96:97], 11, v[96:97]
	v_lshl_add_u64 v[96:97], s[4:5], 0, v[96:97]
	v_lshl_add_u64 v[96:97], v[96:97], 0, v[156:157]
	v_pk_add_f32 v[98:99], v[90:91], 0 op_sel_hi:[1,0]
	v_pk_add_f32 v[90:91], v[88:89], 0 op_sel_hi:[1,0]
	v_cvt_pk_bf16_f32 v88, v92, v93
	v_cvt_pk_bf16_f32 v89, v94, v95
	v_pk_add_f32 v[70:71], v[70:71], 0 op_sel_hi:[1,0]
	v_cvt_pk_bf16_f32 v90, v90, v91
	v_cvt_pk_bf16_f32 v91, v98, v99
	global_store_dwordx4 v[96:97], v[88:91], off
	v_pk_add_f32 v[68:69], v[68:69], 0 op_sel_hi:[1,0]
	v_pk_add_f32 v[60:61], v[60:61], 0 op_sel_hi:[1,0]
	v_pk_add_f32 v[88:89], v[82:83], 0 op_sel_hi:[1,0]
	v_pk_add_f32 v[82:83], v[80:81], 0 op_sel_hi:[1,0]
	v_cvt_pk_bf16_f32 v80, v84, v85
	v_cvt_pk_bf16_f32 v81, v86, v87
	v_pk_add_f32 v[62:63], v[62:63], 0 op_sel_hi:[1,0]
	v_cvt_pk_bf16_f32 v82, v82, v83
	v_cvt_pk_bf16_f32 v83, v88, v89
	global_store_dwordx4 v[96:97], v[80:83], off offset:256
	v_pk_add_f32 v[54:55], v[54:55], 0 op_sel_hi:[1,0]
	v_pk_add_f32 v[52:53], v[52:53], 0 op_sel_hi:[1,0]
	v_or_b32_e32 v80, 48, v152
	v_ashrrev_i32_e32 v81, 31, v80
	v_lshlrev_b64 v[80:81], 11, v[80:81]
	v_lshl_add_u64 v[80:81], s[4:5], 0, v[80:81]
	v_lshl_add_u64 v[80:81], v[80:81], 0, v[156:157]
	v_pk_add_f32 v[82:83], v[74:75], 0 op_sel_hi:[1,0]
	v_pk_add_f32 v[74:75], v[72:73], 0 op_sel_hi:[1,0]
	v_cvt_pk_bf16_f32 v72, v76, v77
	v_cvt_pk_bf16_f32 v73, v78, v79
	v_pk_add_f32 v[48:49], v[48:49], 0 op_sel_hi:[1,0]
	v_cvt_pk_bf16_f32 v74, v74, v75
	v_cvt_pk_bf16_f32 v75, v82, v83
	global_store_dwordx4 v[80:81], v[72:75], off
	v_pk_add_f32 v[38:39], v[38:39], 0 op_sel_hi:[1,0]
	v_pk_add_f32 v[36:37], v[36:37], 0 op_sel_hi:[1,0]
	v_pk_add_f32 v[72:73], v[66:67], 0 op_sel_hi:[1,0]
	v_pk_add_f32 v[66:67], v[64:65], 0 op_sel_hi:[1,0]
	v_cvt_pk_bf16_f32 v64, v68, v69
	v_cvt_pk_bf16_f32 v65, v70, v71
	v_pk_add_f32 v[32:33], v[32:33], 0 op_sel_hi:[1,0]
	v_cvt_pk_bf16_f32 v66, v66, v67
	v_cvt_pk_bf16_f32 v67, v72, v73
	global_store_dwordx4 v[80:81], v[64:67], off offset:256
	v_pk_add_f32 v[22:23], v[22:23], 0 op_sel_hi:[1,0]
	v_pk_add_f32 v[20:21], v[20:21], 0 op_sel_hi:[1,0]
	v_pk_add_f32 v[66:67], v[58:59], 0 op_sel_hi:[1,0]
	v_pk_add_f32 v[58:59], v[56:57], 0 op_sel_hi:[1,0]
	v_cvt_pk_bf16_f32 v56, v60, v61
	v_add_co_u32_e32 v60, vcc, s47, v144
	v_cvt_pk_bf16_f32 v57, v62, v63
	v_cvt_pk_bf16_f32 v58, v58, v59
	v_cvt_pk_bf16_f32 v59, v66, v67
	v_lshl_add_u64 v[64:65], v[144:145], 0, s[0:1]
	s_nop 0
	v_addc_co_u32_e32 v61, vcc, 0, v145, vcc
	global_store_dwordx4 v[60:61], v[56:59], off
	v_pk_add_f32 v[16:17], v[16:17], 0 op_sel_hi:[1,0]
	s_mov_b32 s51, s14
	v_pk_add_f32 v[56:57], v[46:47], 0 op_sel_hi:[1,0]
	v_pk_add_f32 v[46:47], v[44:45], 0 op_sel_hi:[1,0]
	v_cvt_pk_bf16_f32 v44, v52, v53
	v_cvt_pk_bf16_f32 v45, v54, v55
	s_mov_b32 s22, s16
	v_cvt_pk_bf16_f32 v46, v46, v47
	v_cvt_pk_bf16_f32 v47, v56, v57
	global_store_dwordx4 v[64:65], v[44:47], off offset:256
	s_mov_b64 s[26:27], s[20:21]
	s_mov_b64 s[24:25], s[18:19]
	v_pk_add_f32 v[46:47], v[50:51], 0 op_sel_hi:[1,0]
	v_pk_add_f32 v[50:51], v[42:43], 0 op_sel_hi:[1,0]
	v_pk_add_f32 v[42:43], v[40:41], 0 op_sel_hi:[1,0]
	v_cvt_pk_bf16_f32 v40, v48, v49
	v_cvt_pk_bf16_f32 v41, v46, v47
	v_add_co_u32_e32 v46, vcc, s48, v144
	v_cvt_pk_bf16_f32 v42, v42, v43
	v_cvt_pk_bf16_f32 v43, v50, v51
	v_lshl_add_u64 v[44:45], v[144:145], 0, s[8:9]
	s_nop 0
	v_addc_co_u32_e32 v47, vcc, 0, v145, vcc
	global_store_dwordx4 v[46:47], v[40:43], off
	v_pk_add_f32 v[6:7], v[6:7], 0 op_sel_hi:[1,0]
	v_pk_add_f32 v[4:5], v[4:5], 0 op_sel_hi:[1,0]
	v_pk_add_f32 v[40:41], v[30:31], 0 op_sel_hi:[1,0]
	v_pk_add_f32 v[30:31], v[28:29], 0 op_sel_hi:[1,0]
	v_cvt_pk_bf16_f32 v28, v36, v37
	v_cvt_pk_bf16_f32 v29, v38, v39
	s_nop 0
	v_cvt_pk_bf16_f32 v30, v30, v31
	v_cvt_pk_bf16_f32 v31, v40, v41
	global_store_dwordx4 v[44:45], v[28:31], off offset:256
	s_nop 1
	v_pk_add_f32 v[30:31], v[34:35], 0 op_sel_hi:[1,0]
	v_pk_add_f32 v[34:35], v[26:27], 0 op_sel_hi:[1,0]
	v_pk_add_f32 v[26:27], v[24:25], 0 op_sel_hi:[1,0]
	v_cvt_pk_bf16_f32 v24, v32, v33
	v_cvt_pk_bf16_f32 v25, v30, v31
	v_add_co_u32_e32 v30, vcc, s49, v144
	v_cvt_pk_bf16_f32 v26, v26, v27
	v_cvt_pk_bf16_f32 v27, v34, v35
	v_lshl_add_u64 v[28:29], v[144:145], 0, s[10:11]
	s_nop 0
	v_addc_co_u32_e32 v31, vcc, 0, v145, vcc
	global_store_dwordx4 v[30:31], v[24:27], off
	s_nop 1
	v_pk_add_f32 v[24:25], v[14:15], 0 op_sel_hi:[1,0]
	v_pk_add_f32 v[14:15], v[12:13], 0 op_sel_hi:[1,0]
	v_cvt_pk_bf16_f32 v12, v20, v21
	v_cvt_pk_bf16_f32 v13, v22, v23
	s_nop 0
	v_cvt_pk_bf16_f32 v14, v14, v15
	v_cvt_pk_bf16_f32 v15, v24, v25
	global_store_dwordx4 v[28:29], v[12:15], off offset:256
	s_nop 1
	v_pk_add_f32 v[14:15], v[18:19], 0 op_sel_hi:[1,0]
	v_pk_add_f32 v[18:19], v[10:11], 0 op_sel_hi:[1,0]
	v_pk_add_f32 v[10:11], v[8:9], 0 op_sel_hi:[1,0]
	v_cvt_pk_bf16_f32 v8, v16, v17
	v_cvt_pk_bf16_f32 v9, v14, v15
	v_add_co_u32_e32 v14, vcc, s50, v144
	v_lshl_add_u64 v[12:13], v[144:145], 0, s[12:13]
	s_nop 0
	v_addc_co_u32_e32 v15, vcc, 0, v145, vcc
	v_cvt_pk_bf16_f32 v10, v10, v11
	v_cvt_pk_bf16_f32 v11, v18, v19
	global_store_dwordx4 v[14:15], v[8:11], off
	s_and_b64 vcc, exec, s[2:3]
	s_nop 0
	v_pk_add_f32 v[8:9], v[2:3], 0 op_sel_hi:[1,0]
	v_pk_add_f32 v[2:3], v[0:1], 0 op_sel_hi:[1,0]
	v_cvt_pk_bf16_f32 v0, v4, v5
	v_cvt_pk_bf16_f32 v1, v6, v7
	s_nop 0
	v_cvt_pk_bf16_f32 v2, v2, v3
	v_cvt_pk_bf16_f32 v3, v8, v9
	global_store_dwordx4 v[12:13], v[0:3], off offset:256
	s_cbranch_vccz .LBB0_1076
	s_waitcnt vmcnt(0)
	s_cmpk_gt_u32 s31, 0xff
	s_cbranch_scc1 .LBB0_1087
	s_barrier

; #define PG8_STAGE(bufoff, gbase, voff) do { _Pragma("unroll") for (int _i = 0; _i < 2; ++_i) \
;         __builtin_amdgcn_global_load_lds((const unsigned*)((const char*)(gbase) + (voff)[_i]), (PG8_LAS unsigned*)(lds + (bufoff) + ldsw + _i * 8192), 16, 0, 0); } while (0)
; #define PG8_LDA(dst, b, h) do { _Pragma("unroll") for (int m = 0; m < 4; ++m) _Pragma("unroll") for (int k = 0; k < 2; ++k) dst[m][k] = *(const PG8_LAS bf16x8*)(lds + PG8_SA(b, h) + aoff + m * 2048 + k * 1024); } while (0)
; #define PG8_LDB(dst, b, h) do { _Pragma("unroll") for (int n = 0; n < 2; ++n) _Pragma("unroll") for (int k = 0; k < 2; ++k) dst[n][k] = *(const PG8_LAS bf16x8*)(lds + PG8_SB(b, h) + boff + n * 2048 + k * 1024); } while (0)
; #define PG8_MMA(ai, bj, At, Bt) do { __builtin_amdgcn_s_setprio(1); _Pragma("unroll") for (int m = 0; m < 4; ++m) _Pragma("unroll") for (int n = 0; n < 2; ++n) _Pragma("unroll") for (int k = 0; k < 2; ++k) \
;         acc[ai][bj][m][n] = __builtin_amdgcn_mfma_f32_16x16x32_bf16(Bt[n][k], At[m][k], acc[ai][bj][m][n], 0, 0, 0); __builtin_amdgcn_s_setprio(0); } while (0)
; template <class Epi, class Sched>
; __device__ __forceinline__ void gemm_phase(PG8_LAS unsigned char* lds, const Gemm g, const Sched& S, const Epi& E) {
;     ...
;         const bool has_next = S.next(ui + 1, nxt);
;         const char* nA = has_next ? (const char*)g.A + (size_t)nxt.pm * tstep : cA; const char* nB = has_next ? (const char*)g.Bt + (size_t)nxt.pn * tstep : cB;
;         for (int t = 0; t < nt; t += 2) {
;             const bool last = (t == nt - 2);
;             const char* a1 = cA + (size_t)(t + 1) * kstep;
;             const char* a2 = last ? nA : cA + (size_t)(t + 2) * kstep; const char* b2 = last ? nB : cB + (size_t)(t + 2) * kstep;
;             const char* a3 = a2 + kstep; const char* b3 = b2 + kstep;
;             if (last && has_next) S.a_ready(nxt);
;             PG8_LDB(B0, 0, 0); PG8_SCHED; PG8_LDA(At, 0, 0); PG8_STAGE(PG8_SA(1, 1), a1 + hstep, voffA);
;             PG8_WAIT_L(8); PG8_BAR; PG8_WAIT_L(0); PG8_MMA(0, 0, At, B0); PG8_BAR; PG8_SCHED;
;             PG8_LDB(B1, 0, 1); PG8_STAGE(PG8_SB(0, 0), b2, voffB);
;             PG8_BAR; PG8_WAIT_L(0); PG8_MMA(0, 1, At, B1); PG8_BAR;
;             PG8_LDA(At, 0, 1); PG8_STAGE(PG8_SA(0, 0), a2, voffA);
;             PG8_BAR; PG8_WAIT_L(0); PG8_MMA(1, 0, At, B0); PG8_BAR; PG8_SCHED;
.LBB0_1201:
	s_ashr_i32 s9, s8, 31
	v_cmp_lt_i64_e32 vcc, s[10:11], v[140:141]
	s_lshl_b64 s[10:11], s[8:9], 19
	s_add_u32 s10, s24, s10
	s_addc_u32 s11, s25, s11
	s_and_b64 s[12:13], vcc, exec
	s_cselect_b32 s9, s11, s17
	s_cselect_b32 s42, s10, s16
	s_ashr_i32 s7, s6, 31
	s_lshl_b64 s[12:13], s[6:7], 19
	s_add_u32 s12, s84, s12
	s_addc_u32 s13, s85, s13
	s_and_b64 s[20:21], vcc, exec
	s_cselect_b32 s7, s13, s19
	s_cselect_b32 s43, s12, s18
	s_add_u32 s16, s16, 0x40080
	s_addc_u32 s17, s17, 0
	s_add_u32 s44, s18, 0x100
	s_addc_u32 s45, s19, 0
	s_mov_b32 s46, -2
	ds_read_b128 v[144:147], v151
	ds_read_b128 v[154:157], v151 offset:1024
	ds_read_b128 v[158:161], v151 offset:2048
	ds_read_b128 v[162:165], v151 offset:3072
	s_add_u32 s18, s16, 0xfffc0080
	s_addc_u32 s19, s17, -1
	s_cmp_eq_u32 s46, 12
	s_cselect_b32 s21, s9, s19
	s_cselect_b32 s20, s42, s18
	s_cselect_b32 s19, s7, s45
	s_cselect_b32 s18, s43, s44
	s_add_i32 m0, s15, 0xc000
	ds_read_b128 v[166:169], v152
	ds_read_b128 v[170:173], v152 offset:1024
	ds_read_b128 v[182:185], v152 offset:2048
	ds_read_b128 v[190:193], v152 offset:3072
	ds_read_b128 v[194:197], v152 offset:4096
	ds_read_b128 v[198:201], v152 offset:5120
	ds_read_b128 v[202:205], v152 offset:6144
	ds_read_b128 v[206:209], v152 offset:7168
	global_load_lds_dwordx4 v136, s[16:17]
	s_nop 1
	s_add_i32 m0, s15, 0xe000
	s_nop 0
	global_load_lds_dwordx4 v138, s[16:17]
	s_waitcnt lgkmcnt(12)
	ds_read_b128 v[210:213], v153
	ds_read_b128 v[214:217], v153 offset:1024
	ds_read_b128 v[218:221], v153 offset:2048
	ds_read_b128 v[222:225], v153 offset:3072
	s_waitcnt vmcnt(8) lgkmcnt(0)
	s_barrier
	v_mfma_f32_16x16x32_bf16 v[124:127], v[144:147], v[166:169], 0
	v_mfma_f32_16x16x32_bf16 v[120:123], v[158:161], v[166:169], 0
	v_mfma_f32_16x16x32_bf16 v[108:111], v[144:147], v[182:185], 0
	v_mfma_f32_16x16x32_bf16 v[104:107], v[158:161], v[182:185], 0
	v_mfma_f32_16x16x32_bf16 v[92:95], v[144:147], v[194:197], 0
	v_mfma_f32_16x16x32_bf16 v[88:91], v[158:161], v[194:197], 0
	v_mfma_f32_16x16x32_bf16 v[76:79], v[144:147], v[202:205], 0
	v_mfma_f32_16x16x32_bf16 v[72:75], v[158:161], v[202:205], 0
	v_mfma_f32_16x16x32_bf16 v[124:127], v[154:157], v[170:173], v[124:127]
	v_mfma_f32_16x16x32_bf16 v[120:123], v[162:165], v[170:173], v[120:123]
	v_mfma_f32_16x16x32_bf16 v[108:111], v[154:157], v[190:193], v[108:111]
	v_mfma_f32_16x16x32_bf16 v[104:107], v[162:165], v[190:193], v[104:107]
	v_mfma_f32_16x16x32_bf16 v[92:95], v[154:157], v[198:201], v[92:95]
	v_mfma_f32_16x16x32_bf16 v[88:91], v[162:165], v[198:201], v[88:91]
	v_mfma_f32_16x16x32_bf16 v[76:79], v[154:157], v[206:209], v[76:79]
	v_mfma_f32_16x16x32_bf16 v[72:75], v[162:165], v[206:209], v[72:75]
	v_mfma_f32_16x16x32_bf16 v[116:119], v[210:213], v[166:169], 0
	v_mfma_f32_16x16x32_bf16 v[112:115], v[218:221], v[166:169], 0
	v_mfma_f32_16x16x32_bf16 v[100:103], v[210:213], v[182:185], 0
	v_mfma_f32_16x16x32_bf16 v[96:99], v[218:221], v[182:185], 0
	v_mfma_f32_16x16x32_bf16 v[84:87], v[210:213], v[194:197], 0
	v_mfma_f32_16x16x32_bf16 v[80:83], v[218:221], v[194:197], 0
	v_mfma_f32_16x16x32_bf16 v[68:71], v[210:213], v[202:205], 0
	v_mfma_f32_16x16x32_bf16 v[64:67], v[218:221], v[202:205], 0
	v_mfma_f32_16x16x32_bf16 v[116:119], v[214:217], v[170:173], v[116:119]
	v_mfma_f32_16x16x32_bf16 v[112:115], v[222:225], v[170:173], v[112:115]
	v_mfma_f32_16x16x32_bf16 v[100:103], v[214:217], v[190:193], v[100:103]
	v_mfma_f32_16x16x32_bf16 v[96:99], v[222:225], v[190:193], v[96:99]
	v_mfma_f32_16x16x32_bf16 v[84:87], v[214:217], v[198:201], v[84:87]
	v_mfma_f32_16x16x32_bf16 v[80:83], v[222:225], v[198:201], v[80:83]
	v_mfma_f32_16x16x32_bf16 v[68:71], v[214:217], v[206:209], v[68:71]
	v_mfma_f32_16x16x32_bf16 v[64:67], v[222:225], v[206:209], v[64:67]
	s_barrier
	ds_read_b128 v[166:169], v152 offset:16384
	ds_read_b128 v[170:173], v152 offset:17408
	ds_read_b128 v[182:185], v152 offset:18432
	ds_read_b128 v[190:193], v152 offset:19456
	ds_read_b128 v[194:197], v152 offset:20480
	ds_read_b128 v[198:201], v152 offset:21504
	ds_read_b128 v[202:205], v152 offset:22528
	ds_read_b128 v[206:209], v152 offset:23552
	s_add_i32 s47, s38, s26
	s_add_u32 s98, s18, s4
	s_addc_u32 s99, s19, s5
	s_mov_b32 m0, s47
	s_nop 0
	global_load_lds_dwordx4 v132, s[18:19]
	s_nop 1
	s_add_i32 m0, s47, 0x2000
	s_nop 0
	global_load_lds_dwordx4 v128, s[18:19]
	s_nop 1
	s_mov_b32 m0, s15
	s_add_u32 s100, s20, s4
	s_addc_u32 s101, s21, s5
	global_load_lds_dwordx4 v134, s[20:21]
	s_nop 1
	s_mov_b32 m0, s29
	s_nop 0
	global_load_lds_dwordx4 v130, s[20:21]
	s_add_u32 s48, s18, 0x40000
	s_addc_u32 s49, s19, 0
	s_add_i32 s47, s39, s26
	s_mov_b32 m0, s47
	s_nop 0
	global_load_lds_dwordx4 v132, s[48:49]
	s_nop 1
	s_add_i32 m0, s47, 0x2000
	s_nop 0
	global_load_lds_dwordx4 v128, s[48:49]
	s_waitcnt vmcnt(8) lgkmcnt(0)
	s_barrier
; #define PG8_STAGE(bufoff, gbase, voff) do { _Pragma("unroll") for (int _i = 0; _i < 2; ++_i) \
;         __builtin_amdgcn_global_load_lds((const unsigned*)((const char*)(gbase) + (voff)[_i]), (PG8_LAS unsigned*)(lds + (bufoff) + ldsw + _i * 8192), 16, 0, 0); } while (0)
; #define PG8_LDA(dst, b, h) do { _Pragma("unroll") for (int m = 0; m < 4; ++m) _Pragma("unroll") for (int k = 0; k < 2; ++k) dst[m][k] = *(const PG8_LAS bf16x8*)(lds + PG8_SA(b, h) + aoff + m * 2048 + k * 1024); } while (0)
; #define PG8_LDB(dst, b, h) do { _Pragma("unroll") for (int n = 0; n < 2; ++n) _Pragma("unroll") for (int k = 0; k < 2; ++k) dst[n][k] = *(const PG8_LAS bf16x8*)(lds + PG8_SB(b, h) + boff + n * 2048 + k * 1024); } while (0)
; #define PG8_MMA(ai, bj, At, Bt) do { __builtin_amdgcn_s_setprio(1); _Pragma("unroll") for (int m = 0; m < 4; ++m) _Pragma("unroll") for (int n = 0; n < 2; ++n) _Pragma("unroll") for (int k = 0; k < 2; ++k) \
;         acc[ai][bj][m][n] = __builtin_amdgcn_mfma_f32_16x16x32_bf16(Bt[n][k], At[m][k], acc[ai][bj][m][n], 0, 0, 0); __builtin_amdgcn_s_setprio(0); } while (0)
; #define PG8_WAIT_V(n) asm volatile("s_waitcnt vmcnt(" #n ")" ::: "memory")
; #define PG8_WAIT_L(n) asm volatile("s_waitcnt lgkmcnt(" #n ")" ::: "memory")
; #define PG8_BAR __builtin_amdgcn_s_barrier()
; #define PG8_SCHED __builtin_amdgcn_sched_barrier(0)
; template <class Epi, class Sched>
; __device__ __forceinline__ void gemm_phase(PG8_LAS unsigned char* lds, const Gemm g, const Sched& S, const Epi& E) {
;     ...
;             PG8_BAR; PG8_WAIT_L(0); PG8_MMA(1, 0, At, B0); PG8_BAR; PG8_SCHED;
;             PG8_STAGE(PG8_SB(0, 1), b2 + hstep, voffB);
;             PG8_WAIT_V(6); PG8_BAR; PG8_MMA(1, 1, At, B1); PG8_BAR;
;             PG8_LDB(B0, 1, 0); PG8_SCHED; PG8_LDA(At, 1, 0); PG8_STAGE(PG8_SA(0, 1), a2 + hstep, voffA);
;             PG8_WAIT_L(8); PG8_BAR; PG8_WAIT_L(0); PG8_MMA(0, 0, At, B0); PG8_BAR; PG8_SCHED;
;             PG8_LDB(B1, 1, 1); PG8_STAGE(PG8_SB(1, 0), b3, voffB);
;             PG8_BAR; PG8_WAIT_L(0); PG8_MMA(0, 1, At, B1); PG8_BAR;
;             PG8_LDA(At, 1, 1); PG8_STAGE(PG8_SA(1, 0), a3, voffA);
	v_mfma_f32_16x16x32_bf16 v[60:63], v[144:147], v[166:169], 0
	v_mfma_f32_16x16x32_bf16 v[56:59], v[158:161], v[166:169], 0
	v_mfma_f32_16x16x32_bf16 v[44:47], v[144:147], v[182:185], 0
	v_mfma_f32_16x16x32_bf16 v[40:43], v[158:161], v[182:185], 0
	v_mfma_f32_16x16x32_bf16 v[28:31], v[144:147], v[194:197], 0
	v_mfma_f32_16x16x32_bf16 v[24:27], v[158:161], v[194:197], 0
	v_mfma_f32_16x16x32_bf16 v[12:15], v[144:147], v[202:205], 0
	v_mfma_f32_16x16x32_bf16 v[8:11], v[158:161], v[202:205], 0
	v_mfma_f32_16x16x32_bf16 v[60:63], v[154:157], v[170:173], v[60:63]
	v_mfma_f32_16x16x32_bf16 v[56:59], v[162:165], v[170:173], v[56:59]
	v_mfma_f32_16x16x32_bf16 v[44:47], v[154:157], v[190:193], v[44:47]
	v_mfma_f32_16x16x32_bf16 v[40:43], v[162:165], v[190:193], v[40:43]
	v_mfma_f32_16x16x32_bf16 v[28:31], v[154:157], v[198:201], v[28:31]
	v_mfma_f32_16x16x32_bf16 v[24:27], v[162:165], v[198:201], v[24:27]
	v_mfma_f32_16x16x32_bf16 v[12:15], v[154:157], v[206:209], v[12:15]
	v_mfma_f32_16x16x32_bf16 v[8:11], v[162:165], v[206:209], v[8:11]
	v_mfma_f32_16x16x32_bf16 v[52:55], v[210:213], v[166:169], 0
	v_mfma_f32_16x16x32_bf16 v[48:51], v[218:221], v[166:169], 0
	v_mfma_f32_16x16x32_bf16 v[36:39], v[210:213], v[182:185], 0
	v_mfma_f32_16x16x32_bf16 v[32:35], v[218:221], v[182:185], 0
	v_mfma_f32_16x16x32_bf16 v[20:23], v[210:213], v[194:197], 0
	v_mfma_f32_16x16x32_bf16 v[16:19], v[218:221], v[194:197], 0
	v_mfma_f32_16x16x32_bf16 v[4:7], v[210:213], v[202:205], 0
	v_mfma_f32_16x16x32_bf16 v[0:3], v[218:221], v[202:205], 0
	v_mfma_f32_16x16x32_bf16 v[52:55], v[214:217], v[170:173], v[52:55]
	v_mfma_f32_16x16x32_bf16 v[48:51], v[222:225], v[170:173], v[48:51]
	v_mfma_f32_16x16x32_bf16 v[36:39], v[214:217], v[190:193], v[36:39]
	v_mfma_f32_16x16x32_bf16 v[32:35], v[222:225], v[190:193], v[32:35]
	v_mfma_f32_16x16x32_bf16 v[20:23], v[214:217], v[198:201], v[20:23]
	v_mfma_f32_16x16x32_bf16 v[16:19], v[222:225], v[198:201], v[16:19]
	v_mfma_f32_16x16x32_bf16 v[4:7], v[214:217], v[206:209], v[4:7]
	v_mfma_f32_16x16x32_bf16 v[0:3], v[222:225], v[206:209], v[0:3]
	s_barrier
	s_add_i32 s47, 0, 0x18000
	v_add_u32_e32 v162, s47, v149
	ds_read_b128 v[144:147], v162
	ds_read_b128 v[154:157], v162 offset:1024
	ds_read_b128 v[158:161], v162 offset:2048
	ds_read_b128 v[162:165], v162 offset:3072
	s_add_u32 s20, s20, 0x40000
	s_addc_u32 s21, s21, 0
	s_mov_b32 m0, s30
	ds_read_b128 v[166:169], v152 offset:32768
	ds_read_b128 v[170:173], v152 offset:33792
	ds_read_b128 v[182:185], v152 offset:34816
	ds_read_b128 v[190:193], v152 offset:35840
	ds_read_b128 v[194:197], v152 offset:36864
	ds_read_b128 v[198:201], v152 offset:37888
	ds_read_b128 v[202:205], v152 offset:38912
	ds_read_b128 v[206:209], v152 offset:39936
	global_load_lds_dwordx4 v134, s[20:21]
	s_nop 1
	s_mov_b32 m0, s31
	s_nop 0
	global_load_lds_dwordx4 v130, s[20:21]
	s_add_i32 s20, 0, 0x1c000
	v_add_u32_e32 v179, s20, v149
	s_waitcnt lgkmcnt(12)
	ds_read_b128 v[210:213], v179
	ds_read_b128 v[214:217], v179 offset:1024
	ds_read_b128 v[218:221], v179 offset:2048
	ds_read_b128 v[222:225], v179 offset:3072
	s_waitcnt vmcnt(8) lgkmcnt(0)
	s_barrier
	v_mfma_f32_16x16x32_bf16 v[124:127], v[144:147], v[166:169], v[124:127]
	v_mfma_f32_16x16x32_bf16 v[120:123], v[158:161], v[166:169], v[120:123]
	v_mfma_f32_16x16x32_bf16 v[108:111], v[144:147], v[182:185], v[108:111]
	v_mfma_f32_16x16x32_bf16 v[104:107], v[158:161], v[182:185], v[104:107]
	v_mfma_f32_16x16x32_bf16 v[92:95], v[144:147], v[194:197], v[92:95]
	v_mfma_f32_16x16x32_bf16 v[88:91], v[158:161], v[194:197], v[88:91]
	v_mfma_f32_16x16x32_bf16 v[76:79], v[144:147], v[202:205], v[76:79]
	v_mfma_f32_16x16x32_bf16 v[72:75], v[158:161], v[202:205], v[72:75]
	v_mfma_f32_16x16x32_bf16 v[124:127], v[154:157], v[170:173], v[124:127]
	v_mfma_f32_16x16x32_bf16 v[120:123], v[162:165], v[170:173], v[120:123]
	v_mfma_f32_16x16x32_bf16 v[108:111], v[154:157], v[190:193], v[108:111]
	v_mfma_f32_16x16x32_bf16 v[104:107], v[162:165], v[190:193], v[104:107]
	v_mfma_f32_16x16x32_bf16 v[92:95], v[154:157], v[198:201], v[92:95]
	v_mfma_f32_16x16x32_bf16 v[88:91], v[162:165], v[198:201], v[88:91]
	v_mfma_f32_16x16x32_bf16 v[76:79], v[154:157], v[206:209], v[76:79]
	v_mfma_f32_16x16x32_bf16 v[72:75], v[162:165], v[206:209], v[72:75]
	v_mfma_f32_16x16x32_bf16 v[116:119], v[210:213], v[166:169], v[116:119]
	v_mfma_f32_16x16x32_bf16 v[112:115], v[218:221], v[166:169], v[112:115]
	v_mfma_f32_16x16x32_bf16 v[100:103], v[210:213], v[182:185], v[100:103]
	v_mfma_f32_16x16x32_bf16 v[96:99], v[218:221], v[182:185], v[96:99]
	v_mfma_f32_16x16x32_bf16 v[84:87], v[210:213], v[194:197], v[84:87]
	v_mfma_f32_16x16x32_bf16 v[80:83], v[218:221], v[194:197], v[80:83]
	v_mfma_f32_16x16x32_bf16 v[68:71], v[210:213], v[202:205], v[68:71]
	v_mfma_f32_16x16x32_bf16 v[64:67], v[218:221], v[202:205], v[64:67]
	v_mfma_f32_16x16x32_bf16 v[116:119], v[214:217], v[170:173], v[116:119]
	v_mfma_f32_16x16x32_bf16 v[112:115], v[222:225], v[170:173], v[112:115]
	v_mfma_f32_16x16x32_bf16 v[100:103], v[214:217], v[190:193], v[100:103]
	v_mfma_f32_16x16x32_bf16 v[96:99], v[222:225], v[190:193], v[96:99]
	v_mfma_f32_16x16x32_bf16 v[84:87], v[214:217], v[198:201], v[84:87]
	v_mfma_f32_16x16x32_bf16 v[80:83], v[222:225], v[198:201], v[80:83]
	v_mfma_f32_16x16x32_bf16 v[68:71], v[214:217], v[206:209], v[68:71]
	v_mfma_f32_16x16x32_bf16 v[64:67], v[222:225], v[206:209], v[64:67]
	s_barrier
; #define PG8_STAGE(bufoff, gbase, voff) do { _Pragma("unroll") for (int _i = 0; _i < 2; ++_i) \
;         __builtin_amdgcn_global_load_lds((const unsigned*)((const char*)(gbase) + (voff)[_i]), (PG8_LAS unsigned*)(lds + (bufoff) + ldsw + _i * 8192), 16, 0, 0); } while (0)
; #define PG8_LDA(dst, b, h) do { _Pragma("unroll") for (int m = 0; m < 4; ++m) _Pragma("unroll") for (int k = 0; k < 2; ++k) dst[m][k] = *(const PG8_LAS bf16x8*)(lds + PG8_SA(b, h) + aoff + m * 2048 + k * 1024); } while (0)
; #define PG8_LDB(dst, b, h) do { _Pragma("unroll") for (int n = 0; n < 2; ++n) _Pragma("unroll") for (int k = 0; k < 2; ++k) dst[n][k] = *(const PG8_LAS bf16x8*)(lds + PG8_SB(b, h) + boff + n * 2048 + k * 1024); } while (0)
; #define PG8_MMA(ai, bj, At, Bt) do { __builtin_amdgcn_s_setprio(1); _Pragma("unroll") for (int m = 0; m < 4; ++m) _Pragma("unroll") for (int n = 0; n < 2; ++n) _Pragma("unroll") for (int k = 0; k < 2; ++k) \
;         acc[ai][bj][m][n] = __builtin_amdgcn_mfma_f32_16x16x32_bf16(Bt[n][k], At[m][k], acc[ai][bj][m][n], 0, 0, 0); __builtin_amdgcn_s_setprio(0); } while (0)
; #define PG8_WAIT_V(n) asm volatile("s_waitcnt vmcnt(" #n ")" ::: "memory")
; #define PG8_WAIT_L(n) asm volatile("s_waitcnt lgkmcnt(" #n ")" ::: "memory")
; #define PG8_BAR __builtin_amdgcn_s_barrier()
; #define PG8_SCHED __builtin_amdgcn_sched_barrier(0)
; template <class Epi, class Sched>
; __device__ __forceinline__ void gemm_phase(PG8_LAS unsigned char* lds, const Gemm g, const Sched& S, const Epi& E) {
;     ...
;             PG8_LDB(B0, 0, 0); PG8_SCHED; PG8_LDA(At, 0, 0); PG8_STAGE(PG8_SA(1, 1), a1 + hstep, voffA);
;             PG8_WAIT_L(8); PG8_BAR; PG8_WAIT_L(0); PG8_MMA(0, 0, At, B0); PG8_BAR; PG8_SCHED;
;     ...
;             PG8_LDB(B1, 1, 1); PG8_STAGE(PG8_SB(1, 0), b3, voffB);
;             PG8_BAR; PG8_WAIT_L(0); PG8_MMA(0, 1, At, B1); PG8_BAR;
;             PG8_LDA(At, 1, 1); PG8_STAGE(PG8_SA(1, 0), a3, voffA);
;             PG8_BAR; PG8_WAIT_L(0); PG8_MMA(1, 0, At, B0); PG8_BAR; PG8_SCHED;
;             PG8_STAGE(PG8_SB(1, 1), b3 + hstep, voffB);
;             PG8_WAIT_V(6); PG8_BAR; PG8_MMA(1, 1, At, B1); PG8_BAR;
	ds_read_b128 v[166:169], v152 offset:49152
	ds_read_b128 v[170:173], v152 offset:50176
	ds_read_b128 v[182:185], v152 offset:51200
	ds_read_b128 v[190:193], v152 offset:52224
	ds_read_b128 v[194:197], v152 offset:53248
	ds_read_b128 v[198:201], v152 offset:54272
	ds_read_b128 v[202:205], v152 offset:55296
	ds_read_b128 v[206:209], v152 offset:56320
	s_add_i32 s21, s47, s26
	s_mov_b32 m0, s21
	s_nop 0
	global_load_lds_dwordx4 v132, s[98:99]
	s_nop 1
	s_add_i32 m0, s21, 0x2000
	s_nop 0
	global_load_lds_dwordx4 v128, s[98:99]
	s_nop 1
	s_mov_b32 m0, s35
	s_nop 0
	global_load_lds_dwordx4 v134, s[100:101]
	s_nop 1
	s_mov_b32 m0, s36
	s_nop 0
	global_load_lds_dwordx4 v130, s[100:101]
	s_add_u32 s18, s18, 0x40080
	s_addc_u32 s19, s19, 0
	s_add_i32 s20, s20, s26
	s_mov_b32 m0, s20
	s_nop 0
	global_load_lds_dwordx4 v132, s[18:19]
	s_nop 1
	s_add_i32 m0, s20, 0x2000
	s_nop 0
	global_load_lds_dwordx4 v128, s[18:19]
	s_waitcnt vmcnt(8) lgkmcnt(0)
	s_barrier
	v_mfma_f32_16x16x32_bf16 v[60:63], v[144:147], v[166:169], v[60:63]
	v_mfma_f32_16x16x32_bf16 v[56:59], v[158:161], v[166:169], v[56:59]
	v_mfma_f32_16x16x32_bf16 v[44:47], v[144:147], v[182:185], v[44:47]
	v_mfma_f32_16x16x32_bf16 v[40:43], v[158:161], v[182:185], v[40:43]
	v_mfma_f32_16x16x32_bf16 v[28:31], v[144:147], v[194:197], v[28:31]
	v_mfma_f32_16x16x32_bf16 v[24:27], v[158:161], v[194:197], v[24:27]
	v_mfma_f32_16x16x32_bf16 v[12:15], v[144:147], v[202:205], v[12:15]
	v_mfma_f32_16x16x32_bf16 v[8:11], v[158:161], v[202:205], v[8:11]
	v_mfma_f32_16x16x32_bf16 v[60:63], v[154:157], v[170:173], v[60:63]
	v_mfma_f32_16x16x32_bf16 v[56:59], v[162:165], v[170:173], v[56:59]
	v_mfma_f32_16x16x32_bf16 v[44:47], v[154:157], v[190:193], v[44:47]
	v_mfma_f32_16x16x32_bf16 v[40:43], v[162:165], v[190:193], v[40:43]
	v_mfma_f32_16x16x32_bf16 v[28:31], v[154:157], v[198:201], v[28:31]
	v_mfma_f32_16x16x32_bf16 v[24:27], v[162:165], v[198:201], v[24:27]
	v_mfma_f32_16x16x32_bf16 v[12:15], v[154:157], v[206:209], v[12:15]
	v_mfma_f32_16x16x32_bf16 v[8:11], v[162:165], v[206:209], v[8:11]
	v_mfma_f32_16x16x32_bf16 v[52:55], v[210:213], v[166:169], v[52:55]
	v_mfma_f32_16x16x32_bf16 v[48:51], v[218:221], v[166:169], v[48:51]
	v_mfma_f32_16x16x32_bf16 v[36:39], v[210:213], v[182:185], v[36:39]
	v_mfma_f32_16x16x32_bf16 v[32:35], v[218:221], v[182:185], v[32:35]
	v_mfma_f32_16x16x32_bf16 v[20:23], v[210:213], v[194:197], v[20:23]
	v_mfma_f32_16x16x32_bf16 v[16:19], v[218:221], v[194:197], v[16:19]
	v_mfma_f32_16x16x32_bf16 v[4:7], v[210:213], v[202:205], v[4:7]
	v_mfma_f32_16x16x32_bf16 v[0:3], v[218:221], v[202:205], v[0:3]
	v_mfma_f32_16x16x32_bf16 v[52:55], v[214:217], v[170:173], v[52:55]
	v_mfma_f32_16x16x32_bf16 v[48:51], v[222:225], v[170:173], v[48:51]
	v_mfma_f32_16x16x32_bf16 v[36:39], v[214:217], v[190:193], v[36:39]
	v_mfma_f32_16x16x32_bf16 v[32:35], v[222:225], v[190:193], v[32:35]
	v_mfma_f32_16x16x32_bf16 v[20:23], v[214:217], v[198:201], v[20:23]
	v_mfma_f32_16x16x32_bf16 v[16:19], v[222:225], v[198:201], v[16:19]
	v_mfma_f32_16x16x32_bf16 v[4:7], v[214:217], v[206:209], v[4:7]
	v_mfma_f32_16x16x32_bf16 v[0:3], v[222:225], v[206:209], v[0:3]
	s_barrier
	s_add_i32 s46, s46, 2
	s_add_u32 s16, s16, 0x100
	s_addc_u32 s17, s17, 0
	s_add_u32 s44, s44, 0x100
	s_addc_u32 s45, s45, 0
	s_cmp_gt_u32 s46, 13
.LBB0_1202:
	ds_read_b128 v[144:147], v151
	ds_read_b128 v[154:157], v151 offset:1024
	ds_read_b128 v[158:161], v151 offset:2048
	ds_read_b128 v[162:165], v151 offset:3072
	s_add_u32 s18, s16, 0xfffc0080
	s_addc_u32 s19, s17, -1
	s_cmp_eq_u32 s46, 12
	s_cselect_b32 s21, s9, s19
	s_cselect_b32 s20, s42, s18
	s_cselect_b32 s19, s7, s45
	s_cselect_b32 s18, s43, s44
	s_add_i32 m0, s15, 0xc000
	ds_read_b128 v[166:169], v152
	ds_read_b128 v[170:173], v152 offset:1024
	ds_read_b128 v[182:185], v152 offset:2048
	ds_read_b128 v[190:193], v152 offset:3072
	ds_read_b128 v[194:197], v152 offset:4096
	ds_read_b128 v[198:201], v152 offset:5120
	ds_read_b128 v[202:205], v152 offset:6144
	ds_read_b128 v[206:209], v152 offset:7168
	global_load_lds_dwordx4 v136, s[16:17]
	s_nop 1
	s_add_i32 m0, s15, 0xe000
	s_nop 0
	global_load_lds_dwordx4 v138, s[16:17]
	s_waitcnt lgkmcnt(12)
	ds_read_b128 v[210:213], v153
	ds_read_b128 v[214:217], v153 offset:1024
	ds_read_b128 v[218:221], v153 offset:2048
	ds_read_b128 v[222:225], v153 offset:3072
	s_waitcnt vmcnt(8) lgkmcnt(0)
	s_barrier
	v_mfma_f32_16x16x32_bf16 v[124:127], v[144:147], v[166:169], v[124:127]
	v_mfma_f32_16x16x32_bf16 v[120:123], v[158:161], v[166:169], v[120:123]
	v_mfma_f32_16x16x32_bf16 v[108:111], v[144:147], v[182:185], v[108:111]
	v_mfma_f32_16x16x32_bf16 v[104:107], v[158:161], v[182:185], v[104:107]
	v_mfma_f32_16x16x32_bf16 v[92:95], v[144:147], v[194:197], v[92:95]
	v_mfma_f32_16x16x32_bf16 v[88:91], v[158:161], v[194:197], v[88:91]
	v_mfma_f32_16x16x32_bf16 v[76:79], v[144:147], v[202:205], v[76:79]
	v_mfma_f32_16x16x32_bf16 v[72:75], v[158:161], v[202:205], v[72:75]
	v_mfma_f32_16x16x32_bf16 v[124:127], v[154:157], v[170:173], v[124:127]
	v_mfma_f32_16x16x32_bf16 v[120:123], v[162:165], v[170:173], v[120:123]
	v_mfma_f32_16x16x32_bf16 v[108:111], v[154:157], v[190:193], v[108:111]
	v_mfma_f32_16x16x32_bf16 v[104:107], v[162:165], v[190:193], v[104:107]
	v_mfma_f32_16x16x32_bf16 v[92:95], v[154:157], v[198:201], v[92:95]
	v_mfma_f32_16x16x32_bf16 v[88:91], v[162:165], v[198:201], v[88:91]
	v_mfma_f32_16x16x32_bf16 v[76:79], v[154:157], v[206:209], v[76:79]
	v_mfma_f32_16x16x32_bf16 v[72:75], v[162:165], v[206:209], v[72:75]
	v_mfma_f32_16x16x32_bf16 v[116:119], v[210:213], v[166:169], v[116:119]
	v_mfma_f32_16x16x32_bf16 v[112:115], v[218:221], v[166:169], v[112:115]
	v_mfma_f32_16x16x32_bf16 v[100:103], v[210:213], v[182:185], v[100:103]
	v_mfma_f32_16x16x32_bf16 v[96:99], v[218:221], v[182:185], v[96:99]
	v_mfma_f32_16x16x32_bf16 v[84:87], v[210:213], v[194:197], v[84:87]
	v_mfma_f32_16x16x32_bf16 v[80:83], v[218:221], v[194:197], v[80:83]
	v_mfma_f32_16x16x32_bf16 v[68:71], v[210:213], v[202:205], v[68:71]
	v_mfma_f32_16x16x32_bf16 v[64:67], v[218:221], v[202:205], v[64:67]
	v_mfma_f32_16x16x32_bf16 v[116:119], v[214:217], v[170:173], v[116:119]
	v_mfma_f32_16x16x32_bf16 v[112:115], v[222:225], v[170:173], v[112:115]
	v_mfma_f32_16x16x32_bf16 v[100:103], v[214:217], v[190:193], v[100:103]
	v_mfma_f32_16x16x32_bf16 v[96:99], v[222:225], v[190:193], v[96:99]
	v_mfma_f32_16x16x32_bf16 v[84:87], v[214:217], v[198:201], v[84:87]
	v_mfma_f32_16x16x32_bf16 v[80:83], v[222:225], v[198:201], v[80:83]
	v_mfma_f32_16x16x32_bf16 v[68:71], v[214:217], v[206:209], v[68:71]
	v_mfma_f32_16x16x32_bf16 v[64:67], v[222:225], v[206:209], v[64:67]
	s_barrier
; #define PG8_STAGE(bufoff, gbase, voff) do { _Pragma("unroll") for (int _i = 0; _i < 2; ++_i) \
;         __builtin_amdgcn_global_load_lds((const unsigned*)((const char*)(gbase) + (voff)[_i]), (PG8_LAS unsigned*)(lds + (bufoff) + ldsw + _i * 8192), 16, 0, 0); } while (0)
; #define PG8_LDA(dst, b, h) do { _Pragma("unroll") for (int m = 0; m < 4; ++m) _Pragma("unroll") for (int k = 0; k < 2; ++k) dst[m][k] = *(const PG8_LAS bf16x8*)(lds + PG8_SA(b, h) + aoff + m * 2048 + k * 1024); } while (0)
; #define PG8_LDB(dst, b, h) do { _Pragma("unroll") for (int n = 0; n < 2; ++n) _Pragma("unroll") for (int k = 0; k < 2; ++k) dst[n][k] = *(const PG8_LAS bf16x8*)(lds + PG8_SB(b, h) + boff + n * 2048 + k * 1024); } while (0)
; #define PG8_MMA(ai, bj, At, Bt) do { __builtin_amdgcn_s_setprio(1); _Pragma("unroll") for (int m = 0; m < 4; ++m) _Pragma("unroll") for (int n = 0; n < 2; ++n) _Pragma("unroll") for (int k = 0; k < 2; ++k) \
;         acc[ai][bj][m][n] = __builtin_amdgcn_mfma_f32_16x16x32_bf16(Bt[n][k], At[m][k], acc[ai][bj][m][n], 0, 0, 0); __builtin_amdgcn_s_setprio(0); } while (0)
; #define PG8_WAIT_V(n) asm volatile("s_waitcnt vmcnt(" #n ")" ::: "memory")
; #define PG8_WAIT_L(n) asm volatile("s_waitcnt lgkmcnt(" #n ")" ::: "memory")
; #define PG8_BAR __builtin_amdgcn_s_barrier()
; #define PG8_SCHED __builtin_amdgcn_sched_barrier(0)
; template <class Epi, class Sched>
; __device__ __forceinline__ void gemm_phase(PG8_LAS unsigned char* lds, const Gemm g, const Sched& S, const Epi& E) {
;     ...
;             PG8_LDB(B1, 0, 1); PG8_STAGE(PG8_SB(0, 0), b2, voffB);
;             PG8_BAR; PG8_WAIT_L(0); PG8_MMA(0, 1, At, B1); PG8_BAR;
;             PG8_LDA(At, 0, 1); PG8_STAGE(PG8_SA(0, 0), a2, voffA);
;             PG8_BAR; PG8_WAIT_L(0); PG8_MMA(1, 0, At, B0); PG8_BAR; PG8_SCHED;
;             PG8_STAGE(PG8_SB(0, 1), b2 + hstep, voffB);
;             PG8_WAIT_V(6); PG8_BAR; PG8_MMA(1, 1, At, B1); PG8_BAR;
;             PG8_LDB(B0, 1, 0); PG8_SCHED; PG8_LDA(At, 1, 0); PG8_STAGE(PG8_SA(0, 1), a2 + hstep, voffA);
;             PG8_WAIT_L(8); PG8_BAR; PG8_WAIT_L(0); PG8_MMA(0, 0, At, B0); PG8_BAR; PG8_SCHED;
	ds_read_b128 v[166:169], v152 offset:16384
	ds_read_b128 v[170:173], v152 offset:17408
	ds_read_b128 v[182:185], v152 offset:18432
	ds_read_b128 v[190:193], v152 offset:19456
	ds_read_b128 v[194:197], v152 offset:20480
	ds_read_b128 v[198:201], v152 offset:21504
	ds_read_b128 v[202:205], v152 offset:22528
	ds_read_b128 v[206:209], v152 offset:23552
	s_add_i32 s47, s38, s26
	s_add_u32 s98, s18, s4
	s_addc_u32 s99, s19, s5
	s_mov_b32 m0, s47
	s_nop 0
	global_load_lds_dwordx4 v132, s[18:19]
	s_nop 1
	s_add_i32 m0, s47, 0x2000
	s_nop 0
	global_load_lds_dwordx4 v128, s[18:19]
	s_nop 1
	s_mov_b32 m0, s15
	s_add_u32 s100, s20, s4
	s_addc_u32 s101, s21, s5
	global_load_lds_dwordx4 v134, s[20:21]
	s_nop 1
	s_mov_b32 m0, s29
	s_nop 0
	global_load_lds_dwordx4 v130, s[20:21]
	s_add_u32 s48, s18, 0x40000
	s_addc_u32 s49, s19, 0
	s_add_i32 s47, s39, s26
	s_mov_b32 m0, s47
	s_nop 0
	global_load_lds_dwordx4 v132, s[48:49]
	s_nop 1
	s_add_i32 m0, s47, 0x2000
	s_nop 0
	global_load_lds_dwordx4 v128, s[48:49]
	s_waitcnt vmcnt(8) lgkmcnt(0)
	s_barrier
	v_mfma_f32_16x16x32_bf16 v[60:63], v[144:147], v[166:169], v[60:63]
	v_mfma_f32_16x16x32_bf16 v[56:59], v[158:161], v[166:169], v[56:59]
	v_mfma_f32_16x16x32_bf16 v[44:47], v[144:147], v[182:185], v[44:47]
	v_mfma_f32_16x16x32_bf16 v[40:43], v[158:161], v[182:185], v[40:43]
	v_mfma_f32_16x16x32_bf16 v[28:31], v[144:147], v[194:197], v[28:31]
	v_mfma_f32_16x16x32_bf16 v[24:27], v[158:161], v[194:197], v[24:27]
	v_mfma_f32_16x16x32_bf16 v[12:15], v[144:147], v[202:205], v[12:15]
	v_mfma_f32_16x16x32_bf16 v[8:11], v[158:161], v[202:205], v[8:11]
	v_mfma_f32_16x16x32_bf16 v[60:63], v[154:157], v[170:173], v[60:63]
	v_mfma_f32_16x16x32_bf16 v[56:59], v[162:165], v[170:173], v[56:59]
	v_mfma_f32_16x16x32_bf16 v[44:47], v[154:157], v[190:193], v[44:47]
	v_mfma_f32_16x16x32_bf16 v[40:43], v[162:165], v[190:193], v[40:43]
	v_mfma_f32_16x16x32_bf16 v[28:31], v[154:157], v[198:201], v[28:31]
	v_mfma_f32_16x16x32_bf16 v[24:27], v[162:165], v[198:201], v[24:27]
	v_mfma_f32_16x16x32_bf16 v[12:15], v[154:157], v[206:209], v[12:15]
	v_mfma_f32_16x16x32_bf16 v[8:11], v[162:165], v[206:209], v[8:11]
	v_mfma_f32_16x16x32_bf16 v[52:55], v[210:213], v[166:169], v[52:55]
	v_mfma_f32_16x16x32_bf16 v[48:51], v[218:221], v[166:169], v[48:51]
	v_mfma_f32_16x16x32_bf16 v[36:39], v[210:213], v[182:185], v[36:39]
	v_mfma_f32_16x16x32_bf16 v[32:35], v[218:221], v[182:185], v[32:35]
	v_mfma_f32_16x16x32_bf16 v[20:23], v[210:213], v[194:197], v[20:23]
	v_mfma_f32_16x16x32_bf16 v[16:19], v[218:221], v[194:197], v[16:19]
	v_mfma_f32_16x16x32_bf16 v[4:7], v[210:213], v[202:205], v[4:7]
	v_mfma_f32_16x16x32_bf16 v[0:3], v[218:221], v[202:205], v[0:3]
	v_mfma_f32_16x16x32_bf16 v[52:55], v[214:217], v[170:173], v[52:55]
	v_mfma_f32_16x16x32_bf16 v[48:51], v[222:225], v[170:173], v[48:51]
	v_mfma_f32_16x16x32_bf16 v[36:39], v[214:217], v[190:193], v[36:39]
	v_mfma_f32_16x16x32_bf16 v[32:35], v[222:225], v[190:193], v[32:35]
	v_mfma_f32_16x16x32_bf16 v[20:23], v[214:217], v[198:201], v[20:23]
	v_mfma_f32_16x16x32_bf16 v[16:19], v[222:225], v[198:201], v[16:19]
	v_mfma_f32_16x16x32_bf16 v[4:7], v[214:217], v[206:209], v[4:7]
	v_mfma_f32_16x16x32_bf16 v[0:3], v[222:225], v[206:209], v[0:3]
	s_barrier
	s_add_i32 s47, 0, 0x18000
	v_add_u32_e32 v162, s47, v149
	ds_read_b128 v[144:147], v162
	ds_read_b128 v[154:157], v162 offset:1024
	ds_read_b128 v[158:161], v162 offset:2048
	ds_read_b128 v[162:165], v162 offset:3072
	s_add_u32 s20, s20, 0x40000
	s_addc_u32 s21, s21, 0
	s_mov_b32 m0, s30
	ds_read_b128 v[166:169], v152 offset:32768
	ds_read_b128 v[170:173], v152 offset:33792
	ds_read_b128 v[182:185], v152 offset:34816
	ds_read_b128 v[190:193], v152 offset:35840
	ds_read_b128 v[194:197], v152 offset:36864
	ds_read_b128 v[198:201], v152 offset:37888
	ds_read_b128 v[202:205], v152 offset:38912
	ds_read_b128 v[206:209], v152 offset:39936
	global_load_lds_dwordx4 v134, s[20:21]
	s_nop 1
	s_mov_b32 m0, s31
	s_nop 0
	global_load_lds_dwordx4 v130, s[20:21]
	s_add_i32 s20, 0, 0x1c000
	v_add_u32_e32 v179, s20, v149
	s_waitcnt lgkmcnt(12)
	ds_read_b128 v[210:213], v179
	ds_read_b128 v[214:217], v179 offset:1024
	ds_read_b128 v[218:221], v179 offset:2048
	ds_read_b128 v[222:225], v179 offset:3072
	s_waitcnt vmcnt(8) lgkmcnt(0)
	s_barrier
	v_mfma_f32_16x16x32_bf16 v[124:127], v[144:147], v[166:169], v[124:127]
	v_mfma_f32_16x16x32_bf16 v[120:123], v[158:161], v[166:169], v[120:123]
	v_mfma_f32_16x16x32_bf16 v[108:111], v[144:147], v[182:185], v[108:111]
	v_mfma_f32_16x16x32_bf16 v[104:107], v[158:161], v[182:185], v[104:107]
	v_mfma_f32_16x16x32_bf16 v[92:95], v[144:147], v[194:197], v[92:95]
	v_mfma_f32_16x16x32_bf16 v[88:91], v[158:161], v[194:197], v[88:91]
	v_mfma_f32_16x16x32_bf16 v[76:79], v[144:147], v[202:205], v[76:79]
	v_mfma_f32_16x16x32_bf16 v[72:75], v[158:161], v[202:205], v[72:75]
	v_mfma_f32_16x16x32_bf16 v[124:127], v[154:157], v[170:173], v[124:127]
	v_mfma_f32_16x16x32_bf16 v[120:123], v[162:165], v[170:173], v[120:123]
	v_mfma_f32_16x16x32_bf16 v[108:111], v[154:157], v[190:193], v[108:111]
	v_mfma_f32_16x16x32_bf16 v[104:107], v[162:165], v[190:193], v[104:107]
	v_mfma_f32_16x16x32_bf16 v[92:95], v[154:157], v[198:201], v[92:95]
	v_mfma_f32_16x16x32_bf16 v[88:91], v[162:165], v[198:201], v[88:91]
	v_mfma_f32_16x16x32_bf16 v[76:79], v[154:157], v[206:209], v[76:79]
	v_mfma_f32_16x16x32_bf16 v[72:75], v[162:165], v[206:209], v[72:75]
	v_mfma_f32_16x16x32_bf16 v[116:119], v[210:213], v[166:169], v[116:119]
	v_mfma_f32_16x16x32_bf16 v[112:115], v[218:221], v[166:169], v[112:115]
	v_mfma_f32_16x16x32_bf16 v[100:103], v[210:213], v[182:185], v[100:103]
	v_mfma_f32_16x16x32_bf16 v[96:99], v[218:221], v[182:185], v[96:99]
	v_mfma_f32_16x16x32_bf16 v[84:87], v[210:213], v[194:197], v[84:87]
	v_mfma_f32_16x16x32_bf16 v[80:83], v[218:221], v[194:197], v[80:83]
	v_mfma_f32_16x16x32_bf16 v[68:71], v[210:213], v[202:205], v[68:71]
	v_mfma_f32_16x16x32_bf16 v[64:67], v[218:221], v[202:205], v[64:67]
	v_mfma_f32_16x16x32_bf16 v[116:119], v[214:217], v[170:173], v[116:119]
	v_mfma_f32_16x16x32_bf16 v[112:115], v[222:225], v[170:173], v[112:115]
	v_mfma_f32_16x16x32_bf16 v[100:103], v[214:217], v[190:193], v[100:103]
	v_mfma_f32_16x16x32_bf16 v[96:99], v[222:225], v[190:193], v[96:99]
	v_mfma_f32_16x16x32_bf16 v[84:87], v[214:217], v[198:201], v[84:87]
	v_mfma_f32_16x16x32_bf16 v[80:83], v[222:225], v[198:201], v[80:83]
	v_mfma_f32_16x16x32_bf16 v[68:71], v[214:217], v[206:209], v[68:71]
	v_mfma_f32_16x16x32_bf16 v[64:67], v[222:225], v[206:209], v[64:67]
	s_barrier
; __device__ __forceinline__ unsigned cvt_pk_bf16(float lo, float hi) { unsigned r; asm volatile("v_cvt_pk_bf16_f32 %0, %1, %2" : "=v"(r) : "v"(lo), "v"(hi)); return r; }
; #define PG8_STAGE(bufoff, gbase, voff) do { _Pragma("unroll") for (int _i = 0; _i < 2; ++_i) \
;         __builtin_amdgcn_global_load_lds((const unsigned*)((const char*)(gbase) + (voff)[_i]), (PG8_LAS unsigned*)(lds + (bufoff) + ldsw + _i * 8192), 16, 0, 0); } while (0)
; #define PG8_LDA(dst, b, h) do { _Pragma("unroll") for (int m = 0; m < 4; ++m) _Pragma("unroll") for (int k = 0; k < 2; ++k) dst[m][k] = *(const PG8_LAS bf16x8*)(lds + PG8_SA(b, h) + aoff + m * 2048 + k * 1024); } while (0)
; #define PG8_MMA(ai, bj, At, Bt) do { __builtin_amdgcn_s_setprio(1); _Pragma("unroll") for (int m = 0; m < 4; ++m) _Pragma("unroll") for (int n = 0; n < 2; ++n) _Pragma("unroll") for (int k = 0; k < 2; ++k) \
;         acc[ai][bj][m][n] = __builtin_amdgcn_mfma_f32_16x16x32_bf16(Bt[n][k], At[m][k], acc[ai][bj][m][n], 0, 0, 0); __builtin_amdgcn_s_setprio(0); } while (0)
; #define PG8_BAR __builtin_amdgcn_s_barrier()
;     __device__ __forceinline__ void operator()(const f32x4 (&acc)[2][2][4][2], const Unit& u, int wr, int wc, int fr, int fq) const {
;         const int row0 = u.pm * BM + wr * 64 + fr, col0 = u.pn * HALF + wc * 32 + 8 * fq;
; #pragma unroll
;         for (int ai = 0; ai < 2; ++ai)
; #pragma unroll
;             for (int m = 0; m < 4; ++m) { bf16_t* rowp = O + (size_t)(row0 + ai * HALF + m * 16) * ldc + col0;
;                 f32x4 v0, v1;
; #pragma unroll
;                 for (int j = 0; j < 1; ++j) { v0 = acc[ai][0][m][0] * sigmoid4(acc[ai][0][m][0]) * acc[ai][1][m][0]; v1 = acc[ai][0][m][1] * sigmoid4(acc[ai][0][m][1]) * acc[ai][1][m][1]; }
;                 u32x4 w; w.x = cvt_pk_bf16(v0[0], v0[1]); w.y = cvt_pk_bf16(v0[2], v0[3]); w.z = cvt_pk_bf16(v1[0], v1[1]); w.w = cvt_pk_bf16(v1[2], v1[3]);
;                 *(u32x4*)rowp = w; }
; template <class Epi, class Sched>
; __device__ __forceinline__ void gemm_phase(PG8_LAS unsigned char* lds, const Gemm g, const Sched& S, const Epi& E) {
;     ...
;             PG8_LDA(At, 1, 1); PG8_STAGE(PG8_SA(1, 0), a3, voffA);
;             PG8_BAR; PG8_WAIT_L(0); PG8_MMA(1, 0, At, B0); PG8_BAR; PG8_SCHED;
;             PG8_STAGE(PG8_SB(1, 1), b3 + hstep, voffB);
;             PG8_WAIT_V(6); PG8_BAR; PG8_MMA(1, 1, At, B1); PG8_BAR;
	ds_read_b128 v[166:169], v152 offset:49152
	ds_read_b128 v[170:173], v152 offset:50176
	ds_read_b128 v[182:185], v152 offset:51200
	ds_read_b128 v[190:193], v152 offset:52224
	ds_read_b128 v[194:197], v152 offset:53248
	ds_read_b128 v[198:201], v152 offset:54272
	ds_read_b128 v[202:205], v152 offset:55296
	ds_read_b128 v[206:209], v152 offset:56320
	s_add_i32 s21, s47, s26
	s_mov_b32 m0, s21
	s_nop 0
	global_load_lds_dwordx4 v132, s[98:99]
	s_nop 1
	s_add_i32 m0, s21, 0x2000
	s_nop 0
	global_load_lds_dwordx4 v128, s[98:99]
	s_nop 1
	s_mov_b32 m0, s35
	s_nop 0
	global_load_lds_dwordx4 v134, s[100:101]
	s_nop 1
	s_mov_b32 m0, s36
	s_nop 0
	global_load_lds_dwordx4 v130, s[100:101]
	s_add_u32 s18, s18, 0x40080
	s_addc_u32 s19, s19, 0
	s_add_i32 s20, s20, s26
	s_mov_b32 m0, s20
	s_nop 0
	global_load_lds_dwordx4 v132, s[18:19]
	s_nop 1
	s_add_i32 m0, s20, 0x2000
	s_nop 0
	global_load_lds_dwordx4 v128, s[18:19]
	s_waitcnt vmcnt(8) lgkmcnt(0)
	s_barrier
	v_mfma_f32_16x16x32_bf16 v[60:63], v[144:147], v[166:169], v[60:63]
	v_mfma_f32_16x16x32_bf16 v[56:59], v[158:161], v[166:169], v[56:59]
	v_mfma_f32_16x16x32_bf16 v[44:47], v[144:147], v[182:185], v[44:47]
	v_mfma_f32_16x16x32_bf16 v[40:43], v[158:161], v[182:185], v[40:43]
	v_mfma_f32_16x16x32_bf16 v[28:31], v[144:147], v[194:197], v[28:31]
	v_mfma_f32_16x16x32_bf16 v[24:27], v[158:161], v[194:197], v[24:27]
	v_mfma_f32_16x16x32_bf16 v[12:15], v[144:147], v[202:205], v[12:15]
	v_mfma_f32_16x16x32_bf16 v[8:11], v[158:161], v[202:205], v[8:11]
	v_mfma_f32_16x16x32_bf16 v[60:63], v[154:157], v[170:173], v[60:63]
	v_mfma_f32_16x16x32_bf16 v[56:59], v[162:165], v[170:173], v[56:59]
	v_mfma_f32_16x16x32_bf16 v[44:47], v[154:157], v[190:193], v[44:47]
	v_mfma_f32_16x16x32_bf16 v[40:43], v[162:165], v[190:193], v[40:43]
	v_mfma_f32_16x16x32_bf16 v[28:31], v[154:157], v[198:201], v[28:31]
	v_mfma_f32_16x16x32_bf16 v[24:27], v[162:165], v[198:201], v[24:27]
	v_mfma_f32_16x16x32_bf16 v[12:15], v[154:157], v[206:209], v[12:15]
	v_mfma_f32_16x16x32_bf16 v[8:11], v[162:165], v[206:209], v[8:11]
	v_mfma_f32_16x16x32_bf16 v[52:55], v[210:213], v[166:169], v[52:55]
	v_mfma_f32_16x16x32_bf16 v[48:51], v[218:221], v[166:169], v[48:51]
	v_mfma_f32_16x16x32_bf16 v[36:39], v[210:213], v[182:185], v[36:39]
	v_mfma_f32_16x16x32_bf16 v[32:35], v[218:221], v[182:185], v[32:35]
	v_mfma_f32_16x16x32_bf16 v[20:23], v[210:213], v[194:197], v[20:23]
	v_mfma_f32_16x16x32_bf16 v[16:19], v[218:221], v[194:197], v[16:19]
	v_mfma_f32_16x16x32_bf16 v[4:7], v[210:213], v[202:205], v[4:7]
	v_mfma_f32_16x16x32_bf16 v[0:3], v[218:221], v[202:205], v[0:3]
	v_mfma_f32_16x16x32_bf16 v[52:55], v[214:217], v[170:173], v[52:55]
	v_mfma_f32_16x16x32_bf16 v[48:51], v[222:225], v[170:173], v[48:51]
	v_mfma_f32_16x16x32_bf16 v[36:39], v[214:217], v[190:193], v[36:39]
	v_mfma_f32_16x16x32_bf16 v[32:35], v[222:225], v[190:193], v[32:35]
	v_mfma_f32_16x16x32_bf16 v[20:23], v[214:217], v[198:201], v[20:23]
	v_mfma_f32_16x16x32_bf16 v[16:19], v[222:225], v[198:201], v[16:19]
	v_mfma_f32_16x16x32_bf16 v[4:7], v[214:217], v[206:209], v[4:7]
	v_mfma_f32_16x16x32_bf16 v[0:3], v[222:225], v[206:209], v[0:3]
	s_barrier
	s_add_i32 s46, s46, 2
	s_add_u32 s16, s16, 0x100
	s_addc_u32 s17, s17, 0
	s_add_u32 s44, s44, 0x100
	s_addc_u32 s45, s45, 0
	s_cmp_gt_u32 s46, 13
	s_cbranch_scc0 .LBB0_1202
	v_max_f32_e32 v144, 0xc1a00000, v124
	v_mul_f32_e32 v144, 0xbfb8aa3b, v144
	v_exp_f32_e32 v157, v144
	v_max_f32_e32 v144, 0xc1a00000, v125
	v_mul_f32_e32 v144, 0xbfb8aa3b, v144
	v_exp_f32_e32 v156, v144
	v_max_f32_e32 v144, 0xc1a00000, v126
	v_mul_f32_e32 v144, 0xbfb8aa3b, v144
	v_exp_f32_e32 v159, v144
	v_max_f32_e32 v144, 0xc1a00000, v127
	v_mul_f32_e32 v144, 0xbfb8aa3b, v144
	v_exp_f32_e32 v158, v144
	v_pk_add_f32 v[156:157], v[156:157], 1.0 op_sel_hi:[1,0]
	v_lshl_or_b32 v146, s41, 7, v150
	v_pk_add_f32 v[158:159], v[158:159], 1.0 op_sel_hi:[1,0]
	v_mul_f32_e32 v160, v157, v156
	v_mul_f32_e32 v161, v159, v158
	v_lshl_add_u32 v154, s14, 8, v148
	v_mul_f32_e32 v155, v160, v161
	v_rcp_f32_e32 v155, v155
	v_ashrrev_i32_e32 v147, 31, v146
	v_mov_b64_e32 v[144:145], s[0:1]
	v_mad_i64_i32 v[162:163], s[16:17], v154, s40, v[144:145]
	v_mul_f32_e32 v164, v161, v155
	v_mul_f32_e32 v160, v160, v155
	v_max_f32_e32 v155, 0xc1a00000, v120
	v_mul_f32_e32 v155, 0xbfb8aa3b, v155
	v_pk_mul_f32 v[158:159], v[158:159], v[160:161] op_sel_hi:[1,0]
	v_exp_f32_e32 v161, v155
	v_max_f32_e32 v155, 0xc1a00000, v121
	v_mul_f32_e32 v155, 0xbfb8aa3b, v155
	v_exp_f32_e32 v160, v155
	v_max_f32_e32 v155, 0xc1a00000, v122
	v_mul_f32_e32 v155, 0xbfb8aa3b, v155
	v_exp_f32_e32 v167, v155
	v_max_f32_e32 v155, 0xc1a00000, v123
	v_mul_f32_e32 v155, 0xbfb8aa3b, v155
	v_exp_f32_e32 v166, v155
	v_pk_mul_f32 v[156:157], v[156:157], v[164:165] op_sel_hi:[1,0]
	v_pk_mul_f32 v[126:127], v[126:127], v[158:159]
	v_pk_mul_f32 v[124:125], v[124:125], v[156:157]
	v_pk_add_f32 v[156:157], v[160:161], 1.0 op_sel_hi:[1,0]
	v_pk_add_f32 v[160:161], v[166:167], 1.0 op_sel_hi:[1,0]
	v_mul_f32_e32 v164, v157, v156
	v_mul_f32_e32 v165, v161, v160
	v_pk_mul_f32 v[118:119], v[126:127], v[118:119]
	v_mul_f32_e32 v155, v164, v165
	v_rcp_f32_e32 v155, v155
	v_pk_mul_f32 v[116:117], v[124:125], v[116:117]
	v_lshlrev_b64 v[146:147], 1, v[146:147]
	v_lshl_add_u64 v[162:163], v[162:163], 0, v[146:147]
	v_mul_f32_e32 v124, v165, v155
	v_mul_f32_e32 v126, v164, v155
	v_pk_mul_f32 v[126:127], v[160:161], v[126:127] op_sel_hi:[1,0]
	v_pk_mul_f32 v[124:125], v[156:157], v[124:125] op_sel_hi:[1,0]
	v_pk_mul_f32 v[122:123], v[122:123], v[126:127]
	v_pk_mul_f32 v[120:121], v[120:121], v[124:125]
	v_pk_mul_f32 v[122:123], v[122:123], v[114:115]
; __device__ __forceinline__ unsigned cvt_pk_bf16(float lo, float hi) { unsigned r; asm volatile("v_cvt_pk_bf16_f32 %0, %1, %2" : "=v"(r) : "v"(lo), "v"(hi)); return r; }
;     __device__ __forceinline__ void operator()(const f32x4 (&acc)[2][2][4][2], const Unit& u, int wr, int wc, int fr, int fq) const {
;         const int row0 = u.pm * BM + wr * 64 + fr, col0 = u.pn * HALF + wc * 32 + 8 * fq;
; #pragma unroll
;         for (int ai = 0; ai < 2; ++ai)
; #pragma unroll
;             for (int m = 0; m < 4; ++m) { bf16_t* rowp = O + (size_t)(row0 + ai * HALF + m * 16) * ldc + col0;
;                 f32x4 v0, v1;
; #pragma unroll
;                 for (int j = 0; j < 1; ++j) { v0 = acc[ai][0][m][0] * sigmoid4(acc[ai][0][m][0]) * acc[ai][1][m][0]; v1 = acc[ai][0][m][1] * sigmoid4(acc[ai][0][m][1]) * acc[ai][1][m][1]; }
;                 u32x4 w; w.x = cvt_pk_bf16(v0[0], v0[1]); w.y = cvt_pk_bf16(v0[2], v0[3]); w.z = cvt_pk_bf16(v1[0], v1[1]); w.w = cvt_pk_bf16(v1[2], v1[3]);
;                 *(u32x4*)rowp = w; }
	v_pk_mul_f32 v[114:115], v[120:121], v[112:113]
	v_cvt_pk_bf16_f32 v112, v116, v117
	v_cvt_pk_bf16_f32 v113, v118, v119
	v_max_f32_e32 v116, 0xc1a00000, v108
	v_max_f32_e32 v118, 0xc1a00000, v110
	v_mul_f32_e32 v116, 0xbfb8aa3b, v116
	v_mul_f32_e32 v118, 0xbfb8aa3b, v118
	v_exp_f32_e32 v117, v116
	v_exp_f32_e32 v119, v118
	v_max_f32_e32 v116, 0xc1a00000, v109
	v_max_f32_e32 v118, 0xc1a00000, v111
	v_mul_f32_e32 v116, 0xbfb8aa3b, v116
	v_mul_f32_e32 v118, 0xbfb8aa3b, v118
	v_exp_f32_e32 v116, v116
	v_exp_f32_e32 v118, v118
	v_cvt_pk_bf16_f32 v114, v114, v115
	v_cvt_pk_bf16_f32 v115, v122, v123
	global_store_dwordx4 v[162:163], v[112:115], off
	v_or_b32_e32 v120, 16, v154
	s_and_b64 vcc, exec, s[2:3]
	v_pk_add_f32 v[112:113], v[116:117], 1.0 op_sel_hi:[1,0]
	v_pk_add_f32 v[114:115], v[118:119], 1.0 op_sel_hi:[1,0]
	v_mul_f32_e32 v116, v113, v112
	v_mul_f32_e32 v117, v115, v114
	s_mov_b32 s41, s6
	v_mul_f32_e32 v118, v116, v117
	v_rcp_f32_e32 v121, v118
	v_mad_i64_i32 v[118:119], s[16:17], v120, s40, v[144:145]
	v_lshl_add_u64 v[118:119], v[118:119], 0, v[146:147]
	v_mul_f32_e32 v116, v116, v121
	v_mul_f32_e32 v120, v117, v121
	v_pk_mul_f32 v[114:115], v[114:115], v[116:117] op_sel_hi:[1,0]
	v_max_f32_e32 v116, 0xc1a00000, v104
	v_max_f32_e32 v121, 0xc1a00000, v106
	v_mul_f32_e32 v116, 0xbfb8aa3b, v116
	v_mul_f32_e32 v121, 0xbfb8aa3b, v121
	v_exp_f32_e32 v117, v116
	v_exp_f32_e32 v123, v121
	v_max_f32_e32 v116, 0xc1a00000, v105
	v_max_f32_e32 v121, 0xc1a00000, v107
	v_mul_f32_e32 v116, 0xbfb8aa3b, v116
	v_mul_f32_e32 v121, 0xbfb8aa3b, v121
	v_exp_f32_e32 v116, v116
	v_exp_f32_e32 v122, v121
	v_pk_mul_f32 v[112:113], v[112:113], v[120:121] op_sel_hi:[1,0]
	v_pk_mul_f32 v[110:111], v[110:111], v[114:115]
	v_pk_mul_f32 v[108:109], v[108:109], v[112:113]
	v_pk_add_f32 v[112:113], v[116:117], 1.0 op_sel_hi:[1,0]
	v_pk_add_f32 v[116:117], v[122:123], 1.0 op_sel_hi:[1,0]
	v_mul_f32_e32 v120, v113, v112
	v_mul_f32_e32 v121, v117, v116
	v_pk_mul_f32 v[102:103], v[110:111], v[102:103]
	v_mul_f32_e32 v122, v120, v121
	v_rcp_f32_e32 v122, v122
	v_pk_mul_f32 v[100:101], v[108:109], v[100:101]
	s_mov_b32 s14, s8
	s_mov_b64 s[18:19], s[12:13]
	v_mul_f32_e32 v108, v121, v122
	v_mul_f32_e32 v110, v120, v122
	v_pk_mul_f32 v[110:111], v[116:117], v[110:111] op_sel_hi:[1,0]
	v_pk_mul_f32 v[108:109], v[112:113], v[108:109] op_sel_hi:[1,0]
	v_pk_mul_f32 v[106:107], v[106:107], v[110:111]
	v_pk_mul_f32 v[104:105], v[104:105], v[108:109]
	v_pk_mul_f32 v[106:107], v[106:107], v[98:99]
	v_pk_mul_f32 v[98:99], v[104:105], v[96:97]
	v_cvt_pk_bf16_f32 v96, v100, v101
	v_cvt_pk_bf16_f32 v97, v102, v103
	v_max_f32_e32 v100, 0xc1a00000, v92
	v_max_f32_e32 v102, 0xc1a00000, v94
	v_mul_f32_e32 v100, 0xbfb8aa3b, v100
	v_mul_f32_e32 v102, 0xbfb8aa3b, v102
	v_exp_f32_e32 v101, v100
	v_exp_f32_e32 v103, v102
	v_max_f32_e32 v100, 0xc1a00000, v93
	v_max_f32_e32 v102, 0xc1a00000, v95
	v_mul_f32_e32 v100, 0xbfb8aa3b, v100
	v_mul_f32_e32 v102, 0xbfb8aa3b, v102
	v_exp_f32_e32 v100, v100
	v_exp_f32_e32 v102, v102
	v_cvt_pk_bf16_f32 v98, v98, v99
	v_cvt_pk_bf16_f32 v99, v106, v107
	global_store_dwordx4 v[118:119], v[96:99], off
	v_or_b32_e32 v104, 32, v154
	s_nop 0
	v_pk_add_f32 v[96:97], v[100:101], 1.0 op_sel_hi:[1,0]
	v_pk_add_f32 v[98:99], v[102:103], 1.0 op_sel_hi:[1,0]
	v_mul_f32_e32 v100, v97, v96
	v_mul_f32_e32 v101, v99, v98
	s_nop 0
	v_mul_f32_e32 v102, v100, v101
	v_rcp_f32_e32 v105, v102
	v_mad_i64_i32 v[102:103], s[16:17], v104, s40, v[144:145]
	v_lshl_add_u64 v[102:103], v[102:103], 0, v[146:147]
	v_mul_f32_e32 v100, v100, v105
	v_mul_f32_e32 v104, v101, v105
	v_pk_mul_f32 v[98:99], v[98:99], v[100:101] op_sel_hi:[1,0]
	v_max_f32_e32 v100, 0xc1a00000, v88
	v_max_f32_e32 v105, 0xc1a00000, v90
	v_mul_f32_e32 v100, 0xbfb8aa3b, v100
	v_mul_f32_e32 v105, 0xbfb8aa3b, v105
	v_exp_f32_e32 v101, v100
	v_exp_f32_e32 v107, v105
	v_max_f32_e32 v100, 0xc1a00000, v89
	v_max_f32_e32 v105, 0xc1a00000, v91
	v_mul_f32_e32 v100, 0xbfb8aa3b, v100
	v_mul_f32_e32 v105, 0xbfb8aa3b, v105
	v_exp_f32_e32 v100, v100
	v_exp_f32_e32 v106, v105
	v_pk_mul_f32 v[96:97], v[96:97], v[104:105] op_sel_hi:[1,0]
	v_pk_mul_f32 v[94:95], v[94:95], v[98:99]
	v_pk_mul_f32 v[92:93], v[92:93], v[96:97]
	v_pk_add_f32 v[96:97], v[100:101], 1.0 op_sel_hi:[1,0]
	v_pk_add_f32 v[100:101], v[106:107], 1.0 op_sel_hi:[1,0]
	v_mul_f32_e32 v104, v97, v96
	v_mul_f32_e32 v105, v101, v100
	v_pk_mul_f32 v[86:87], v[94:95], v[86:87]
	v_mul_f32_e32 v106, v104, v105
	v_rcp_f32_e32 v106, v106
	v_pk_mul_f32 v[84:85], v[92:93], v[84:85]
	v_mul_f32_e32 v92, v105, v106
	v_mul_f32_e32 v94, v104, v106
	v_pk_mul_f32 v[94:95], v[100:101], v[94:95] op_sel_hi:[1,0]
	v_pk_mul_f32 v[92:93], v[96:97], v[92:93] op_sel_hi:[1,0]
	v_pk_mul_f32 v[90:91], v[90:91], v[94:95]
	v_pk_mul_f32 v[88:89], v[88:89], v[92:93]
	v_pk_mul_f32 v[90:91], v[90:91], v[82:83]
	v_pk_mul_f32 v[82:83], v[88:89], v[80:81]
	v_cvt_pk_bf16_f32 v80, v84, v85
	v_cvt_pk_bf16_f32 v81, v86, v87
	v_max_f32_e32 v84, 0xc1a00000, v76
	v_max_f32_e32 v86, 0xc1a00000, v78
	v_mul_f32_e32 v84, 0xbfb8aa3b, v84
	v_mul_f32_e32 v86, 0xbfb8aa3b, v86
	v_exp_f32_e32 v85, v84
	v_exp_f32_e32 v87, v86
	v_max_f32_e32 v84, 0xc1a00000, v77
	v_max_f32_e32 v86, 0xc1a00000, v79
	v_mul_f32_e32 v84, 0xbfb8aa3b, v84
	v_mul_f32_e32 v86, 0xbfb8aa3b, v86
	v_exp_f32_e32 v84, v84
	v_exp_f32_e32 v86, v86
	v_cvt_pk_bf16_f32 v82, v82, v83
	v_cvt_pk_bf16_f32 v83, v90, v91
	global_store_dwordx4 v[102:103], v[80:83], off
	v_or_b32_e32 v88, 48, v154
	s_nop 0
	v_pk_add_f32 v[80:81], v[84:85], 1.0 op_sel_hi:[1,0]
	v_pk_add_f32 v[82:83], v[86:87], 1.0 op_sel_hi:[1,0]
	v_mul_f32_e32 v84, v81, v80
	v_mul_f32_e32 v85, v83, v82
; __device__ __forceinline__ unsigned cvt_pk_bf16(float lo, float hi) { unsigned r; asm volatile("v_cvt_pk_bf16_f32 %0, %1, %2" : "=v"(r) : "v"(lo), "v"(hi)); return r; }
; __device__ __forceinline__ f32x4 sigmoid4(f32x4 x) {
;     f32x4 d;
; #pragma unroll
;     for (int j = 0; j < 4; ++j) d[j] = 1.0f + __expf(-fmaxf(x[j], -20.0f));
;     const float p01 = d[0] * d[1], p23 = d[2] * d[3], r = __builtin_amdgcn_rcpf(p01 * p23), r01 = r * p23, r23 = r * p01;
;     return (f32x4){r01 * d[1], r01 * d[0], r23 * d[3], r23 * d[2]};
; }
;     __device__ __forceinline__ void operator()(const f32x4 (&acc)[2][2][4][2], const Unit& u, int wr, int wc, int fr, int fq) const {
;         const int row0 = u.pm * BM + wr * 64 + fr, col0 = u.pn * HALF + wc * 32 + 8 * fq;
; #pragma unroll
;         for (int ai = 0; ai < 2; ++ai)
; #pragma unroll
;             for (int m = 0; m < 4; ++m) { bf16_t* rowp = O + (size_t)(row0 + ai * HALF + m * 16) * ldc + col0;
;                 f32x4 v0, v1;
; #pragma unroll
;                 for (int j = 0; j < 1; ++j) { v0 = acc[ai][0][m][0] * sigmoid4(acc[ai][0][m][0]) * acc[ai][1][m][0]; v1 = acc[ai][0][m][1] * sigmoid4(acc[ai][0][m][1]) * acc[ai][1][m][1]; }
;                 u32x4 w; w.x = cvt_pk_bf16(v0[0], v0[1]); w.y = cvt_pk_bf16(v0[2], v0[3]); w.z = cvt_pk_bf16(v1[0], v1[1]); w.w = cvt_pk_bf16(v1[2], v1[3]);
;                 *(u32x4*)rowp = w; }
	s_nop 0
	v_mul_f32_e32 v86, v84, v85
	v_rcp_f32_e32 v89, v86
	v_mad_i64_i32 v[86:87], s[16:17], v88, s40, v[144:145]
	v_lshl_add_u64 v[86:87], v[86:87], 0, v[146:147]
	v_mul_f32_e32 v84, v84, v89
	v_mul_f32_e32 v88, v85, v89
	v_pk_mul_f32 v[82:83], v[82:83], v[84:85] op_sel_hi:[1,0]
	v_max_f32_e32 v84, 0xc1a00000, v72
	v_max_f32_e32 v89, 0xc1a00000, v74
	v_mul_f32_e32 v84, 0xbfb8aa3b, v84
	v_mul_f32_e32 v89, 0xbfb8aa3b, v89
	v_exp_f32_e32 v85, v84
	v_exp_f32_e32 v91, v89
	v_max_f32_e32 v84, 0xc1a00000, v73
	v_max_f32_e32 v89, 0xc1a00000, v75
	v_mul_f32_e32 v84, 0xbfb8aa3b, v84
	v_mul_f32_e32 v89, 0xbfb8aa3b, v89
	v_exp_f32_e32 v84, v84
	v_exp_f32_e32 v90, v89
	v_pk_mul_f32 v[80:81], v[80:81], v[88:89] op_sel_hi:[1,0]
	v_pk_mul_f32 v[78:79], v[78:79], v[82:83]
	v_pk_mul_f32 v[76:77], v[76:77], v[80:81]
	v_pk_add_f32 v[80:81], v[84:85], 1.0 op_sel_hi:[1,0]
	v_pk_add_f32 v[84:85], v[90:91], 1.0 op_sel_hi:[1,0]
	v_mul_f32_e32 v88, v81, v80
	v_mul_f32_e32 v89, v85, v84
	v_pk_mul_f32 v[70:71], v[78:79], v[70:71]
	v_mul_f32_e32 v90, v88, v89
	v_rcp_f32_e32 v90, v90
	v_pk_mul_f32 v[68:69], v[76:77], v[68:69]
	v_mul_f32_e32 v76, v89, v90
	v_mul_f32_e32 v78, v88, v90
	v_pk_mul_f32 v[78:79], v[84:85], v[78:79] op_sel_hi:[1,0]
	v_pk_mul_f32 v[76:77], v[80:81], v[76:77] op_sel_hi:[1,0]
	v_pk_mul_f32 v[74:75], v[74:75], v[78:79]
	v_pk_mul_f32 v[72:73], v[72:73], v[76:77]
	v_pk_mul_f32 v[74:75], v[74:75], v[66:67]
	v_pk_mul_f32 v[66:67], v[72:73], v[64:65]
	v_cvt_pk_bf16_f32 v64, v68, v69
	v_cvt_pk_bf16_f32 v65, v70, v71
	v_max_f32_e32 v68, 0xc1a00000, v60
	v_max_f32_e32 v70, 0xc1a00000, v62
	v_mul_f32_e32 v68, 0xbfb8aa3b, v68
	v_mul_f32_e32 v70, 0xbfb8aa3b, v70
	v_exp_f32_e32 v69, v68
	v_exp_f32_e32 v71, v70
	v_max_f32_e32 v68, 0xc1a00000, v61
	v_max_f32_e32 v70, 0xc1a00000, v63
	v_mul_f32_e32 v68, 0xbfb8aa3b, v68
	v_mul_f32_e32 v70, 0xbfb8aa3b, v70
	v_exp_f32_e32 v68, v68
	v_exp_f32_e32 v70, v70
	v_cvt_pk_bf16_f32 v66, v66, v67
	v_cvt_pk_bf16_f32 v67, v74, v75
	global_store_dwordx4 v[86:87], v[64:67], off
	v_add_u32_e32 v72, 0x80, v154
	s_nop 0
	v_pk_add_f32 v[64:65], v[68:69], 1.0 op_sel_hi:[1,0]
	v_pk_add_f32 v[66:67], v[70:71], 1.0 op_sel_hi:[1,0]
	v_mul_f32_e32 v68, v65, v64
	v_mul_f32_e32 v69, v67, v66
	s_nop 0
	v_mul_f32_e32 v70, v68, v69
	v_rcp_f32_e32 v73, v70
	v_mad_i64_i32 v[70:71], s[16:17], v72, s40, v[144:145]
	v_lshl_add_u64 v[70:71], v[70:71], 0, v[146:147]
	v_mul_f32_e32 v68, v68, v73
	v_mul_f32_e32 v72, v69, v73
	v_pk_mul_f32 v[66:67], v[66:67], v[68:69] op_sel_hi:[1,0]
	v_max_f32_e32 v68, 0xc1a00000, v56
	v_max_f32_e32 v73, 0xc1a00000, v58
	v_mul_f32_e32 v68, 0xbfb8aa3b, v68
	v_mul_f32_e32 v73, 0xbfb8aa3b, v73
	v_exp_f32_e32 v69, v68
	v_exp_f32_e32 v75, v73
	v_max_f32_e32 v68, 0xc1a00000, v57
	v_max_f32_e32 v73, 0xc1a00000, v59
	v_mul_f32_e32 v68, 0xbfb8aa3b, v68
	v_mul_f32_e32 v73, 0xbfb8aa3b, v73
	v_exp_f32_e32 v68, v68
	v_exp_f32_e32 v74, v73
	v_pk_mul_f32 v[64:65], v[64:65], v[72:73] op_sel_hi:[1,0]
	v_pk_mul_f32 v[62:63], v[62:63], v[66:67]
	v_pk_mul_f32 v[60:61], v[60:61], v[64:65]
	v_pk_add_f32 v[64:65], v[68:69], 1.0 op_sel_hi:[1,0]
	v_pk_add_f32 v[68:69], v[74:75], 1.0 op_sel_hi:[1,0]
	v_mul_f32_e32 v72, v65, v64
	v_mul_f32_e32 v73, v69, v68
	v_pk_mul_f32 v[54:55], v[62:63], v[54:55]
	v_mul_f32_e32 v74, v72, v73
	v_rcp_f32_e32 v74, v74
	v_pk_mul_f32 v[52:53], v[60:61], v[52:53]
	v_mul_f32_e32 v60, v73, v74
	v_mul_f32_e32 v62, v72, v74
	v_pk_mul_f32 v[62:63], v[68:69], v[62:63] op_sel_hi:[1,0]
	v_pk_mul_f32 v[60:61], v[64:65], v[60:61] op_sel_hi:[1,0]
	v_pk_mul_f32 v[58:59], v[58:59], v[62:63]
	v_pk_mul_f32 v[56:57], v[56:57], v[60:61]
	v_pk_mul_f32 v[58:59], v[58:59], v[50:51]
	v_pk_mul_f32 v[50:51], v[56:57], v[48:49]
	v_cvt_pk_bf16_f32 v48, v52, v53
	v_cvt_pk_bf16_f32 v49, v54, v55
	v_max_f32_e32 v52, 0xc1a00000, v44
	v_max_f32_e32 v54, 0xc1a00000, v46
	v_mul_f32_e32 v52, 0xbfb8aa3b, v52
	v_mul_f32_e32 v54, 0xbfb8aa3b, v54
	v_exp_f32_e32 v53, v52
	v_exp_f32_e32 v55, v54
	v_max_f32_e32 v52, 0xc1a00000, v45
	v_max_f32_e32 v54, 0xc1a00000, v47
	v_mul_f32_e32 v52, 0xbfb8aa3b, v52
	v_mul_f32_e32 v54, 0xbfb8aa3b, v54
	v_exp_f32_e32 v52, v52
	v_exp_f32_e32 v54, v54
	v_cvt_pk_bf16_f32 v50, v50, v51
	v_cvt_pk_bf16_f32 v51, v58, v59
	global_store_dwordx4 v[70:71], v[48:51], off
	v_add_u32_e32 v56, 0x90, v154
	s_nop 0
	v_pk_add_f32 v[48:49], v[52:53], 1.0 op_sel_hi:[1,0]
	v_pk_add_f32 v[50:51], v[54:55], 1.0 op_sel_hi:[1,0]
	v_mul_f32_e32 v52, v49, v48
	v_mul_f32_e32 v53, v51, v50
	s_nop 0
	v_mul_f32_e32 v54, v52, v53
	v_rcp_f32_e32 v57, v54
	v_mad_i64_i32 v[54:55], s[16:17], v56, s40, v[144:145]
	v_lshl_add_u64 v[54:55], v[54:55], 0, v[146:147]
	v_mul_f32_e32 v52, v52, v57
	v_mul_f32_e32 v56, v53, v57
	v_pk_mul_f32 v[50:51], v[50:51], v[52:53] op_sel_hi:[1,0]
	v_max_f32_e32 v52, 0xc1a00000, v40
	v_max_f32_e32 v57, 0xc1a00000, v42
	v_mul_f32_e32 v52, 0xbfb8aa3b, v52
	v_mul_f32_e32 v57, 0xbfb8aa3b, v57
	v_exp_f32_e32 v53, v52
	v_exp_f32_e32 v59, v57
	v_max_f32_e32 v52, 0xc1a00000, v41
	v_max_f32_e32 v57, 0xc1a00000, v43
	v_mul_f32_e32 v52, 0xbfb8aa3b, v52
	v_mul_f32_e32 v57, 0xbfb8aa3b, v57
	v_exp_f32_e32 v52, v52
	v_exp_f32_e32 v58, v57
	v_pk_mul_f32 v[48:49], v[48:49], v[56:57] op_sel_hi:[1,0]
	v_pk_mul_f32 v[46:47], v[46:47], v[50:51]
	v_pk_mul_f32 v[44:45], v[44:45], v[48:49]
	v_pk_add_f32 v[48:49], v[52:53], 1.0 op_sel_hi:[1,0]
; __device__ __forceinline__ unsigned cvt_pk_bf16(float lo, float hi) { unsigned r; asm volatile("v_cvt_pk_bf16_f32 %0, %1, %2" : "=v"(r) : "v"(lo), "v"(hi)); return r; }
; #define PG8_WAIT_V(n) asm volatile("s_waitcnt vmcnt(" #n ")" ::: "memory")
; #define PG8_BAR __builtin_amdgcn_s_barrier()
;     __device__ __forceinline__ void operator()(const f32x4 (&acc)[2][2][4][2], const Unit& u, int wr, int wc, int fr, int fq) const {
;         const int row0 = u.pm * BM + wr * 64 + fr, col0 = u.pn * HALF + wc * 32 + 8 * fq;
; #pragma unroll
;         for (int ai = 0; ai < 2; ++ai)
; #pragma unroll
;             for (int m = 0; m < 4; ++m) { bf16_t* rowp = O + (size_t)(row0 + ai * HALF + m * 16) * ldc + col0;
;                 f32x4 v0, v1;
; #pragma unroll
;                 for (int j = 0; j < 1; ++j) { v0 = acc[ai][0][m][0] * sigmoid4(acc[ai][0][m][0]) * acc[ai][1][m][0]; v1 = acc[ai][0][m][1] * sigmoid4(acc[ai][0][m][1]) * acc[ai][1][m][1]; }
;                 u32x4 w; w.x = cvt_pk_bf16(v0[0], v0[1]); w.y = cvt_pk_bf16(v0[2], v0[3]); w.z = cvt_pk_bf16(v1[0], v1[1]); w.w = cvt_pk_bf16(v1[2], v1[3]);
;                 *(u32x4*)rowp = w; }
; template <class Epi, class Sched>
; __device__ __forceinline__ void gemm_phase(PG8_LAS unsigned char* lds, const Gemm g, const Sched& S, const Epi& E) {
;     ...
;         if (!has_next) break;
; #pragma unroll
;         for (int a = 0; a < 2; ++a)
; #pragma unroll
;             for (int b = 0; b < 2; ++b)
; #pragma unroll
;                 for (int m = 0; m < 4; ++m)
; #pragma unroll
;                     for (int n = 0; n < 2; ++n) acc[a][b][m][n] = (f32x4){0.f, 0.f, 0.f, 0.f};
;         cur = nxt; cA = nA; cB = nB; ++ui;
;     }
;     PG8_WAIT_V(0);
;     if (wr == 0) PG8_BAR;
;     PG8_BAR;
	v_pk_add_f32 v[52:53], v[58:59], 1.0 op_sel_hi:[1,0]
	v_mul_f32_e32 v56, v49, v48
	v_mul_f32_e32 v57, v53, v52
	v_pk_mul_f32 v[38:39], v[46:47], v[38:39]
	v_mul_f32_e32 v58, v56, v57
	v_rcp_f32_e32 v58, v58
	v_pk_mul_f32 v[36:37], v[44:45], v[36:37]
	v_mul_f32_e32 v44, v57, v58
	v_mul_f32_e32 v46, v56, v58
	v_pk_mul_f32 v[46:47], v[52:53], v[46:47] op_sel_hi:[1,0]
	v_pk_mul_f32 v[44:45], v[48:49], v[44:45] op_sel_hi:[1,0]
	v_pk_mul_f32 v[42:43], v[42:43], v[46:47]
	v_pk_mul_f32 v[40:41], v[40:41], v[44:45]
	v_pk_mul_f32 v[42:43], v[42:43], v[34:35]
	v_pk_mul_f32 v[34:35], v[40:41], v[32:33]
	v_cvt_pk_bf16_f32 v32, v36, v37
	v_cvt_pk_bf16_f32 v33, v38, v39
	v_max_f32_e32 v36, 0xc1a00000, v28
	v_max_f32_e32 v38, 0xc1a00000, v30
	v_mul_f32_e32 v36, 0xbfb8aa3b, v36
	v_mul_f32_e32 v38, 0xbfb8aa3b, v38
	v_exp_f32_e32 v37, v36
	v_exp_f32_e32 v39, v38
	v_max_f32_e32 v36, 0xc1a00000, v29
	v_max_f32_e32 v38, 0xc1a00000, v31
	v_mul_f32_e32 v36, 0xbfb8aa3b, v36
	v_mul_f32_e32 v38, 0xbfb8aa3b, v38
	v_exp_f32_e32 v36, v36
	v_exp_f32_e32 v38, v38
	v_cvt_pk_bf16_f32 v34, v34, v35
	v_cvt_pk_bf16_f32 v35, v42, v43
	global_store_dwordx4 v[54:55], v[32:35], off
	v_add_u32_e32 v40, 0xa0, v154
	s_nop 0
	v_pk_add_f32 v[32:33], v[36:37], 1.0 op_sel_hi:[1,0]
	v_pk_add_f32 v[34:35], v[38:39], 1.0 op_sel_hi:[1,0]
	v_mul_f32_e32 v36, v33, v32
	v_mul_f32_e32 v37, v35, v34
	s_nop 0
	v_mul_f32_e32 v38, v36, v37
	v_rcp_f32_e32 v41, v38
	v_mad_i64_i32 v[38:39], s[16:17], v40, s40, v[144:145]
	v_lshl_add_u64 v[38:39], v[38:39], 0, v[146:147]
	v_mul_f32_e32 v36, v36, v41
	v_mul_f32_e32 v40, v37, v41
	v_pk_mul_f32 v[34:35], v[34:35], v[36:37] op_sel_hi:[1,0]
	v_max_f32_e32 v36, 0xc1a00000, v24
	v_max_f32_e32 v41, 0xc1a00000, v26
	v_mul_f32_e32 v36, 0xbfb8aa3b, v36
	v_mul_f32_e32 v41, 0xbfb8aa3b, v41
	v_exp_f32_e32 v37, v36
	v_exp_f32_e32 v43, v41
	v_max_f32_e32 v36, 0xc1a00000, v25
	v_max_f32_e32 v41, 0xc1a00000, v27
	v_mul_f32_e32 v36, 0xbfb8aa3b, v36
	v_mul_f32_e32 v41, 0xbfb8aa3b, v41
	v_exp_f32_e32 v36, v36
	v_exp_f32_e32 v42, v41
	v_pk_mul_f32 v[32:33], v[32:33], v[40:41] op_sel_hi:[1,0]
	v_pk_mul_f32 v[30:31], v[30:31], v[34:35]
	v_pk_mul_f32 v[28:29], v[28:29], v[32:33]
	v_pk_add_f32 v[32:33], v[36:37], 1.0 op_sel_hi:[1,0]
	v_pk_add_f32 v[36:37], v[42:43], 1.0 op_sel_hi:[1,0]
	v_mul_f32_e32 v40, v33, v32
	v_mul_f32_e32 v41, v37, v36
	v_pk_mul_f32 v[22:23], v[30:31], v[22:23]
	v_mul_f32_e32 v42, v40, v41
	v_rcp_f32_e32 v42, v42
	v_pk_mul_f32 v[20:21], v[28:29], v[20:21]
	v_mul_f32_e32 v28, v41, v42
	v_mul_f32_e32 v30, v40, v42
	v_pk_mul_f32 v[30:31], v[36:37], v[30:31] op_sel_hi:[1,0]
	v_pk_mul_f32 v[28:29], v[32:33], v[28:29] op_sel_hi:[1,0]
	v_pk_mul_f32 v[26:27], v[26:27], v[30:31]
	v_pk_mul_f32 v[24:25], v[24:25], v[28:29]
	v_pk_mul_f32 v[26:27], v[26:27], v[18:19]
	v_pk_mul_f32 v[18:19], v[24:25], v[16:17]
	v_cvt_pk_bf16_f32 v16, v20, v21
	v_cvt_pk_bf16_f32 v17, v22, v23
	v_max_f32_e32 v20, 0xc1a00000, v12
	v_max_f32_e32 v22, 0xc1a00000, v14
	v_mul_f32_e32 v20, 0xbfb8aa3b, v20
	v_mul_f32_e32 v22, 0xbfb8aa3b, v22
	v_exp_f32_e32 v21, v20
	v_exp_f32_e32 v23, v22
	v_max_f32_e32 v20, 0xc1a00000, v13
	v_max_f32_e32 v22, 0xc1a00000, v15
	v_mul_f32_e32 v20, 0xbfb8aa3b, v20
	v_mul_f32_e32 v22, 0xbfb8aa3b, v22
	v_exp_f32_e32 v20, v20
	v_exp_f32_e32 v22, v22
	v_cvt_pk_bf16_f32 v18, v18, v19
	v_cvt_pk_bf16_f32 v19, v26, v27
	global_store_dwordx4 v[38:39], v[16:19], off
	v_add_u32_e32 v24, 0xb0, v154
	s_nop 0
	v_pk_add_f32 v[16:17], v[20:21], 1.0 op_sel_hi:[1,0]
	v_pk_add_f32 v[18:19], v[22:23], 1.0 op_sel_hi:[1,0]
	v_mul_f32_e32 v20, v17, v16
	v_mul_f32_e32 v21, v19, v18
	s_nop 0
	v_mul_f32_e32 v22, v20, v21
	v_rcp_f32_e32 v25, v22
	v_mad_i64_i32 v[22:23], s[16:17], v24, s40, v[144:145]
	v_lshl_add_u64 v[22:23], v[22:23], 0, v[146:147]
	v_mul_f32_e32 v20, v20, v25
	v_mul_f32_e32 v24, v21, v25
	v_pk_mul_f32 v[18:19], v[18:19], v[20:21] op_sel_hi:[1,0]
	v_max_f32_e32 v20, 0xc1a00000, v8
	v_max_f32_e32 v25, 0xc1a00000, v10
	v_mul_f32_e32 v20, 0xbfb8aa3b, v20
	v_mul_f32_e32 v25, 0xbfb8aa3b, v25
	v_exp_f32_e32 v21, v20
	v_exp_f32_e32 v27, v25
	v_max_f32_e32 v20, 0xc1a00000, v9
	v_max_f32_e32 v25, 0xc1a00000, v11
	v_mul_f32_e32 v20, 0xbfb8aa3b, v20
	v_mul_f32_e32 v25, 0xbfb8aa3b, v25
	v_exp_f32_e32 v20, v20
	v_exp_f32_e32 v26, v25
	v_pk_mul_f32 v[16:17], v[16:17], v[24:25] op_sel_hi:[1,0]
	v_pk_mul_f32 v[14:15], v[14:15], v[18:19]
	v_pk_mul_f32 v[12:13], v[12:13], v[16:17]
	v_pk_add_f32 v[16:17], v[20:21], 1.0 op_sel_hi:[1,0]
	v_pk_add_f32 v[20:21], v[26:27], 1.0 op_sel_hi:[1,0]
	v_mul_f32_e32 v24, v17, v16
	v_mul_f32_e32 v25, v21, v20
	v_pk_mul_f32 v[6:7], v[14:15], v[6:7]
	v_mul_f32_e32 v26, v24, v25
	v_rcp_f32_e32 v26, v26
	v_pk_mul_f32 v[4:5], v[12:13], v[4:5]
	s_mov_b64 s[16:17], s[10:11]
	v_mul_f32_e32 v12, v25, v26
	v_mul_f32_e32 v14, v24, v26
	v_pk_mul_f32 v[14:15], v[20:21], v[14:15] op_sel_hi:[1,0]
	v_pk_mul_f32 v[12:13], v[16:17], v[12:13] op_sel_hi:[1,0]
	v_pk_mul_f32 v[10:11], v[10:11], v[14:15]
	v_pk_mul_f32 v[8:9], v[8:9], v[12:13]
	v_pk_mul_f32 v[10:11], v[10:11], v[2:3]
	v_pk_mul_f32 v[2:3], v[8:9], v[0:1]
	v_cvt_pk_bf16_f32 v0, v4, v5
	v_cvt_pk_bf16_f32 v1, v6, v7
	s_nop 0
	v_cvt_pk_bf16_f32 v2, v2, v3
	v_cvt_pk_bf16_f32 v3, v10, v11
	global_store_dwordx4 v[22:23], v[0:3], off
	s_cbranch_vccz .LBB0_1199
	s_waitcnt vmcnt(0)
	s_cmpk_gt_u32 s23, 0xff
	s_cbranch_scc1 .LBB0_1206
	s_barrier

; #define PG8_STAGE(bufoff, gbase, voff) do { _Pragma("unroll") for (int _i = 0; _i < 2; ++_i) \
;         __builtin_amdgcn_global_load_lds((const unsigned*)((const char*)(gbase) + (voff)[_i]), (PG8_LAS unsigned*)(lds + (bufoff) + ldsw + _i * 8192), 16, 0, 0); } while (0)
; #define PG8_LDA(dst, b, h) do { _Pragma("unroll") for (int m = 0; m < 4; ++m) _Pragma("unroll") for (int k = 0; k < 2; ++k) dst[m][k] = *(const PG8_LAS bf16x8*)(lds + PG8_SA(b, h) + aoff + m * 2048 + k * 1024); } while (0)
; #define PG8_LDB(dst, b, h) do { _Pragma("unroll") for (int n = 0; n < 2; ++n) _Pragma("unroll") for (int k = 0; k < 2; ++k) dst[n][k] = *(const PG8_LAS bf16x8*)(lds + PG8_SB(b, h) + boff + n * 2048 + k * 1024); } while (0)
; #define PG8_MMA(ai, bj, At, Bt) do { __builtin_amdgcn_s_setprio(1); _Pragma("unroll") for (int m = 0; m < 4; ++m) _Pragma("unroll") for (int n = 0; n < 2; ++n) _Pragma("unroll") for (int k = 0; k < 2; ++k) \
;         acc[ai][bj][m][n] = __builtin_amdgcn_mfma_f32_16x16x32_bf16(Bt[n][k], At[m][k], acc[ai][bj][m][n], 0, 0, 0); __builtin_amdgcn_s_setprio(0); } while (0)
; template <class Epi, class Sched>
; __device__ __forceinline__ void gemm_phase(PG8_LAS unsigned char* lds, const Gemm g, const Sched& S, const Epi& E) {
;     ...
;         const bool has_next = S.next(ui + 1, nxt);
;         const char* nA = has_next ? (const char*)g.A + (size_t)nxt.pm * tstep : cA; const char* nB = has_next ? (const char*)g.Bt + (size_t)nxt.pn * tstep : cB;
;         for (int t = 0; t < nt; t += 2) {
;             const bool last = (t == nt - 2);
;             const char* a1 = cA + (size_t)(t + 1) * kstep;
;             const char* a2 = last ? nA : cA + (size_t)(t + 2) * kstep; const char* b2 = last ? nB : cB + (size_t)(t + 2) * kstep;
;             const char* a3 = a2 + kstep; const char* b3 = b2 + kstep;
;             if (last && has_next) S.a_ready(nxt);
;             PG8_LDB(B0, 0, 0); PG8_SCHED; PG8_LDA(At, 0, 0); PG8_STAGE(PG8_SA(1, 1), a1 + hstep, voffA);
;             PG8_WAIT_L(8); PG8_BAR; PG8_WAIT_L(0); PG8_MMA(0, 0, At, B0); PG8_BAR; PG8_SCHED;
;             PG8_LDB(B1, 0, 1); PG8_STAGE(PG8_SB(0, 0), b2, voffB);
;             PG8_BAR; PG8_WAIT_L(0); PG8_MMA(0, 1, At, B1); PG8_BAR;
;             PG8_LDA(At, 0, 1); PG8_STAGE(PG8_SA(0, 0), a2, voffA);
;             PG8_BAR; PG8_WAIT_L(0); PG8_MMA(1, 0, At, B0); PG8_BAR; PG8_SCHED;
.LBB0_1277:
	s_add_u32 s52, s20, 0x100
	s_addc_u32 s53, s21, 0
	s_mov_b32 s54, -2
	ds_read_b128 v[152:155], v149
	ds_read_b128 v[156:159], v149 offset:1024
	ds_read_b128 v[160:163], v149 offset:2048
	ds_read_b128 v[164:167], v149 offset:3072
	s_add_u32 s20, s18, 0x100
	s_addc_u32 s21, s19, 0
	s_cmp_eq_u32 s54, 40
	s_cselect_b32 s25, s1, s21
	s_cselect_b32 s24, s0, s20
	s_cselect_b32 s23, s5, s53
	s_cselect_b32 s22, s4, s52
	s_add_i32 m0, s34, 0xc000
	ds_read_b128 v[168:171], v150
	ds_read_b128 v[172:175], v150 offset:1024
	ds_read_b128 v[182:185], v150 offset:2048
	ds_read_b128 v[190:193], v150 offset:3072
	ds_read_b128 v[194:197], v150 offset:4096
	ds_read_b128 v[198:201], v150 offset:5120
	ds_read_b128 v[202:205], v150 offset:6144
	ds_read_b128 v[206:209], v150 offset:7168
	global_load_lds_dwordx4 v136, s[18:19]
	s_nop 1
	s_add_i32 m0, s34, 0xe000
	s_nop 0
	global_load_lds_dwordx4 v138, s[18:19]
	s_waitcnt lgkmcnt(12)
	ds_read_b128 v[210:213], v151
	ds_read_b128 v[214:217], v151 offset:1024
	ds_read_b128 v[218:221], v151 offset:2048
	ds_read_b128 v[222:225], v151 offset:3072
	s_waitcnt vmcnt(8) lgkmcnt(0)
	s_barrier
	v_mfma_f32_16x16x32_bf16 v[124:127], v[152:155], v[168:171], 0
	v_mfma_f32_16x16x32_bf16 v[120:123], v[160:163], v[168:171], 0
	v_mfma_f32_16x16x32_bf16 v[108:111], v[152:155], v[182:185], 0
	v_mfma_f32_16x16x32_bf16 v[104:107], v[160:163], v[182:185], 0
	v_mfma_f32_16x16x32_bf16 v[92:95], v[152:155], v[194:197], 0
	v_mfma_f32_16x16x32_bf16 v[88:91], v[160:163], v[194:197], 0
	v_mfma_f32_16x16x32_bf16 v[76:79], v[152:155], v[202:205], 0
	v_mfma_f32_16x16x32_bf16 v[72:75], v[160:163], v[202:205], 0
	v_mfma_f32_16x16x32_bf16 v[124:127], v[156:159], v[172:175], v[124:127]
	v_mfma_f32_16x16x32_bf16 v[120:123], v[164:167], v[172:175], v[120:123]
	v_mfma_f32_16x16x32_bf16 v[108:111], v[156:159], v[190:193], v[108:111]
	v_mfma_f32_16x16x32_bf16 v[104:107], v[164:167], v[190:193], v[104:107]
	v_mfma_f32_16x16x32_bf16 v[92:95], v[156:159], v[198:201], v[92:95]
	v_mfma_f32_16x16x32_bf16 v[88:91], v[164:167], v[198:201], v[88:91]
	v_mfma_f32_16x16x32_bf16 v[76:79], v[156:159], v[206:209], v[76:79]
	v_mfma_f32_16x16x32_bf16 v[72:75], v[164:167], v[206:209], v[72:75]
	v_mfma_f32_16x16x32_bf16 v[116:119], v[210:213], v[168:171], 0
	v_mfma_f32_16x16x32_bf16 v[112:115], v[218:221], v[168:171], 0
	v_mfma_f32_16x16x32_bf16 v[100:103], v[210:213], v[182:185], 0
	v_mfma_f32_16x16x32_bf16 v[96:99], v[218:221], v[182:185], 0
	v_mfma_f32_16x16x32_bf16 v[84:87], v[210:213], v[194:197], 0
	v_mfma_f32_16x16x32_bf16 v[80:83], v[218:221], v[194:197], 0
	v_mfma_f32_16x16x32_bf16 v[68:71], v[210:213], v[202:205], 0
	v_mfma_f32_16x16x32_bf16 v[64:67], v[218:221], v[202:205], 0
	v_mfma_f32_16x16x32_bf16 v[116:119], v[214:217], v[172:175], v[116:119]
	v_mfma_f32_16x16x32_bf16 v[112:115], v[222:225], v[172:175], v[112:115]
	v_mfma_f32_16x16x32_bf16 v[100:103], v[214:217], v[190:193], v[100:103]
	v_mfma_f32_16x16x32_bf16 v[96:99], v[222:225], v[190:193], v[96:99]
	v_mfma_f32_16x16x32_bf16 v[84:87], v[214:217], v[198:201], v[84:87]
	v_mfma_f32_16x16x32_bf16 v[80:83], v[222:225], v[198:201], v[80:83]
	v_mfma_f32_16x16x32_bf16 v[68:71], v[214:217], v[206:209], v[68:71]
	v_mfma_f32_16x16x32_bf16 v[64:67], v[222:225], v[206:209], v[64:67]
	s_barrier
	ds_read_b128 v[168:171], v150 offset:16384
	ds_read_b128 v[172:175], v150 offset:17408
	ds_read_b128 v[182:185], v150 offset:18432
	ds_read_b128 v[190:193], v150 offset:19456
	ds_read_b128 v[194:197], v150 offset:20480
	ds_read_b128 v[198:201], v150 offset:21504
	ds_read_b128 v[202:205], v150 offset:22528
	ds_read_b128 v[206:209], v150 offset:23552
	s_add_i32 s18, s42, s31
	s_add_u32 s98, s22, s8
	s_addc_u32 s99, s23, s9
	s_mov_b32 m0, s18
	s_nop 0
	global_load_lds_dwordx4 v130, s[22:23]
	s_nop 1
	s_add_i32 m0, s18, 0x2000
	s_nop 0
	global_load_lds_dwordx4 v134, s[22:23]
	s_nop 1
	s_mov_b32 m0, s34
	s_add_u32 s100, s24, s8
	s_addc_u32 s101, s25, s9
	global_load_lds_dwordx4 v128, s[24:25]
	s_nop 1
	s_mov_b32 m0, s35
	s_nop 0
	global_load_lds_dwordx4 v132, s[24:25]
	s_add_u32 s18, s22, 0xb0000
	s_addc_u32 s19, s23, 0
	s_add_i32 s55, s43, s31
	s_mov_b32 m0, s55
	s_nop 0
	global_load_lds_dwordx4 v130, s[18:19]
	s_nop 1
	s_add_i32 m0, s55, 0x2000
	s_nop 0
	global_load_lds_dwordx4 v134, s[18:19]
	s_waitcnt vmcnt(8) lgkmcnt(0)
	s_barrier
	v_mfma_f32_16x16x32_bf16 v[60:63], v[152:155], v[168:171], 0
	v_mfma_f32_16x16x32_bf16 v[56:59], v[160:163], v[168:171], 0
	v_mfma_f32_16x16x32_bf16 v[48:51], v[152:155], v[182:185], 0
	v_mfma_f32_16x16x32_bf16 v[40:43], v[160:163], v[182:185], 0
	v_mfma_f32_16x16x32_bf16 v[32:35], v[152:155], v[194:197], 0
	v_mfma_f32_16x16x32_bf16 v[24:27], v[160:163], v[194:197], 0
	v_mfma_f32_16x16x32_bf16 v[16:19], v[152:155], v[202:205], 0
	v_mfma_f32_16x16x32_bf16 v[8:11], v[160:163], v[202:205], 0
	v_mfma_f32_16x16x32_bf16 v[60:63], v[156:159], v[172:175], v[60:63]
	v_mfma_f32_16x16x32_bf16 v[56:59], v[164:167], v[172:175], v[56:59]
	v_mfma_f32_16x16x32_bf16 v[48:51], v[156:159], v[190:193], v[48:51]
	v_mfma_f32_16x16x32_bf16 v[40:43], v[164:167], v[190:193], v[40:43]
	v_mfma_f32_16x16x32_bf16 v[32:35], v[156:159], v[198:201], v[32:35]
	v_mfma_f32_16x16x32_bf16 v[24:27], v[164:167], v[198:201], v[24:27]
	v_mfma_f32_16x16x32_bf16 v[16:19], v[156:159], v[206:209], v[16:19]
	v_mfma_f32_16x16x32_bf16 v[8:11], v[164:167], v[206:209], v[8:11]
	v_mfma_f32_16x16x32_bf16 v[52:55], v[210:213], v[168:171], 0
	v_mfma_f32_16x16x32_bf16 v[44:47], v[218:221], v[168:171], 0
	v_mfma_f32_16x16x32_bf16 v[36:39], v[210:213], v[182:185], 0
	v_mfma_f32_16x16x32_bf16 v[28:31], v[218:221], v[182:185], 0
	v_mfma_f32_16x16x32_bf16 v[20:23], v[210:213], v[194:197], 0
	v_mfma_f32_16x16x32_bf16 v[12:15], v[218:221], v[194:197], 0
	v_mfma_f32_16x16x32_bf16 v[4:7], v[210:213], v[202:205], 0
	v_mfma_f32_16x16x32_bf16 v[0:3], v[218:221], v[202:205], 0
	v_mfma_f32_16x16x32_bf16 v[52:55], v[214:217], v[172:175], v[52:55]
	v_mfma_f32_16x16x32_bf16 v[44:47], v[222:225], v[172:175], v[44:47]
	v_mfma_f32_16x16x32_bf16 v[36:39], v[214:217], v[190:193], v[36:39]
	v_mfma_f32_16x16x32_bf16 v[28:31], v[222:225], v[190:193], v[28:31]
	v_mfma_f32_16x16x32_bf16 v[20:23], v[214:217], v[198:201], v[20:23]
	v_mfma_f32_16x16x32_bf16 v[12:15], v[222:225], v[198:201], v[12:15]
	v_mfma_f32_16x16x32_bf16 v[4:7], v[214:217], v[206:209], v[4:7]
	v_mfma_f32_16x16x32_bf16 v[0:3], v[222:225], v[206:209], v[0:3]
	s_barrier
; #define PG8_STAGE(bufoff, gbase, voff) do { _Pragma("unroll") for (int _i = 0; _i < 2; ++_i) \
;         __builtin_amdgcn_global_load_lds((const unsigned*)((const char*)(gbase) + (voff)[_i]), (PG8_LAS unsigned*)(lds + (bufoff) + ldsw + _i * 8192), 16, 0, 0); } while (0)
; #define PG8_LDA(dst, b, h) do { _Pragma("unroll") for (int m = 0; m < 4; ++m) _Pragma("unroll") for (int k = 0; k < 2; ++k) dst[m][k] = *(const PG8_LAS bf16x8*)(lds + PG8_SA(b, h) + aoff + m * 2048 + k * 1024); } while (0)
; #define PG8_LDB(dst, b, h) do { _Pragma("unroll") for (int n = 0; n < 2; ++n) _Pragma("unroll") for (int k = 0; k < 2; ++k) dst[n][k] = *(const PG8_LAS bf16x8*)(lds + PG8_SB(b, h) + boff + n * 2048 + k * 1024); } while (0)
; #define PG8_MMA(ai, bj, At, Bt) do { __builtin_amdgcn_s_setprio(1); _Pragma("unroll") for (int m = 0; m < 4; ++m) _Pragma("unroll") for (int n = 0; n < 2; ++n) _Pragma("unroll") for (int k = 0; k < 2; ++k) \
;         acc[ai][bj][m][n] = __builtin_amdgcn_mfma_f32_16x16x32_bf16(Bt[n][k], At[m][k], acc[ai][bj][m][n], 0, 0, 0); __builtin_amdgcn_s_setprio(0); } while (0)
; #define PG8_WAIT_V(n) asm volatile("s_waitcnt vmcnt(" #n ")" ::: "memory")
; #define PG8_WAIT_L(n) asm volatile("s_waitcnt lgkmcnt(" #n ")" ::: "memory")
; #define PG8_BAR __builtin_amdgcn_s_barrier()
; #define PG8_SCHED __builtin_amdgcn_sched_barrier(0)
; template <class Epi, class Sched>
; __device__ __forceinline__ void gemm_phase(PG8_LAS unsigned char* lds, const Gemm g, const Sched& S, const Epi& E) {
;     ...
;             PG8_BAR; PG8_WAIT_L(0); PG8_MMA(1, 0, At, B0); PG8_BAR; PG8_SCHED;
;             PG8_STAGE(PG8_SB(0, 1), b2 + hstep, voffB);
;             PG8_WAIT_V(6); PG8_BAR; PG8_MMA(1, 1, At, B1); PG8_BAR;
;             PG8_LDB(B0, 1, 0); PG8_SCHED; PG8_LDA(At, 1, 0); PG8_STAGE(PG8_SA(0, 1), a2 + hstep, voffA);
;             PG8_WAIT_L(8); PG8_BAR; PG8_WAIT_L(0); PG8_MMA(0, 0, At, B0); PG8_BAR; PG8_SCHED;
;             PG8_LDB(B1, 1, 1); PG8_STAGE(PG8_SB(1, 0), b3, voffB);
;             PG8_BAR; PG8_WAIT_L(0); PG8_MMA(0, 1, At, B1); PG8_BAR;
;             PG8_LDA(At, 1, 1); PG8_STAGE(PG8_SA(1, 0), a3, voffA);
;             PG8_BAR; PG8_WAIT_L(0); PG8_MMA(1, 0, At, B0); PG8_BAR; PG8_SCHED;
;             PG8_STAGE(PG8_SB(1, 1), b3 + hstep, voffB);
;             PG8_WAIT_V(6); PG8_BAR; PG8_MMA(1, 1, At, B1); PG8_BAR;
	s_add_i32 s55, 0, 0x18000
	v_add_u32_e32 v164, s55, v147
	ds_read_b128 v[152:155], v164
	ds_read_b128 v[156:159], v164 offset:1024
	ds_read_b128 v[160:163], v164 offset:2048
	ds_read_b128 v[164:167], v164 offset:3072
	s_add_u32 s18, s24, 0xb0000
	s_addc_u32 s19, s25, 0
	s_mov_b32 m0, s36
	ds_read_b128 v[168:171], v150 offset:32768
	ds_read_b128 v[172:175], v150 offset:33792
	ds_read_b128 v[182:185], v150 offset:34816
	ds_read_b128 v[190:193], v150 offset:35840
	ds_read_b128 v[194:197], v150 offset:36864
	ds_read_b128 v[198:201], v150 offset:37888
	ds_read_b128 v[202:205], v150 offset:38912
	ds_read_b128 v[206:209], v150 offset:39936
	global_load_lds_dwordx4 v128, s[18:19]
	s_nop 1
	s_mov_b32 m0, s37
	s_nop 0
	global_load_lds_dwordx4 v132, s[18:19]
	s_add_i32 s24, 0, 0x1c000
	v_add_u32_e32 v179, s24, v147
	s_waitcnt lgkmcnt(12)
	ds_read_b128 v[210:213], v179
	ds_read_b128 v[214:217], v179 offset:1024
	ds_read_b128 v[218:221], v179 offset:2048
	ds_read_b128 v[222:225], v179 offset:3072
	s_waitcnt vmcnt(8) lgkmcnt(0)
	s_barrier
	v_mfma_f32_16x16x32_bf16 v[124:127], v[152:155], v[168:171], v[124:127]
	v_mfma_f32_16x16x32_bf16 v[120:123], v[160:163], v[168:171], v[120:123]
	v_mfma_f32_16x16x32_bf16 v[108:111], v[152:155], v[182:185], v[108:111]
	v_mfma_f32_16x16x32_bf16 v[104:107], v[160:163], v[182:185], v[104:107]
	v_mfma_f32_16x16x32_bf16 v[92:95], v[152:155], v[194:197], v[92:95]
	v_mfma_f32_16x16x32_bf16 v[88:91], v[160:163], v[194:197], v[88:91]
	v_mfma_f32_16x16x32_bf16 v[76:79], v[152:155], v[202:205], v[76:79]
	v_mfma_f32_16x16x32_bf16 v[72:75], v[160:163], v[202:205], v[72:75]
	v_mfma_f32_16x16x32_bf16 v[124:127], v[156:159], v[172:175], v[124:127]
	v_mfma_f32_16x16x32_bf16 v[120:123], v[164:167], v[172:175], v[120:123]
	v_mfma_f32_16x16x32_bf16 v[108:111], v[156:159], v[190:193], v[108:111]
	v_mfma_f32_16x16x32_bf16 v[104:107], v[164:167], v[190:193], v[104:107]
	v_mfma_f32_16x16x32_bf16 v[92:95], v[156:159], v[198:201], v[92:95]
	v_mfma_f32_16x16x32_bf16 v[88:91], v[164:167], v[198:201], v[88:91]
	v_mfma_f32_16x16x32_bf16 v[76:79], v[156:159], v[206:209], v[76:79]
	v_mfma_f32_16x16x32_bf16 v[72:75], v[164:167], v[206:209], v[72:75]
	v_mfma_f32_16x16x32_bf16 v[116:119], v[210:213], v[168:171], v[116:119]
	v_mfma_f32_16x16x32_bf16 v[112:115], v[218:221], v[168:171], v[112:115]
	v_mfma_f32_16x16x32_bf16 v[100:103], v[210:213], v[182:185], v[100:103]
	v_mfma_f32_16x16x32_bf16 v[96:99], v[218:221], v[182:185], v[96:99]
	v_mfma_f32_16x16x32_bf16 v[84:87], v[210:213], v[194:197], v[84:87]
	v_mfma_f32_16x16x32_bf16 v[80:83], v[218:221], v[194:197], v[80:83]
	v_mfma_f32_16x16x32_bf16 v[68:71], v[210:213], v[202:205], v[68:71]
	v_mfma_f32_16x16x32_bf16 v[64:67], v[218:221], v[202:205], v[64:67]
	v_mfma_f32_16x16x32_bf16 v[116:119], v[214:217], v[172:175], v[116:119]
	v_mfma_f32_16x16x32_bf16 v[112:115], v[222:225], v[172:175], v[112:115]
	v_mfma_f32_16x16x32_bf16 v[100:103], v[214:217], v[190:193], v[100:103]
	v_mfma_f32_16x16x32_bf16 v[96:99], v[222:225], v[190:193], v[96:99]
	v_mfma_f32_16x16x32_bf16 v[84:87], v[214:217], v[198:201], v[84:87]
	v_mfma_f32_16x16x32_bf16 v[80:83], v[222:225], v[198:201], v[80:83]
	v_mfma_f32_16x16x32_bf16 v[68:71], v[214:217], v[206:209], v[68:71]
	v_mfma_f32_16x16x32_bf16 v[64:67], v[222:225], v[206:209], v[64:67]
	s_barrier
	ds_read_b128 v[168:171], v150 offset:49152
	ds_read_b128 v[172:175], v150 offset:50176
	ds_read_b128 v[182:185], v150 offset:51200
	ds_read_b128 v[190:193], v150 offset:52224
	ds_read_b128 v[194:197], v150 offset:53248
	ds_read_b128 v[198:201], v150 offset:54272
	ds_read_b128 v[202:205], v150 offset:55296
	ds_read_b128 v[206:209], v150 offset:56320
	s_add_i32 s18, s55, s31
	s_mov_b32 m0, s18
	s_nop 0
	global_load_lds_dwordx4 v130, s[98:99]
	s_nop 1
	s_add_i32 m0, s18, 0x2000
	s_nop 0
	global_load_lds_dwordx4 v134, s[98:99]
	s_nop 1
	s_mov_b32 m0, s39
	s_nop 0
	global_load_lds_dwordx4 v128, s[100:101]
	s_nop 1
	s_mov_b32 m0, s40
	s_nop 0
	global_load_lds_dwordx4 v132, s[100:101]
	s_add_u32 s18, s22, 0xb0080
	s_addc_u32 s19, s23, 0
	s_add_i32 s22, s24, s31
	s_mov_b32 m0, s22
	s_nop 0
	global_load_lds_dwordx4 v130, s[18:19]
	s_nop 1
	s_add_i32 m0, s22, 0x2000
	s_nop 0
	global_load_lds_dwordx4 v134, s[18:19]
	s_waitcnt vmcnt(8) lgkmcnt(0)
	s_barrier
	v_mfma_f32_16x16x32_bf16 v[60:63], v[152:155], v[168:171], v[60:63]
	v_mfma_f32_16x16x32_bf16 v[56:59], v[160:163], v[168:171], v[56:59]
	v_mfma_f32_16x16x32_bf16 v[48:51], v[152:155], v[182:185], v[48:51]
	v_mfma_f32_16x16x32_bf16 v[40:43], v[160:163], v[182:185], v[40:43]
	v_mfma_f32_16x16x32_bf16 v[32:35], v[152:155], v[194:197], v[32:35]
	v_mfma_f32_16x16x32_bf16 v[24:27], v[160:163], v[194:197], v[24:27]
	v_mfma_f32_16x16x32_bf16 v[16:19], v[152:155], v[202:205], v[16:19]
	v_mfma_f32_16x16x32_bf16 v[8:11], v[160:163], v[202:205], v[8:11]
	v_mfma_f32_16x16x32_bf16 v[60:63], v[156:159], v[172:175], v[60:63]
	v_mfma_f32_16x16x32_bf16 v[56:59], v[164:167], v[172:175], v[56:59]
	v_mfma_f32_16x16x32_bf16 v[48:51], v[156:159], v[190:193], v[48:51]
	v_mfma_f32_16x16x32_bf16 v[40:43], v[164:167], v[190:193], v[40:43]
	v_mfma_f32_16x16x32_bf16 v[32:35], v[156:159], v[198:201], v[32:35]
	v_mfma_f32_16x16x32_bf16 v[24:27], v[164:167], v[198:201], v[24:27]
	v_mfma_f32_16x16x32_bf16 v[16:19], v[156:159], v[206:209], v[16:19]
	v_mfma_f32_16x16x32_bf16 v[8:11], v[164:167], v[206:209], v[8:11]
	v_mfma_f32_16x16x32_bf16 v[52:55], v[210:213], v[168:171], v[52:55]
	v_mfma_f32_16x16x32_bf16 v[44:47], v[218:221], v[168:171], v[44:47]
	v_mfma_f32_16x16x32_bf16 v[36:39], v[210:213], v[182:185], v[36:39]
	v_mfma_f32_16x16x32_bf16 v[28:31], v[218:221], v[182:185], v[28:31]
	v_mfma_f32_16x16x32_bf16 v[20:23], v[210:213], v[194:197], v[20:23]
	v_mfma_f32_16x16x32_bf16 v[12:15], v[218:221], v[194:197], v[12:15]
	v_mfma_f32_16x16x32_bf16 v[4:7], v[210:213], v[202:205], v[4:7]
	v_mfma_f32_16x16x32_bf16 v[0:3], v[218:221], v[202:205], v[0:3]
	v_mfma_f32_16x16x32_bf16 v[52:55], v[214:217], v[172:175], v[52:55]
	v_mfma_f32_16x16x32_bf16 v[44:47], v[222:225], v[172:175], v[44:47]
	v_mfma_f32_16x16x32_bf16 v[36:39], v[214:217], v[190:193], v[36:39]
	v_mfma_f32_16x16x32_bf16 v[28:31], v[222:225], v[190:193], v[28:31]
	v_mfma_f32_16x16x32_bf16 v[20:23], v[214:217], v[198:201], v[20:23]
	v_mfma_f32_16x16x32_bf16 v[12:15], v[222:225], v[198:201], v[12:15]
	v_mfma_f32_16x16x32_bf16 v[4:7], v[214:217], v[206:209], v[4:7]
	v_mfma_f32_16x16x32_bf16 v[0:3], v[222:225], v[206:209], v[0:3]
	s_barrier
	s_add_i32 s54, s54, 2
	s_add_u32 s52, s52, 0x100
	s_addc_u32 s53, s53, 0
	s_cmp_gt_u32 s54, 41
	s_mov_b64 s[18:19], s[20:21]
; #define PG8_STAGE(bufoff, gbase, voff) do { _Pragma("unroll") for (int _i = 0; _i < 2; ++_i) \
;         __builtin_amdgcn_global_load_lds((const unsigned*)((const char*)(gbase) + (voff)[_i]), (PG8_LAS unsigned*)(lds + (bufoff) + ldsw + _i * 8192), 16, 0, 0); } while (0)
; #define PG8_LDA(dst, b, h) do { _Pragma("unroll") for (int m = 0; m < 4; ++m) _Pragma("unroll") for (int k = 0; k < 2; ++k) dst[m][k] = *(const PG8_LAS bf16x8*)(lds + PG8_SA(b, h) + aoff + m * 2048 + k * 1024); } while (0)
; #define PG8_LDB(dst, b, h) do { _Pragma("unroll") for (int n = 0; n < 2; ++n) _Pragma("unroll") for (int k = 0; k < 2; ++k) dst[n][k] = *(const PG8_LAS bf16x8*)(lds + PG8_SB(b, h) + boff + n * 2048 + k * 1024); } while (0)
; #define PG8_MMA(ai, bj, At, Bt) do { __builtin_amdgcn_s_setprio(1); _Pragma("unroll") for (int m = 0; m < 4; ++m) _Pragma("unroll") for (int n = 0; n < 2; ++n) _Pragma("unroll") for (int k = 0; k < 2; ++k) \
;         acc[ai][bj][m][n] = __builtin_amdgcn_mfma_f32_16x16x32_bf16(Bt[n][k], At[m][k], acc[ai][bj][m][n], 0, 0, 0); __builtin_amdgcn_s_setprio(0); } while (0)
; #define PG8_WAIT_V(n) asm volatile("s_waitcnt vmcnt(" #n ")" ::: "memory")
; #define PG8_WAIT_L(n) asm volatile("s_waitcnt lgkmcnt(" #n ")" ::: "memory")
; template <class Epi, class Sched>
; __device__ __forceinline__ void gemm_phase(PG8_LAS unsigned char* lds, const Gemm g, const Sched& S, const Epi& E) {
;     ...
;             const bool last = (t == nt - 2);
;             const char* a1 = cA + (size_t)(t + 1) * kstep;
;             const char* a2 = last ? nA : cA + (size_t)(t + 2) * kstep; const char* b2 = last ? nB : cB + (size_t)(t + 2) * kstep;
;             const char* a3 = a2 + kstep; const char* b3 = b2 + kstep;
;             if (last && has_next) S.a_ready(nxt);
;             PG8_LDB(B0, 0, 0); PG8_SCHED; PG8_LDA(At, 0, 0); PG8_STAGE(PG8_SA(1, 1), a1 + hstep, voffA);
;             PG8_WAIT_L(8); PG8_BAR; PG8_WAIT_L(0); PG8_MMA(0, 0, At, B0); PG8_BAR; PG8_SCHED;
;             PG8_LDB(B1, 0, 1); PG8_STAGE(PG8_SB(0, 0), b2, voffB);
;             PG8_BAR; PG8_WAIT_L(0); PG8_MMA(0, 1, At, B1); PG8_BAR;
;             PG8_LDA(At, 0, 1); PG8_STAGE(PG8_SA(0, 0), a2, voffA);
;             PG8_BAR; PG8_WAIT_L(0); PG8_MMA(1, 0, At, B0); PG8_BAR; PG8_SCHED;
;             PG8_STAGE(PG8_SB(0, 1), b2 + hstep, voffB);
;             PG8_WAIT_V(6); PG8_BAR; PG8_MMA(1, 1, At, B1); PG8_BAR;
.LBB0_1278:
	ds_read_b128 v[152:155], v149
	ds_read_b128 v[156:159], v149 offset:1024
	ds_read_b128 v[160:163], v149 offset:2048
	ds_read_b128 v[164:167], v149 offset:3072
	s_add_u32 s20, s18, 0x100
	s_addc_u32 s21, s19, 0
	s_cmp_eq_u32 s54, 40
	s_cselect_b32 s25, s1, s21
	s_cselect_b32 s24, s0, s20
	s_cselect_b32 s23, s5, s53
	s_cselect_b32 s22, s4, s52
	s_add_i32 m0, s34, 0xc000
	ds_read_b128 v[168:171], v150
	ds_read_b128 v[172:175], v150 offset:1024
	ds_read_b128 v[182:185], v150 offset:2048
	ds_read_b128 v[190:193], v150 offset:3072
	ds_read_b128 v[194:197], v150 offset:4096
	ds_read_b128 v[198:201], v150 offset:5120
	ds_read_b128 v[202:205], v150 offset:6144
	ds_read_b128 v[206:209], v150 offset:7168
	global_load_lds_dwordx4 v136, s[18:19]
	s_nop 1
	s_add_i32 m0, s34, 0xe000
	s_nop 0
	global_load_lds_dwordx4 v138, s[18:19]
	s_waitcnt lgkmcnt(12)
	ds_read_b128 v[210:213], v151
	ds_read_b128 v[214:217], v151 offset:1024
	ds_read_b128 v[218:221], v151 offset:2048
	ds_read_b128 v[222:225], v151 offset:3072
	s_waitcnt vmcnt(8) lgkmcnt(0)
	s_barrier
	v_mfma_f32_16x16x32_bf16 v[124:127], v[152:155], v[168:171], v[124:127]
	v_mfma_f32_16x16x32_bf16 v[120:123], v[160:163], v[168:171], v[120:123]
	v_mfma_f32_16x16x32_bf16 v[108:111], v[152:155], v[182:185], v[108:111]
	v_mfma_f32_16x16x32_bf16 v[104:107], v[160:163], v[182:185], v[104:107]
	v_mfma_f32_16x16x32_bf16 v[92:95], v[152:155], v[194:197], v[92:95]
	v_mfma_f32_16x16x32_bf16 v[88:91], v[160:163], v[194:197], v[88:91]
	v_mfma_f32_16x16x32_bf16 v[76:79], v[152:155], v[202:205], v[76:79]
	v_mfma_f32_16x16x32_bf16 v[72:75], v[160:163], v[202:205], v[72:75]
	v_mfma_f32_16x16x32_bf16 v[124:127], v[156:159], v[172:175], v[124:127]
	v_mfma_f32_16x16x32_bf16 v[120:123], v[164:167], v[172:175], v[120:123]
	v_mfma_f32_16x16x32_bf16 v[108:111], v[156:159], v[190:193], v[108:111]
	v_mfma_f32_16x16x32_bf16 v[104:107], v[164:167], v[190:193], v[104:107]
	v_mfma_f32_16x16x32_bf16 v[92:95], v[156:159], v[198:201], v[92:95]
	v_mfma_f32_16x16x32_bf16 v[88:91], v[164:167], v[198:201], v[88:91]
	v_mfma_f32_16x16x32_bf16 v[76:79], v[156:159], v[206:209], v[76:79]
	v_mfma_f32_16x16x32_bf16 v[72:75], v[164:167], v[206:209], v[72:75]
	v_mfma_f32_16x16x32_bf16 v[116:119], v[210:213], v[168:171], v[116:119]
	v_mfma_f32_16x16x32_bf16 v[112:115], v[218:221], v[168:171], v[112:115]
	v_mfma_f32_16x16x32_bf16 v[100:103], v[210:213], v[182:185], v[100:103]
	v_mfma_f32_16x16x32_bf16 v[96:99], v[218:221], v[182:185], v[96:99]
	v_mfma_f32_16x16x32_bf16 v[84:87], v[210:213], v[194:197], v[84:87]
	v_mfma_f32_16x16x32_bf16 v[80:83], v[218:221], v[194:197], v[80:83]
	v_mfma_f32_16x16x32_bf16 v[68:71], v[210:213], v[202:205], v[68:71]
	v_mfma_f32_16x16x32_bf16 v[64:67], v[218:221], v[202:205], v[64:67]
	v_mfma_f32_16x16x32_bf16 v[116:119], v[214:217], v[172:175], v[116:119]
	v_mfma_f32_16x16x32_bf16 v[112:115], v[222:225], v[172:175], v[112:115]
	v_mfma_f32_16x16x32_bf16 v[100:103], v[214:217], v[190:193], v[100:103]
	v_mfma_f32_16x16x32_bf16 v[96:99], v[222:225], v[190:193], v[96:99]
	v_mfma_f32_16x16x32_bf16 v[84:87], v[214:217], v[198:201], v[84:87]
	v_mfma_f32_16x16x32_bf16 v[80:83], v[222:225], v[198:201], v[80:83]
	v_mfma_f32_16x16x32_bf16 v[68:71], v[214:217], v[206:209], v[68:71]
	v_mfma_f32_16x16x32_bf16 v[64:67], v[222:225], v[206:209], v[64:67]
	s_barrier
	ds_read_b128 v[168:171], v150 offset:16384
	ds_read_b128 v[172:175], v150 offset:17408
	ds_read_b128 v[182:185], v150 offset:18432
	ds_read_b128 v[190:193], v150 offset:19456
	ds_read_b128 v[194:197], v150 offset:20480
	ds_read_b128 v[198:201], v150 offset:21504
	ds_read_b128 v[202:205], v150 offset:22528
	ds_read_b128 v[206:209], v150 offset:23552
	s_add_i32 s18, s42, s31
	s_add_u32 s98, s22, s8
	s_addc_u32 s99, s23, s9
	s_mov_b32 m0, s18
	s_nop 0
	global_load_lds_dwordx4 v130, s[22:23]
	s_nop 1
	s_add_i32 m0, s18, 0x2000
	s_nop 0
	global_load_lds_dwordx4 v134, s[22:23]
	s_nop 1
	s_mov_b32 m0, s34
	s_add_u32 s100, s24, s8
	s_addc_u32 s101, s25, s9
	global_load_lds_dwordx4 v128, s[24:25]
	s_nop 1
	s_mov_b32 m0, s35
	s_nop 0
	global_load_lds_dwordx4 v132, s[24:25]
	s_add_u32 s18, s22, 0xb0000
	s_addc_u32 s19, s23, 0
	s_add_i32 s55, s43, s31
	s_mov_b32 m0, s55
	s_nop 0
	global_load_lds_dwordx4 v130, s[18:19]
	s_nop 1
	s_add_i32 m0, s55, 0x2000
	s_nop 0
	global_load_lds_dwordx4 v134, s[18:19]
	s_waitcnt vmcnt(8) lgkmcnt(0)
	s_barrier
	v_mfma_f32_16x16x32_bf16 v[60:63], v[152:155], v[168:171], v[60:63]
	v_mfma_f32_16x16x32_bf16 v[56:59], v[160:163], v[168:171], v[56:59]
	v_mfma_f32_16x16x32_bf16 v[48:51], v[152:155], v[182:185], v[48:51]
	v_mfma_f32_16x16x32_bf16 v[40:43], v[160:163], v[182:185], v[40:43]
	v_mfma_f32_16x16x32_bf16 v[32:35], v[152:155], v[194:197], v[32:35]
	v_mfma_f32_16x16x32_bf16 v[24:27], v[160:163], v[194:197], v[24:27]
	v_mfma_f32_16x16x32_bf16 v[16:19], v[152:155], v[202:205], v[16:19]
	v_mfma_f32_16x16x32_bf16 v[8:11], v[160:163], v[202:205], v[8:11]
	v_mfma_f32_16x16x32_bf16 v[60:63], v[156:159], v[172:175], v[60:63]
	v_mfma_f32_16x16x32_bf16 v[56:59], v[164:167], v[172:175], v[56:59]
	v_mfma_f32_16x16x32_bf16 v[48:51], v[156:159], v[190:193], v[48:51]
	v_mfma_f32_16x16x32_bf16 v[40:43], v[164:167], v[190:193], v[40:43]
	v_mfma_f32_16x16x32_bf16 v[32:35], v[156:159], v[198:201], v[32:35]
	v_mfma_f32_16x16x32_bf16 v[24:27], v[164:167], v[198:201], v[24:27]
	v_mfma_f32_16x16x32_bf16 v[16:19], v[156:159], v[206:209], v[16:19]
	v_mfma_f32_16x16x32_bf16 v[8:11], v[164:167], v[206:209], v[8:11]
	v_mfma_f32_16x16x32_bf16 v[52:55], v[210:213], v[168:171], v[52:55]
	v_mfma_f32_16x16x32_bf16 v[44:47], v[218:221], v[168:171], v[44:47]
	v_mfma_f32_16x16x32_bf16 v[36:39], v[210:213], v[182:185], v[36:39]
	v_mfma_f32_16x16x32_bf16 v[28:31], v[218:221], v[182:185], v[28:31]
	v_mfma_f32_16x16x32_bf16 v[20:23], v[210:213], v[194:197], v[20:23]
	v_mfma_f32_16x16x32_bf16 v[12:15], v[218:221], v[194:197], v[12:15]
	v_mfma_f32_16x16x32_bf16 v[4:7], v[210:213], v[202:205], v[4:7]
	v_mfma_f32_16x16x32_bf16 v[0:3], v[218:221], v[202:205], v[0:3]
	v_mfma_f32_16x16x32_bf16 v[52:55], v[214:217], v[172:175], v[52:55]
	v_mfma_f32_16x16x32_bf16 v[44:47], v[222:225], v[172:175], v[44:47]
	v_mfma_f32_16x16x32_bf16 v[36:39], v[214:217], v[190:193], v[36:39]
	v_mfma_f32_16x16x32_bf16 v[28:31], v[222:225], v[190:193], v[28:31]
	v_mfma_f32_16x16x32_bf16 v[20:23], v[214:217], v[198:201], v[20:23]
	v_mfma_f32_16x16x32_bf16 v[12:15], v[222:225], v[198:201], v[12:15]
	v_mfma_f32_16x16x32_bf16 v[4:7], v[214:217], v[206:209], v[4:7]
	v_mfma_f32_16x16x32_bf16 v[0:3], v[222:225], v[206:209], v[0:3]
	s_barrier
; #define PG8_STAGE(bufoff, gbase, voff) do { _Pragma("unroll") for (int _i = 0; _i < 2; ++_i) \
;         __builtin_amdgcn_global_load_lds((const unsigned*)((const char*)(gbase) + (voff)[_i]), (PG8_LAS unsigned*)(lds + (bufoff) + ldsw + _i * 8192), 16, 0, 0); } while (0)
; #define PG8_LDA(dst, b, h) do { _Pragma("unroll") for (int m = 0; m < 4; ++m) _Pragma("unroll") for (int k = 0; k < 2; ++k) dst[m][k] = *(const PG8_LAS bf16x8*)(lds + PG8_SA(b, h) + aoff + m * 2048 + k * 1024); } while (0)
; #define PG8_LDB(dst, b, h) do { _Pragma("unroll") for (int n = 0; n < 2; ++n) _Pragma("unroll") for (int k = 0; k < 2; ++k) dst[n][k] = *(const PG8_LAS bf16x8*)(lds + PG8_SB(b, h) + boff + n * 2048 + k * 1024); } while (0)
; #define PG8_MMA(ai, bj, At, Bt) do { __builtin_amdgcn_s_setprio(1); _Pragma("unroll") for (int m = 0; m < 4; ++m) _Pragma("unroll") for (int n = 0; n < 2; ++n) _Pragma("unroll") for (int k = 0; k < 2; ++k) \
;         acc[ai][bj][m][n] = __builtin_amdgcn_mfma_f32_16x16x32_bf16(Bt[n][k], At[m][k], acc[ai][bj][m][n], 0, 0, 0); __builtin_amdgcn_s_setprio(0); } while (0)
; #define PG8_WAIT_V(n) asm volatile("s_waitcnt vmcnt(" #n ")" ::: "memory")
; #define PG8_WAIT_L(n) asm volatile("s_waitcnt lgkmcnt(" #n ")" ::: "memory")
; #define PG8_BAR __builtin_amdgcn_s_barrier()
; #define PG8_SCHED __builtin_amdgcn_sched_barrier(0)
; template <class Epi, class Sched>
; __device__ __forceinline__ void gemm_phase(PG8_LAS unsigned char* lds, const Gemm g, const Sched& S, const Epi& E) {
;     ...
;             PG8_LDB(B0, 1, 0); PG8_SCHED; PG8_LDA(At, 1, 0); PG8_STAGE(PG8_SA(0, 1), a2 + hstep, voffA);
;             PG8_WAIT_L(8); PG8_BAR; PG8_WAIT_L(0); PG8_MMA(0, 0, At, B0); PG8_BAR; PG8_SCHED;
;             PG8_LDB(B1, 1, 1); PG8_STAGE(PG8_SB(1, 0), b3, voffB);
;             PG8_BAR; PG8_WAIT_L(0); PG8_MMA(0, 1, At, B1); PG8_BAR;
;             PG8_LDA(At, 1, 1); PG8_STAGE(PG8_SA(1, 0), a3, voffA);
;             PG8_BAR; PG8_WAIT_L(0); PG8_MMA(1, 0, At, B0); PG8_BAR; PG8_SCHED;
;             PG8_STAGE(PG8_SB(1, 1), b3 + hstep, voffB);
;             PG8_WAIT_V(6); PG8_BAR; PG8_MMA(1, 1, At, B1); PG8_BAR;
	s_add_i32 s55, 0, 0x18000
	v_add_u32_e32 v164, s55, v147
	ds_read_b128 v[152:155], v164
	ds_read_b128 v[156:159], v164 offset:1024
	ds_read_b128 v[160:163], v164 offset:2048
	ds_read_b128 v[164:167], v164 offset:3072
	s_add_u32 s18, s24, 0xb0000
	s_addc_u32 s19, s25, 0
	s_mov_b32 m0, s36
	ds_read_b128 v[168:171], v150 offset:32768
	ds_read_b128 v[172:175], v150 offset:33792
	ds_read_b128 v[182:185], v150 offset:34816
	ds_read_b128 v[190:193], v150 offset:35840
	ds_read_b128 v[194:197], v150 offset:36864
	ds_read_b128 v[198:201], v150 offset:37888
	ds_read_b128 v[202:205], v150 offset:38912
	ds_read_b128 v[206:209], v150 offset:39936
	global_load_lds_dwordx4 v128, s[18:19]
	s_nop 1
	s_mov_b32 m0, s37
	s_nop 0
	global_load_lds_dwordx4 v132, s[18:19]
	s_add_i32 s24, 0, 0x1c000
	v_add_u32_e32 v179, s24, v147
	s_waitcnt lgkmcnt(12)
	ds_read_b128 v[210:213], v179
	ds_read_b128 v[214:217], v179 offset:1024
	ds_read_b128 v[218:221], v179 offset:2048
	ds_read_b128 v[222:225], v179 offset:3072
	s_waitcnt vmcnt(8) lgkmcnt(0)
	s_barrier
	v_mfma_f32_16x16x32_bf16 v[124:127], v[152:155], v[168:171], v[124:127]
	v_mfma_f32_16x16x32_bf16 v[120:123], v[160:163], v[168:171], v[120:123]
	v_mfma_f32_16x16x32_bf16 v[108:111], v[152:155], v[182:185], v[108:111]
	v_mfma_f32_16x16x32_bf16 v[104:107], v[160:163], v[182:185], v[104:107]
	v_mfma_f32_16x16x32_bf16 v[92:95], v[152:155], v[194:197], v[92:95]
	v_mfma_f32_16x16x32_bf16 v[88:91], v[160:163], v[194:197], v[88:91]
	v_mfma_f32_16x16x32_bf16 v[76:79], v[152:155], v[202:205], v[76:79]
	v_mfma_f32_16x16x32_bf16 v[72:75], v[160:163], v[202:205], v[72:75]
	v_mfma_f32_16x16x32_bf16 v[124:127], v[156:159], v[172:175], v[124:127]
	v_mfma_f32_16x16x32_bf16 v[120:123], v[164:167], v[172:175], v[120:123]
	v_mfma_f32_16x16x32_bf16 v[108:111], v[156:159], v[190:193], v[108:111]
	v_mfma_f32_16x16x32_bf16 v[104:107], v[164:167], v[190:193], v[104:107]
	v_mfma_f32_16x16x32_bf16 v[92:95], v[156:159], v[198:201], v[92:95]
	v_mfma_f32_16x16x32_bf16 v[88:91], v[164:167], v[198:201], v[88:91]
	v_mfma_f32_16x16x32_bf16 v[76:79], v[156:159], v[206:209], v[76:79]
	v_mfma_f32_16x16x32_bf16 v[72:75], v[164:167], v[206:209], v[72:75]
	v_mfma_f32_16x16x32_bf16 v[116:119], v[210:213], v[168:171], v[116:119]
	v_mfma_f32_16x16x32_bf16 v[112:115], v[218:221], v[168:171], v[112:115]
	v_mfma_f32_16x16x32_bf16 v[100:103], v[210:213], v[182:185], v[100:103]
	v_mfma_f32_16x16x32_bf16 v[96:99], v[218:221], v[182:185], v[96:99]
	v_mfma_f32_16x16x32_bf16 v[84:87], v[210:213], v[194:197], v[84:87]
	v_mfma_f32_16x16x32_bf16 v[80:83], v[218:221], v[194:197], v[80:83]
	v_mfma_f32_16x16x32_bf16 v[68:71], v[210:213], v[202:205], v[68:71]
	v_mfma_f32_16x16x32_bf16 v[64:67], v[218:221], v[202:205], v[64:67]
	v_mfma_f32_16x16x32_bf16 v[116:119], v[214:217], v[172:175], v[116:119]
	v_mfma_f32_16x16x32_bf16 v[112:115], v[222:225], v[172:175], v[112:115]
	v_mfma_f32_16x16x32_bf16 v[100:103], v[214:217], v[190:193], v[100:103]
	v_mfma_f32_16x16x32_bf16 v[96:99], v[222:225], v[190:193], v[96:99]
	v_mfma_f32_16x16x32_bf16 v[84:87], v[214:217], v[198:201], v[84:87]
	v_mfma_f32_16x16x32_bf16 v[80:83], v[222:225], v[198:201], v[80:83]
	v_mfma_f32_16x16x32_bf16 v[68:71], v[214:217], v[206:209], v[68:71]
	v_mfma_f32_16x16x32_bf16 v[64:67], v[222:225], v[206:209], v[64:67]
	s_barrier
	ds_read_b128 v[168:171], v150 offset:49152
	ds_read_b128 v[172:175], v150 offset:50176
	ds_read_b128 v[182:185], v150 offset:51200
	ds_read_b128 v[190:193], v150 offset:52224
	ds_read_b128 v[194:197], v150 offset:53248
	ds_read_b128 v[198:201], v150 offset:54272
	ds_read_b128 v[202:205], v150 offset:55296
	ds_read_b128 v[206:209], v150 offset:56320
	s_add_i32 s18, s55, s31
	s_mov_b32 m0, s18
	s_nop 0
	global_load_lds_dwordx4 v130, s[98:99]
	s_nop 1
	s_add_i32 m0, s18, 0x2000
	s_nop 0
	global_load_lds_dwordx4 v134, s[98:99]
	s_nop 1
	s_mov_b32 m0, s39
	s_nop 0
	global_load_lds_dwordx4 v128, s[100:101]
	s_nop 1
	s_mov_b32 m0, s40
	s_nop 0
	global_load_lds_dwordx4 v132, s[100:101]
	s_add_u32 s18, s22, 0xb0080
	s_addc_u32 s19, s23, 0
	s_add_i32 s22, s24, s31
	s_mov_b32 m0, s22
	s_nop 0
	global_load_lds_dwordx4 v130, s[18:19]
	s_nop 1
	s_add_i32 m0, s22, 0x2000
	s_nop 0
	global_load_lds_dwordx4 v134, s[18:19]
	s_waitcnt vmcnt(8) lgkmcnt(0)
	s_barrier
	v_mfma_f32_16x16x32_bf16 v[60:63], v[152:155], v[168:171], v[60:63]
	v_mfma_f32_16x16x32_bf16 v[56:59], v[160:163], v[168:171], v[56:59]
	v_mfma_f32_16x16x32_bf16 v[48:51], v[152:155], v[182:185], v[48:51]
	v_mfma_f32_16x16x32_bf16 v[40:43], v[160:163], v[182:185], v[40:43]
	v_mfma_f32_16x16x32_bf16 v[32:35], v[152:155], v[194:197], v[32:35]
	v_mfma_f32_16x16x32_bf16 v[24:27], v[160:163], v[194:197], v[24:27]
	v_mfma_f32_16x16x32_bf16 v[16:19], v[152:155], v[202:205], v[16:19]
	v_mfma_f32_16x16x32_bf16 v[8:11], v[160:163], v[202:205], v[8:11]
	v_mfma_f32_16x16x32_bf16 v[60:63], v[156:159], v[172:175], v[60:63]
	v_mfma_f32_16x16x32_bf16 v[56:59], v[164:167], v[172:175], v[56:59]
	v_mfma_f32_16x16x32_bf16 v[48:51], v[156:159], v[190:193], v[48:51]
	v_mfma_f32_16x16x32_bf16 v[40:43], v[164:167], v[190:193], v[40:43]
	v_mfma_f32_16x16x32_bf16 v[32:35], v[156:159], v[198:201], v[32:35]
	v_mfma_f32_16x16x32_bf16 v[24:27], v[164:167], v[198:201], v[24:27]
	v_mfma_f32_16x16x32_bf16 v[16:19], v[156:159], v[206:209], v[16:19]
	v_mfma_f32_16x16x32_bf16 v[8:11], v[164:167], v[206:209], v[8:11]
	v_mfma_f32_16x16x32_bf16 v[52:55], v[210:213], v[168:171], v[52:55]
	v_mfma_f32_16x16x32_bf16 v[44:47], v[218:221], v[168:171], v[44:47]
	v_mfma_f32_16x16x32_bf16 v[36:39], v[210:213], v[182:185], v[36:39]
	v_mfma_f32_16x16x32_bf16 v[28:31], v[218:221], v[182:185], v[28:31]
	v_mfma_f32_16x16x32_bf16 v[20:23], v[210:213], v[194:197], v[20:23]
	v_mfma_f32_16x16x32_bf16 v[12:15], v[218:221], v[194:197], v[12:15]
	v_mfma_f32_16x16x32_bf16 v[4:7], v[210:213], v[202:205], v[4:7]
	v_mfma_f32_16x16x32_bf16 v[0:3], v[218:221], v[202:205], v[0:3]
	v_mfma_f32_16x16x32_bf16 v[52:55], v[214:217], v[172:175], v[52:55]
	v_mfma_f32_16x16x32_bf16 v[44:47], v[222:225], v[172:175], v[44:47]
	v_mfma_f32_16x16x32_bf16 v[36:39], v[214:217], v[190:193], v[36:39]
	v_mfma_f32_16x16x32_bf16 v[28:31], v[222:225], v[190:193], v[28:31]
	v_mfma_f32_16x16x32_bf16 v[20:23], v[214:217], v[198:201], v[20:23]
	v_mfma_f32_16x16x32_bf16 v[12:15], v[222:225], v[198:201], v[12:15]
	v_mfma_f32_16x16x32_bf16 v[4:7], v[214:217], v[206:209], v[4:7]
	v_mfma_f32_16x16x32_bf16 v[0:3], v[222:225], v[206:209], v[0:3]
	s_barrier
; __device__ __forceinline__ unsigned cvt_pk_bf16(float lo, float hi) { unsigned r; asm volatile("v_cvt_pk_bf16_f32 %0, %1, %2" : "=v"(r) : "v"(lo), "v"(hi)); return r; }
; __device__ __forceinline__ float flogsig16(float x) { return (fminf(x, 0.f) - __logf(1.0f + __expf(-fabsf(x)))) * 0.0625f; }
;     __device__ __forceinline__ void operator()(const f32x4 (&acc)[2][2][4][2], const Unit& u, int wr, int wc, int fr, int fq) const {
;     ...
;         const int row0 = u.pm * BM + wr * 64 + fr, col0 = u.pn * BM + wc * 32 + 8 * fq, bcol0 = wc * 32 + 8 * fq;
;         f32x4 bv[2][2];
; #pragma unroll
;         for (int bj = 0; bj < 2; ++bj)
; #pragma unroll
;             for (int n = 0; n < 2; ++n) bv[bj][n] = bias ? *(const f32x4*)(bias + bcol0 + bj * HALF + 4 * n) : (f32x4){0.f, 0.f, 0.f, 0.f};
; #pragma unroll
;         for (int ai = 0; ai < 2; ++ai)
; #pragma unroll
;             for (int m = 0; m < 4; ++m) { bf16_t* rowp = O + (size_t)(row0 + ai * HALF + m * 16) * ldc + col0;
; #pragma unroll
;                 for (int bj = 0; bj < 2; ++bj) { f32x4 v0 = acc[ai][bj][m][0] + bv[bj][0], v1 = acc[ai][bj][m][1] + bv[bj][1];
;                     if (act == 1) {
; #pragma unroll
;                         for (int j = 0; j < 1; ++j) { v0 = v0 * sigmoid4(v0); v1 = v1 * sigmoid4(v1); } }
;                     else if (act == 2) {
; #pragma unroll
;                         for (int j = 0; j < 1; ++j) { v0 = sigmoid4(v0); v1 = sigmoid4(v1); } }
;                     else if (act == 3) {
; #pragma unroll
;                         for (int j = 0; j < 4; ++j) { v0[j] = flogsig16(v0[j]); v1[j] = flogsig16(v1[j]); } }
;                     u32x4 w; w.x = cvt_pk_bf16(v0[0], v0[1]); w.y = cvt_pk_bf16(v0[2], v0[3]); w.z = cvt_pk_bf16(v1[0], v1[1]); w.w = cvt_pk_bf16(v1[2], v1[3]);
;                     *(u32x4*)(rowp + bj * HALF) = w; } }
	s_add_i32 s54, s54, 2
	s_add_u32 s52, s52, 0x100
	s_addc_u32 s53, s53, 0
	s_cmp_gt_u32 s54, 41
	s_mov_b64 s[18:19], s[20:21]
	s_cbranch_scc0 .LBB0_1278
	v_lshl_add_u32 v152, s50, 8, v146
	v_lshl_or_b32 v144, s51, 8, v148
	v_ashrrev_i32_e32 v153, 31, v152
	v_ashrrev_i32_e32 v145, 31, v144
	v_lshlrev_b64 v[154:155], 11, v[152:153]
	v_lshl_add_u64 v[154:155], s[6:7], 0, v[154:155]
	v_lshlrev_b64 v[156:157], 1, v[144:145]
	v_lshl_add_u64 v[144:145], v[154:155], 0, v[156:157]
	v_pk_add_f32 v[126:127], v[126:127], 0 op_sel_hi:[1,0]
	v_pk_add_f32 v[124:125], v[124:125], 0 op_sel_hi:[1,0]
	v_pk_add_f32 v[154:155], v[122:123], 0 op_sel_hi:[1,0]
	v_pk_add_f32 v[122:123], v[120:121], 0 op_sel_hi:[1,0]
	v_cvt_pk_bf16_f32 v120, v124, v125
	v_cvt_pk_bf16_f32 v121, v126, v127
	v_pk_add_f32 v[116:117], v[116:117], 0 op_sel_hi:[1,0]
	v_cvt_pk_bf16_f32 v122, v122, v123
	v_cvt_pk_bf16_f32 v123, v154, v155
	global_store_dwordx4 v[144:145], v[120:123], off
	v_pk_add_f32 v[118:119], v[118:119], 0 op_sel_hi:[1,0]
	v_pk_add_f32 v[110:111], v[110:111], 0 op_sel_hi:[1,0]
	v_pk_add_f32 v[120:121], v[114:115], 0 op_sel_hi:[1,0]
	v_pk_add_f32 v[114:115], v[112:113], 0 op_sel_hi:[1,0]
	v_cvt_pk_bf16_f32 v112, v116, v117
	v_cvt_pk_bf16_f32 v113, v118, v119
	v_pk_add_f32 v[108:109], v[108:109], 0 op_sel_hi:[1,0]
	v_cvt_pk_bf16_f32 v114, v114, v115
	v_cvt_pk_bf16_f32 v115, v120, v121
	global_store_dwordx4 v[144:145], v[112:115], off offset:256
	v_pk_add_f32 v[100:101], v[100:101], 0 op_sel_hi:[1,0]
	v_pk_add_f32 v[102:103], v[102:103], 0 op_sel_hi:[1,0]
	v_or_b32_e32 v112, 16, v152
	v_ashrrev_i32_e32 v113, 31, v112
	v_lshlrev_b64 v[112:113], 11, v[112:113]
	v_lshl_add_u64 v[112:113], s[6:7], 0, v[112:113]
	v_lshl_add_u64 v[112:113], v[112:113], 0, v[156:157]
	v_pk_add_f32 v[114:115], v[106:107], 0 op_sel_hi:[1,0]
	v_pk_add_f32 v[106:107], v[104:105], 0 op_sel_hi:[1,0]
	v_cvt_pk_bf16_f32 v104, v108, v109
	v_cvt_pk_bf16_f32 v105, v110, v111
	v_pk_add_f32 v[94:95], v[94:95], 0 op_sel_hi:[1,0]
	v_cvt_pk_bf16_f32 v106, v106, v107
	v_cvt_pk_bf16_f32 v107, v114, v115
	global_store_dwordx4 v[112:113], v[104:107], off
	v_pk_add_f32 v[92:93], v[92:93], 0 op_sel_hi:[1,0]
	v_pk_add_f32 v[84:85], v[84:85], 0 op_sel_hi:[1,0]
	v_pk_add_f32 v[104:105], v[98:99], 0 op_sel_hi:[1,0]
	v_pk_add_f32 v[98:99], v[96:97], 0 op_sel_hi:[1,0]
	v_cvt_pk_bf16_f32 v96, v100, v101
	v_cvt_pk_bf16_f32 v97, v102, v103
	v_pk_add_f32 v[86:87], v[86:87], 0 op_sel_hi:[1,0]
	v_cvt_pk_bf16_f32 v98, v98, v99
	v_cvt_pk_bf16_f32 v99, v104, v105
	global_store_dwordx4 v[112:113], v[96:99], off offset:256
	v_pk_add_f32 v[78:79], v[78:79], 0 op_sel_hi:[1,0]
	v_pk_add_f32 v[76:77], v[76:77], 0 op_sel_hi:[1,0]
	v_or_b32_e32 v96, 32, v152
	v_ashrrev_i32_e32 v97, 31, v96
	v_lshlrev_b64 v[96:97], 11, v[96:97]
	v_lshl_add_u64 v[96:97], s[6:7], 0, v[96:97]
	v_lshl_add_u64 v[96:97], v[96:97], 0, v[156:157]
	v_pk_add_f32 v[98:99], v[90:91], 0 op_sel_hi:[1,0]
	v_pk_add_f32 v[90:91], v[88:89], 0 op_sel_hi:[1,0]
	v_cvt_pk_bf16_f32 v88, v92, v93
	v_cvt_pk_bf16_f32 v89, v94, v95
	v_pk_add_f32 v[70:71], v[70:71], 0 op_sel_hi:[1,0]
	v_cvt_pk_bf16_f32 v90, v90, v91
	v_cvt_pk_bf16_f32 v91, v98, v99
	global_store_dwordx4 v[96:97], v[88:91], off
	v_pk_add_f32 v[68:69], v[68:69], 0 op_sel_hi:[1,0]
	v_pk_add_f32 v[60:61], v[60:61], 0 op_sel_hi:[1,0]
	v_pk_add_f32 v[88:89], v[82:83], 0 op_sel_hi:[1,0]
	v_pk_add_f32 v[82:83], v[80:81], 0 op_sel_hi:[1,0]
	v_cvt_pk_bf16_f32 v80, v84, v85
	v_cvt_pk_bf16_f32 v81, v86, v87
	v_pk_add_f32 v[62:63], v[62:63], 0 op_sel_hi:[1,0]
	v_cvt_pk_bf16_f32 v82, v82, v83
	v_cvt_pk_bf16_f32 v83, v88, v89
	global_store_dwordx4 v[96:97], v[80:83], off offset:256
	v_pk_add_f32 v[54:55], v[54:55], 0 op_sel_hi:[1,0]
	v_pk_add_f32 v[52:53], v[52:53], 0 op_sel_hi:[1,0]
	v_or_b32_e32 v80, 48, v152
	v_ashrrev_i32_e32 v81, 31, v80
	v_lshlrev_b64 v[80:81], 11, v[80:81]
	v_lshl_add_u64 v[80:81], s[6:7], 0, v[80:81]
	v_lshl_add_u64 v[80:81], v[80:81], 0, v[156:157]
	v_pk_add_f32 v[82:83], v[74:75], 0 op_sel_hi:[1,0]
	v_pk_add_f32 v[74:75], v[72:73], 0 op_sel_hi:[1,0]
	v_cvt_pk_bf16_f32 v72, v76, v77
	v_cvt_pk_bf16_f32 v73, v78, v79
; __device__ __forceinline__ unsigned cvt_pk_bf16(float lo, float hi) { unsigned r; asm volatile("v_cvt_pk_bf16_f32 %0, %1, %2" : "=v"(r) : "v"(lo), "v"(hi)); return r; }
; __device__ __forceinline__ float flogsig16(float x) { return (fminf(x, 0.f) - __logf(1.0f + __expf(-fabsf(x)))) * 0.0625f; }
; #define PG8_WAIT_V(n) asm volatile("s_waitcnt vmcnt(" #n ")" ::: "memory")
; #define PG8_BAR __builtin_amdgcn_s_barrier()
;     __device__ __forceinline__ void operator()(const f32x4 (&acc)[2][2][4][2], const Unit& u, int wr, int wc, int fr, int fq) const {
;     ...
;             for (int m = 0; m < 4; ++m) { bf16_t* rowp = O + (size_t)(row0 + ai * HALF + m * 16) * ldc + col0;
; #pragma unroll
;                 for (int bj = 0; bj < 2; ++bj) { f32x4 v0 = acc[ai][bj][m][0] + bv[bj][0], v1 = acc[ai][bj][m][1] + bv[bj][1];
;                     if (act == 1) {
; #pragma unroll
;                         for (int j = 0; j < 1; ++j) { v0 = v0 * sigmoid4(v0); v1 = v1 * sigmoid4(v1); } }
;                     else if (act == 2) {
; #pragma unroll
;                         for (int j = 0; j < 1; ++j) { v0 = sigmoid4(v0); v1 = sigmoid4(v1); } }
;                     else if (act == 3) {
; #pragma unroll
;                         for (int j = 0; j < 4; ++j) { v0[j] = flogsig16(v0[j]); v1[j] = flogsig16(v1[j]); } }
;                     u32x4 w; w.x = cvt_pk_bf16(v0[0], v0[1]); w.y = cvt_pk_bf16(v0[2], v0[3]); w.z = cvt_pk_bf16(v1[0], v1[1]); w.w = cvt_pk_bf16(v1[2], v1[3]);
;                     *(u32x4*)(rowp + bj * HALF) = w; } }
; template <class Epi, class Sched>
; __device__ __forceinline__ void gemm_phase(PG8_LAS unsigned char* lds, const Gemm g, const Sched& S, const Epi& E) {
;     ...
;         if (!has_next) break;
; #pragma unroll
;         for (int a = 0; a < 2; ++a)
; #pragma unroll
;             for (int b = 0; b < 2; ++b)
; #pragma unroll
;                 for (int m = 0; m < 4; ++m)
; #pragma unroll
;                     for (int n = 0; n < 2; ++n) acc[a][b][m][n] = (f32x4){0.f, 0.f, 0.f, 0.f};
;         cur = nxt; cA = nA; cB = nB; ++ui;
;     }
;     PG8_WAIT_V(0);
;     if (wr == 0) PG8_BAR;
	v_pk_add_f32 v[48:49], v[48:49], 0 op_sel_hi:[1,0]
	v_cvt_pk_bf16_f32 v74, v74, v75
	v_cvt_pk_bf16_f32 v75, v82, v83
	global_store_dwordx4 v[80:81], v[72:75], off
	v_pk_add_f32 v[38:39], v[38:39], 0 op_sel_hi:[1,0]
	v_pk_add_f32 v[36:37], v[36:37], 0 op_sel_hi:[1,0]
	v_pk_add_f32 v[72:73], v[66:67], 0 op_sel_hi:[1,0]
	v_pk_add_f32 v[66:67], v[64:65], 0 op_sel_hi:[1,0]
	v_cvt_pk_bf16_f32 v64, v68, v69
	v_cvt_pk_bf16_f32 v65, v70, v71
	v_pk_add_f32 v[32:33], v[32:33], 0 op_sel_hi:[1,0]
	v_cvt_pk_bf16_f32 v66, v66, v67
	v_cvt_pk_bf16_f32 v67, v72, v73
	global_store_dwordx4 v[80:81], v[64:67], off offset:256
	v_pk_add_f32 v[22:23], v[22:23], 0 op_sel_hi:[1,0]
	v_pk_add_f32 v[20:21], v[20:21], 0 op_sel_hi:[1,0]
	v_pk_add_f32 v[66:67], v[58:59], 0 op_sel_hi:[1,0]
	v_pk_add_f32 v[58:59], v[56:57], 0 op_sel_hi:[1,0]
	v_cvt_pk_bf16_f32 v56, v60, v61
	v_add_co_u32_e32 v60, vcc, s44, v144
	v_cvt_pk_bf16_f32 v57, v62, v63
	v_cvt_pk_bf16_f32 v58, v58, v59
	v_cvt_pk_bf16_f32 v59, v66, v67
	v_lshl_add_u64 v[64:65], v[144:145], 0, s[10:11]
	s_nop 0
	v_addc_co_u32_e32 v61, vcc, 0, v145, vcc
	global_store_dwordx4 v[60:61], v[56:59], off
	v_pk_add_f32 v[16:17], v[16:17], 0 op_sel_hi:[1,0]
	s_mov_b32 s51, s48
	v_pk_add_f32 v[56:57], v[46:47], 0 op_sel_hi:[1,0]
	v_pk_add_f32 v[46:47], v[44:45], 0 op_sel_hi:[1,0]
	v_cvt_pk_bf16_f32 v44, v52, v53
	v_cvt_pk_bf16_f32 v45, v54, v55
	s_mov_b32 s50, s49
	v_cvt_pk_bf16_f32 v46, v46, v47
	v_cvt_pk_bf16_f32 v47, v56, v57
	global_store_dwordx4 v[64:65], v[44:47], off offset:256
	s_mov_b64 s[20:21], s[4:5]
	s_mov_b64 s[18:19], s[0:1]
	v_pk_add_f32 v[46:47], v[50:51], 0 op_sel_hi:[1,0]
	v_pk_add_f32 v[50:51], v[42:43], 0 op_sel_hi:[1,0]
	v_pk_add_f32 v[42:43], v[40:41], 0 op_sel_hi:[1,0]
	v_cvt_pk_bf16_f32 v40, v48, v49
	v_cvt_pk_bf16_f32 v41, v46, v47
	v_add_co_u32_e32 v46, vcc, s45, v144
	v_cvt_pk_bf16_f32 v42, v42, v43
	v_cvt_pk_bf16_f32 v43, v50, v51
	v_lshl_add_u64 v[44:45], v[144:145], 0, s[12:13]
	s_nop 0
	v_addc_co_u32_e32 v47, vcc, 0, v145, vcc
	global_store_dwordx4 v[46:47], v[40:43], off
	v_pk_add_f32 v[6:7], v[6:7], 0 op_sel_hi:[1,0]
	v_pk_add_f32 v[4:5], v[4:5], 0 op_sel_hi:[1,0]
	v_pk_add_f32 v[40:41], v[30:31], 0 op_sel_hi:[1,0]
	v_pk_add_f32 v[30:31], v[28:29], 0 op_sel_hi:[1,0]
	v_cvt_pk_bf16_f32 v28, v36, v37
	v_cvt_pk_bf16_f32 v29, v38, v39
	s_nop 0
	v_cvt_pk_bf16_f32 v30, v30, v31
	v_cvt_pk_bf16_f32 v31, v40, v41
	global_store_dwordx4 v[44:45], v[28:31], off offset:256
	s_nop 1
	v_pk_add_f32 v[30:31], v[34:35], 0 op_sel_hi:[1,0]
	v_pk_add_f32 v[34:35], v[26:27], 0 op_sel_hi:[1,0]
	v_pk_add_f32 v[26:27], v[24:25], 0 op_sel_hi:[1,0]
	v_cvt_pk_bf16_f32 v24, v32, v33
	v_cvt_pk_bf16_f32 v25, v30, v31
	v_add_co_u32_e32 v30, vcc, s46, v144
	v_cvt_pk_bf16_f32 v26, v26, v27
	v_cvt_pk_bf16_f32 v27, v34, v35
	v_lshl_add_u64 v[28:29], v[144:145], 0, s[14:15]
	s_nop 0
	v_addc_co_u32_e32 v31, vcc, 0, v145, vcc
	global_store_dwordx4 v[30:31], v[24:27], off
	s_nop 1
	v_pk_add_f32 v[24:25], v[14:15], 0 op_sel_hi:[1,0]
	v_pk_add_f32 v[14:15], v[12:13], 0 op_sel_hi:[1,0]
	v_cvt_pk_bf16_f32 v12, v20, v21
	v_cvt_pk_bf16_f32 v13, v22, v23
	s_nop 0
	v_cvt_pk_bf16_f32 v14, v14, v15
	v_cvt_pk_bf16_f32 v15, v24, v25
	global_store_dwordx4 v[28:29], v[12:15], off offset:256
	s_nop 1
	v_pk_add_f32 v[14:15], v[18:19], 0 op_sel_hi:[1,0]
	v_pk_add_f32 v[18:19], v[10:11], 0 op_sel_hi:[1,0]
	v_pk_add_f32 v[10:11], v[8:9], 0 op_sel_hi:[1,0]
	v_cvt_pk_bf16_f32 v8, v16, v17
	v_cvt_pk_bf16_f32 v9, v14, v15
	v_add_co_u32_e32 v14, vcc, s47, v144
	v_lshl_add_u64 v[12:13], v[144:145], 0, s[16:17]
	s_nop 0
	v_addc_co_u32_e32 v15, vcc, 0, v145, vcc
	v_cvt_pk_bf16_f32 v10, v10, v11
	v_cvt_pk_bf16_f32 v11, v18, v19
	global_store_dwordx4 v[14:15], v[8:11], off
	s_and_b64 vcc, exec, s[2:3]
	s_nop 0
	v_pk_add_f32 v[8:9], v[2:3], 0 op_sel_hi:[1,0]
	v_pk_add_f32 v[2:3], v[0:1], 0 op_sel_hi:[1,0]
	v_cvt_pk_bf16_f32 v0, v4, v5
	v_cvt_pk_bf16_f32 v1, v6, v7
	s_nop 0
	v_cvt_pk_bf16_f32 v2, v2, v3
	v_cvt_pk_bf16_f32 v3, v8, v9
	global_store_dwordx4 v[12:13], v[0:3], off offset:256
	s_cbranch_vccz .LBB0_1267
	s_waitcnt vmcnt(0)
	s_cmpk_gt_u32 s27, 0xff
	s_cbranch_scc1 .LBB0_1282
	s_barrier
